# instruction selection: 194 xor-16/xor-32 cross-lane reduction hops use v_permlane16/32_swap (VALU) instead of ds_bpermute LDS round trips
# speedup vs baseline: 1.0056x; 1.0004x over previous
.LBB0_95:
	s_mov_b32 s5, -1
	s_getreg_b32 s6, hwreg(HW_REG_HW_ID, 0, 6)
	s_and_b32 s6, s6, 63
	s_lshl_b32 s6, s6, 2
	s_add_i32 s6, s6, 0
	s_add_i32 s6, s6, 0x20200
	v_mov_b32_e32 v140, s6
	ds_read_b32 v140, v140
	v_mbcnt_lo_u32_b32 v142, s5, 0
	v_mbcnt_hi_u32_b32 v142, s5, v142
	v_bfrev_b32_e32 v144, 0.5
	s_mov_b64 s[8:9], -1
	s_waitcnt lgkmcnt(0)
	v_readfirstlane_b32 s5, v140
	s_nop 1
	v_lshl_add_u32 v142, s5, 6, v142
	v_and_b32_e32 v184, 63, v142
	v_and_b32_e32 v185, 3, v184
	v_lshrrev_b32_e32 v186, 2, v184
	v_and_b32_e32 v187, 60, v184
	v_lshl_or_b32 v169, v185, 6, v187
	v_and_b32_e32 v187, 15, v184
	v_lshrrev_b32_e32 v184, 4, v184
	v_sub_u32_e32 v186, v186, v187
	v_sub_u32_e32 v185, v185, v184
	v_lshlrev_b32_e32 v186, 7, v186
	v_lshl_add_u32 v170, v185, 4, v186
	v_ashrrev_i32_e32 v171, 31, v170
	s_lshl_b32 s5, s46, 8
	v_readfirstlane_b32 s10, v142
	s_ashr_i32 s6, s10, 2
	s_andn2_b32 s6, s6, 63
	v_bfe_u32 v140, v142, 4, 2
	s_cmp_gt_u32 s94, 3
	v_and_or_b32 v158, v142, 15, s6
	v_lshlrev_b32_e32 v143, 2, v140
	v_lshlrev_b32_e32 v142, 2, v142
	s_cselect_b64 s[6:7], -1, 0
	v_add_u32_e32 v162, s5, v158
	v_bitop3_b32 v168, v142, 64, v144 bitop3:0x6c
	v_bitop3_b32 v167, v142, s84, v144 bitop3:0x6c
	s_and_b64 vcc, exec, s[6:7]
	v_lshlrev_b32_e32 v160, 2, v143
	s_cbranch_vccz .LBB0_97
	v_ashrrev_i32_e32 v163, 31, v162
	v_lshlrev_b64 v[142:143], 6, v[162:163]
	v_lshl_add_u64 v[142:143], s[44:45], 0, v[142:143]
	v_mov_b32_e32 v161, v141
	v_lshl_add_u64 v[142:143], v[142:143], 0, v[160:161]
	flat_load_dwordx4 v[142:145], v[142:143]
	s_mov_b64 s[8:9], 0
	s_waitcnt vmcnt(0) lgkmcnt(0)
	v_mov_b32_e32 v146, v143
	v_mov_b32_e32 v147, v144
	v_mov_b32_e32 v143, v145
	v_pk_add_f32 v[142:143], v[146:147], v[142:143]
	s_nop 0
	v_add_f32_e32 v142, v142, v143
	v_mov_b32_e32 v143, v142
	s_nop 1
	v_permlane16_swap_b32_e32 v143, v142
	s_waitcnt lgkmcnt(0)
	v_add_f32_e32 v142, v142, v143
	ds_bpermute_b32 v143, v167, v142
	s_waitcnt lgkmcnt(0)
	v_add_f32_e32 v142, v142, v143
	v_fmamk_f32 v142, v142, 0x3a800000, v250
	v_rsq_f32_e32 v164, v142

.LBB0_99:
	s_lshr_b32 s8, s10, 1
	s_lshl_b32 s4, s4, 8
	s_and_b32 s9, s8, 64
	v_lshlrev_b32_e32 v140, 3, v140
	s_or_b32 s4, s9, s4
	v_and_or_b32 v140, s8, 32, v140
	s_lshl_b32 s8, s46, 6
	s_ashr_i32 s4, s4, 6
	s_waitcnt lgkmcnt(0)
	v_pk_mul_f32 v[122:123], v[122:123], v[164:165] op_sel_hi:[1,0]
	v_pk_mul_f32 v[120:121], v[120:121], v[164:165] op_sel_hi:[1,0]
	s_add_i32 s8, s4, s8
	v_pk_mul_f32 v[126:127], v[126:127], v[164:165] op_sel_hi:[1,0]
	v_pk_mul_f32 v[124:125], v[124:125], v[164:165] op_sel_hi:[1,0]
	v_max_f32_e32 v120, 0, v120
	v_max_f32_e32 v121, 0, v121
	v_max_f32_e32 v122, 0, v122
	s_ashr_i32 s9, s8, 31
	v_max_f32_e32 v124, 0, v124
	v_mul_f32_e32 v142, v120, v120
	v_max_f32_e32 v120, 0, v125
	v_mul_f32_e32 v125, v121, v121
	v_max_f32_e32 v121, 0, v126
	v_mul_f32_e32 v126, v122, v122
	v_max_f32_e32 v122, 0, v127
	s_lshl_b64 s[10:11], s[8:9], 15
	v_mul_f32_e32 v124, v124, v124
	v_mul_f32_e32 v120, v120, v120
	v_mul_f32_e32 v121, v121, v121
	v_max_f32_e32 v123, 0, v123
	v_mul_f32_e32 v122, v122, v122
	v_ashrrev_i32_e32 v159, 31, v158
	s_add_u32 s58, s86, s10
	v_mul_f32_e32 v123, v123, v123
	v_cvt_pk_bf16_f32 v120, v124, v120
	v_cvt_pk_bf16_f32 v121, v121, v122
	v_cvt_pk_bf16_f32 v122, v142, v125
	s_addc_u32 s59, s87, s11
	v_lshlrev_b64 v[124:125], 7, v[158:159]
	s_or_b32 s8, s8, 2
	v_cvt_pk_bf16_f32 v123, v126, v123
	v_lshl_add_u64 v[126:127], s[58:59], 0, v[124:125]
	v_lshlrev_b32_e32 v140, 1, v140
	v_pk_mul_f32 v[114:115], v[114:115], v[164:165] op_sel_hi:[1,0]
	v_pk_mul_f32 v[112:113], v[112:113], v[164:165] op_sel_hi:[1,0]
	s_ashr_i32 s9, s8, 31
	v_lshl_add_u64 v[126:127], v[126:127], 0, v[140:141]
	v_pk_mul_f32 v[118:119], v[118:119], v[164:165] op_sel_hi:[1,0]
	v_pk_mul_f32 v[116:117], v[116:117], v[164:165] op_sel_hi:[1,0]
	v_max_f32_e32 v112, 0, v112
	v_max_f32_e32 v113, 0, v113
	v_max_f32_e32 v114, 0, v114
	s_lshl_b64 s[8:9], s[8:9], 15
	ds_bpermute_b32 v172, v169, v120
	ds_bpermute_b32 v173, v169, v121
	ds_bpermute_b32 v174, v169, v122
	ds_bpermute_b32 v175, v169, v123
	v_lshl_add_u64 v[176:177], v[126:127], 0, v[170:171]
	v_max_f32_e32 v116, 0, v116
	s_add_u32 s74, s86, s8
	v_mul_f32_e32 v120, v112, v112
	v_max_f32_e32 v112, 0, v117
	v_mul_f32_e32 v117, v113, v113
	v_max_f32_e32 v113, 0, v118
	v_mul_f32_e32 v118, v114, v114
	v_max_f32_e32 v114, 0, v119
	v_mul_f32_e32 v116, v116, v116
	v_mul_f32_e32 v112, v112, v112
	v_mul_f32_e32 v113, v113, v113
	v_mul_f32_e32 v114, v114, v114
	s_addc_u32 s75, s87, s9
	v_max_f32_e32 v115, 0, v115
	v_cvt_pk_bf16_f32 v112, v116, v112
	v_cvt_pk_bf16_f32 v113, v113, v114
	v_cvt_pk_bf16_f32 v114, v120, v117
	v_lshl_add_u64 v[116:117], s[74:75], 0, v[124:125]
	v_mul_f32_e32 v115, v115, v115
	v_lshl_add_u64 v[116:117], v[116:117], 0, v[140:141]
	v_cvt_pk_bf16_f32 v115, v118, v115
	s_waitcnt lgkmcnt(0)
	global_store_dwordx4 v[176:177], v[172:175], off nt
	ds_bpermute_b32 v178, v169, v112
	ds_bpermute_b32 v179, v169, v113
	ds_bpermute_b32 v180, v169, v114
	ds_bpermute_b32 v181, v169, v115
	v_lshl_add_u64 v[182:183], v[116:117], 0, v[170:171]
	v_or_b32_e32 v116, 16, v162
	s_mov_b64 s[8:9], -1
	s_and_b64 vcc, exec, s[6:7]
	v_subrev_u32_e32 v113, s5, v116
	v_mov_b32_e32 v198, v220
	v_mov_b32_e32 v199, v221
	v_mov_b32_e32 v205, v223
	v_mov_b32_e32 v196, v224
	s_cbranch_vccz .LBB0_101
	v_ashrrev_i32_e32 v117, 31, v116
	v_lshlrev_b64 v[114:115], 6, v[116:117]
	v_lshl_add_u64 v[114:115], s[44:45], 0, v[114:115]
	v_mov_b32_e32 v161, v141
	v_lshl_add_u64 v[114:115], v[114:115], 0, v[160:161]
	flat_load_dwordx4 v[118:121], v[114:115]
	s_mov_b64 s[8:9], 0
	s_waitcnt vmcnt(0) lgkmcnt(0)
	v_mov_b32_e32 v114, v119
	v_mov_b32_e32 v115, v120
	v_mov_b32_e32 v119, v121
	v_pk_add_f32 v[114:115], v[114:115], v[118:119]
	s_nop 0
	v_add_f32_e32 v112, v114, v115
	v_mov_b32_e32 v114, v112
	s_nop 1
	v_permlane16_swap_b32_e32 v114, v112
	s_waitcnt lgkmcnt(0)
	v_add_f32_e32 v112, v112, v114
	v_mov_b32_e32 v114, v112
	s_nop 1
	v_permlane32_swap_b32_e32 v114, v112
	s_waitcnt lgkmcnt(0)
	v_add_f32_e32 v112, v112, v114
	v_fmamk_f32 v112, v112, 0x3a800000, v250
	v_rsq_f32_e32 v112, v112
	v_subrev_u32_e32 v114, s5, v116

.LBB0_103:
	s_waitcnt lgkmcnt(0)
	v_pk_mul_f32 v[106:107], v[106:107], v[112:113] op_sel_hi:[1,0]
	v_pk_mul_f32 v[104:105], v[104:105], v[112:113] op_sel_hi:[1,0]
	v_pk_mul_f32 v[110:111], v[110:111], v[112:113] op_sel_hi:[1,0]
	v_pk_mul_f32 v[108:109], v[108:109], v[112:113] op_sel_hi:[1,0]
	v_max_f32_e32 v104, 0, v104
	v_max_f32_e32 v105, 0, v105
	v_max_f32_e32 v106, 0, v106
	v_max_f32_e32 v108, 0, v108
	v_mul_f32_e32 v113, v104, v104
	v_max_f32_e32 v104, 0, v109
	v_mul_f32_e32 v109, v105, v105
	v_max_f32_e32 v105, 0, v110
	v_mul_f32_e32 v110, v106, v106
	v_max_f32_e32 v106, 0, v111
	v_mul_f32_e32 v108, v108, v108
	v_mul_f32_e32 v104, v104, v104
	v_mul_f32_e32 v105, v105, v105
	v_max_f32_e32 v107, 0, v107
	v_mul_f32_e32 v106, v106, v106
	v_ashrrev_i32_e32 v115, 31, v114
	v_mul_f32_e32 v107, v107, v107
	v_cvt_pk_bf16_f32 v104, v108, v104
	v_cvt_pk_bf16_f32 v105, v105, v106
	v_cvt_pk_bf16_f32 v106, v113, v109
	v_lshlrev_b64 v[108:109], 7, v[114:115]
	v_cvt_pk_bf16_f32 v107, v110, v107
	v_lshl_add_u64 v[110:111], s[58:59], 0, v[108:109]
	v_pk_mul_f32 v[98:99], v[98:99], v[112:113] op_sel_hi:[1,0]
	v_pk_mul_f32 v[96:97], v[96:97], v[112:113] op_sel_hi:[1,0]
	v_lshl_add_u64 v[110:111], v[110:111], 0, v[140:141]
	v_pk_mul_f32 v[102:103], v[102:103], v[112:113] op_sel_hi:[1,0]
	v_pk_mul_f32 v[100:101], v[100:101], v[112:113] op_sel_hi:[1,0]
	v_max_f32_e32 v96, 0, v96
	v_max_f32_e32 v97, 0, v97
	v_max_f32_e32 v98, 0, v98
	s_waitcnt lgkmcnt(0)
	global_store_dwordx4 v[182:183], v[178:181], off nt
	ds_bpermute_b32 v172, v169, v104
	ds_bpermute_b32 v173, v169, v105
	ds_bpermute_b32 v174, v169, v106
	ds_bpermute_b32 v175, v169, v107
	v_lshl_add_u64 v[176:177], v[110:111], 0, v[170:171]
	v_max_f32_e32 v100, 0, v100
	v_mul_f32_e32 v100, v100, v100
	v_mul_f32_e32 v104, v96, v96
	v_max_f32_e32 v96, 0, v101
	v_mul_f32_e32 v101, v97, v97
	v_max_f32_e32 v97, 0, v102
	v_mul_f32_e32 v102, v98, v98
	v_max_f32_e32 v98, 0, v103
	v_mul_f32_e32 v96, v96, v96
	v_mul_f32_e32 v97, v97, v97
	v_mul_f32_e32 v98, v98, v98
	v_max_f32_e32 v99, 0, v99
	v_cvt_pk_bf16_f32 v96, v100, v96
	v_cvt_pk_bf16_f32 v97, v97, v98
	v_cvt_pk_bf16_f32 v98, v104, v101
	v_lshl_add_u64 v[100:101], s[74:75], 0, v[108:109]
	v_mul_f32_e32 v99, v99, v99
	v_lshl_add_u64 v[100:101], v[100:101], 0, v[140:141]
	v_cvt_pk_bf16_f32 v99, v102, v99
	s_waitcnt lgkmcnt(0)
	global_store_dwordx4 v[176:177], v[172:175], off nt
	ds_bpermute_b32 v178, v169, v96
	ds_bpermute_b32 v179, v169, v97
	ds_bpermute_b32 v180, v169, v98
	ds_bpermute_b32 v181, v169, v99
	v_lshl_add_u64 v[182:183], v[100:101], 0, v[170:171]
	v_or_b32_e32 v100, 32, v162
	s_mov_b64 s[8:9], -1
	s_and_b64 vcc, exec, s[6:7]
	v_subrev_u32_e32 v97, s5, v100
	s_cbranch_vccz .LBB0_105
	v_ashrrev_i32_e32 v101, 31, v100
	v_lshlrev_b64 v[98:99], 6, v[100:101]
	v_lshl_add_u64 v[98:99], s[44:45], 0, v[98:99]
	v_mov_b32_e32 v161, v141
	v_lshl_add_u64 v[98:99], v[98:99], 0, v[160:161]
	flat_load_dwordx4 v[102:105], v[98:99]
	s_mov_b64 s[8:9], 0
	s_waitcnt vmcnt(0) lgkmcnt(0)
	v_mov_b32_e32 v98, v103
	v_mov_b32_e32 v99, v104
	v_mov_b32_e32 v103, v105
	v_pk_add_f32 v[98:99], v[98:99], v[102:103]
	s_nop 0
	v_add_f32_e32 v96, v98, v99
	v_mov_b32_e32 v98, v96
	s_nop 1
	v_permlane16_swap_b32_e32 v98, v96
	s_waitcnt lgkmcnt(0)
	v_add_f32_e32 v96, v96, v98
	v_mov_b32_e32 v98, v96
	s_nop 1
	v_permlane32_swap_b32_e32 v98, v96
	s_waitcnt lgkmcnt(0)
	v_add_f32_e32 v96, v96, v98
	v_fmamk_f32 v96, v96, 0x3a800000, v250
	v_rsq_f32_e32 v96, v96
	v_subrev_u32_e32 v98, s5, v100

.LBB0_107:
	s_waitcnt lgkmcnt(0)
	v_pk_mul_f32 v[90:91], v[90:91], v[96:97] op_sel_hi:[1,0]
	v_pk_mul_f32 v[88:89], v[88:89], v[96:97] op_sel_hi:[1,0]
	v_pk_mul_f32 v[94:95], v[94:95], v[96:97] op_sel_hi:[1,0]
	v_pk_mul_f32 v[92:93], v[92:93], v[96:97] op_sel_hi:[1,0]
	v_max_f32_e32 v88, 0, v88
	v_max_f32_e32 v89, 0, v89
	v_max_f32_e32 v90, 0, v90
	v_max_f32_e32 v92, 0, v92
	v_mul_f32_e32 v97, v88, v88
	v_max_f32_e32 v88, 0, v93
	v_mul_f32_e32 v93, v89, v89
	v_max_f32_e32 v89, 0, v94
	v_mul_f32_e32 v94, v90, v90
	v_max_f32_e32 v90, 0, v95
	v_mul_f32_e32 v92, v92, v92
	v_mul_f32_e32 v88, v88, v88
	v_mul_f32_e32 v89, v89, v89
	v_max_f32_e32 v91, 0, v91
	v_mul_f32_e32 v90, v90, v90
	v_ashrrev_i32_e32 v99, 31, v98
	v_mul_f32_e32 v91, v91, v91
	v_cvt_pk_bf16_f32 v88, v92, v88
	v_cvt_pk_bf16_f32 v89, v89, v90
	v_cvt_pk_bf16_f32 v90, v97, v93
	v_lshlrev_b64 v[92:93], 7, v[98:99]
	v_cvt_pk_bf16_f32 v91, v94, v91
	v_lshl_add_u64 v[94:95], s[58:59], 0, v[92:93]
	v_pk_mul_f32 v[82:83], v[82:83], v[96:97] op_sel_hi:[1,0]
	v_pk_mul_f32 v[80:81], v[80:81], v[96:97] op_sel_hi:[1,0]
	v_lshl_add_u64 v[94:95], v[94:95], 0, v[140:141]
	v_pk_mul_f32 v[86:87], v[86:87], v[96:97] op_sel_hi:[1,0]
	v_pk_mul_f32 v[84:85], v[84:85], v[96:97] op_sel_hi:[1,0]
	v_max_f32_e32 v80, 0, v80
	v_max_f32_e32 v81, 0, v81
	v_max_f32_e32 v82, 0, v82
	s_waitcnt lgkmcnt(0)
	global_store_dwordx4 v[182:183], v[178:181], off nt
	ds_bpermute_b32 v172, v169, v88
	ds_bpermute_b32 v173, v169, v89
	ds_bpermute_b32 v174, v169, v90
	ds_bpermute_b32 v175, v169, v91
	v_lshl_add_u64 v[176:177], v[94:95], 0, v[170:171]
	v_max_f32_e32 v84, 0, v84
	v_mul_f32_e32 v84, v84, v84
	v_mul_f32_e32 v88, v80, v80
	v_max_f32_e32 v80, 0, v85
	v_mul_f32_e32 v85, v81, v81
	v_max_f32_e32 v81, 0, v86
	v_mul_f32_e32 v86, v82, v82
	v_max_f32_e32 v82, 0, v87
	v_mul_f32_e32 v80, v80, v80
	v_mul_f32_e32 v81, v81, v81
	v_mul_f32_e32 v82, v82, v82
	v_max_f32_e32 v83, 0, v83
	v_cvt_pk_bf16_f32 v80, v84, v80
	v_cvt_pk_bf16_f32 v81, v81, v82
	v_cvt_pk_bf16_f32 v82, v88, v85
	v_lshl_add_u64 v[84:85], s[74:75], 0, v[92:93]
	v_mul_f32_e32 v83, v83, v83
	v_lshl_add_u64 v[84:85], v[84:85], 0, v[140:141]
	v_cvt_pk_bf16_f32 v83, v86, v83
	s_waitcnt lgkmcnt(0)
	global_store_dwordx4 v[176:177], v[172:175], off nt
	ds_bpermute_b32 v178, v169, v80
	ds_bpermute_b32 v179, v169, v81
	ds_bpermute_b32 v180, v169, v82
	ds_bpermute_b32 v181, v169, v83
	v_lshl_add_u64 v[182:183], v[84:85], 0, v[170:171]
	v_or_b32_e32 v84, 48, v162
	s_mov_b64 s[8:9], -1
	s_and_b64 vcc, exec, s[6:7]
	v_subrev_u32_e32 v81, s5, v84
	s_cbranch_vccz .LBB0_109
	v_ashrrev_i32_e32 v85, 31, v84
	v_lshlrev_b64 v[82:83], 6, v[84:85]
	v_lshl_add_u64 v[82:83], s[44:45], 0, v[82:83]
	v_mov_b32_e32 v161, v141
	v_lshl_add_u64 v[82:83], v[82:83], 0, v[160:161]
	flat_load_dwordx4 v[86:89], v[82:83]
	s_mov_b64 s[8:9], 0
	s_waitcnt vmcnt(0) lgkmcnt(0)
	v_mov_b32_e32 v82, v87
	v_mov_b32_e32 v83, v88
	v_mov_b32_e32 v87, v89
	v_pk_add_f32 v[82:83], v[82:83], v[86:87]
	s_nop 0
	v_add_f32_e32 v80, v82, v83
	v_mov_b32_e32 v82, v80
	s_nop 1
	v_permlane16_swap_b32_e32 v82, v80
	s_waitcnt lgkmcnt(0)
	v_add_f32_e32 v80, v80, v82
	v_mov_b32_e32 v82, v80
	s_nop 1
	v_permlane32_swap_b32_e32 v82, v80
	s_waitcnt lgkmcnt(0)
	v_add_f32_e32 v80, v80, v82
	v_fmamk_f32 v80, v80, 0x3a800000, v250
	v_rsq_f32_e32 v80, v80
	v_subrev_u32_e32 v82, s5, v84

.LBB0_111:
	s_waitcnt lgkmcnt(0)
	v_pk_mul_f32 v[74:75], v[74:75], v[80:81] op_sel_hi:[1,0]
	v_pk_mul_f32 v[72:73], v[72:73], v[80:81] op_sel_hi:[1,0]
	v_pk_mul_f32 v[78:79], v[78:79], v[80:81] op_sel_hi:[1,0]
	v_pk_mul_f32 v[76:77], v[76:77], v[80:81] op_sel_hi:[1,0]
	v_max_f32_e32 v72, 0, v72
	v_max_f32_e32 v73, 0, v73
	v_max_f32_e32 v74, 0, v74
	v_max_f32_e32 v76, 0, v76
	v_mul_f32_e32 v81, v72, v72
	v_max_f32_e32 v72, 0, v77
	v_mul_f32_e32 v77, v73, v73
	v_max_f32_e32 v73, 0, v78
	v_mul_f32_e32 v78, v74, v74
	v_max_f32_e32 v74, 0, v79
	v_mul_f32_e32 v76, v76, v76
	v_mul_f32_e32 v72, v72, v72
	v_mul_f32_e32 v73, v73, v73
	v_max_f32_e32 v75, 0, v75
	v_mul_f32_e32 v74, v74, v74
	v_ashrrev_i32_e32 v83, 31, v82
	v_mul_f32_e32 v75, v75, v75
	v_cvt_pk_bf16_f32 v72, v76, v72
	v_cvt_pk_bf16_f32 v73, v73, v74
	v_cvt_pk_bf16_f32 v74, v81, v77
	v_lshlrev_b64 v[76:77], 7, v[82:83]
	v_cvt_pk_bf16_f32 v75, v78, v75
	v_lshl_add_u64 v[78:79], s[58:59], 0, v[76:77]
	v_pk_mul_f32 v[66:67], v[66:67], v[80:81] op_sel_hi:[1,0]
	v_pk_mul_f32 v[64:65], v[64:65], v[80:81] op_sel_hi:[1,0]
	v_lshl_add_u64 v[78:79], v[78:79], 0, v[140:141]
	v_pk_mul_f32 v[70:71], v[70:71], v[80:81] op_sel_hi:[1,0]
	v_pk_mul_f32 v[68:69], v[68:69], v[80:81] op_sel_hi:[1,0]
	v_max_f32_e32 v64, 0, v64
	v_max_f32_e32 v65, 0, v65
	v_max_f32_e32 v66, 0, v66
	s_waitcnt lgkmcnt(0)
	global_store_dwordx4 v[182:183], v[178:181], off nt
	ds_bpermute_b32 v172, v169, v72
	ds_bpermute_b32 v173, v169, v73
	ds_bpermute_b32 v174, v169, v74
	ds_bpermute_b32 v175, v169, v75
	v_lshl_add_u64 v[176:177], v[78:79], 0, v[170:171]
	v_max_f32_e32 v68, 0, v68
	v_mul_f32_e32 v68, v68, v68
	v_mul_f32_e32 v72, v64, v64
	v_max_f32_e32 v64, 0, v69
	v_mul_f32_e32 v69, v65, v65
	v_max_f32_e32 v65, 0, v70
	v_mul_f32_e32 v70, v66, v66
	v_max_f32_e32 v66, 0, v71
	v_mul_f32_e32 v64, v64, v64
	v_mul_f32_e32 v65, v65, v65
	v_mul_f32_e32 v66, v66, v66
	v_max_f32_e32 v67, 0, v67
	v_cvt_pk_bf16_f32 v64, v68, v64
	v_cvt_pk_bf16_f32 v65, v65, v66
	v_cvt_pk_bf16_f32 v66, v72, v69
	v_lshl_add_u64 v[68:69], s[74:75], 0, v[76:77]
	v_mul_f32_e32 v67, v67, v67
	v_lshl_add_u64 v[68:69], v[68:69], 0, v[140:141]
	v_cvt_pk_bf16_f32 v67, v70, v67
	s_waitcnt lgkmcnt(0)
	global_store_dwordx4 v[176:177], v[172:175], off nt
	ds_bpermute_b32 v178, v169, v64
	ds_bpermute_b32 v179, v169, v65
	ds_bpermute_b32 v180, v169, v66
	ds_bpermute_b32 v181, v169, v67
	v_lshl_add_u64 v[182:183], v[68:69], 0, v[170:171]
	v_add_u32_e32 v68, 0x80, v162
	s_mov_b64 s[8:9], -1
	s_and_b64 vcc, exec, s[6:7]
	v_subrev_u32_e32 v65, s5, v68
	s_cbranch_vccz .LBB0_113
	v_ashrrev_i32_e32 v69, 31, v68
	v_lshlrev_b64 v[66:67], 6, v[68:69]
	v_lshl_add_u64 v[66:67], s[44:45], 0, v[66:67]
	v_mov_b32_e32 v161, v141
	v_lshl_add_u64 v[66:67], v[66:67], 0, v[160:161]
	flat_load_dwordx4 v[70:73], v[66:67]
	s_mov_b64 s[8:9], 0
	s_waitcnt vmcnt(0) lgkmcnt(0)
	v_mov_b32_e32 v66, v71
	v_mov_b32_e32 v67, v72
	v_mov_b32_e32 v71, v73
	v_pk_add_f32 v[66:67], v[66:67], v[70:71]
	s_nop 0
	v_add_f32_e32 v64, v66, v67
	v_mov_b32_e32 v66, v64
	s_nop 1
	v_permlane16_swap_b32_e32 v66, v64
	s_waitcnt lgkmcnt(0)
	v_add_f32_e32 v64, v64, v66
	v_mov_b32_e32 v66, v64
	s_nop 1
	v_permlane32_swap_b32_e32 v66, v64
	s_waitcnt lgkmcnt(0)
	v_add_f32_e32 v64, v64, v66
	v_fmamk_f32 v64, v64, 0x3a800000, v250
	v_rsq_f32_e32 v64, v64
	v_subrev_u32_e32 v66, s5, v68

.LBB0_115:
	s_waitcnt lgkmcnt(0)
	v_pk_mul_f32 v[58:59], v[58:59], v[64:65] op_sel_hi:[1,0]
	v_pk_mul_f32 v[56:57], v[56:57], v[64:65] op_sel_hi:[1,0]
	v_pk_mul_f32 v[62:63], v[62:63], v[64:65] op_sel_hi:[1,0]
	v_pk_mul_f32 v[60:61], v[60:61], v[64:65] op_sel_hi:[1,0]
	v_max_f32_e32 v56, 0, v56
	v_max_f32_e32 v57, 0, v57
	v_max_f32_e32 v58, 0, v58
	v_max_f32_e32 v60, 0, v60
	v_mul_f32_e32 v65, v56, v56
	v_max_f32_e32 v56, 0, v61
	v_mul_f32_e32 v61, v57, v57
	v_max_f32_e32 v57, 0, v62
	v_mul_f32_e32 v62, v58, v58
	v_max_f32_e32 v58, 0, v63
	v_mul_f32_e32 v60, v60, v60
	v_mul_f32_e32 v56, v56, v56
	v_mul_f32_e32 v57, v57, v57
	v_max_f32_e32 v59, 0, v59
	v_mul_f32_e32 v58, v58, v58
	v_ashrrev_i32_e32 v67, 31, v66
	v_mul_f32_e32 v59, v59, v59
	v_cvt_pk_bf16_f32 v56, v60, v56
	v_cvt_pk_bf16_f32 v57, v57, v58
	v_cvt_pk_bf16_f32 v58, v65, v61
	v_lshlrev_b64 v[60:61], 7, v[66:67]
	v_cvt_pk_bf16_f32 v59, v62, v59
	v_lshl_add_u64 v[62:63], s[58:59], 0, v[60:61]
	v_pk_mul_f32 v[50:51], v[50:51], v[64:65] op_sel_hi:[1,0]
	v_pk_mul_f32 v[48:49], v[48:49], v[64:65] op_sel_hi:[1,0]
	v_lshl_add_u64 v[62:63], v[62:63], 0, v[140:141]
	v_pk_mul_f32 v[54:55], v[54:55], v[64:65] op_sel_hi:[1,0]
	v_pk_mul_f32 v[52:53], v[52:53], v[64:65] op_sel_hi:[1,0]
	v_max_f32_e32 v48, 0, v48
	v_max_f32_e32 v49, 0, v49
	v_max_f32_e32 v50, 0, v50
	s_waitcnt lgkmcnt(0)
	global_store_dwordx4 v[182:183], v[178:181], off nt
	ds_bpermute_b32 v172, v169, v56
	ds_bpermute_b32 v173, v169, v57
	ds_bpermute_b32 v174, v169, v58
	ds_bpermute_b32 v175, v169, v59
	v_lshl_add_u64 v[176:177], v[62:63], 0, v[170:171]
	v_max_f32_e32 v52, 0, v52
	v_mul_f32_e32 v52, v52, v52
	v_mul_f32_e32 v56, v48, v48
	v_max_f32_e32 v48, 0, v53
	v_mul_f32_e32 v53, v49, v49
	v_max_f32_e32 v49, 0, v54
	v_mul_f32_e32 v54, v50, v50
	v_max_f32_e32 v50, 0, v55
	v_mul_f32_e32 v48, v48, v48
	v_mul_f32_e32 v49, v49, v49
	v_mul_f32_e32 v50, v50, v50
	v_max_f32_e32 v51, 0, v51
	v_cvt_pk_bf16_f32 v48, v52, v48
	v_cvt_pk_bf16_f32 v49, v49, v50
	v_cvt_pk_bf16_f32 v50, v56, v53
	v_lshl_add_u64 v[52:53], s[74:75], 0, v[60:61]
	v_mul_f32_e32 v51, v51, v51
	v_lshl_add_u64 v[52:53], v[52:53], 0, v[140:141]
	v_cvt_pk_bf16_f32 v51, v54, v51
	s_waitcnt lgkmcnt(0)
	global_store_dwordx4 v[176:177], v[172:175], off nt
	ds_bpermute_b32 v178, v169, v48
	ds_bpermute_b32 v179, v169, v49
	ds_bpermute_b32 v180, v169, v50
	ds_bpermute_b32 v181, v169, v51
	v_lshl_add_u64 v[182:183], v[52:53], 0, v[170:171]
	v_add_u32_e32 v52, 0x90, v162
	s_mov_b64 s[8:9], -1
	s_and_b64 vcc, exec, s[6:7]
	v_subrev_u32_e32 v49, s5, v52
	s_cbranch_vccz .LBB0_117
	v_ashrrev_i32_e32 v53, 31, v52
	v_lshlrev_b64 v[50:51], 6, v[52:53]
	v_lshl_add_u64 v[50:51], s[44:45], 0, v[50:51]
	v_mov_b32_e32 v161, v141
	v_lshl_add_u64 v[50:51], v[50:51], 0, v[160:161]
	flat_load_dwordx4 v[54:57], v[50:51]
	s_mov_b64 s[8:9], 0
	s_waitcnt vmcnt(0) lgkmcnt(0)
	v_mov_b32_e32 v50, v55
	v_mov_b32_e32 v51, v56
	v_mov_b32_e32 v55, v57
	v_pk_add_f32 v[50:51], v[50:51], v[54:55]
	s_nop 0
	v_add_f32_e32 v48, v50, v51
	v_mov_b32_e32 v50, v48
	s_nop 1
	v_permlane16_swap_b32_e32 v50, v48
	s_waitcnt lgkmcnt(0)
	v_add_f32_e32 v48, v48, v50
	v_mov_b32_e32 v50, v48
	s_nop 1
	v_permlane32_swap_b32_e32 v50, v48
	s_waitcnt lgkmcnt(0)
	v_add_f32_e32 v48, v48, v50
	v_fmamk_f32 v48, v48, 0x3a800000, v250
	v_rsq_f32_e32 v48, v48
	v_subrev_u32_e32 v50, s5, v52

.LBB0_119:
	s_waitcnt lgkmcnt(0)
	v_pk_mul_f32 v[42:43], v[42:43], v[48:49] op_sel_hi:[1,0]
	v_pk_mul_f32 v[40:41], v[40:41], v[48:49] op_sel_hi:[1,0]
	v_pk_mul_f32 v[46:47], v[46:47], v[48:49] op_sel_hi:[1,0]
	v_pk_mul_f32 v[44:45], v[44:45], v[48:49] op_sel_hi:[1,0]
	v_max_f32_e32 v40, 0, v40
	v_max_f32_e32 v41, 0, v41
	v_max_f32_e32 v42, 0, v42
	v_max_f32_e32 v44, 0, v44
	v_mul_f32_e32 v49, v40, v40
	v_max_f32_e32 v40, 0, v45
	v_mul_f32_e32 v45, v41, v41
	v_max_f32_e32 v41, 0, v46
	v_mul_f32_e32 v46, v42, v42
	v_max_f32_e32 v42, 0, v47
	v_mul_f32_e32 v44, v44, v44
	v_mul_f32_e32 v40, v40, v40
	v_mul_f32_e32 v41, v41, v41
	v_max_f32_e32 v43, 0, v43
	v_mul_f32_e32 v42, v42, v42
	v_ashrrev_i32_e32 v51, 31, v50
	v_mul_f32_e32 v43, v43, v43
	v_cvt_pk_bf16_f32 v40, v44, v40
	v_cvt_pk_bf16_f32 v41, v41, v42
	v_cvt_pk_bf16_f32 v42, v49, v45
	v_lshlrev_b64 v[44:45], 7, v[50:51]
	v_cvt_pk_bf16_f32 v43, v46, v43
	v_lshl_add_u64 v[46:47], s[58:59], 0, v[44:45]
	v_pk_mul_f32 v[34:35], v[34:35], v[48:49] op_sel_hi:[1,0]
	v_pk_mul_f32 v[32:33], v[32:33], v[48:49] op_sel_hi:[1,0]
	v_lshl_add_u64 v[46:47], v[46:47], 0, v[140:141]
	v_pk_mul_f32 v[38:39], v[38:39], v[48:49] op_sel_hi:[1,0]
	v_pk_mul_f32 v[36:37], v[36:37], v[48:49] op_sel_hi:[1,0]
	v_max_f32_e32 v32, 0, v32
	v_max_f32_e32 v33, 0, v33
	v_max_f32_e32 v34, 0, v34
	s_waitcnt lgkmcnt(0)
	global_store_dwordx4 v[182:183], v[178:181], off nt
	ds_bpermute_b32 v172, v169, v40
	ds_bpermute_b32 v173, v169, v41
	ds_bpermute_b32 v174, v169, v42
	ds_bpermute_b32 v175, v169, v43
	v_lshl_add_u64 v[176:177], v[46:47], 0, v[170:171]
	v_max_f32_e32 v36, 0, v36
	v_mul_f32_e32 v36, v36, v36
	v_mul_f32_e32 v40, v32, v32
	v_max_f32_e32 v32, 0, v37
	v_mul_f32_e32 v37, v33, v33
	v_max_f32_e32 v33, 0, v38
	v_mul_f32_e32 v38, v34, v34
	v_max_f32_e32 v34, 0, v39
	v_mul_f32_e32 v32, v32, v32
	v_mul_f32_e32 v33, v33, v33
	v_mul_f32_e32 v34, v34, v34
	v_max_f32_e32 v35, 0, v35
	v_cvt_pk_bf16_f32 v32, v36, v32
	v_cvt_pk_bf16_f32 v33, v33, v34
	v_cvt_pk_bf16_f32 v34, v40, v37
	v_lshl_add_u64 v[36:37], s[74:75], 0, v[44:45]
	v_mul_f32_e32 v35, v35, v35
	v_lshl_add_u64 v[36:37], v[36:37], 0, v[140:141]
	v_cvt_pk_bf16_f32 v35, v38, v35
	s_waitcnt lgkmcnt(0)
	global_store_dwordx4 v[176:177], v[172:175], off nt
	ds_bpermute_b32 v178, v169, v32
	ds_bpermute_b32 v179, v169, v33
	ds_bpermute_b32 v180, v169, v34
	ds_bpermute_b32 v181, v169, v35
	v_lshl_add_u64 v[182:183], v[36:37], 0, v[170:171]
	v_add_u32_e32 v36, 0xa0, v162
	s_mov_b64 s[8:9], -1
	s_and_b64 vcc, exec, s[6:7]
	v_subrev_u32_e32 v33, s5, v36
	s_cbranch_vccz .LBB0_121
	v_ashrrev_i32_e32 v37, 31, v36
	v_lshlrev_b64 v[34:35], 6, v[36:37]
	v_lshl_add_u64 v[34:35], s[44:45], 0, v[34:35]
	v_mov_b32_e32 v161, v141
	v_lshl_add_u64 v[34:35], v[34:35], 0, v[160:161]
	flat_load_dwordx4 v[38:41], v[34:35]
	s_mov_b64 s[8:9], 0
	s_waitcnt vmcnt(0) lgkmcnt(0)
	v_mov_b32_e32 v34, v39
	v_mov_b32_e32 v35, v40
	v_mov_b32_e32 v39, v41
	v_pk_add_f32 v[34:35], v[34:35], v[38:39]
	s_nop 0
	v_add_f32_e32 v32, v34, v35
	v_mov_b32_e32 v34, v32
	s_nop 1
	v_permlane16_swap_b32_e32 v34, v32
	s_waitcnt lgkmcnt(0)
	v_add_f32_e32 v32, v32, v34
	v_mov_b32_e32 v34, v32
	s_nop 1
	v_permlane32_swap_b32_e32 v34, v32
	s_waitcnt lgkmcnt(0)
	v_add_f32_e32 v32, v32, v34
	v_fmamk_f32 v32, v32, 0x3a800000, v250
	v_rsq_f32_e32 v32, v32
	v_subrev_u32_e32 v34, s5, v36

.LBB0_123:
	s_waitcnt lgkmcnt(0)
	v_pk_mul_f32 v[26:27], v[26:27], v[32:33] op_sel_hi:[1,0]
	v_pk_mul_f32 v[24:25], v[24:25], v[32:33] op_sel_hi:[1,0]
	v_pk_mul_f32 v[30:31], v[30:31], v[32:33] op_sel_hi:[1,0]
	v_pk_mul_f32 v[28:29], v[28:29], v[32:33] op_sel_hi:[1,0]
	v_max_f32_e32 v24, 0, v24
	v_max_f32_e32 v25, 0, v25
	v_max_f32_e32 v26, 0, v26
	v_max_f32_e32 v28, 0, v28
	v_mul_f32_e32 v33, v24, v24
	v_max_f32_e32 v24, 0, v29
	v_mul_f32_e32 v29, v25, v25
	v_max_f32_e32 v25, 0, v30
	v_mul_f32_e32 v30, v26, v26
	v_max_f32_e32 v26, 0, v31
	v_mul_f32_e32 v28, v28, v28
	v_mul_f32_e32 v24, v24, v24
	v_mul_f32_e32 v25, v25, v25
	v_max_f32_e32 v27, 0, v27
	v_mul_f32_e32 v26, v26, v26
	v_ashrrev_i32_e32 v35, 31, v34
	v_mul_f32_e32 v27, v27, v27
	v_cvt_pk_bf16_f32 v24, v28, v24
	v_cvt_pk_bf16_f32 v25, v25, v26
	v_cvt_pk_bf16_f32 v26, v33, v29
	v_lshlrev_b64 v[28:29], 7, v[34:35]
	v_cvt_pk_bf16_f32 v27, v30, v27
	v_lshl_add_u64 v[30:31], s[58:59], 0, v[28:29]
	v_pk_mul_f32 v[18:19], v[18:19], v[32:33] op_sel_hi:[1,0]
	v_pk_mul_f32 v[16:17], v[16:17], v[32:33] op_sel_hi:[1,0]
	v_lshl_add_u64 v[30:31], v[30:31], 0, v[140:141]
	v_pk_mul_f32 v[22:23], v[22:23], v[32:33] op_sel_hi:[1,0]
	v_pk_mul_f32 v[20:21], v[20:21], v[32:33] op_sel_hi:[1,0]
	v_max_f32_e32 v16, 0, v16
	v_max_f32_e32 v17, 0, v17
	v_max_f32_e32 v18, 0, v18
	s_waitcnt lgkmcnt(0)
	global_store_dwordx4 v[182:183], v[178:181], off nt
	ds_bpermute_b32 v172, v169, v24
	ds_bpermute_b32 v173, v169, v25
	ds_bpermute_b32 v174, v169, v26
	ds_bpermute_b32 v175, v169, v27
	v_lshl_add_u64 v[176:177], v[30:31], 0, v[170:171]
	v_max_f32_e32 v20, 0, v20
	v_mul_f32_e32 v20, v20, v20
	v_mul_f32_e32 v24, v16, v16
	v_max_f32_e32 v16, 0, v21
	v_mul_f32_e32 v21, v17, v17
	v_max_f32_e32 v17, 0, v22
	v_mul_f32_e32 v22, v18, v18
	v_max_f32_e32 v18, 0, v23
	v_mul_f32_e32 v16, v16, v16
	v_mul_f32_e32 v17, v17, v17
	v_mul_f32_e32 v18, v18, v18
	v_max_f32_e32 v19, 0, v19
	v_cvt_pk_bf16_f32 v16, v20, v16
	v_cvt_pk_bf16_f32 v17, v17, v18
	v_cvt_pk_bf16_f32 v18, v24, v21
	v_lshl_add_u64 v[20:21], s[74:75], 0, v[28:29]
	v_mul_f32_e32 v19, v19, v19
	v_lshl_add_u64 v[20:21], v[20:21], 0, v[140:141]
	v_cvt_pk_bf16_f32 v19, v22, v19
	s_waitcnt lgkmcnt(0)
	global_store_dwordx4 v[176:177], v[172:175], off nt
	ds_bpermute_b32 v178, v169, v16
	ds_bpermute_b32 v179, v169, v17
	ds_bpermute_b32 v180, v169, v18
	ds_bpermute_b32 v181, v169, v19
	v_lshl_add_u64 v[182:183], v[20:21], 0, v[170:171]
	v_add_u32_e32 v20, 0xb0, v162
	s_mov_b64 s[8:9], -1
	s_and_b64 vcc, exec, s[6:7]
	v_subrev_u32_e32 v17, s5, v20
	s_cbranch_vccz .LBB0_125
	v_ashrrev_i32_e32 v21, 31, v20
	v_lshlrev_b64 v[18:19], 6, v[20:21]
	v_lshl_add_u64 v[18:19], s[44:45], 0, v[18:19]
	v_mov_b32_e32 v161, v141
	v_lshl_add_u64 v[18:19], v[18:19], 0, v[160:161]
	flat_load_dwordx4 v[22:25], v[18:19]
	s_mov_b64 s[8:9], 0
	s_waitcnt vmcnt(0) lgkmcnt(0)
	v_mov_b32_e32 v18, v23
	v_mov_b32_e32 v19, v24
	v_mov_b32_e32 v23, v25
	v_pk_add_f32 v[18:19], v[18:19], v[22:23]
	s_nop 0
	v_add_f32_e32 v16, v18, v19
	v_mov_b32_e32 v18, v16
	s_nop 1
	v_permlane16_swap_b32_e32 v18, v16
	s_waitcnt lgkmcnt(0)
	v_add_f32_e32 v16, v16, v18
	v_mov_b32_e32 v18, v16
	s_nop 1
	v_permlane32_swap_b32_e32 v18, v16
	s_waitcnt lgkmcnt(0)
	v_add_f32_e32 v16, v16, v18
	v_fmamk_f32 v16, v16, 0x3a800000, v250
	v_rsq_f32_e32 v16, v16
	v_subrev_u32_e32 v18, s5, v20

.LBB0_150:
	s_mov_b32 s6, -1
	s_lshl_b32 s5, s5, 8
	v_mbcnt_lo_u32_b32 v128, s6, 0
	v_mbcnt_hi_u32_b32 v128, s6, v128
	s_getreg_b32 s6, hwreg(HW_REG_HW_ID, 0, 6)
	s_and_b32 s6, s6, 63
	s_lshl_b32 s6, s6, 2
	s_add_i32 s6, s6, 0
	s_add_i32 s6, s6, 0x20200
	v_mov_b32_e32 v129, s6
	ds_read_b32 v129, v129
	v_bfrev_b32_e32 v130, 0.5
	s_movk_i32 s84, 0x80
	s_lshl_b32 s74, s4, 2
	s_ashr_i32 s75, s74, 31
	s_waitcnt lgkmcnt(0)
	v_readfirstlane_b32 s6, v129
	s_nop 1
	v_lshl_add_u32 v128, s6, 6, v128
	s_nop 0
	v_readfirstlane_b32 s6, v128
	s_bfe_u32 s8, s6, 0x20006
	s_ashr_i32 s6, s6, 2
	s_andn2_b32 s6, s6, 63
	s_add_i32 s6, s6, s5
	v_and_or_b32 v170, v128, 15, s6
	s_lshl_b32 s5, s4, 8
	s_lshl_b32 s6, s8, 5
	v_bfe_u32 v129, v128, 4, 2
	s_or_b32 s5, s6, s5
	v_lshl_or_b32 v168, v129, 3, s5
	v_ashrrev_i32_e32 v169, 31, v168
	v_lshlrev_b64 v[146:147], 1, v[168:169]
	v_ashrrev_i32_e32 v171, 31, v170
	v_lshlrev_b32_e32 v128, 2, v128
	v_lshl_add_u64 v[172:173], s[68:69], 0, v[146:147]
	v_lshlrev_b64 v[148:149], 11, v[170:171]
	v_bitop3_b32 v180, v128, 64, v130 bitop3:0x6c
	v_bitop3_b32 v181, v128, s84, v130 bitop3:0x6c
	v_cmp_eq_u32_e32 vcc, 0, v129
	v_lshl_add_u64 v[128:129], v[172:173], 0, v[148:149]
	global_load_dwordx4 v[142:145], v[128:129], off
	global_load_dwordx4 v[136:139], v[128:129], off offset:256
	v_or_b32_e32 v174, 16, v170
	v_ashrrev_i32_e32 v175, 31, v174
	v_lshlrev_b64 v[176:177], 11, v[174:175]
	v_lshl_add_u64 v[128:129], v[172:173], 0, v[176:177]
	global_load_dwordx4 v[132:135], v[128:129], off
	s_nop 0
	global_load_dwordx4 v[128:131], v[128:129], off offset:256
	s_waitcnt vmcnt(0)
	v_lshlrev_b32_e32 v150, 16, v142
	v_and_b32_e32 v151, 0xffff0000, v142
	v_lshlrev_b32_e32 v142, 16, v143
	v_and_b32_e32 v143, 0xffff0000, v143
	v_lshlrev_b32_e32 v152, 16, v144
	v_and_b32_e32 v153, 0xffff0000, v144
	v_lshlrev_b32_e32 v144, 16, v145
	v_and_b32_e32 v145, 0xffff0000, v145
	v_pk_add_f32 v[124:125], v[124:125], v[150:151]
	v_pk_add_f32 v[126:127], v[126:127], v[142:143]
	v_pk_add_f32 v[142:143], v[122:123], v[144:145]
	v_pk_add_f32 v[122:123], v[120:121], v[152:153]
	v_cvt_pk_bf16_f32 v120, v124, v125
	v_lshl_add_u64 v[124:125], s[68:69], 0, v[148:149]
	v_lshl_add_u64 v[124:125], v[124:125], 0, v[146:147]
	v_cvt_pk_bf16_f32 v121, v126, v127
	v_cvt_pk_bf16_f32 v122, v122, v123
	v_cvt_pk_bf16_f32 v123, v142, v143
	global_store_dwordx4 v[124:125], v[120:123], off nt
	v_lshlrev_b32_e32 v126, 16, v120
	v_and_b32_e32 v127, 0xffff0000, v138
	v_and_b32_e32 v120, 0xffff0000, v120
	v_mul_f32_e32 v120, v120, v120
	v_fmac_f32_e32 v120, v126, v126
	v_lshlrev_b32_e32 v126, 16, v121
	v_and_b32_e32 v121, 0xffff0000, v121
	v_mul_f32_e32 v121, v121, v121
	v_fmac_f32_e32 v121, v126, v126
	v_add_f32_e32 v120, v120, v121
	v_lshlrev_b32_e32 v121, 16, v122
	v_and_b32_e32 v122, 0xffff0000, v122
	v_mul_f32_e32 v122, v122, v122
	v_fmac_f32_e32 v122, v121, v121
	v_add_f32_e32 v120, v120, v122
	v_and_b32_e32 v122, 0xffff0000, v123
	v_lshlrev_b32_e32 v121, 16, v123
	v_mul_f32_e32 v122, v122, v122
	v_fmac_f32_e32 v122, v121, v121
	v_add_f32_e32 v142, v120, v122
	v_lshlrev_b32_e32 v120, 16, v136
	v_and_b32_e32 v121, 0xffff0000, v136
	v_lshlrev_b32_e32 v122, 16, v137
	v_and_b32_e32 v123, 0xffff0000, v137
	v_lshlrev_b32_e32 v126, 16, v138
	v_lshlrev_b32_e32 v136, 16, v139
	v_and_b32_e32 v137, 0xffff0000, v139
	v_pk_add_f32 v[116:117], v[116:117], v[120:121]
	v_pk_add_f32 v[120:121], v[114:115], v[136:137]
	v_pk_add_f32 v[114:115], v[112:113], v[126:127]
	v_cvt_pk_bf16_f32 v112, v116, v117
	v_pk_add_f32 v[118:119], v[118:119], v[122:123]
	v_lshlrev_b32_e32 v116, 16, v112
	v_cvt_pk_bf16_f32 v113, v118, v119
	v_cvt_pk_bf16_f32 v114, v114, v115
	v_cvt_pk_bf16_f32 v115, v120, v121
	global_store_dwordx4 v[124:125], v[112:115], off offset:256 nt
	s_nop 1
	v_and_b32_e32 v112, 0xffff0000, v112
	v_mul_f32_e32 v112, v112, v112
	v_fmac_f32_e32 v112, v116, v116
	v_lshlrev_b32_e32 v116, 16, v113
	v_and_b32_e32 v113, 0xffff0000, v113
	v_mul_f32_e32 v113, v113, v113
	v_add_f32_e32 v112, v142, v112
	v_fmac_f32_e32 v113, v116, v116
	v_add_f32_e32 v112, v112, v113
	v_lshlrev_b32_e32 v113, 16, v114
	v_and_b32_e32 v114, 0xffff0000, v114
	v_mul_f32_e32 v114, v114, v114
	v_fmac_f32_e32 v114, v113, v113
	v_add_f32_e32 v112, v112, v114
	v_and_b32_e32 v114, 0xffff0000, v115
	v_lshlrev_b32_e32 v113, 16, v115
	v_mul_f32_e32 v114, v114, v114
	v_fmac_f32_e32 v114, v113, v113
	v_add_f32_e32 v112, v112, v114
	v_mov_b32_e32 v113, v112
	s_nop 1
	v_permlane16_swap_b32_e32 v113, v112
	s_waitcnt lgkmcnt(0)
	v_add_f32_e32 v112, v112, v113
	v_mov_b32_e32 v113, v112
	s_nop 1
	v_permlane32_swap_b32_e32 v113, v112
	s_and_saveexec_b64 s[6:7], vcc
	s_cbranch_execz .LBB0_152
	s_waitcnt lgkmcnt(0)
	v_add_f32_e32 v114, v112, v113
	v_lshlrev_b64 v[112:113], 6, v[170:171]
	v_lshl_add_u64 v[112:113], s[48:49], 0, v[112:113]
	v_lshl_add_u64 v[112:113], s[74:75], 2, v[112:113]
	s_lshl_b32 s38, s8, 2
	v_lshl_add_u64 v[112:113], v[112:113], 0, s[38:39]
	flat_store_dword v[112:113], v114
.LBB0_152:
	s_or_b64 exec, exec, s[6:7]
	v_lshlrev_b32_e32 v112, 16, v132
	s_waitcnt lgkmcnt(0)
	v_and_b32_e32 v113, 0xffff0000, v132
	v_lshlrev_b32_e32 v116, 16, v134
	v_and_b32_e32 v117, 0xffff0000, v134
	v_lshlrev_b32_e32 v118, 16, v135
	v_and_b32_e32 v119, 0xffff0000, v135
	v_pk_add_f32 v[108:109], v[108:109], v[112:113]
	v_lshlrev_b32_e32 v114, 16, v133
	v_and_b32_e32 v115, 0xffff0000, v133
	v_pk_add_f32 v[112:113], v[106:107], v[118:119]
	v_pk_add_f32 v[106:107], v[104:105], v[116:117]
	v_cvt_pk_bf16_f32 v104, v108, v109
	v_lshl_add_u64 v[108:109], s[68:69], 0, v[176:177]
	v_pk_add_f32 v[110:111], v[110:111], v[114:115]
	v_lshl_add_u64 v[108:109], v[168:169], 1, v[108:109]
	v_cvt_pk_bf16_f32 v105, v110, v111
	v_cvt_pk_bf16_f32 v106, v106, v107
	v_cvt_pk_bf16_f32 v107, v112, v113
	global_store_dwordx4 v[108:109], v[104:107], off nt
	v_lshlrev_b32_e32 v110, 16, v104
	v_and_b32_e32 v111, 0xffff0000, v130
	v_and_b32_e32 v104, 0xffff0000, v104
	v_mul_f32_e32 v104, v104, v104
	v_fmac_f32_e32 v104, v110, v110
	v_lshlrev_b32_e32 v110, 16, v105
	v_and_b32_e32 v105, 0xffff0000, v105
	v_mul_f32_e32 v105, v105, v105
	v_fmac_f32_e32 v105, v110, v110
	v_add_f32_e32 v104, v104, v105
	v_lshlrev_b32_e32 v105, 16, v106
	v_and_b32_e32 v106, 0xffff0000, v106
	v_mul_f32_e32 v106, v106, v106
	v_fmac_f32_e32 v106, v105, v105
	v_add_f32_e32 v104, v104, v106
	v_and_b32_e32 v106, 0xffff0000, v107
	v_lshlrev_b32_e32 v105, 16, v107
	v_mul_f32_e32 v106, v106, v106
	v_fmac_f32_e32 v106, v105, v105
	v_add_f32_e32 v114, v104, v106
	v_lshlrev_b32_e32 v104, 16, v128
	v_and_b32_e32 v105, 0xffff0000, v128
	v_lshlrev_b32_e32 v110, 16, v130
	v_lshlrev_b32_e32 v106, 16, v129
	v_and_b32_e32 v107, 0xffff0000, v129
	v_lshlrev_b32_e32 v112, 16, v131
	v_and_b32_e32 v113, 0xffff0000, v131
	v_pk_add_f32 v[100:101], v[100:101], v[104:105]
	v_pk_add_f32 v[96:97], v[96:97], v[110:111]
	v_pk_add_f32 v[102:103], v[102:103], v[106:107]
	v_pk_add_f32 v[104:105], v[98:99], v[112:113]
	v_cvt_pk_bf16_f32 v98, v100, v101
	v_cvt_pk_bf16_f32 v99, v102, v103
	v_cvt_pk_bf16_f32 v100, v96, v97
	s_nop 0
	v_and_b32_e32 v97, 0xffff0000, v98
	v_lshlrev_b32_e32 v96, 16, v98
	v_mul_f32_e32 v97, v97, v97
	v_fmac_f32_e32 v97, v96, v96
	v_and_b32_e32 v102, 0xffff0000, v99
	v_add_f32_e32 v96, v114, v97
	v_lshlrev_b32_e32 v97, 16, v99
	v_mul_f32_e32 v102, v102, v102
	v_fmac_f32_e32 v102, v97, v97
	v_add_f32_e32 v96, v96, v102
	v_and_b32_e32 v102, 0xffff0000, v100
	v_lshlrev_b32_e32 v97, 16, v100
	v_mul_f32_e32 v102, v102, v102
	v_fmac_f32_e32 v102, v97, v97
	v_cvt_pk_bf16_f32 v101, v104, v105
	v_add_f32_e32 v96, v96, v102
	v_and_b32_e32 v102, 0xffff0000, v101
	v_lshlrev_b32_e32 v97, 16, v101
	v_mul_f32_e32 v102, v102, v102
	v_fmac_f32_e32 v102, v97, v97
	v_add_f32_e32 v96, v96, v102
	v_mov_b32_e32 v97, v96
	s_nop 1
	v_permlane16_swap_b32_e32 v97, v96
	global_store_dwordx4 v[108:109], v[98:101], off offset:256 nt
	s_waitcnt lgkmcnt(0)
	v_add_f32_e32 v96, v96, v97
	v_mov_b32_e32 v97, v96
	s_nop 1
	v_permlane32_swap_b32_e32 v97, v96
	s_and_saveexec_b64 s[6:7], vcc
	s_cbranch_execz .LBB0_154
	s_waitcnt lgkmcnt(0)
	v_add_f32_e32 v98, v96, v97
	v_lshlrev_b64 v[96:97], 6, v[174:175]
	v_lshl_add_u64 v[96:97], s[48:49], 0, v[96:97]
	v_lshl_add_u64 v[96:97], s[74:75], 2, v[96:97]
	s_lshl_b32 s38, s8, 2
	v_lshl_add_u64 v[96:97], v[96:97], 0, s[38:39]
	flat_store_dword v[96:97], v98
.LBB0_154:
	s_or_b64 exec, exec, s[6:7]
	v_or_b32_e32 v112, 32, v170
	v_ashrrev_i32_e32 v113, 31, v112
	v_lshlrev_b64 v[118:119], 11, v[112:113]
	s_waitcnt lgkmcnt(0)
	v_lshl_add_u64 v[96:97], v[172:173], 0, v[118:119]
	global_load_dwordx4 v[114:117], v[96:97], off
	global_load_dwordx4 v[104:107], v[96:97], off offset:256
	v_or_b32_e32 v108, 48, v170
	v_ashrrev_i32_e32 v109, 31, v108
	v_lshlrev_b64 v[110:111], 11, v[108:109]
	v_lshl_add_u64 v[96:97], v[172:173], 0, v[110:111]
	global_load_dwordx4 v[100:103], v[96:97], off
	s_nop 0
	global_load_dwordx4 v[96:99], v[96:97], off offset:256
	s_waitcnt vmcnt(0)
	v_lshlrev_b32_e32 v120, 16, v114
	v_and_b32_e32 v121, 0xffff0000, v114
	v_lshlrev_b32_e32 v114, 16, v115
	v_and_b32_e32 v115, 0xffff0000, v115
	v_lshlrev_b32_e32 v122, 16, v116
	v_and_b32_e32 v123, 0xffff0000, v116
	v_lshlrev_b32_e32 v116, 16, v117
	v_and_b32_e32 v117, 0xffff0000, v117
	v_pk_add_f32 v[92:93], v[92:93], v[120:121]
	v_pk_add_f32 v[94:95], v[94:95], v[114:115]
	v_pk_add_f32 v[114:115], v[90:91], v[116:117]
	v_pk_add_f32 v[90:91], v[88:89], v[122:123]
	v_cvt_pk_bf16_f32 v88, v92, v93
	v_lshl_add_u64 v[92:93], s[68:69], 0, v[118:119]
	v_lshl_add_u64 v[92:93], v[168:169], 1, v[92:93]
	v_cvt_pk_bf16_f32 v89, v94, v95
	v_cvt_pk_bf16_f32 v90, v90, v91
	v_cvt_pk_bf16_f32 v91, v114, v115
	global_store_dwordx4 v[92:93], v[88:91], off nt
	v_lshlrev_b32_e32 v94, 16, v88
	v_and_b32_e32 v95, 0xffff0000, v106
	v_and_b32_e32 v88, 0xffff0000, v88
	v_mul_f32_e32 v88, v88, v88
	v_fmac_f32_e32 v88, v94, v94
	v_lshlrev_b32_e32 v94, 16, v89
	v_and_b32_e32 v89, 0xffff0000, v89
	v_mul_f32_e32 v89, v89, v89
	v_fmac_f32_e32 v89, v94, v94
	v_add_f32_e32 v88, v88, v89
	v_lshlrev_b32_e32 v89, 16, v90
	v_and_b32_e32 v90, 0xffff0000, v90
	v_mul_f32_e32 v90, v90, v90
	v_fmac_f32_e32 v90, v89, v89
	v_add_f32_e32 v88, v88, v90
	v_and_b32_e32 v90, 0xffff0000, v91
	v_lshlrev_b32_e32 v89, 16, v91
	v_mul_f32_e32 v90, v90, v90
	v_fmac_f32_e32 v90, v89, v89
	v_add_f32_e32 v114, v88, v90
	v_lshlrev_b32_e32 v88, 16, v104
	v_and_b32_e32 v89, 0xffff0000, v104
	v_lshlrev_b32_e32 v90, 16, v105
	v_and_b32_e32 v91, 0xffff0000, v105
	v_lshlrev_b32_e32 v94, 16, v106
	v_lshlrev_b32_e32 v104, 16, v107
	v_and_b32_e32 v105, 0xffff0000, v107
	v_pk_add_f32 v[84:85], v[84:85], v[88:89]
	v_pk_add_f32 v[88:89], v[82:83], v[104:105]
	v_pk_add_f32 v[82:83], v[80:81], v[94:95]
	v_cvt_pk_bf16_f32 v80, v84, v85
	v_pk_add_f32 v[86:87], v[86:87], v[90:91]
	v_lshlrev_b32_e32 v84, 16, v80
	v_cvt_pk_bf16_f32 v81, v86, v87
	v_cvt_pk_bf16_f32 v82, v82, v83
	v_cvt_pk_bf16_f32 v83, v88, v89
	global_store_dwordx4 v[92:93], v[80:83], off offset:256 nt
	s_nop 1
	v_and_b32_e32 v80, 0xffff0000, v80
	v_mul_f32_e32 v80, v80, v80
	v_fmac_f32_e32 v80, v84, v84
	v_lshlrev_b32_e32 v84, 16, v81
	v_and_b32_e32 v81, 0xffff0000, v81
	v_mul_f32_e32 v81, v81, v81
	v_add_f32_e32 v80, v114, v80
	v_fmac_f32_e32 v81, v84, v84
	v_add_f32_e32 v80, v80, v81
	v_lshlrev_b32_e32 v81, 16, v82
	v_and_b32_e32 v82, 0xffff0000, v82
	v_mul_f32_e32 v82, v82, v82
	v_fmac_f32_e32 v82, v81, v81
	v_add_f32_e32 v80, v80, v82
	v_and_b32_e32 v82, 0xffff0000, v83
	v_lshlrev_b32_e32 v81, 16, v83
	v_mul_f32_e32 v82, v82, v82
	v_fmac_f32_e32 v82, v81, v81
	v_add_f32_e32 v80, v80, v82
	v_mov_b32_e32 v81, v80
	s_nop 1
	v_permlane16_swap_b32_e32 v81, v80
	s_waitcnt lgkmcnt(0)
	v_add_f32_e32 v80, v80, v81
	v_mov_b32_e32 v81, v80
	s_nop 1
	v_permlane32_swap_b32_e32 v81, v80
	s_mov_b64 s[6:7], exec
	s_and_b64 s[4:5], s[6:7], vcc
	v_mov_b32_e32 v198, v216
	v_mov_b32_e32 v199, v217
	v_mov_b32_e32 v248, v218
	v_mov_b32_e32 v205, v219
	v_mov_b32_e32 v196, v220
	s_mov_b64 exec, s[4:5]
	s_cbranch_execz .LBB0_156
	s_waitcnt lgkmcnt(0)
	v_add_f32_e32 v82, v80, v81
	v_lshlrev_b64 v[80:81], 6, v[112:113]
	v_lshl_add_u64 v[80:81], s[48:49], 0, v[80:81]
	v_lshl_add_u64 v[80:81], s[74:75], 2, v[80:81]
	s_lshl_b32 s38, s8, 2
	v_lshl_add_u64 v[80:81], v[80:81], 0, s[38:39]
	flat_store_dword v[80:81], v82
.LBB0_156:
	s_or_b64 exec, exec, s[6:7]
	v_lshlrev_b32_e32 v80, 16, v100
	s_waitcnt lgkmcnt(0)
	v_and_b32_e32 v81, 0xffff0000, v100
	v_lshlrev_b32_e32 v84, 16, v102
	v_and_b32_e32 v85, 0xffff0000, v102
	v_lshlrev_b32_e32 v86, 16, v103
	v_and_b32_e32 v87, 0xffff0000, v103
	v_pk_add_f32 v[76:77], v[76:77], v[80:81]
	v_lshlrev_b32_e32 v82, 16, v101
	v_and_b32_e32 v83, 0xffff0000, v101
	v_pk_add_f32 v[80:81], v[74:75], v[86:87]
	v_pk_add_f32 v[74:75], v[72:73], v[84:85]
	v_cvt_pk_bf16_f32 v72, v76, v77
	v_lshl_add_u64 v[76:77], s[68:69], 0, v[110:111]
	v_pk_add_f32 v[78:79], v[78:79], v[82:83]
	v_lshl_add_u64 v[76:77], v[168:169], 1, v[76:77]
	v_cvt_pk_bf16_f32 v73, v78, v79
	v_cvt_pk_bf16_f32 v74, v74, v75
	v_cvt_pk_bf16_f32 v75, v80, v81
	global_store_dwordx4 v[76:77], v[72:75], off nt
	v_lshlrev_b32_e32 v78, 16, v72
	v_and_b32_e32 v79, 0xffff0000, v98
	v_and_b32_e32 v72, 0xffff0000, v72
	v_mul_f32_e32 v72, v72, v72
	v_fmac_f32_e32 v72, v78, v78
	v_lshlrev_b32_e32 v78, 16, v73
	v_and_b32_e32 v73, 0xffff0000, v73
	v_mul_f32_e32 v73, v73, v73
	v_fmac_f32_e32 v73, v78, v78
	v_add_f32_e32 v72, v72, v73
	v_lshlrev_b32_e32 v73, 16, v74
	v_and_b32_e32 v74, 0xffff0000, v74
	v_mul_f32_e32 v74, v74, v74
	v_fmac_f32_e32 v74, v73, v73
	v_add_f32_e32 v72, v72, v74
	v_and_b32_e32 v74, 0xffff0000, v75
	v_lshlrev_b32_e32 v73, 16, v75
	v_mul_f32_e32 v74, v74, v74
	v_fmac_f32_e32 v74, v73, v73
	v_add_f32_e32 v82, v72, v74
	v_lshlrev_b32_e32 v72, 16, v96
	v_and_b32_e32 v73, 0xffff0000, v96
	v_lshlrev_b32_e32 v78, 16, v98
	v_lshlrev_b32_e32 v74, 16, v97
	v_and_b32_e32 v75, 0xffff0000, v97
	v_lshlrev_b32_e32 v80, 16, v99
	v_and_b32_e32 v81, 0xffff0000, v99
	v_pk_add_f32 v[68:69], v[68:69], v[72:73]
	v_pk_add_f32 v[64:65], v[64:65], v[78:79]
	v_pk_add_f32 v[70:71], v[70:71], v[74:75]
	v_pk_add_f32 v[72:73], v[66:67], v[80:81]
	v_cvt_pk_bf16_f32 v66, v68, v69
	v_cvt_pk_bf16_f32 v67, v70, v71
	v_cvt_pk_bf16_f32 v68, v64, v65
	s_nop 0
	v_and_b32_e32 v65, 0xffff0000, v66
	v_lshlrev_b32_e32 v64, 16, v66
	v_mul_f32_e32 v65, v65, v65
	v_fmac_f32_e32 v65, v64, v64
	v_and_b32_e32 v70, 0xffff0000, v67
	v_add_f32_e32 v64, v82, v65
	v_lshlrev_b32_e32 v65, 16, v67
	v_mul_f32_e32 v70, v70, v70
	v_fmac_f32_e32 v70, v65, v65
	v_add_f32_e32 v64, v64, v70
	v_and_b32_e32 v70, 0xffff0000, v68
	v_lshlrev_b32_e32 v65, 16, v68
	v_mul_f32_e32 v70, v70, v70
	v_fmac_f32_e32 v70, v65, v65
	v_cvt_pk_bf16_f32 v69, v72, v73
	v_add_f32_e32 v64, v64, v70
	v_and_b32_e32 v70, 0xffff0000, v69
	v_lshlrev_b32_e32 v65, 16, v69
	v_mul_f32_e32 v70, v70, v70
	v_fmac_f32_e32 v70, v65, v65
	v_add_f32_e32 v64, v64, v70
	v_mov_b32_e32 v65, v64
	s_nop 1
	v_permlane16_swap_b32_e32 v65, v64
	global_store_dwordx4 v[76:77], v[66:69], off offset:256 nt
	s_waitcnt lgkmcnt(0)
	v_add_f32_e32 v64, v64, v65
	v_mov_b32_e32 v65, v64
	s_nop 1
	v_permlane32_swap_b32_e32 v65, v64
	s_and_saveexec_b64 s[6:7], vcc
	s_cbranch_execz .LBB0_158
	s_waitcnt lgkmcnt(0)
	v_add_f32_e32 v66, v64, v65
	v_lshlrev_b64 v[64:65], 6, v[108:109]
	v_lshl_add_u64 v[64:65], s[48:49], 0, v[64:65]
	v_lshl_add_u64 v[64:65], s[74:75], 2, v[64:65]
	s_lshl_b32 s38, s8, 2
	v_lshl_add_u64 v[64:65], v[64:65], 0, s[38:39]
	flat_store_dword v[64:65], v66
.LBB0_158:
	s_or_b64 exec, exec, s[6:7]
	v_add_u32_e32 v80, 0x80, v170
	v_ashrrev_i32_e32 v81, 31, v80
	v_lshlrev_b64 v[86:87], 11, v[80:81]
	s_waitcnt lgkmcnt(0)
	v_lshl_add_u64 v[64:65], v[172:173], 0, v[86:87]
	global_load_dwordx4 v[82:85], v[64:65], off
	global_load_dwordx4 v[72:75], v[64:65], off offset:256
	v_add_u32_e32 v76, 0x90, v170
	v_ashrrev_i32_e32 v77, 31, v76
	v_lshlrev_b64 v[78:79], 11, v[76:77]
	v_lshl_add_u64 v[64:65], v[172:173], 0, v[78:79]
	global_load_dwordx4 v[68:71], v[64:65], off
	s_nop 0
	global_load_dwordx4 v[64:67], v[64:65], off offset:256
	s_waitcnt vmcnt(0)
	v_lshlrev_b32_e32 v88, 16, v82
	v_and_b32_e32 v89, 0xffff0000, v82
	v_lshlrev_b32_e32 v82, 16, v83
	v_and_b32_e32 v83, 0xffff0000, v83
	v_lshlrev_b32_e32 v90, 16, v84
	v_and_b32_e32 v91, 0xffff0000, v84
	v_lshlrev_b32_e32 v84, 16, v85
	v_and_b32_e32 v85, 0xffff0000, v85
	v_pk_add_f32 v[60:61], v[60:61], v[88:89]
	v_pk_add_f32 v[62:63], v[62:63], v[82:83]
	v_pk_add_f32 v[82:83], v[58:59], v[84:85]
	v_pk_add_f32 v[58:59], v[56:57], v[90:91]
	v_cvt_pk_bf16_f32 v56, v60, v61
	v_lshl_add_u64 v[60:61], s[68:69], 0, v[86:87]
	v_lshl_add_u64 v[60:61], v[168:169], 1, v[60:61]
	v_cvt_pk_bf16_f32 v57, v62, v63
	v_cvt_pk_bf16_f32 v58, v58, v59
	v_cvt_pk_bf16_f32 v59, v82, v83
	global_store_dwordx4 v[60:61], v[56:59], off nt
	v_lshlrev_b32_e32 v62, 16, v56
	v_and_b32_e32 v63, 0xffff0000, v74
	v_and_b32_e32 v56, 0xffff0000, v56
	v_mul_f32_e32 v56, v56, v56
	v_fmac_f32_e32 v56, v62, v62
	v_lshlrev_b32_e32 v62, 16, v57
	v_and_b32_e32 v57, 0xffff0000, v57
	v_mul_f32_e32 v57, v57, v57
	v_fmac_f32_e32 v57, v62, v62
	v_add_f32_e32 v56, v56, v57
	v_lshlrev_b32_e32 v57, 16, v58
	v_and_b32_e32 v58, 0xffff0000, v58
	v_mul_f32_e32 v58, v58, v58
	v_fmac_f32_e32 v58, v57, v57
	v_add_f32_e32 v56, v56, v58
	v_and_b32_e32 v58, 0xffff0000, v59
	v_lshlrev_b32_e32 v57, 16, v59
	v_mul_f32_e32 v58, v58, v58
	v_fmac_f32_e32 v58, v57, v57
	v_add_f32_e32 v82, v56, v58
	v_lshlrev_b32_e32 v56, 16, v72
	v_and_b32_e32 v57, 0xffff0000, v72
	v_lshlrev_b32_e32 v58, 16, v73
	v_and_b32_e32 v59, 0xffff0000, v73
	v_lshlrev_b32_e32 v62, 16, v74
	v_lshlrev_b32_e32 v72, 16, v75
	v_and_b32_e32 v73, 0xffff0000, v75
	v_pk_add_f32 v[52:53], v[52:53], v[56:57]
	v_pk_add_f32 v[56:57], v[50:51], v[72:73]
	v_pk_add_f32 v[50:51], v[48:49], v[62:63]
	v_cvt_pk_bf16_f32 v48, v52, v53
	v_pk_add_f32 v[54:55], v[54:55], v[58:59]
	v_lshlrev_b32_e32 v52, 16, v48
	v_cvt_pk_bf16_f32 v49, v54, v55
	v_cvt_pk_bf16_f32 v50, v50, v51
	v_cvt_pk_bf16_f32 v51, v56, v57
	global_store_dwordx4 v[60:61], v[48:51], off offset:256 nt
	s_nop 1
	v_and_b32_e32 v48, 0xffff0000, v48
	v_mul_f32_e32 v48, v48, v48
	v_fmac_f32_e32 v48, v52, v52
	v_lshlrev_b32_e32 v52, 16, v49
	v_and_b32_e32 v49, 0xffff0000, v49
	v_mul_f32_e32 v49, v49, v49
	v_add_f32_e32 v48, v82, v48
	v_fmac_f32_e32 v49, v52, v52
	v_add_f32_e32 v48, v48, v49
	v_lshlrev_b32_e32 v49, 16, v50
	v_and_b32_e32 v50, 0xffff0000, v50
	v_mul_f32_e32 v50, v50, v50
	v_fmac_f32_e32 v50, v49, v49
	v_add_f32_e32 v48, v48, v50
	v_and_b32_e32 v50, 0xffff0000, v51
	v_lshlrev_b32_e32 v49, 16, v51
	v_mul_f32_e32 v50, v50, v50
	v_fmac_f32_e32 v50, v49, v49
	v_add_f32_e32 v48, v48, v50
	v_mov_b32_e32 v49, v48
	s_nop 1
	v_permlane16_swap_b32_e32 v49, v48
	s_waitcnt lgkmcnt(0)
	v_add_f32_e32 v48, v48, v49
	v_mov_b32_e32 v49, v48
	s_nop 1
	v_permlane32_swap_b32_e32 v49, v48
	s_and_saveexec_b64 s[6:7], vcc
	s_cbranch_execz .LBB0_160
	s_waitcnt lgkmcnt(0)
	v_add_f32_e32 v50, v48, v49
	v_lshlrev_b64 v[48:49], 6, v[80:81]
	v_lshl_add_u64 v[48:49], s[48:49], 0, v[48:49]
	v_lshl_add_u64 v[48:49], s[74:75], 2, v[48:49]
	s_lshl_b32 s38, s8, 2
	v_lshl_add_u64 v[48:49], v[48:49], 0, s[38:39]
	flat_store_dword v[48:49], v50
.LBB0_160:
	s_or_b64 exec, exec, s[6:7]
	v_lshlrev_b32_e32 v48, 16, v68
	s_waitcnt lgkmcnt(0)
	v_and_b32_e32 v49, 0xffff0000, v68
	v_lshlrev_b32_e32 v52, 16, v70
	v_and_b32_e32 v53, 0xffff0000, v70
	v_lshlrev_b32_e32 v54, 16, v71
	v_and_b32_e32 v55, 0xffff0000, v71
	v_pk_add_f32 v[44:45], v[44:45], v[48:49]
	v_lshlrev_b32_e32 v50, 16, v69
	v_and_b32_e32 v51, 0xffff0000, v69
	v_pk_add_f32 v[48:49], v[42:43], v[54:55]
	v_pk_add_f32 v[42:43], v[40:41], v[52:53]
	v_cvt_pk_bf16_f32 v40, v44, v45
	v_lshl_add_u64 v[44:45], s[68:69], 0, v[78:79]
	v_pk_add_f32 v[46:47], v[46:47], v[50:51]
	v_lshl_add_u64 v[44:45], v[168:169], 1, v[44:45]
	v_cvt_pk_bf16_f32 v41, v46, v47
	v_cvt_pk_bf16_f32 v42, v42, v43
	v_cvt_pk_bf16_f32 v43, v48, v49
	global_store_dwordx4 v[44:45], v[40:43], off nt
	v_lshlrev_b32_e32 v46, 16, v40
	v_and_b32_e32 v47, 0xffff0000, v66
	v_and_b32_e32 v40, 0xffff0000, v40
	v_mul_f32_e32 v40, v40, v40
	v_fmac_f32_e32 v40, v46, v46
	v_lshlrev_b32_e32 v46, 16, v41
	v_and_b32_e32 v41, 0xffff0000, v41
	v_mul_f32_e32 v41, v41, v41
	v_fmac_f32_e32 v41, v46, v46
	v_add_f32_e32 v40, v40, v41
	v_lshlrev_b32_e32 v41, 16, v42
	v_and_b32_e32 v42, 0xffff0000, v42
	v_mul_f32_e32 v42, v42, v42
	v_fmac_f32_e32 v42, v41, v41
	v_add_f32_e32 v40, v40, v42
	v_and_b32_e32 v42, 0xffff0000, v43
	v_lshlrev_b32_e32 v41, 16, v43
	v_mul_f32_e32 v42, v42, v42
	v_fmac_f32_e32 v42, v41, v41
	v_add_f32_e32 v50, v40, v42
	v_lshlrev_b32_e32 v40, 16, v64
	v_and_b32_e32 v41, 0xffff0000, v64
	v_lshlrev_b32_e32 v46, 16, v66
	v_lshlrev_b32_e32 v42, 16, v65
	v_and_b32_e32 v43, 0xffff0000, v65
	v_lshlrev_b32_e32 v48, 16, v67
	v_and_b32_e32 v49, 0xffff0000, v67
	v_pk_add_f32 v[36:37], v[36:37], v[40:41]
	v_pk_add_f32 v[32:33], v[32:33], v[46:47]
	v_pk_add_f32 v[38:39], v[38:39], v[42:43]
	v_pk_add_f32 v[40:41], v[34:35], v[48:49]
	v_cvt_pk_bf16_f32 v34, v36, v37
	v_cvt_pk_bf16_f32 v35, v38, v39
	v_cvt_pk_bf16_f32 v36, v32, v33
	s_nop 0
	v_and_b32_e32 v33, 0xffff0000, v34
	v_lshlrev_b32_e32 v32, 16, v34
	v_mul_f32_e32 v33, v33, v33
	v_fmac_f32_e32 v33, v32, v32
	v_and_b32_e32 v38, 0xffff0000, v35
	v_add_f32_e32 v32, v50, v33
	v_lshlrev_b32_e32 v33, 16, v35
	v_mul_f32_e32 v38, v38, v38
	v_fmac_f32_e32 v38, v33, v33
	v_add_f32_e32 v32, v32, v38
	v_and_b32_e32 v38, 0xffff0000, v36
	v_lshlrev_b32_e32 v33, 16, v36
	v_mul_f32_e32 v38, v38, v38
	v_fmac_f32_e32 v38, v33, v33
	v_cvt_pk_bf16_f32 v37, v40, v41
	v_add_f32_e32 v32, v32, v38
	v_and_b32_e32 v38, 0xffff0000, v37
	v_lshlrev_b32_e32 v33, 16, v37
	v_mul_f32_e32 v38, v38, v38
	v_fmac_f32_e32 v38, v33, v33
	v_add_f32_e32 v32, v32, v38
	v_mov_b32_e32 v33, v32
	s_nop 1
	v_permlane16_swap_b32_e32 v33, v32
	global_store_dwordx4 v[44:45], v[34:37], off offset:256 nt
	s_waitcnt lgkmcnt(0)
	v_add_f32_e32 v32, v32, v33
	v_mov_b32_e32 v33, v32
	s_nop 1
	v_permlane32_swap_b32_e32 v33, v32
	s_and_saveexec_b64 s[6:7], vcc
	s_cbranch_execz .LBB0_162
	s_waitcnt lgkmcnt(0)
	v_add_f32_e32 v34, v32, v33
	v_lshlrev_b64 v[32:33], 6, v[76:77]
	v_lshl_add_u64 v[32:33], s[48:49], 0, v[32:33]
	v_lshl_add_u64 v[32:33], s[74:75], 2, v[32:33]
	s_lshl_b32 s38, s8, 2
	v_lshl_add_u64 v[32:33], v[32:33], 0, s[38:39]
	flat_store_dword v[32:33], v34
.LBB0_162:
	s_or_b64 exec, exec, s[6:7]
	v_add_u32_e32 v48, 0xa0, v170
	v_ashrrev_i32_e32 v49, 31, v48
	v_lshlrev_b64 v[54:55], 11, v[48:49]
	s_waitcnt lgkmcnt(0)
	v_lshl_add_u64 v[32:33], v[172:173], 0, v[54:55]
	global_load_dwordx4 v[50:53], v[32:33], off
	global_load_dwordx4 v[40:43], v[32:33], off offset:256
	v_add_u32_e32 v44, 0xb0, v170
	v_ashrrev_i32_e32 v45, 31, v44
	v_lshlrev_b64 v[46:47], 11, v[44:45]
	v_lshl_add_u64 v[32:33], v[172:173], 0, v[46:47]
	global_load_dwordx4 v[36:39], v[32:33], off
	s_nop 0
	global_load_dwordx4 v[32:35], v[32:33], off offset:256
	s_waitcnt vmcnt(0)
	v_lshlrev_b32_e32 v56, 16, v50
	v_and_b32_e32 v57, 0xffff0000, v50
	v_lshlrev_b32_e32 v50, 16, v51
	v_and_b32_e32 v51, 0xffff0000, v51
	v_lshlrev_b32_e32 v58, 16, v52
	v_and_b32_e32 v59, 0xffff0000, v52
	v_lshlrev_b32_e32 v52, 16, v53
	v_and_b32_e32 v53, 0xffff0000, v53
	v_pk_add_f32 v[28:29], v[28:29], v[56:57]
	v_pk_add_f32 v[30:31], v[30:31], v[50:51]
	v_pk_add_f32 v[50:51], v[26:27], v[52:53]
	v_pk_add_f32 v[26:27], v[24:25], v[58:59]
	v_cvt_pk_bf16_f32 v24, v28, v29
	v_lshl_add_u64 v[28:29], s[68:69], 0, v[54:55]
	v_lshl_add_u64 v[28:29], v[168:169], 1, v[28:29]
	v_cvt_pk_bf16_f32 v25, v30, v31
	v_cvt_pk_bf16_f32 v26, v26, v27
	v_cvt_pk_bf16_f32 v27, v50, v51
	global_store_dwordx4 v[28:29], v[24:27], off nt
	v_lshlrev_b32_e32 v30, 16, v24
	v_and_b32_e32 v31, 0xffff0000, v42
	v_and_b32_e32 v24, 0xffff0000, v24
	v_mul_f32_e32 v24, v24, v24
	v_fmac_f32_e32 v24, v30, v30
	v_lshlrev_b32_e32 v30, 16, v25
	v_and_b32_e32 v25, 0xffff0000, v25
	v_mul_f32_e32 v25, v25, v25
	v_fmac_f32_e32 v25, v30, v30
	v_add_f32_e32 v24, v24, v25
	v_lshlrev_b32_e32 v25, 16, v26
	v_and_b32_e32 v26, 0xffff0000, v26
	v_mul_f32_e32 v26, v26, v26
	v_fmac_f32_e32 v26, v25, v25
	v_add_f32_e32 v24, v24, v26
	v_and_b32_e32 v26, 0xffff0000, v27
	v_lshlrev_b32_e32 v25, 16, v27
	v_mul_f32_e32 v26, v26, v26
	v_fmac_f32_e32 v26, v25, v25
	v_add_f32_e32 v50, v24, v26
	v_lshlrev_b32_e32 v24, 16, v40
	v_and_b32_e32 v25, 0xffff0000, v40
	v_lshlrev_b32_e32 v26, 16, v41
	v_and_b32_e32 v27, 0xffff0000, v41
	v_lshlrev_b32_e32 v30, 16, v42
	v_lshlrev_b32_e32 v40, 16, v43
	v_and_b32_e32 v41, 0xffff0000, v43
	v_pk_add_f32 v[20:21], v[20:21], v[24:25]
	v_pk_add_f32 v[24:25], v[18:19], v[40:41]
	v_pk_add_f32 v[18:19], v[16:17], v[30:31]
	v_cvt_pk_bf16_f32 v16, v20, v21
	v_pk_add_f32 v[22:23], v[22:23], v[26:27]
	v_lshlrev_b32_e32 v20, 16, v16
	v_cvt_pk_bf16_f32 v17, v22, v23
	v_cvt_pk_bf16_f32 v18, v18, v19
	v_cvt_pk_bf16_f32 v19, v24, v25
	global_store_dwordx4 v[28:29], v[16:19], off offset:256 nt
	s_nop 1
	v_and_b32_e32 v16, 0xffff0000, v16
	v_mul_f32_e32 v16, v16, v16
	v_fmac_f32_e32 v16, v20, v20
	v_lshlrev_b32_e32 v20, 16, v17
	v_and_b32_e32 v17, 0xffff0000, v17
	v_mul_f32_e32 v17, v17, v17
	v_add_f32_e32 v16, v50, v16
	v_fmac_f32_e32 v17, v20, v20
	v_add_f32_e32 v16, v16, v17
	v_lshlrev_b32_e32 v17, 16, v18
	v_and_b32_e32 v18, 0xffff0000, v18
	v_mul_f32_e32 v18, v18, v18
	v_fmac_f32_e32 v18, v17, v17
	v_add_f32_e32 v16, v16, v18
	v_and_b32_e32 v18, 0xffff0000, v19
	v_lshlrev_b32_e32 v17, 16, v19
	v_mul_f32_e32 v18, v18, v18
	v_fmac_f32_e32 v18, v17, v17
	v_add_f32_e32 v16, v16, v18
	v_mov_b32_e32 v17, v16
	s_nop 1
	v_permlane16_swap_b32_e32 v17, v16
	s_waitcnt lgkmcnt(0)
	v_add_f32_e32 v16, v16, v17
	v_mov_b32_e32 v17, v16
	s_nop 1
	v_permlane32_swap_b32_e32 v17, v16
	s_and_saveexec_b64 s[6:7], vcc
	s_cbranch_execz .LBB0_164
	s_waitcnt lgkmcnt(0)
	v_add_f32_e32 v18, v16, v17
	v_lshlrev_b64 v[16:17], 6, v[48:49]
	v_lshl_add_u64 v[16:17], s[48:49], 0, v[16:17]
	v_lshl_add_u64 v[16:17], s[74:75], 2, v[16:17]
	s_lshl_b32 s38, s8, 2
	v_lshl_add_u64 v[16:17], v[16:17], 0, s[38:39]
	flat_store_dword v[16:17], v18
.LBB0_164:
	s_or_b64 exec, exec, s[6:7]
	v_lshlrev_b32_e32 v16, 16, v36
	s_waitcnt lgkmcnt(0)
	v_and_b32_e32 v17, 0xffff0000, v36
	v_lshlrev_b32_e32 v20, 16, v38
	v_and_b32_e32 v21, 0xffff0000, v38
	v_lshlrev_b32_e32 v22, 16, v39
	v_and_b32_e32 v23, 0xffff0000, v39
	v_pk_add_f32 v[12:13], v[12:13], v[16:17]
	v_lshlrev_b32_e32 v18, 16, v37
	v_and_b32_e32 v19, 0xffff0000, v37
	v_pk_add_f32 v[16:17], v[10:11], v[22:23]
	v_pk_add_f32 v[10:11], v[8:9], v[20:21]
	v_cvt_pk_bf16_f32 v8, v12, v13
	v_lshl_add_u64 v[12:13], s[68:69], 0, v[46:47]
	v_pk_add_f32 v[14:15], v[14:15], v[18:19]
	v_lshl_add_u64 v[12:13], v[168:169], 1, v[12:13]
	v_cvt_pk_bf16_f32 v9, v14, v15
	v_cvt_pk_bf16_f32 v10, v10, v11
	v_cvt_pk_bf16_f32 v11, v16, v17
	global_store_dwordx4 v[12:13], v[8:11], off nt
	v_lshlrev_b32_e32 v14, 16, v8
	v_and_b32_e32 v15, 0xffff0000, v34
	v_and_b32_e32 v8, 0xffff0000, v8
	v_mul_f32_e32 v8, v8, v8
	v_fmac_f32_e32 v8, v14, v14
	v_lshlrev_b32_e32 v14, 16, v9
	v_and_b32_e32 v9, 0xffff0000, v9
	v_mul_f32_e32 v9, v9, v9
	v_fmac_f32_e32 v9, v14, v14
	v_add_f32_e32 v8, v8, v9
	v_lshlrev_b32_e32 v9, 16, v10
	v_and_b32_e32 v10, 0xffff0000, v10
	v_mul_f32_e32 v10, v10, v10
	v_fmac_f32_e32 v10, v9, v9
	v_add_f32_e32 v8, v8, v10
	v_and_b32_e32 v10, 0xffff0000, v11
	v_lshlrev_b32_e32 v9, 16, v11
	v_mul_f32_e32 v10, v10, v10
	v_fmac_f32_e32 v10, v9, v9
	v_add_f32_e32 v18, v8, v10
	v_lshlrev_b32_e32 v8, 16, v32
	v_and_b32_e32 v9, 0xffff0000, v32
	v_lshlrev_b32_e32 v14, 16, v34
	v_lshlrev_b32_e32 v10, 16, v33
	v_and_b32_e32 v11, 0xffff0000, v33
	v_lshlrev_b32_e32 v16, 16, v35
	v_and_b32_e32 v17, 0xffff0000, v35
	v_pk_add_f32 v[4:5], v[4:5], v[8:9]
	v_pk_add_f32 v[0:1], v[0:1], v[14:15]
	v_pk_add_f32 v[6:7], v[6:7], v[10:11]
	v_pk_add_f32 v[8:9], v[2:3], v[16:17]
	v_cvt_pk_bf16_f32 v2, v4, v5
	v_cvt_pk_bf16_f32 v3, v6, v7
	v_cvt_pk_bf16_f32 v4, v0, v1
	s_nop 0
	v_and_b32_e32 v1, 0xffff0000, v2
	v_lshlrev_b32_e32 v0, 16, v2
	v_mul_f32_e32 v1, v1, v1
	v_fmac_f32_e32 v1, v0, v0
	v_and_b32_e32 v6, 0xffff0000, v3
	v_add_f32_e32 v0, v18, v1
	v_lshlrev_b32_e32 v1, 16, v3
	v_mul_f32_e32 v6, v6, v6
	v_fmac_f32_e32 v6, v1, v1
	v_add_f32_e32 v0, v0, v6
	v_and_b32_e32 v6, 0xffff0000, v4
	v_lshlrev_b32_e32 v1, 16, v4
	v_mul_f32_e32 v6, v6, v6
	v_fmac_f32_e32 v6, v1, v1
	v_cvt_pk_bf16_f32 v5, v8, v9
	v_add_f32_e32 v0, v0, v6
	v_and_b32_e32 v6, 0xffff0000, v5
	v_lshlrev_b32_e32 v1, 16, v5
	v_mul_f32_e32 v6, v6, v6
	v_fmac_f32_e32 v6, v1, v1
	v_add_f32_e32 v0, v0, v6
	v_mov_b32_e32 v1, v0
	s_nop 1
	v_permlane16_swap_b32_e32 v1, v0
	global_store_dwordx4 v[12:13], v[2:5], off offset:256 nt
	s_waitcnt lgkmcnt(0)
	v_add_f32_e32 v0, v0, v1
	v_mov_b32_e32 v1, v0
	s_nop 1
	v_permlane32_swap_b32_e32 v1, v0
	s_and_saveexec_b64 s[6:7], vcc
	s_cbranch_execz .LBB0_166
	s_waitcnt lgkmcnt(0)
	v_add_f32_e32 v2, v0, v1
	v_lshlrev_b64 v[0:1], 6, v[44:45]
	v_lshl_add_u64 v[0:1], s[48:49], 0, v[0:1]
	v_lshl_add_u64 v[0:1], s[74:75], 2, v[0:1]
	s_lshl_b32 s38, s8, 2
	v_lshl_add_u64 v[0:1], v[0:1], 0, s[38:39]
	flat_store_dword v[0:1], v2

.LBB0_237:
	s_mov_b32 s4, -1
	s_getreg_b32 s5, hwreg(HW_REG_HW_ID, 0, 6)
	s_and_b32 s5, s5, 63
	s_lshl_b32 s5, s5, 2
	s_add_i32 s5, s5, 0
	s_add_i32 s5, s5, 0x20200
	v_mov_b32_e32 v140, s5
	ds_read_b32 v140, v140
	v_mbcnt_lo_u32_b32 v142, s4, 0
	v_mbcnt_hi_u32_b32 v142, s4, v142
	s_mov_b64 s[8:9], -1
	s_waitcnt lgkmcnt(0)
	v_readfirstlane_b32 s4, v140
	s_nop 1
	v_lshl_add_u32 v140, s4, 6, v142
	v_bfrev_b32_e32 v142, 0.5
	v_readfirstlane_b32 s4, v140
	s_ashr_i32 s5, s4, 2
	s_andn2_b32 s5, s5, 63
	v_bfe_u32 v208, v140, 4, 2
	v_and_or_b32 v172, v140, 15, s5
	v_lshlrev_b32_e32 v140, 2, v140
	s_cmp_gt_u32 s58, 3
	v_bitop3_b32 v211, v140, 64, v142 bitop3:0x6c
	v_bitop3_b32 v210, v140, s84, v142 bitop3:0x6c
	v_lshlrev_b32_e32 v140, 2, v208
	s_cselect_b64 s[6:7], -1, 0
	s_and_b64 vcc, exec, s[6:7]
	v_lshl_add_u32 v158, s74, 8, v172
	v_lshlrev_b32_e32 v140, 2, v140
	s_cbranch_vccz .LBB0_239
	v_ashrrev_i32_e32 v159, 31, v158
	v_lshlrev_b64 v[142:143], 6, v[158:159]
	v_lshl_add_u64 v[142:143], s[44:45], 0, v[142:143]
	v_lshl_add_u64 v[142:143], v[142:143], 0, v[140:141]
	flat_load_dwordx4 v[142:145], v[142:143]
	s_mov_b64 s[8:9], 0
	s_waitcnt vmcnt(0) lgkmcnt(0)
	v_mov_b32_e32 v146, v143
	v_mov_b32_e32 v147, v144
	v_mov_b32_e32 v143, v145
	v_pk_add_f32 v[142:143], v[146:147], v[142:143]
	s_nop 0
	v_add_f32_e32 v142, v142, v143
	v_mov_b32_e32 v143, v142
	s_nop 1
	v_permlane16_swap_b32_e32 v143, v142
	s_waitcnt lgkmcnt(0)
	v_add_f32_e32 v142, v142, v143
	v_mov_b32_e32 v143, v142
	s_nop 1
	v_permlane32_swap_b32_e32 v143, v142
	s_waitcnt lgkmcnt(0)
	v_add_f32_e32 v142, v142, v143
	v_fmamk_f32 v142, v142, 0x3a800000, v250
	v_rsq_f32_e32 v160, v142

.LBB0_241:
	s_waitcnt lgkmcnt(0)
	v_pk_mul_f32 v[124:125], v[124:125], v[160:161] op_sel_hi:[1,0]
	v_pk_mul_f32 v[126:127], v[126:127], v[160:161] op_sel_hi:[1,0]
	v_max3_f32 v142, v124, s95, v125
	v_max3_f32 v142, v142, v126, v127
	v_pk_mul_f32 v[120:121], v[120:121], v[160:161] op_sel_hi:[1,0]
	v_pk_mul_f32 v[122:123], v[122:123], v[160:161] op_sel_hi:[1,0]
	v_max3_f32 v142, v142, v120, v121
	v_max3_f32 v142, v142, v122, v123
	v_pk_mul_f32 v[116:117], v[116:117], v[160:161] op_sel_hi:[1,0]
	v_pk_mul_f32 v[118:119], v[118:119], v[160:161] op_sel_hi:[1,0]
	v_max3_f32 v142, v142, v116, v117
	v_max3_f32 v142, v142, v118, v119
	v_pk_mul_f32 v[112:113], v[112:113], v[160:161] op_sel_hi:[1,0]
	v_pk_mul_f32 v[114:115], v[114:115], v[160:161] op_sel_hi:[1,0]
	v_max3_f32 v142, v142, v112, v113
	v_max3_f32 v142, v142, v114, v115
	v_mov_b32_e32 v143, v142
	s_nop 1
	v_permlane16_swap_b32_e32 v143, v142
	s_bfe_u32 s4, s4, 0x20006
	v_cmp_eq_u32_e64 s[42:43], 0, v208
	s_waitcnt lgkmcnt(0)
	v_max_f32_e32 v143, v143, v143
	v_max_f32_e32 v159, v142, v143
	v_mov_b32_e32 v160, v159
	s_nop 1
	v_permlane32_swap_b32_e32 v160, v159
	s_mov_b64 s[8:9], exec
	s_and_b64 s[10:11], s[8:9], s[42:43]
	v_mov_b32_e32 v198, v218
	v_mov_b32_e32 v199, v219
	v_mov_b32_e32 v205, v221
	v_mov_b32_e32 v196, v222
	s_mov_b64 exec, s[10:11]
	s_cbranch_execz .LBB0_243
	s_lshl_b32 s5, s4, 2
	s_add_i32 s5, s5, 0
	v_lshl_add_u32 v142, v172, 4, s5
	s_waitcnt lgkmcnt(0)
	v_max_f32_e32 v143, v160, v160
	v_max_f32_e32 v144, v159, v159
	v_add_u32_e32 v142, 0x20400, v142
	v_max_f32_e32 v143, v144, v143
	ds_write_b32 v142, v143
.LBB0_243:
	s_or_b64 exec, exec, s[8:9]
	v_or_b32_e32 v209, 16, v172
	s_mov_b64 s[8:9], -1
	s_and_b64 vcc, exec, s[6:7]
	s_cbranch_vccz .LBB0_245
	v_lshl_add_u32 v142, s74, 8, v209
	v_ashrrev_i32_e32 v143, 31, v142
	v_lshlrev_b64 v[142:143], 6, v[142:143]
	v_lshl_add_u64 v[142:143], s[44:45], 0, v[142:143]
	v_lshl_add_u64 v[142:143], v[142:143], 0, v[140:141]
	flat_load_dwordx4 v[142:145], v[142:143]
	s_mov_b64 s[8:9], 0
	s_waitcnt vmcnt(0) lgkmcnt(0)
	v_mov_b32_e32 v146, v143
	v_mov_b32_e32 v147, v144
	v_mov_b32_e32 v143, v145
	v_pk_add_f32 v[142:143], v[146:147], v[142:143]
	s_nop 0
	v_add_f32_e32 v142, v142, v143
	v_mov_b32_e32 v143, v142
	s_nop 1
	v_permlane16_swap_b32_e32 v143, v142
	s_waitcnt lgkmcnt(0)
	v_add_f32_e32 v142, v142, v143
	v_mov_b32_e32 v143, v142
	s_nop 1
	v_permlane32_swap_b32_e32 v143, v142
	s_waitcnt lgkmcnt(0)
	v_add_f32_e32 v142, v142, v143
	v_fmamk_f32 v142, v142, 0x3a800000, v250
	v_rsq_f32_e32 v160, v142

.LBB0_247:
	s_waitcnt lgkmcnt(0)
	v_pk_mul_f32 v[108:109], v[108:109], v[160:161] op_sel_hi:[1,0]
	v_pk_mul_f32 v[110:111], v[110:111], v[160:161] op_sel_hi:[1,0]
	v_max3_f32 v142, v108, s95, v109
	v_max3_f32 v142, v142, v110, v111
	v_pk_mul_f32 v[104:105], v[104:105], v[160:161] op_sel_hi:[1,0]
	v_pk_mul_f32 v[106:107], v[106:107], v[160:161] op_sel_hi:[1,0]
	v_max3_f32 v142, v142, v104, v105
	v_max3_f32 v142, v142, v106, v107
	v_pk_mul_f32 v[100:101], v[100:101], v[160:161] op_sel_hi:[1,0]
	v_pk_mul_f32 v[102:103], v[102:103], v[160:161] op_sel_hi:[1,0]
	v_max3_f32 v142, v142, v100, v101
	v_max3_f32 v142, v142, v102, v103
	v_pk_mul_f32 v[96:97], v[96:97], v[160:161] op_sel_hi:[1,0]
	v_pk_mul_f32 v[98:99], v[98:99], v[160:161] op_sel_hi:[1,0]
	v_max3_f32 v142, v142, v96, v97
	v_max3_f32 v142, v142, v98, v99
	v_mov_b32_e32 v143, v142
	s_nop 1
	v_permlane16_swap_b32_e32 v143, v142
	s_waitcnt lgkmcnt(0)
	v_max_f32_e32 v143, v143, v143
	v_max_f32_e32 v159, v142, v143
	v_mov_b32_e32 v160, v159
	s_nop 1
	v_permlane32_swap_b32_e32 v160, v159
	s_and_saveexec_b64 s[8:9], s[42:43]
	s_cbranch_execz .LBB0_249
	s_lshl_b32 s5, s4, 2
	s_add_i32 s5, s5, 0
	v_lshl_add_u32 v142, v209, 4, s5
	s_waitcnt lgkmcnt(0)
	v_max_f32_e32 v143, v160, v160
	v_max_f32_e32 v144, v159, v159
	v_add_u32_e32 v142, 0x20400, v142
	v_max_f32_e32 v143, v144, v143
	ds_write_b32 v142, v143
.LBB0_249:
	s_or_b64 exec, exec, s[8:9]
	v_or_b32_e32 v212, 32, v172
	s_mov_b64 s[8:9], -1
	s_and_b64 vcc, exec, s[6:7]
	s_cbranch_vccz .LBB0_251
	v_lshl_add_u32 v142, s74, 8, v212
	v_ashrrev_i32_e32 v143, 31, v142
	v_lshlrev_b64 v[142:143], 6, v[142:143]
	v_lshl_add_u64 v[142:143], s[44:45], 0, v[142:143]
	v_lshl_add_u64 v[142:143], v[142:143], 0, v[140:141]
	flat_load_dwordx4 v[142:145], v[142:143]
	s_mov_b64 s[8:9], 0
	s_waitcnt vmcnt(0) lgkmcnt(0)
	v_mov_b32_e32 v146, v143
	v_mov_b32_e32 v147, v144
	v_mov_b32_e32 v143, v145
	v_pk_add_f32 v[142:143], v[146:147], v[142:143]
	s_nop 0
	v_add_f32_e32 v142, v142, v143
	v_mov_b32_e32 v143, v142
	s_nop 1
	v_permlane16_swap_b32_e32 v143, v142
	s_waitcnt lgkmcnt(0)
	v_add_f32_e32 v142, v142, v143
	v_mov_b32_e32 v143, v142
	s_nop 1
	v_permlane32_swap_b32_e32 v143, v142
	s_waitcnt lgkmcnt(0)
	v_add_f32_e32 v142, v142, v143
	v_fmamk_f32 v142, v142, 0x3a800000, v250
	v_rsq_f32_e32 v160, v142

.LBB0_253:
	s_waitcnt lgkmcnt(0)
	v_pk_mul_f32 v[92:93], v[92:93], v[160:161] op_sel_hi:[1,0]
	v_pk_mul_f32 v[94:95], v[94:95], v[160:161] op_sel_hi:[1,0]
	v_max3_f32 v142, v92, s95, v93
	v_max3_f32 v142, v142, v94, v95
	v_pk_mul_f32 v[88:89], v[88:89], v[160:161] op_sel_hi:[1,0]
	v_pk_mul_f32 v[90:91], v[90:91], v[160:161] op_sel_hi:[1,0]
	v_max3_f32 v142, v142, v88, v89
	v_max3_f32 v142, v142, v90, v91
	v_pk_mul_f32 v[84:85], v[84:85], v[160:161] op_sel_hi:[1,0]
	v_pk_mul_f32 v[86:87], v[86:87], v[160:161] op_sel_hi:[1,0]
	v_max3_f32 v142, v142, v84, v85
	v_max3_f32 v142, v142, v86, v87
	v_pk_mul_f32 v[80:81], v[80:81], v[160:161] op_sel_hi:[1,0]
	v_pk_mul_f32 v[82:83], v[82:83], v[160:161] op_sel_hi:[1,0]
	v_max3_f32 v142, v142, v80, v81
	v_max3_f32 v142, v142, v82, v83
	v_mov_b32_e32 v143, v142
	s_nop 1
	v_permlane16_swap_b32_e32 v143, v142
	s_waitcnt lgkmcnt(0)
	v_max_f32_e32 v143, v143, v143
	v_max_f32_e32 v159, v142, v143
	v_mov_b32_e32 v160, v159
	s_nop 1
	v_permlane32_swap_b32_e32 v160, v159
	s_and_saveexec_b64 s[8:9], s[42:43]
	s_cbranch_execz .LBB0_255
	s_lshl_b32 s5, s4, 2
	s_add_i32 s5, s5, 0
	v_lshl_add_u32 v142, v212, 4, s5
	s_waitcnt lgkmcnt(0)
	v_max_f32_e32 v143, v160, v160
	v_max_f32_e32 v144, v159, v159
	v_add_u32_e32 v142, 0x20400, v142
	v_max_f32_e32 v143, v144, v143
	ds_write_b32 v142, v143
.LBB0_255:
	s_or_b64 exec, exec, s[8:9]
	v_or_b32_e32 v213, 48, v172
	s_mov_b64 s[8:9], -1
	s_and_b64 vcc, exec, s[6:7]
	s_cbranch_vccz .LBB0_257
	v_lshl_add_u32 v142, s74, 8, v213
	v_ashrrev_i32_e32 v143, 31, v142
	v_lshlrev_b64 v[142:143], 6, v[142:143]
	v_lshl_add_u64 v[142:143], s[44:45], 0, v[142:143]
	v_lshl_add_u64 v[142:143], v[142:143], 0, v[140:141]
	flat_load_dwordx4 v[142:145], v[142:143]
	s_mov_b64 s[8:9], 0
	s_waitcnt vmcnt(0) lgkmcnt(0)
	v_mov_b32_e32 v146, v143
	v_mov_b32_e32 v147, v144
	v_mov_b32_e32 v143, v145
	v_pk_add_f32 v[142:143], v[146:147], v[142:143]
	s_nop 0
	v_add_f32_e32 v142, v142, v143
	v_mov_b32_e32 v143, v142
	s_nop 1
	v_permlane16_swap_b32_e32 v143, v142
	s_waitcnt lgkmcnt(0)
	v_add_f32_e32 v142, v142, v143
	v_mov_b32_e32 v143, v142
	s_nop 1
	v_permlane32_swap_b32_e32 v143, v142
	s_waitcnt lgkmcnt(0)
	v_add_f32_e32 v142, v142, v143
	v_fmamk_f32 v142, v142, 0x3a800000, v250
	v_rsq_f32_e32 v162, v142

.LBB0_259:
	s_waitcnt lgkmcnt(0)
	v_pk_mul_f32 v[160:161], v[76:77], v[162:163] op_sel_hi:[1,0]
	v_pk_mul_f32 v[78:79], v[78:79], v[162:163] op_sel_hi:[1,0]
	v_max3_f32 v76, v160, s95, v161
	v_max3_f32 v76, v76, v78, v79
	v_pk_mul_f32 v[72:73], v[72:73], v[162:163] op_sel_hi:[1,0]
	v_pk_mul_f32 v[74:75], v[74:75], v[162:163] op_sel_hi:[1,0]
	v_max3_f32 v76, v76, v72, v73
	v_max3_f32 v76, v76, v74, v75
	v_pk_mul_f32 v[68:69], v[68:69], v[162:163] op_sel_hi:[1,0]
	v_pk_mul_f32 v[70:71], v[70:71], v[162:163] op_sel_hi:[1,0]
	v_max3_f32 v76, v76, v68, v69
	v_max3_f32 v76, v76, v70, v71
	v_pk_mul_f32 v[64:65], v[64:65], v[162:163] op_sel_hi:[1,0]
	v_pk_mul_f32 v[66:67], v[66:67], v[162:163] op_sel_hi:[1,0]
	v_max3_f32 v76, v76, v64, v65
	v_max3_f32 v76, v76, v66, v67
	v_mov_b32_e32 v77, v76
	s_nop 1
	v_permlane16_swap_b32_e32 v77, v76
	s_waitcnt lgkmcnt(0)
	v_max_f32_e32 v77, v77, v77
	v_max_f32_e32 v76, v76, v77
	v_mov_b32_e32 v77, v76
	s_nop 1
	v_permlane32_swap_b32_e32 v77, v76
	s_and_saveexec_b64 s[8:9], s[42:43]
	s_cbranch_execz .LBB0_261
	s_lshl_b32 s5, s4, 2
	s_add_i32 s5, s5, 0
	v_lshl_add_u32 v142, v213, 4, s5
	s_waitcnt lgkmcnt(0)
	v_max_f32_e32 v77, v77, v77
	v_max_f32_e32 v76, v76, v76
	v_add_u32_e32 v142, 0x20400, v142
	v_max_f32_e32 v76, v76, v77
	ds_write_b32 v142, v76
.LBB0_261:
	s_or_b64 exec, exec, s[8:9]
	v_add_u32_e32 v214, 0x80, v172
	s_mov_b64 s[8:9], -1
	s_and_b64 vcc, exec, s[6:7]
	s_cbranch_vccz .LBB0_263
	v_lshl_add_u32 v76, s74, 8, v214
	s_waitcnt lgkmcnt(0)
	v_ashrrev_i32_e32 v77, 31, v76
	v_lshlrev_b64 v[76:77], 6, v[76:77]
	v_lshl_add_u64 v[76:77], s[44:45], 0, v[76:77]
	v_lshl_add_u64 v[76:77], v[76:77], 0, v[140:141]
	flat_load_dwordx4 v[142:145], v[76:77]
	s_mov_b64 s[8:9], 0
	s_waitcnt vmcnt(0) lgkmcnt(0)
	v_mov_b32_e32 v76, v143
	v_mov_b32_e32 v77, v144
	v_mov_b32_e32 v143, v145
	v_pk_add_f32 v[76:77], v[76:77], v[142:143]
	s_nop 0
	v_add_f32_e32 v76, v76, v77
	v_mov_b32_e32 v77, v76
	s_nop 1
	v_permlane16_swap_b32_e32 v77, v76
	s_waitcnt lgkmcnt(0)
	v_add_f32_e32 v76, v76, v77
	v_mov_b32_e32 v77, v76
	s_nop 1
	v_permlane32_swap_b32_e32 v77, v76
	s_waitcnt lgkmcnt(0)
	v_add_f32_e32 v76, v76, v77
	v_fmamk_f32 v76, v76, 0x3a800000, v250
	v_rsq_f32_e32 v168, v76

.LBB0_265:
	s_waitcnt lgkmcnt(0)
	v_pk_mul_f32 v[166:167], v[60:61], v[168:169] op_sel_hi:[1,0]
	v_pk_mul_f32 v[62:63], v[62:63], v[168:169] op_sel_hi:[1,0]
	v_max3_f32 v60, v166, s95, v167
	v_max3_f32 v60, v60, v62, v63
	v_pk_mul_f32 v[164:165], v[58:59], v[168:169] op_sel_hi:[1,0]
	v_pk_mul_f32 v[58:59], v[56:57], v[168:169] op_sel_hi:[1,0]
	v_pk_mul_f32 v[162:163], v[52:53], v[168:169] op_sel_hi:[1,0]
	v_max3_f32 v56, v60, v58, v59
	v_max3_f32 v56, v56, v164, v165
	v_pk_mul_f32 v[76:77], v[54:55], v[168:169] op_sel_hi:[1,0]
	v_max3_f32 v52, v56, v162, v163
	v_max3_f32 v52, v52, v76, v77
	v_pk_mul_f32 v[48:49], v[48:49], v[168:169] op_sel_hi:[1,0]
	v_pk_mul_f32 v[54:55], v[50:51], v[168:169] op_sel_hi:[1,0]
	v_max3_f32 v50, v52, v48, v49
	v_max3_f32 v50, v50, v54, v55
	v_mov_b32_e32 v51, v50
	s_nop 1
	v_permlane16_swap_b32_e32 v51, v50
	s_waitcnt lgkmcnt(0)
	v_max_f32_e32 v51, v51, v51
	v_max_f32_e32 v50, v50, v51
	v_mov_b32_e32 v51, v50
	s_nop 1
	v_permlane32_swap_b32_e32 v51, v50
	s_and_saveexec_b64 s[8:9], s[42:43]
	s_cbranch_execz .LBB0_267
	s_lshl_b32 s5, s4, 2
	s_add_i32 s5, s5, 0
	v_lshl_add_u32 v52, v214, 4, s5
	s_waitcnt lgkmcnt(0)
	v_max_f32_e32 v51, v51, v51
	v_max_f32_e32 v50, v50, v50
	v_add_u32_e32 v52, 0x20400, v52
	v_max_f32_e32 v50, v50, v51
	ds_write_b32 v52, v50
.LBB0_267:
	s_or_b64 exec, exec, s[8:9]
	v_add_u32_e32 v215, 0x90, v172
	s_mov_b64 s[8:9], -1
	s_and_b64 vcc, exec, s[6:7]
	s_cbranch_vccz .LBB0_269
	v_lshl_add_u32 v50, s74, 8, v215
	s_waitcnt lgkmcnt(0)
	v_ashrrev_i32_e32 v51, 31, v50
	v_lshlrev_b64 v[50:51], 6, v[50:51]
	v_lshl_add_u64 v[50:51], s[44:45], 0, v[50:51]
	v_lshl_add_u64 v[50:51], v[50:51], 0, v[140:141]
	flat_load_dwordx4 v[50:53], v[50:51]
	s_mov_b64 s[8:9], 0
	s_waitcnt vmcnt(0) lgkmcnt(0)
	v_mov_b32_e32 v56, v51
	v_mov_b32_e32 v57, v52
	v_mov_b32_e32 v51, v53
	v_pk_add_f32 v[50:51], v[56:57], v[50:51]
	s_nop 0
	v_add_f32_e32 v50, v50, v51
	v_mov_b32_e32 v51, v50
	s_nop 1
	v_permlane16_swap_b32_e32 v51, v50
	s_waitcnt lgkmcnt(0)
	v_add_f32_e32 v50, v50, v51
	ds_bpermute_b32 v51, v210, v50
	s_waitcnt lgkmcnt(0)
	v_add_f32_e32 v50, v50, v51
	v_fmamk_f32 v50, v50, 0x3a800000, v250
	v_rsq_f32_e32 v50, v50

.LBB0_271:
	s_waitcnt lgkmcnt(0)
	v_pk_mul_f32 v[44:45], v[44:45], v[50:51] op_sel_hi:[1,0]
	v_pk_mul_f32 v[174:175], v[46:47], v[50:51] op_sel_hi:[1,0]
	v_max3_f32 v46, v44, s95, v45
	v_max3_f32 v46, v46, v174, v175
	v_pk_mul_f32 v[170:171], v[42:43], v[50:51] op_sel_hi:[1,0]
	v_pk_mul_f32 v[42:43], v[40:41], v[50:51] op_sel_hi:[1,0]
	v_pk_mul_f32 v[168:169], v[36:37], v[50:51] op_sel_hi:[1,0]
	v_max3_f32 v40, v46, v42, v43
	v_max3_f32 v40, v40, v170, v171
	v_pk_mul_f32 v[46:47], v[38:39], v[50:51] op_sel_hi:[1,0]
	v_max3_f32 v36, v40, v168, v169
	v_max3_f32 v36, v36, v46, v47
	v_pk_mul_f32 v[32:33], v[32:33], v[50:51] op_sel_hi:[1,0]
	v_pk_mul_f32 v[38:39], v[34:35], v[50:51] op_sel_hi:[1,0]
	v_max3_f32 v34, v36, v32, v33
	v_max3_f32 v34, v34, v38, v39
	v_mov_b32_e32 v35, v34
	s_nop 1
	v_permlane16_swap_b32_e32 v35, v34
	s_waitcnt lgkmcnt(0)
	v_max_f32_e32 v35, v35, v35
	v_max_f32_e32 v34, v34, v35
	v_mov_b32_e32 v35, v34
	s_nop 1
	v_permlane32_swap_b32_e32 v35, v34
	s_and_saveexec_b64 s[8:9], s[42:43]
	s_cbranch_execz .LBB0_273
	s_lshl_b32 s5, s4, 2
	s_add_i32 s5, s5, 0
	v_lshl_add_u32 v36, v215, 4, s5
	s_waitcnt lgkmcnt(0)
	v_max_f32_e32 v35, v35, v35
	v_max_f32_e32 v34, v34, v34
	v_add_u32_e32 v36, 0x20400, v36
	v_max_f32_e32 v34, v34, v35
	ds_write_b32 v36, v34
.LBB0_273:
	s_or_b64 exec, exec, s[8:9]
	v_add_u32_e32 v216, 0xa0, v172
	s_mov_b64 s[8:9], -1
	s_and_b64 vcc, exec, s[6:7]
	s_cbranch_vccz .LBB0_275
	v_lshl_add_u32 v34, s74, 8, v216
	s_waitcnt lgkmcnt(0)
	v_ashrrev_i32_e32 v35, 31, v34
	v_lshlrev_b64 v[34:35], 6, v[34:35]
	v_lshl_add_u64 v[34:35], s[44:45], 0, v[34:35]
	v_lshl_add_u64 v[34:35], v[34:35], 0, v[140:141]
	flat_load_dwordx4 v[34:37], v[34:35]
	s_mov_b64 s[8:9], 0
	s_waitcnt vmcnt(0) lgkmcnt(0)
	v_mov_b32_e32 v40, v35
	v_mov_b32_e32 v41, v36
	v_mov_b32_e32 v35, v37
	v_pk_add_f32 v[34:35], v[40:41], v[34:35]
	s_nop 0
	v_add_f32_e32 v34, v34, v35
	v_mov_b32_e32 v35, v34
	s_nop 1
	v_permlane16_swap_b32_e32 v35, v34
	s_waitcnt lgkmcnt(0)
	v_add_f32_e32 v34, v34, v35
	ds_bpermute_b32 v35, v210, v34
	s_waitcnt lgkmcnt(0)
	v_add_f32_e32 v34, v34, v35
	v_fmamk_f32 v34, v34, 0x3a800000, v250
	v_rsq_f32_e32 v34, v34

.LBB0_277:
	s_waitcnt lgkmcnt(0)
	v_pk_mul_f32 v[28:29], v[28:29], v[34:35] op_sel_hi:[1,0]
	v_pk_mul_f32 v[180:181], v[30:31], v[34:35] op_sel_hi:[1,0]
	v_max3_f32 v30, v28, s95, v29
	v_max3_f32 v30, v30, v180, v181
	v_pk_mul_f32 v[178:179], v[26:27], v[34:35] op_sel_hi:[1,0]
	v_pk_mul_f32 v[26:27], v[24:25], v[34:35] op_sel_hi:[1,0]
	v_pk_mul_f32 v[20:21], v[20:21], v[34:35] op_sel_hi:[1,0]
	v_max3_f32 v24, v30, v26, v27
	v_max3_f32 v24, v24, v178, v179
	v_pk_mul_f32 v[176:177], v[22:23], v[34:35] op_sel_hi:[1,0]
	v_max3_f32 v22, v24, v20, v21
	v_max3_f32 v22, v22, v176, v177
	v_pk_mul_f32 v[16:17], v[16:17], v[34:35] op_sel_hi:[1,0]
	v_pk_mul_f32 v[30:31], v[18:19], v[34:35] op_sel_hi:[1,0]
	v_max3_f32 v18, v22, v16, v17
	v_max3_f32 v18, v18, v30, v31
	v_mov_b32_e32 v19, v18
	s_nop 1
	v_permlane16_swap_b32_e32 v19, v18
	s_waitcnt lgkmcnt(0)
	v_max_f32_e32 v19, v19, v19
	v_max_f32_e32 v18, v18, v19
	v_mov_b32_e32 v19, v18
	s_nop 1
	v_permlane32_swap_b32_e32 v19, v18
	s_and_saveexec_b64 s[8:9], s[42:43]
	s_cbranch_execz .LBB0_279
	s_lshl_b32 s5, s4, 2
	s_add_i32 s5, s5, 0
	v_lshl_add_u32 v22, v216, 4, s5
	s_waitcnt lgkmcnt(0)
	v_max_f32_e32 v19, v19, v19
	v_max_f32_e32 v18, v18, v18
	v_add_u32_e32 v22, 0x20400, v22
	v_max_f32_e32 v18, v18, v19
	ds_write_b32 v22, v18
.LBB0_279:
	s_or_b64 exec, exec, s[8:9]
	v_add_u32_e32 v217, 0xb0, v172
	s_mov_b64 s[8:9], -1
	s_and_b64 vcc, exec, s[6:7]
	s_cbranch_vccz .LBB0_281
	v_lshl_add_u32 v18, s74, 8, v217
	s_waitcnt lgkmcnt(0)
	v_ashrrev_i32_e32 v19, 31, v18
	v_lshlrev_b64 v[18:19], 6, v[18:19]
	v_lshl_add_u64 v[18:19], s[44:45], 0, v[18:19]
	v_lshl_add_u64 v[18:19], v[18:19], 0, v[140:141]
	flat_load_dwordx4 v[22:25], v[18:19]
	s_mov_b64 s[8:9], 0
	s_waitcnt vmcnt(0) lgkmcnt(0)
	v_mov_b32_e32 v18, v23
	v_mov_b32_e32 v19, v24
	v_mov_b32_e32 v23, v25
	v_pk_add_f32 v[18:19], v[18:19], v[22:23]
	s_nop 0
	v_add_f32_e32 v18, v18, v19
	v_mov_b32_e32 v19, v18
	s_nop 1
	v_permlane16_swap_b32_e32 v19, v18
	s_waitcnt lgkmcnt(0)
	v_add_f32_e32 v18, v18, v19
	ds_bpermute_b32 v19, v210, v18
	s_waitcnt lgkmcnt(0)
	v_add_f32_e32 v18, v18, v19
	v_fmamk_f32 v18, v18, 0x3a800000, v250
	v_rsq_f32_e32 v18, v18

.LBB0_283:
	s_waitcnt lgkmcnt(0)
	v_pk_mul_f32 v[12:13], v[12:13], v[18:19] op_sel_hi:[1,0]
	v_pk_mul_f32 v[186:187], v[14:15], v[18:19] op_sel_hi:[1,0]
	v_max3_f32 v14, v12, s95, v13
	v_max3_f32 v14, v14, v186, v187
	v_pk_mul_f32 v[8:9], v[8:9], v[18:19] op_sel_hi:[1,0]
	v_pk_mul_f32 v[184:185], v[10:11], v[18:19] op_sel_hi:[1,0]
	v_max3_f32 v10, v14, v8, v9
	v_max3_f32 v10, v10, v184, v185
	v_pk_mul_f32 v[4:5], v[4:5], v[18:19] op_sel_hi:[1,0]
	v_pk_mul_f32 v[182:183], v[6:7], v[18:19] op_sel_hi:[1,0]
	v_max3_f32 v6, v10, v4, v5
	v_max3_f32 v6, v6, v182, v183
	v_pk_mul_f32 v[14:15], v[2:3], v[18:19] op_sel_hi:[1,0]
	v_pk_mul_f32 v[2:3], v[0:1], v[18:19] op_sel_hi:[1,0]
	s_nop 0
	v_max3_f32 v0, v6, v2, v3
	v_max3_f32 v0, v0, v14, v15
	v_mov_b32_e32 v1, v0
	s_nop 1
	v_permlane16_swap_b32_e32 v1, v0
	s_waitcnt lgkmcnt(0)
	v_max_f32_e32 v1, v1, v1
	v_max_f32_e32 v0, v0, v1
	v_mov_b32_e32 v1, v0
	s_nop 1
	v_permlane32_swap_b32_e32 v1, v0
	s_and_saveexec_b64 s[6:7], s[42:43]
	s_cbranch_execz .LBB0_285
	s_lshl_b32 s5, s4, 2
	s_add_i32 s5, s5, 0
	v_lshl_add_u32 v6, v217, 4, s5
	s_waitcnt lgkmcnt(0)
	v_max_f32_e32 v1, v1, v1
	v_max_f32_e32 v0, v0, v0
	v_add_u32_e32 v6, 0x20400, v6
	v_max_f32_e32 v0, v0, v1
	ds_write_b32 v6, v0
.LBB0_285:
	s_or_b64 exec, exec, s[6:7]
	v_lshlrev_b32_e32 v140, 4, v172
	v_add_u32_e32 v0, 0, v140
	s_waitcnt lgkmcnt(0)
	s_barrier
	v_add_u32_e32 v0, 0x20400, v0
	ds_read_b128 v[22:25], v0
	v_lshl_add_u32 v159, s4, 2, v0
	s_waitcnt lgkmcnt(0)
	v_max_f32_e32 v1, v25, v25
	v_max_f32_e32 v6, v24, v24
	v_max_f32_e32 v1, v6, v1
	v_max3_f32 v1, v22, v23, v1
	v_sub_f32_e32 v6, v124, v1
	v_exp_f32_e32 v124, v6
	v_sub_f32_e32 v6, v125, v1
	v_exp_f32_e32 v125, v6
	v_sub_f32_e32 v6, v126, v1
	v_exp_f32_e32 v126, v6
	v_sub_f32_e32 v6, v127, v1
	v_exp_f32_e32 v127, v6
	v_sub_f32_e32 v7, v120, v1
	v_add_f32_e32 v6, 0, v124
	v_exp_f32_e32 v120, v7
	v_sub_f32_e32 v7, v121, v1
	v_add_f32_e32 v6, v125, v6
	v_exp_f32_e32 v121, v7
	v_sub_f32_e32 v7, v122, v1
	v_add_f32_e32 v6, v126, v6
	v_exp_f32_e32 v172, v7
	v_sub_f32_e32 v7, v123, v1
	v_add_f32_e32 v6, v127, v6
	v_exp_f32_e32 v173, v7
	v_sub_f32_e32 v7, v116, v1
	v_add_f32_e32 v6, v120, v6
	v_exp_f32_e32 v116, v7
	v_sub_f32_e32 v7, v117, v1
	v_add_f32_e32 v6, v121, v6
	v_exp_f32_e32 v117, v7
	v_sub_f32_e32 v7, v118, v1
	v_add_f32_e32 v6, v172, v6
	v_exp_f32_e32 v122, v7
	v_sub_f32_e32 v7, v119, v1
	v_add_f32_e32 v6, v173, v6
	v_exp_f32_e32 v123, v7
	v_sub_f32_e32 v7, v112, v1
	v_add_f32_e32 v6, v116, v6
	v_exp_f32_e32 v118, v7
	v_sub_f32_e32 v7, v113, v1
	v_add_f32_e32 v6, v117, v6
	v_exp_f32_e32 v119, v7
	v_sub_f32_e32 v7, v114, v1
	v_add_f32_e32 v6, v122, v6
	v_exp_f32_e32 v114, v7
	v_sub_f32_e32 v1, v115, v1
	v_add_f32_e32 v6, v123, v6
	v_exp_f32_e32 v115, v1
	v_add_f32_e32 v1, v118, v6
	v_add_f32_e32 v1, v119, v1
	v_add_f32_e32 v1, v114, v1
	v_add_f32_e32 v1, v115, v1
	v_mov_b32_e32 v6, v1
	s_nop 1
	v_permlane16_swap_b32_e32 v6, v1
	s_waitcnt lgkmcnt(0)
	v_add_f32_e32 v1, v1, v6
	v_mov_b32_e32 v6, v1
	s_nop 1
	v_permlane32_swap_b32_e32 v6, v1
	s_and_saveexec_b64 s[6:7], s[42:43]
	s_cbranch_execz .LBB0_287
	s_waitcnt lgkmcnt(0)
	v_add_f32_e32 v1, v1, v6
	ds_write_b32 v159, v1 offset:4096
.LBB0_287:
	s_or_b64 exec, exec, s[6:7]
	ds_read_b128 v[22:25], v0 offset:256
	s_waitcnt lgkmcnt(0)
	v_max_f32_e32 v1, v25, v25
	v_max_f32_e32 v6, v24, v24
	v_max_f32_e32 v1, v6, v1
	v_max3_f32 v1, v22, v23, v1
	v_sub_f32_e32 v6, v108, v1
	v_sub_f32_e32 v7, v109, v1
	v_exp_f32_e32 v108, v6
	v_sub_f32_e32 v10, v110, v1
	v_exp_f32_e32 v109, v7
	v_sub_f32_e32 v11, v111, v1
	v_exp_f32_e32 v110, v10
	v_exp_f32_e32 v111, v11
	v_sub_f32_e32 v7, v104, v1
	v_add_f32_e32 v6, 0, v108
	v_exp_f32_e32 v104, v7
	v_sub_f32_e32 v7, v105, v1
	v_add_f32_e32 v6, v109, v6
	v_exp_f32_e32 v105, v7
	v_sub_f32_e32 v7, v106, v1
	v_add_f32_e32 v6, v110, v6
	v_exp_f32_e32 v112, v7
	v_sub_f32_e32 v7, v107, v1
	v_add_f32_e32 v6, v111, v6
	v_exp_f32_e32 v113, v7
	v_sub_f32_e32 v7, v100, v1
	v_add_f32_e32 v6, v104, v6
	v_exp_f32_e32 v100, v7
	v_sub_f32_e32 v7, v101, v1
	v_add_f32_e32 v6, v105, v6
	v_exp_f32_e32 v101, v7
	v_sub_f32_e32 v7, v102, v1
	v_add_f32_e32 v6, v112, v6
	v_exp_f32_e32 v106, v7
	v_sub_f32_e32 v7, v103, v1
	v_add_f32_e32 v6, v113, v6
	v_exp_f32_e32 v107, v7
	v_sub_f32_e32 v7, v96, v1
	v_add_f32_e32 v6, v100, v6
	v_exp_f32_e32 v102, v7
	v_sub_f32_e32 v7, v97, v1
	v_add_f32_e32 v6, v101, v6
	v_exp_f32_e32 v103, v7
	v_sub_f32_e32 v7, v98, v1
	v_add_f32_e32 v6, v106, v6
	v_exp_f32_e32 v98, v7
	v_sub_f32_e32 v1, v99, v1
	v_add_f32_e32 v6, v107, v6
	v_exp_f32_e32 v99, v1
	v_add_f32_e32 v1, v102, v6
	v_add_f32_e32 v1, v103, v1
	v_add_f32_e32 v1, v98, v1
	v_add_f32_e32 v1, v99, v1
	v_mov_b32_e32 v6, v1
	s_nop 1
	v_permlane16_swap_b32_e32 v6, v1
	s_waitcnt lgkmcnt(0)
	v_add_f32_e32 v1, v1, v6
	v_mov_b32_e32 v6, v1
	s_nop 1
	v_permlane32_swap_b32_e32 v6, v1
	s_and_saveexec_b64 s[6:7], s[42:43]
	s_cbranch_execz .LBB0_289
	s_waitcnt lgkmcnt(0)
	v_add_f32_e32 v1, v1, v6
	ds_write_b32 v159, v1 offset:4352
.LBB0_289:
	s_or_b64 exec, exec, s[6:7]
	ds_read_b128 v[22:25], v0 offset:512
	s_waitcnt lgkmcnt(0)
	v_max_f32_e32 v1, v25, v25
	v_max_f32_e32 v6, v24, v24
	v_max_f32_e32 v1, v6, v1
	v_max3_f32 v1, v22, v23, v1
	v_sub_f32_e32 v6, v92, v1
	v_sub_f32_e32 v7, v93, v1
	v_exp_f32_e32 v92, v6
	v_sub_f32_e32 v10, v94, v1
	v_exp_f32_e32 v93, v7
	v_sub_f32_e32 v11, v95, v1
	v_exp_f32_e32 v94, v10
	v_exp_f32_e32 v95, v11
	v_sub_f32_e32 v7, v88, v1
	v_add_f32_e32 v6, 0, v92
	v_exp_f32_e32 v88, v7
	v_sub_f32_e32 v7, v89, v1
	v_add_f32_e32 v6, v93, v6
	v_exp_f32_e32 v89, v7
	v_sub_f32_e32 v7, v90, v1
	v_add_f32_e32 v6, v94, v6
	v_exp_f32_e32 v96, v7
	v_sub_f32_e32 v7, v91, v1
	v_add_f32_e32 v6, v95, v6
	v_exp_f32_e32 v97, v7
	v_sub_f32_e32 v7, v84, v1
	v_add_f32_e32 v6, v88, v6
	v_exp_f32_e32 v84, v7
	v_sub_f32_e32 v7, v85, v1
	v_add_f32_e32 v6, v89, v6
	v_exp_f32_e32 v85, v7
	v_sub_f32_e32 v7, v86, v1
	v_add_f32_e32 v6, v96, v6
	v_exp_f32_e32 v90, v7
	v_sub_f32_e32 v7, v87, v1
	v_add_f32_e32 v6, v97, v6
	v_exp_f32_e32 v91, v7
	v_sub_f32_e32 v7, v80, v1
	v_add_f32_e32 v6, v84, v6
	v_exp_f32_e32 v86, v7
	v_sub_f32_e32 v7, v81, v1
	v_add_f32_e32 v6, v85, v6
	v_exp_f32_e32 v87, v7
	v_sub_f32_e32 v7, v82, v1
	v_add_f32_e32 v6, v90, v6
	v_exp_f32_e32 v82, v7
	v_sub_f32_e32 v1, v83, v1
	v_add_f32_e32 v6, v91, v6
	v_exp_f32_e32 v83, v1
	v_add_f32_e32 v1, v86, v6
	v_add_f32_e32 v1, v87, v1
	v_add_f32_e32 v1, v82, v1
	v_add_f32_e32 v1, v83, v1
	v_mov_b32_e32 v6, v1
	s_nop 1
	v_permlane16_swap_b32_e32 v6, v1
	s_waitcnt lgkmcnt(0)
	v_add_f32_e32 v1, v1, v6
	v_mov_b32_e32 v6, v1
	s_nop 1
	v_permlane32_swap_b32_e32 v6, v1
	s_and_saveexec_b64 s[6:7], s[42:43]
	s_cbranch_execz .LBB0_291
	s_waitcnt lgkmcnt(0)
	v_add_f32_e32 v1, v1, v6
	ds_write_b32 v159, v1 offset:4608
.LBB0_291:
	s_or_b64 exec, exec, s[6:7]
	ds_read_b128 v[22:25], v0 offset:768
	s_waitcnt lgkmcnt(0)
	v_max_f32_e32 v1, v25, v25
	v_max_f32_e32 v6, v24, v24
	v_max_f32_e32 v1, v6, v1
	v_max3_f32 v1, v22, v23, v1
	v_sub_f32_e32 v6, v160, v1
	v_sub_f32_e32 v7, v161, v1
	v_exp_f32_e32 v60, v6
	v_sub_f32_e32 v10, v78, v1
	v_exp_f32_e32 v61, v7
	v_sub_f32_e32 v11, v79, v1
	v_exp_f32_e32 v78, v10
	v_exp_f32_e32 v79, v11
	v_sub_f32_e32 v7, v72, v1
	v_add_f32_e32 v6, 0, v60
	v_exp_f32_e32 v72, v7
	v_sub_f32_e32 v7, v73, v1
	v_add_f32_e32 v6, v61, v6
	v_exp_f32_e32 v73, v7
	v_sub_f32_e32 v7, v74, v1
	v_add_f32_e32 v6, v78, v6
	v_exp_f32_e32 v74, v7
	v_sub_f32_e32 v7, v75, v1
	v_add_f32_e32 v6, v79, v6
	v_exp_f32_e32 v75, v7
	v_sub_f32_e32 v7, v68, v1
	v_add_f32_e32 v6, v72, v6
	v_exp_f32_e32 v52, v7
	v_sub_f32_e32 v7, v69, v1
	v_add_f32_e32 v6, v73, v6
	v_exp_f32_e32 v53, v7
	v_sub_f32_e32 v7, v70, v1
	v_add_f32_e32 v6, v74, v6
	v_exp_f32_e32 v70, v7
	v_sub_f32_e32 v7, v71, v1
	v_add_f32_e32 v6, v75, v6
	v_exp_f32_e32 v71, v7
	v_sub_f32_e32 v7, v64, v1
	v_add_f32_e32 v6, v52, v6
	v_exp_f32_e32 v68, v7
	v_sub_f32_e32 v7, v65, v1
	v_add_f32_e32 v6, v53, v6
	v_exp_f32_e32 v69, v7
	v_sub_f32_e32 v7, v66, v1
	v_add_f32_e32 v6, v70, v6
	v_exp_f32_e32 v80, v7
	v_sub_f32_e32 v1, v67, v1
	v_add_f32_e32 v6, v71, v6
	v_exp_f32_e32 v81, v1
	v_add_f32_e32 v1, v68, v6
	v_add_f32_e32 v1, v69, v1
	v_add_f32_e32 v1, v80, v1
	v_add_f32_e32 v1, v81, v1
	v_mov_b32_e32 v6, v1
	s_nop 1
	v_permlane16_swap_b32_e32 v6, v1
	s_waitcnt lgkmcnt(0)
	v_add_f32_e32 v1, v1, v6
	v_mov_b32_e32 v6, v1
	s_nop 1
	v_permlane32_swap_b32_e32 v6, v1
	s_and_saveexec_b64 s[6:7], s[42:43]
	s_cbranch_execz .LBB0_293
	s_waitcnt lgkmcnt(0)
	v_add_f32_e32 v1, v1, v6
	ds_write_b32 v159, v1 offset:4864
.LBB0_293:
	s_or_b64 exec, exec, s[6:7]
	ds_read_b128 v[22:25], v0 offset:2048
	s_waitcnt lgkmcnt(0)
	v_max_f32_e32 v1, v25, v25
	v_max_f32_e32 v6, v24, v24
	v_max_f32_e32 v1, v6, v1
	v_max3_f32 v1, v22, v23, v1
	v_sub_f32_e32 v6, v166, v1
	v_sub_f32_e32 v7, v167, v1
	v_exp_f32_e32 v56, v6
	v_sub_f32_e32 v10, v62, v1
	v_exp_f32_e32 v57, v7
	v_sub_f32_e32 v11, v63, v1
	v_exp_f32_e32 v62, v10
	v_exp_f32_e32 v63, v11
	v_sub_f32_e32 v7, v58, v1
	v_add_f32_e32 v6, 0, v56
	v_exp_f32_e32 v58, v7
	v_sub_f32_e32 v7, v59, v1
	v_add_f32_e32 v6, v57, v6
	v_exp_f32_e32 v59, v7
	v_sub_f32_e32 v7, v164, v1
	v_add_f32_e32 v6, v62, v6
	v_exp_f32_e32 v66, v7
	v_sub_f32_e32 v7, v165, v1
	v_add_f32_e32 v6, v63, v6
	v_exp_f32_e32 v67, v7
	v_sub_f32_e32 v7, v162, v1
	v_add_f32_e32 v6, v58, v6
	v_exp_f32_e32 v40, v7
	v_sub_f32_e32 v7, v163, v1
	v_add_f32_e32 v6, v59, v6
	v_exp_f32_e32 v41, v7
	v_sub_f32_e32 v7, v76, v1
	v_add_f32_e32 v6, v66, v6
	v_exp_f32_e32 v50, v7
	v_sub_f32_e32 v7, v77, v1
	v_add_f32_e32 v6, v67, v6
	v_exp_f32_e32 v51, v7
	v_sub_f32_e32 v7, v48, v1
	v_add_f32_e32 v6, v40, v6
	v_exp_f32_e32 v48, v7
	v_sub_f32_e32 v7, v49, v1
	v_add_f32_e32 v6, v41, v6
	v_exp_f32_e32 v49, v7
	v_sub_f32_e32 v7, v54, v1
	v_add_f32_e32 v6, v50, v6
	v_exp_f32_e32 v64, v7
	v_sub_f32_e32 v1, v55, v1
	v_add_f32_e32 v6, v51, v6
	v_exp_f32_e32 v65, v1
	v_add_f32_e32 v1, v48, v6
	v_add_f32_e32 v1, v49, v1
	v_add_f32_e32 v1, v64, v1
	v_add_f32_e32 v1, v65, v1
	v_mov_b32_e32 v6, v1
	s_nop 1
	v_permlane16_swap_b32_e32 v6, v1
	s_waitcnt lgkmcnt(0)
	v_add_f32_e32 v1, v1, v6
	v_mov_b32_e32 v6, v1
	s_nop 1
	v_permlane32_swap_b32_e32 v6, v1
	s_and_saveexec_b64 s[6:7], s[42:43]
	s_cbranch_execz .LBB0_295
	s_waitcnt lgkmcnt(0)
	v_add_f32_e32 v1, v1, v6
	ds_write_b32 v159, v1 offset:6144
.LBB0_295:
	s_or_b64 exec, exec, s[6:7]
	ds_read_b128 v[22:25], v0 offset:2304
	s_waitcnt lgkmcnt(0)
	v_max_f32_e32 v1, v25, v25
	v_max_f32_e32 v6, v24, v24
	v_max_f32_e32 v1, v6, v1
	v_max3_f32 v1, v22, v23, v1
	v_sub_f32_e32 v6, v44, v1
	v_sub_f32_e32 v7, v45, v1
	v_exp_f32_e32 v36, v6
	v_sub_f32_e32 v10, v174, v1
	v_exp_f32_e32 v37, v7
	v_sub_f32_e32 v11, v175, v1
	v_exp_f32_e32 v44, v10
	v_exp_f32_e32 v45, v11
	v_sub_f32_e32 v7, v42, v1
	v_add_f32_e32 v6, 0, v36
	v_exp_f32_e32 v42, v7
	v_sub_f32_e32 v7, v43, v1
	v_add_f32_e32 v6, v37, v6
	v_exp_f32_e32 v43, v7
	v_sub_f32_e32 v7, v170, v1
	v_add_f32_e32 v6, v44, v6
	v_exp_f32_e32 v54, v7
	v_sub_f32_e32 v7, v171, v1
	v_add_f32_e32 v6, v45, v6
	v_exp_f32_e32 v55, v7
	v_sub_f32_e32 v7, v168, v1
	v_add_f32_e32 v6, v42, v6
	v_exp_f32_e32 v24, v7
	v_sub_f32_e32 v7, v169, v1
	v_add_f32_e32 v6, v43, v6
	v_exp_f32_e32 v25, v7
	v_sub_f32_e32 v7, v46, v1
	v_add_f32_e32 v6, v54, v6
	v_exp_f32_e32 v34, v7
	v_sub_f32_e32 v7, v47, v1
	v_add_f32_e32 v6, v55, v6
	v_exp_f32_e32 v35, v7
	v_sub_f32_e32 v7, v32, v1
	v_add_f32_e32 v6, v24, v6
	v_exp_f32_e32 v32, v7
	v_sub_f32_e32 v7, v33, v1
	v_add_f32_e32 v6, v25, v6
	v_exp_f32_e32 v33, v7
	v_sub_f32_e32 v7, v38, v1
	v_add_f32_e32 v6, v34, v6
	v_exp_f32_e32 v46, v7
	v_sub_f32_e32 v1, v39, v1
	v_add_f32_e32 v6, v35, v6
	v_exp_f32_e32 v47, v1
	v_add_f32_e32 v1, v32, v6
	v_add_f32_e32 v1, v33, v1
	v_add_f32_e32 v1, v46, v1
	v_add_f32_e32 v1, v47, v1
	v_mov_b32_e32 v6, v1
	s_nop 1
	v_permlane16_swap_b32_e32 v6, v1
	s_waitcnt lgkmcnt(0)
	v_add_f32_e32 v1, v1, v6
	v_mov_b32_e32 v6, v1
	s_nop 1
	v_permlane32_swap_b32_e32 v6, v1
	s_and_saveexec_b64 s[6:7], s[42:43]
	s_cbranch_execz .LBB0_297
	s_waitcnt lgkmcnt(0)
	v_add_f32_e32 v1, v1, v6
	ds_write_b32 v159, v1 offset:6400
.LBB0_297:
	s_or_b64 exec, exec, s[6:7]
	ds_read_b128 v[142:145], v0 offset:2560
	s_waitcnt lgkmcnt(0)
	v_max_f32_e32 v1, v145, v145
	v_max_f32_e32 v6, v144, v144
	v_max_f32_e32 v1, v6, v1
	v_max3_f32 v1, v142, v143, v1
	v_sub_f32_e32 v6, v28, v1
	v_sub_f32_e32 v7, v29, v1
	v_exp_f32_e32 v22, v6
	v_sub_f32_e32 v10, v180, v1
	v_exp_f32_e32 v23, v7
	v_sub_f32_e32 v11, v181, v1
	v_exp_f32_e32 v28, v10
	v_exp_f32_e32 v29, v11
	v_sub_f32_e32 v7, v26, v1
	v_add_f32_e32 v6, 0, v22
	v_exp_f32_e32 v26, v7
	v_sub_f32_e32 v7, v27, v1
	v_add_f32_e32 v6, v23, v6
	v_exp_f32_e32 v27, v7
	v_sub_f32_e32 v7, v178, v1
	v_add_f32_e32 v6, v28, v6
	v_exp_f32_e32 v38, v7
	v_sub_f32_e32 v7, v179, v1
	v_add_f32_e32 v6, v29, v6
	v_exp_f32_e32 v39, v7
	v_sub_f32_e32 v7, v20, v1
	v_add_f32_e32 v6, v26, v6
	v_exp_f32_e32 v10, v7
	v_sub_f32_e32 v7, v21, v1
	v_add_f32_e32 v6, v27, v6
	v_exp_f32_e32 v11, v7
	v_sub_f32_e32 v7, v176, v1
	v_add_f32_e32 v6, v38, v6
	v_exp_f32_e32 v20, v7
	v_sub_f32_e32 v7, v177, v1
	v_add_f32_e32 v6, v39, v6
	v_exp_f32_e32 v21, v7
	v_sub_f32_e32 v7, v16, v1
	v_add_f32_e32 v6, v10, v6
	v_exp_f32_e32 v18, v7
	v_sub_f32_e32 v7, v17, v1
	v_add_f32_e32 v6, v11, v6
	v_exp_f32_e32 v19, v7
	v_sub_f32_e32 v7, v30, v1
	v_add_f32_e32 v6, v20, v6
	v_exp_f32_e32 v30, v7
	v_sub_f32_e32 v1, v31, v1
	v_add_f32_e32 v6, v21, v6
	v_exp_f32_e32 v31, v1
	v_add_f32_e32 v1, v18, v6
	v_add_f32_e32 v1, v19, v1
	v_add_f32_e32 v1, v30, v1
	v_add_f32_e32 v1, v31, v1
	v_mov_b32_e32 v6, v1
	s_nop 1
	v_permlane16_swap_b32_e32 v6, v1
	s_waitcnt lgkmcnt(0)
	v_add_f32_e32 v1, v1, v6
	v_mov_b32_e32 v6, v1
	s_nop 1
	v_permlane32_swap_b32_e32 v6, v1
	s_and_saveexec_b64 s[6:7], s[42:43]
	s_cbranch_execz .LBB0_299
	s_waitcnt lgkmcnt(0)
	v_add_f32_e32 v1, v1, v6
	ds_write_b32 v159, v1 offset:6656
.LBB0_299:
	s_or_b64 exec, exec, s[6:7]
	ds_read_b128 v[142:145], v0 offset:2816
	s_waitcnt lgkmcnt(0)
	v_max_f32_e32 v0, v145, v145
	v_max_f32_e32 v1, v144, v144
	v_max_f32_e32 v0, v1, v0
	v_max3_f32 v76, v142, v143, v0
	v_sub_f32_e32 v0, v12, v76
	v_sub_f32_e32 v1, v13, v76
	v_exp_f32_e32 v6, v0
	v_sub_f32_e32 v12, v186, v76
	v_exp_f32_e32 v7, v1
	v_sub_f32_e32 v13, v187, v76
	v_exp_f32_e32 v12, v12
	v_exp_f32_e32 v13, v13
	v_sub_f32_e32 v1, v8, v76
	v_add_f32_e32 v0, 0, v6
	v_exp_f32_e32 v8, v1
	v_sub_f32_e32 v1, v9, v76
	v_add_f32_e32 v0, v7, v0
	v_exp_f32_e32 v9, v1
	v_sub_f32_e32 v1, v184, v76
	v_add_f32_e32 v0, v12, v0
	v_exp_f32_e32 v16, v1
	v_sub_f32_e32 v1, v185, v76
	v_add_f32_e32 v0, v13, v0
	v_exp_f32_e32 v17, v1
	v_add_f32_e32 v0, v8, v0
	v_add_f32_e32 v0, v9, v0
	v_add_f32_e32 v0, v16, v0
	v_add_f32_e32 v77, v17, v0
	v_sub_f32_e32 v0, v4, v76
	v_exp_f32_e32 v0, v0
	v_sub_f32_e32 v1, v5, v76
	v_exp_f32_e32 v1, v1
	v_sub_f32_e32 v4, v182, v76
	v_exp_f32_e32 v4, v4
	v_sub_f32_e32 v5, v183, v76
	v_exp_f32_e32 v5, v5
	v_sub_f32_e32 v2, v2, v76
	v_add_f32_e32 v77, v0, v77
	v_exp_f32_e32 v2, v2
	v_sub_f32_e32 v3, v3, v76
	v_add_f32_e32 v77, v1, v77
	v_exp_f32_e32 v3, v3
	v_sub_f32_e32 v14, v14, v76
	v_add_f32_e32 v77, v4, v77
	v_exp_f32_e32 v14, v14
	v_sub_f32_e32 v15, v15, v76
	v_add_f32_e32 v77, v5, v77
	v_exp_f32_e32 v15, v15
	v_add_f32_e32 v76, v2, v77
	v_add_f32_e32 v76, v3, v76
	v_add_f32_e32 v76, v14, v76
	v_add_f32_e32 v76, v15, v76
	v_mov_b32_e32 v77, v76
	s_nop 1
	v_permlane16_swap_b32_e32 v77, v76
	s_waitcnt lgkmcnt(0)
	v_add_f32_e32 v76, v76, v77
	v_mov_b32_e32 v77, v76
	s_nop 1
	v_permlane32_swap_b32_e32 v77, v76
	s_and_saveexec_b64 s[6:7], s[42:43]
	s_cbranch_execz .LBB0_301
	s_waitcnt lgkmcnt(0)
	v_add_f32_e32 v76, v76, v77
	ds_write_b32 v159, v76 offset:6912

.LBB0_336:
	s_mov_b32 s6, -1
	s_lshl_b32 s5, s5, 8
	v_mbcnt_lo_u32_b32 v128, s6, 0
	v_mbcnt_hi_u32_b32 v128, s6, v128
	s_getreg_b32 s6, hwreg(HW_REG_HW_ID, 0, 6)
	s_and_b32 s6, s6, 63
	s_lshl_b32 s6, s6, 2
	s_add_i32 s6, s6, 0
	s_add_i32 s6, s6, 0x20200
	v_mov_b32_e32 v129, s6
	ds_read_b32 v129, v129
	v_bfrev_b32_e32 v130, 0.5
	s_lshl_b32 s56, s4, 2
	s_ashr_i32 s57, s56, 31
	s_waitcnt lgkmcnt(0)
	v_readfirstlane_b32 s6, v129
	s_nop 1
	v_lshl_add_u32 v128, s6, 6, v128
	s_nop 0
	v_readfirstlane_b32 s6, v128
	s_bfe_u32 s8, s6, 0x20006
	s_ashr_i32 s6, s6, 2
	s_andn2_b32 s6, s6, 63
	s_add_i32 s6, s6, s5
	v_and_or_b32 v170, v128, 15, s6
	s_lshl_b32 s5, s4, 8
	s_lshl_b32 s6, s8, 5
	v_bfe_u32 v129, v128, 4, 2
	s_or_b32 s5, s6, s5
	v_lshl_or_b32 v168, v129, 3, s5
	v_ashrrev_i32_e32 v169, 31, v168
	v_lshlrev_b64 v[146:147], 1, v[168:169]
	v_ashrrev_i32_e32 v171, 31, v170
	v_lshlrev_b32_e32 v128, 2, v128
	v_lshl_add_u64 v[172:173], s[68:69], 0, v[146:147]
	v_lshlrev_b64 v[148:149], 11, v[170:171]
	v_bitop3_b32 v181, v128, 64, v130 bitop3:0x6c
	v_bitop3_b32 v180, v128, s84, v130 bitop3:0x6c
	v_cmp_eq_u32_e32 vcc, 0, v129
	v_lshl_add_u64 v[128:129], v[172:173], 0, v[148:149]
	global_load_dwordx4 v[142:145], v[128:129], off
	global_load_dwordx4 v[136:139], v[128:129], off offset:256
	v_or_b32_e32 v174, 16, v170
	v_ashrrev_i32_e32 v175, 31, v174
	v_lshlrev_b64 v[176:177], 11, v[174:175]
	v_lshl_add_u64 v[128:129], v[172:173], 0, v[176:177]
	global_load_dwordx4 v[132:135], v[128:129], off
	s_nop 0
	global_load_dwordx4 v[128:131], v[128:129], off offset:256
	s_waitcnt vmcnt(0)
	v_lshlrev_b32_e32 v150, 16, v142
	v_and_b32_e32 v151, 0xffff0000, v142
	v_lshlrev_b32_e32 v142, 16, v143
	v_and_b32_e32 v143, 0xffff0000, v143
	v_lshlrev_b32_e32 v152, 16, v144
	v_and_b32_e32 v153, 0xffff0000, v144
	v_lshlrev_b32_e32 v144, 16, v145
	v_and_b32_e32 v145, 0xffff0000, v145
	v_pk_add_f32 v[124:125], v[124:125], v[150:151]
	v_pk_add_f32 v[126:127], v[126:127], v[142:143]
	v_pk_add_f32 v[142:143], v[122:123], v[144:145]
	v_pk_add_f32 v[122:123], v[120:121], v[152:153]
	v_cvt_pk_bf16_f32 v120, v124, v125
	v_lshl_add_u64 v[124:125], s[68:69], 0, v[148:149]
	v_lshl_add_u64 v[124:125], v[124:125], 0, v[146:147]
	v_cvt_pk_bf16_f32 v121, v126, v127
	v_cvt_pk_bf16_f32 v122, v122, v123
	v_cvt_pk_bf16_f32 v123, v142, v143
	global_store_dwordx4 v[124:125], v[120:123], off nt
	v_lshlrev_b32_e32 v126, 16, v120
	v_and_b32_e32 v127, 0xffff0000, v138
	v_and_b32_e32 v120, 0xffff0000, v120
	v_mul_f32_e32 v120, v120, v120
	v_fmac_f32_e32 v120, v126, v126
	v_lshlrev_b32_e32 v126, 16, v121
	v_and_b32_e32 v121, 0xffff0000, v121
	v_mul_f32_e32 v121, v121, v121
	v_fmac_f32_e32 v121, v126, v126
	v_add_f32_e32 v120, v120, v121
	v_lshlrev_b32_e32 v121, 16, v122
	v_and_b32_e32 v122, 0xffff0000, v122
	v_mul_f32_e32 v122, v122, v122
	v_fmac_f32_e32 v122, v121, v121
	v_add_f32_e32 v120, v120, v122
	v_and_b32_e32 v122, 0xffff0000, v123
	v_lshlrev_b32_e32 v121, 16, v123
	v_mul_f32_e32 v122, v122, v122
	v_fmac_f32_e32 v122, v121, v121
	v_add_f32_e32 v142, v120, v122
	v_lshlrev_b32_e32 v120, 16, v136
	v_and_b32_e32 v121, 0xffff0000, v136
	v_lshlrev_b32_e32 v122, 16, v137
	v_and_b32_e32 v123, 0xffff0000, v137
	v_lshlrev_b32_e32 v126, 16, v138
	v_lshlrev_b32_e32 v136, 16, v139
	v_and_b32_e32 v137, 0xffff0000, v139
	v_pk_add_f32 v[116:117], v[116:117], v[120:121]
	v_pk_add_f32 v[120:121], v[114:115], v[136:137]
	v_pk_add_f32 v[114:115], v[112:113], v[126:127]
	v_cvt_pk_bf16_f32 v112, v116, v117
	v_pk_add_f32 v[118:119], v[118:119], v[122:123]
	v_lshlrev_b32_e32 v116, 16, v112
	v_cvt_pk_bf16_f32 v113, v118, v119
	v_cvt_pk_bf16_f32 v114, v114, v115
	v_cvt_pk_bf16_f32 v115, v120, v121
	global_store_dwordx4 v[124:125], v[112:115], off offset:256 nt
	s_nop 1
	v_and_b32_e32 v112, 0xffff0000, v112
	v_mul_f32_e32 v112, v112, v112
	v_fmac_f32_e32 v112, v116, v116
	v_lshlrev_b32_e32 v116, 16, v113
	v_and_b32_e32 v113, 0xffff0000, v113
	v_mul_f32_e32 v113, v113, v113
	v_add_f32_e32 v112, v142, v112
	v_fmac_f32_e32 v113, v116, v116
	v_add_f32_e32 v112, v112, v113
	v_lshlrev_b32_e32 v113, 16, v114
	v_and_b32_e32 v114, 0xffff0000, v114
	v_mul_f32_e32 v114, v114, v114
	v_fmac_f32_e32 v114, v113, v113
	v_add_f32_e32 v112, v112, v114
	v_and_b32_e32 v114, 0xffff0000, v115
	v_lshlrev_b32_e32 v113, 16, v115
	v_mul_f32_e32 v114, v114, v114
	v_fmac_f32_e32 v114, v113, v113
	v_add_f32_e32 v112, v112, v114
	v_mov_b32_e32 v113, v112
	s_nop 1
	v_permlane16_swap_b32_e32 v113, v112
	s_waitcnt lgkmcnt(0)
	v_add_f32_e32 v112, v112, v113
	v_mov_b32_e32 v113, v112
	s_nop 1
	v_permlane32_swap_b32_e32 v113, v112
	s_and_saveexec_b64 s[6:7], vcc
	s_cbranch_execz .LBB0_338
	s_waitcnt lgkmcnt(0)
	v_add_f32_e32 v114, v112, v113
	v_lshlrev_b64 v[112:113], 6, v[170:171]
	v_lshl_add_u64 v[112:113], s[46:47], 0, v[112:113]
	v_lshl_add_u64 v[112:113], s[56:57], 2, v[112:113]
	s_lshl_b32 s38, s8, 2
	v_lshl_add_u64 v[112:113], v[112:113], 0, s[38:39]
	flat_store_dword v[112:113], v114
.LBB0_338:
	s_or_b64 exec, exec, s[6:7]
	v_lshlrev_b32_e32 v112, 16, v132
	s_waitcnt lgkmcnt(0)
	v_and_b32_e32 v113, 0xffff0000, v132
	v_lshlrev_b32_e32 v116, 16, v134
	v_and_b32_e32 v117, 0xffff0000, v134
	v_lshlrev_b32_e32 v118, 16, v135
	v_and_b32_e32 v119, 0xffff0000, v135
	v_pk_add_f32 v[108:109], v[108:109], v[112:113]
	v_lshlrev_b32_e32 v114, 16, v133
	v_and_b32_e32 v115, 0xffff0000, v133
	v_pk_add_f32 v[112:113], v[106:107], v[118:119]
	v_pk_add_f32 v[106:107], v[104:105], v[116:117]
	v_cvt_pk_bf16_f32 v104, v108, v109
	v_lshl_add_u64 v[108:109], s[68:69], 0, v[176:177]
	v_pk_add_f32 v[110:111], v[110:111], v[114:115]
	v_lshl_add_u64 v[108:109], v[168:169], 1, v[108:109]
	v_cvt_pk_bf16_f32 v105, v110, v111
	v_cvt_pk_bf16_f32 v106, v106, v107
	v_cvt_pk_bf16_f32 v107, v112, v113
	global_store_dwordx4 v[108:109], v[104:107], off nt
	v_lshlrev_b32_e32 v110, 16, v104
	v_and_b32_e32 v111, 0xffff0000, v130
	v_and_b32_e32 v104, 0xffff0000, v104
	v_mul_f32_e32 v104, v104, v104
	v_fmac_f32_e32 v104, v110, v110
	v_lshlrev_b32_e32 v110, 16, v105
	v_and_b32_e32 v105, 0xffff0000, v105
	v_mul_f32_e32 v105, v105, v105
	v_fmac_f32_e32 v105, v110, v110
	v_add_f32_e32 v104, v104, v105
	v_lshlrev_b32_e32 v105, 16, v106
	v_and_b32_e32 v106, 0xffff0000, v106
	v_mul_f32_e32 v106, v106, v106
	v_fmac_f32_e32 v106, v105, v105
	v_add_f32_e32 v104, v104, v106
	v_and_b32_e32 v106, 0xffff0000, v107
	v_lshlrev_b32_e32 v105, 16, v107
	v_mul_f32_e32 v106, v106, v106
	v_fmac_f32_e32 v106, v105, v105
	v_add_f32_e32 v114, v104, v106
	v_lshlrev_b32_e32 v104, 16, v128
	v_and_b32_e32 v105, 0xffff0000, v128
	v_lshlrev_b32_e32 v110, 16, v130
	v_lshlrev_b32_e32 v106, 16, v129
	v_and_b32_e32 v107, 0xffff0000, v129
	v_lshlrev_b32_e32 v112, 16, v131
	v_and_b32_e32 v113, 0xffff0000, v131
	v_pk_add_f32 v[100:101], v[100:101], v[104:105]
	v_pk_add_f32 v[96:97], v[96:97], v[110:111]
	v_pk_add_f32 v[102:103], v[102:103], v[106:107]
	v_pk_add_f32 v[104:105], v[98:99], v[112:113]
	v_cvt_pk_bf16_f32 v98, v100, v101
	v_cvt_pk_bf16_f32 v99, v102, v103
	v_cvt_pk_bf16_f32 v100, v96, v97
	s_nop 0
	v_and_b32_e32 v97, 0xffff0000, v98
	v_lshlrev_b32_e32 v96, 16, v98
	v_mul_f32_e32 v97, v97, v97
	v_fmac_f32_e32 v97, v96, v96
	v_and_b32_e32 v102, 0xffff0000, v99
	v_add_f32_e32 v96, v114, v97
	v_lshlrev_b32_e32 v97, 16, v99
	v_mul_f32_e32 v102, v102, v102
	v_fmac_f32_e32 v102, v97, v97
	v_add_f32_e32 v96, v96, v102
	v_and_b32_e32 v102, 0xffff0000, v100
	v_lshlrev_b32_e32 v97, 16, v100
	v_mul_f32_e32 v102, v102, v102
	v_fmac_f32_e32 v102, v97, v97
	v_cvt_pk_bf16_f32 v101, v104, v105
	v_add_f32_e32 v96, v96, v102
	v_and_b32_e32 v102, 0xffff0000, v101
	v_lshlrev_b32_e32 v97, 16, v101
	v_mul_f32_e32 v102, v102, v102
	v_fmac_f32_e32 v102, v97, v97
	v_add_f32_e32 v96, v96, v102
	v_mov_b32_e32 v97, v96
	s_nop 1
	v_permlane16_swap_b32_e32 v97, v96
	global_store_dwordx4 v[108:109], v[98:101], off offset:256 nt
	s_waitcnt lgkmcnt(0)
	v_add_f32_e32 v96, v96, v97
	v_mov_b32_e32 v97, v96
	s_nop 1
	v_permlane32_swap_b32_e32 v97, v96
	s_and_saveexec_b64 s[6:7], vcc
	s_cbranch_execz .LBB0_340
	s_waitcnt lgkmcnt(0)
	v_add_f32_e32 v98, v96, v97
	v_lshlrev_b64 v[96:97], 6, v[174:175]
	v_lshl_add_u64 v[96:97], s[46:47], 0, v[96:97]
	v_lshl_add_u64 v[96:97], s[56:57], 2, v[96:97]
	s_lshl_b32 s38, s8, 2
	v_lshl_add_u64 v[96:97], v[96:97], 0, s[38:39]
	flat_store_dword v[96:97], v98
.LBB0_340:
	s_or_b64 exec, exec, s[6:7]
	v_or_b32_e32 v112, 32, v170
	v_ashrrev_i32_e32 v113, 31, v112
	v_lshlrev_b64 v[118:119], 11, v[112:113]
	s_waitcnt lgkmcnt(0)
	v_lshl_add_u64 v[96:97], v[172:173], 0, v[118:119]
	global_load_dwordx4 v[114:117], v[96:97], off
	global_load_dwordx4 v[104:107], v[96:97], off offset:256
	v_or_b32_e32 v108, 48, v170
	v_ashrrev_i32_e32 v109, 31, v108
	v_lshlrev_b64 v[110:111], 11, v[108:109]
	v_lshl_add_u64 v[96:97], v[172:173], 0, v[110:111]
	global_load_dwordx4 v[100:103], v[96:97], off
	s_nop 0
	global_load_dwordx4 v[96:99], v[96:97], off offset:256
	s_waitcnt vmcnt(0)
	v_lshlrev_b32_e32 v120, 16, v114
	v_and_b32_e32 v121, 0xffff0000, v114
	v_lshlrev_b32_e32 v114, 16, v115
	v_and_b32_e32 v115, 0xffff0000, v115
	v_lshlrev_b32_e32 v122, 16, v116
	v_and_b32_e32 v123, 0xffff0000, v116
	v_lshlrev_b32_e32 v116, 16, v117
	v_and_b32_e32 v117, 0xffff0000, v117
	v_pk_add_f32 v[92:93], v[92:93], v[120:121]
	v_pk_add_f32 v[94:95], v[94:95], v[114:115]
	v_pk_add_f32 v[114:115], v[90:91], v[116:117]
	v_pk_add_f32 v[90:91], v[88:89], v[122:123]
	v_cvt_pk_bf16_f32 v88, v92, v93
	v_lshl_add_u64 v[92:93], s[68:69], 0, v[118:119]
	v_lshl_add_u64 v[92:93], v[168:169], 1, v[92:93]
	v_cvt_pk_bf16_f32 v89, v94, v95
	v_cvt_pk_bf16_f32 v90, v90, v91
	v_cvt_pk_bf16_f32 v91, v114, v115
	global_store_dwordx4 v[92:93], v[88:91], off nt
	v_lshlrev_b32_e32 v94, 16, v88
	v_and_b32_e32 v95, 0xffff0000, v106
	v_and_b32_e32 v88, 0xffff0000, v88
	v_mul_f32_e32 v88, v88, v88
	v_fmac_f32_e32 v88, v94, v94
	v_lshlrev_b32_e32 v94, 16, v89
	v_and_b32_e32 v89, 0xffff0000, v89
	v_mul_f32_e32 v89, v89, v89
	v_fmac_f32_e32 v89, v94, v94
	v_add_f32_e32 v88, v88, v89
	v_lshlrev_b32_e32 v89, 16, v90
	v_and_b32_e32 v90, 0xffff0000, v90
	v_mul_f32_e32 v90, v90, v90
	v_fmac_f32_e32 v90, v89, v89
	v_add_f32_e32 v88, v88, v90
	v_and_b32_e32 v90, 0xffff0000, v91
	v_lshlrev_b32_e32 v89, 16, v91
	v_mul_f32_e32 v90, v90, v90
	v_fmac_f32_e32 v90, v89, v89
	v_add_f32_e32 v114, v88, v90
	v_lshlrev_b32_e32 v88, 16, v104
	v_and_b32_e32 v89, 0xffff0000, v104
	v_lshlrev_b32_e32 v90, 16, v105
	v_and_b32_e32 v91, 0xffff0000, v105
	v_lshlrev_b32_e32 v94, 16, v106
	v_lshlrev_b32_e32 v104, 16, v107
	v_and_b32_e32 v105, 0xffff0000, v107
	v_pk_add_f32 v[84:85], v[84:85], v[88:89]
	v_pk_add_f32 v[88:89], v[82:83], v[104:105]
	v_pk_add_f32 v[82:83], v[80:81], v[94:95]
	v_cvt_pk_bf16_f32 v80, v84, v85
	v_pk_add_f32 v[86:87], v[86:87], v[90:91]
	v_lshlrev_b32_e32 v84, 16, v80
	v_cvt_pk_bf16_f32 v81, v86, v87
	v_cvt_pk_bf16_f32 v82, v82, v83
	v_cvt_pk_bf16_f32 v83, v88, v89
	global_store_dwordx4 v[92:93], v[80:83], off offset:256 nt
	s_nop 1
	v_and_b32_e32 v80, 0xffff0000, v80
	v_mul_f32_e32 v80, v80, v80
	v_fmac_f32_e32 v80, v84, v84
	v_lshlrev_b32_e32 v84, 16, v81
	v_and_b32_e32 v81, 0xffff0000, v81
	v_mul_f32_e32 v81, v81, v81
	v_add_f32_e32 v80, v114, v80
	v_fmac_f32_e32 v81, v84, v84
	v_add_f32_e32 v80, v80, v81
	v_lshlrev_b32_e32 v81, 16, v82
	v_and_b32_e32 v82, 0xffff0000, v82
	v_mul_f32_e32 v82, v82, v82
	v_fmac_f32_e32 v82, v81, v81
	v_add_f32_e32 v80, v80, v82
	v_and_b32_e32 v82, 0xffff0000, v83
	v_lshlrev_b32_e32 v81, 16, v83
	v_mul_f32_e32 v82, v82, v82
	v_fmac_f32_e32 v82, v81, v81
	v_add_f32_e32 v80, v80, v82
	v_mov_b32_e32 v81, v80
	s_nop 1
	v_permlane16_swap_b32_e32 v81, v80
	s_waitcnt lgkmcnt(0)
	v_add_f32_e32 v80, v80, v81
	v_mov_b32_e32 v81, v80
	s_nop 1
	v_permlane32_swap_b32_e32 v81, v80
	s_mov_b64 s[6:7], exec
	s_and_b64 s[4:5], s[6:7], vcc
	v_mov_b32_e32 v198, v216
	v_mov_b32_e32 v199, v217
	v_mov_b32_e32 v248, v218
	v_mov_b32_e32 v205, v219
	v_mov_b32_e32 v196, v220
	s_mov_b64 exec, s[4:5]
	s_cbranch_execz .LBB0_342
	s_waitcnt lgkmcnt(0)
	v_add_f32_e32 v82, v80, v81
	v_lshlrev_b64 v[80:81], 6, v[112:113]
	v_lshl_add_u64 v[80:81], s[46:47], 0, v[80:81]
	v_lshl_add_u64 v[80:81], s[56:57], 2, v[80:81]
	s_lshl_b32 s38, s8, 2
	v_lshl_add_u64 v[80:81], v[80:81], 0, s[38:39]
	flat_store_dword v[80:81], v82
.LBB0_342:
	s_or_b64 exec, exec, s[6:7]
	v_lshlrev_b32_e32 v80, 16, v100
	s_waitcnt lgkmcnt(0)
	v_and_b32_e32 v81, 0xffff0000, v100
	v_lshlrev_b32_e32 v84, 16, v102
	v_and_b32_e32 v85, 0xffff0000, v102
	v_lshlrev_b32_e32 v86, 16, v103
	v_and_b32_e32 v87, 0xffff0000, v103
	v_pk_add_f32 v[76:77], v[76:77], v[80:81]
	v_lshlrev_b32_e32 v82, 16, v101
	v_and_b32_e32 v83, 0xffff0000, v101
	v_pk_add_f32 v[80:81], v[74:75], v[86:87]
	v_pk_add_f32 v[74:75], v[72:73], v[84:85]
	v_cvt_pk_bf16_f32 v72, v76, v77
	v_lshl_add_u64 v[76:77], s[68:69], 0, v[110:111]
	v_pk_add_f32 v[78:79], v[78:79], v[82:83]
	v_lshl_add_u64 v[76:77], v[168:169], 1, v[76:77]
	v_cvt_pk_bf16_f32 v73, v78, v79
	v_cvt_pk_bf16_f32 v74, v74, v75
	v_cvt_pk_bf16_f32 v75, v80, v81
	global_store_dwordx4 v[76:77], v[72:75], off nt
	v_lshlrev_b32_e32 v78, 16, v72
	v_and_b32_e32 v79, 0xffff0000, v98
	v_and_b32_e32 v72, 0xffff0000, v72
	v_mul_f32_e32 v72, v72, v72
	v_fmac_f32_e32 v72, v78, v78
	v_lshlrev_b32_e32 v78, 16, v73
	v_and_b32_e32 v73, 0xffff0000, v73
	v_mul_f32_e32 v73, v73, v73
	v_fmac_f32_e32 v73, v78, v78
	v_add_f32_e32 v72, v72, v73
	v_lshlrev_b32_e32 v73, 16, v74
	v_and_b32_e32 v74, 0xffff0000, v74
	v_mul_f32_e32 v74, v74, v74
	v_fmac_f32_e32 v74, v73, v73
	v_add_f32_e32 v72, v72, v74
	v_and_b32_e32 v74, 0xffff0000, v75
	v_lshlrev_b32_e32 v73, 16, v75
	v_mul_f32_e32 v74, v74, v74
	v_fmac_f32_e32 v74, v73, v73
	v_add_f32_e32 v82, v72, v74
	v_lshlrev_b32_e32 v72, 16, v96
	v_and_b32_e32 v73, 0xffff0000, v96
	v_lshlrev_b32_e32 v78, 16, v98
	v_lshlrev_b32_e32 v74, 16, v97
	v_and_b32_e32 v75, 0xffff0000, v97
	v_lshlrev_b32_e32 v80, 16, v99
	v_and_b32_e32 v81, 0xffff0000, v99
	v_pk_add_f32 v[68:69], v[68:69], v[72:73]
	v_pk_add_f32 v[64:65], v[64:65], v[78:79]
	v_pk_add_f32 v[70:71], v[70:71], v[74:75]
	v_pk_add_f32 v[72:73], v[66:67], v[80:81]
	v_cvt_pk_bf16_f32 v66, v68, v69
	v_cvt_pk_bf16_f32 v67, v70, v71
	v_cvt_pk_bf16_f32 v68, v64, v65
	s_nop 0
	v_and_b32_e32 v65, 0xffff0000, v66
	v_lshlrev_b32_e32 v64, 16, v66
	v_mul_f32_e32 v65, v65, v65
	v_fmac_f32_e32 v65, v64, v64
	v_and_b32_e32 v70, 0xffff0000, v67
	v_add_f32_e32 v64, v82, v65
	v_lshlrev_b32_e32 v65, 16, v67
	v_mul_f32_e32 v70, v70, v70
	v_fmac_f32_e32 v70, v65, v65
	v_add_f32_e32 v64, v64, v70
	v_and_b32_e32 v70, 0xffff0000, v68
	v_lshlrev_b32_e32 v65, 16, v68
	v_mul_f32_e32 v70, v70, v70
	v_fmac_f32_e32 v70, v65, v65
	v_cvt_pk_bf16_f32 v69, v72, v73
	v_add_f32_e32 v64, v64, v70
	v_and_b32_e32 v70, 0xffff0000, v69
	v_lshlrev_b32_e32 v65, 16, v69
	v_mul_f32_e32 v70, v70, v70
	v_fmac_f32_e32 v70, v65, v65
	v_add_f32_e32 v64, v64, v70
	v_mov_b32_e32 v65, v64
	s_nop 1
	v_permlane16_swap_b32_e32 v65, v64
	global_store_dwordx4 v[76:77], v[66:69], off offset:256 nt
	s_waitcnt lgkmcnt(0)
	v_add_f32_e32 v64, v64, v65
	v_mov_b32_e32 v65, v64
	s_nop 1
	v_permlane32_swap_b32_e32 v65, v64
	s_and_saveexec_b64 s[6:7], vcc
	s_cbranch_execz .LBB0_344
	s_waitcnt lgkmcnt(0)
	v_add_f32_e32 v66, v64, v65
	v_lshlrev_b64 v[64:65], 6, v[108:109]
	v_lshl_add_u64 v[64:65], s[46:47], 0, v[64:65]
	v_lshl_add_u64 v[64:65], s[56:57], 2, v[64:65]
	s_lshl_b32 s38, s8, 2
	v_lshl_add_u64 v[64:65], v[64:65], 0, s[38:39]
	flat_store_dword v[64:65], v66
.LBB0_344:
	s_or_b64 exec, exec, s[6:7]
	v_add_u32_e32 v80, 0x80, v170
	v_ashrrev_i32_e32 v81, 31, v80
	v_lshlrev_b64 v[86:87], 11, v[80:81]
	s_waitcnt lgkmcnt(0)
	v_lshl_add_u64 v[64:65], v[172:173], 0, v[86:87]
	global_load_dwordx4 v[82:85], v[64:65], off
	global_load_dwordx4 v[72:75], v[64:65], off offset:256
	v_add_u32_e32 v76, 0x90, v170
	v_ashrrev_i32_e32 v77, 31, v76
	v_lshlrev_b64 v[78:79], 11, v[76:77]
	v_lshl_add_u64 v[64:65], v[172:173], 0, v[78:79]
	global_load_dwordx4 v[68:71], v[64:65], off
	s_nop 0
	global_load_dwordx4 v[64:67], v[64:65], off offset:256
	s_waitcnt vmcnt(0)
	v_lshlrev_b32_e32 v88, 16, v82
	v_and_b32_e32 v89, 0xffff0000, v82
	v_lshlrev_b32_e32 v82, 16, v83
	v_and_b32_e32 v83, 0xffff0000, v83
	v_lshlrev_b32_e32 v90, 16, v84
	v_and_b32_e32 v91, 0xffff0000, v84
	v_lshlrev_b32_e32 v84, 16, v85
	v_and_b32_e32 v85, 0xffff0000, v85
	v_pk_add_f32 v[60:61], v[60:61], v[88:89]
	v_pk_add_f32 v[62:63], v[62:63], v[82:83]
	v_pk_add_f32 v[82:83], v[58:59], v[84:85]
	v_pk_add_f32 v[58:59], v[56:57], v[90:91]
	v_cvt_pk_bf16_f32 v56, v60, v61
	v_lshl_add_u64 v[60:61], s[68:69], 0, v[86:87]
	v_lshl_add_u64 v[60:61], v[168:169], 1, v[60:61]
	v_cvt_pk_bf16_f32 v57, v62, v63
	v_cvt_pk_bf16_f32 v58, v58, v59
	v_cvt_pk_bf16_f32 v59, v82, v83
	global_store_dwordx4 v[60:61], v[56:59], off nt
	v_lshlrev_b32_e32 v62, 16, v56
	v_and_b32_e32 v63, 0xffff0000, v74
	v_and_b32_e32 v56, 0xffff0000, v56
	v_mul_f32_e32 v56, v56, v56
	v_fmac_f32_e32 v56, v62, v62
	v_lshlrev_b32_e32 v62, 16, v57
	v_and_b32_e32 v57, 0xffff0000, v57
	v_mul_f32_e32 v57, v57, v57
	v_fmac_f32_e32 v57, v62, v62
	v_add_f32_e32 v56, v56, v57
	v_lshlrev_b32_e32 v57, 16, v58
	v_and_b32_e32 v58, 0xffff0000, v58
	v_mul_f32_e32 v58, v58, v58
	v_fmac_f32_e32 v58, v57, v57
	v_add_f32_e32 v56, v56, v58
	v_and_b32_e32 v58, 0xffff0000, v59
	v_lshlrev_b32_e32 v57, 16, v59
	v_mul_f32_e32 v58, v58, v58
	v_fmac_f32_e32 v58, v57, v57
	v_add_f32_e32 v82, v56, v58
	v_lshlrev_b32_e32 v56, 16, v72
	v_and_b32_e32 v57, 0xffff0000, v72
	v_lshlrev_b32_e32 v58, 16, v73
	v_and_b32_e32 v59, 0xffff0000, v73
	v_lshlrev_b32_e32 v62, 16, v74
	v_lshlrev_b32_e32 v72, 16, v75
	v_and_b32_e32 v73, 0xffff0000, v75
	v_pk_add_f32 v[52:53], v[52:53], v[56:57]
	v_pk_add_f32 v[56:57], v[50:51], v[72:73]
	v_pk_add_f32 v[50:51], v[48:49], v[62:63]
	v_cvt_pk_bf16_f32 v48, v52, v53
	v_pk_add_f32 v[54:55], v[54:55], v[58:59]
	v_lshlrev_b32_e32 v52, 16, v48
	v_cvt_pk_bf16_f32 v49, v54, v55
	v_cvt_pk_bf16_f32 v50, v50, v51
	v_cvt_pk_bf16_f32 v51, v56, v57
	global_store_dwordx4 v[60:61], v[48:51], off offset:256 nt
	s_nop 1
	v_and_b32_e32 v48, 0xffff0000, v48
	v_mul_f32_e32 v48, v48, v48
	v_fmac_f32_e32 v48, v52, v52
	v_lshlrev_b32_e32 v52, 16, v49
	v_and_b32_e32 v49, 0xffff0000, v49
	v_mul_f32_e32 v49, v49, v49
	v_add_f32_e32 v48, v82, v48
	v_fmac_f32_e32 v49, v52, v52
	v_add_f32_e32 v48, v48, v49
	v_lshlrev_b32_e32 v49, 16, v50
	v_and_b32_e32 v50, 0xffff0000, v50
	v_mul_f32_e32 v50, v50, v50
	v_fmac_f32_e32 v50, v49, v49
	v_add_f32_e32 v48, v48, v50
	v_and_b32_e32 v50, 0xffff0000, v51
	v_lshlrev_b32_e32 v49, 16, v51
	v_mul_f32_e32 v50, v50, v50
	v_fmac_f32_e32 v50, v49, v49
	v_add_f32_e32 v48, v48, v50
	v_mov_b32_e32 v49, v48
	s_nop 1
	v_permlane16_swap_b32_e32 v49, v48
	s_waitcnt lgkmcnt(0)
	v_add_f32_e32 v48, v48, v49
	v_mov_b32_e32 v49, v48
	s_nop 1
	v_permlane32_swap_b32_e32 v49, v48
	s_and_saveexec_b64 s[6:7], vcc
	s_cbranch_execz .LBB0_346
	s_waitcnt lgkmcnt(0)
	v_add_f32_e32 v50, v48, v49
	v_lshlrev_b64 v[48:49], 6, v[80:81]
	v_lshl_add_u64 v[48:49], s[46:47], 0, v[48:49]
	v_lshl_add_u64 v[48:49], s[56:57], 2, v[48:49]
	s_lshl_b32 s38, s8, 2
	v_lshl_add_u64 v[48:49], v[48:49], 0, s[38:39]
	flat_store_dword v[48:49], v50
.LBB0_346:
	s_or_b64 exec, exec, s[6:7]
	v_lshlrev_b32_e32 v48, 16, v68
	s_waitcnt lgkmcnt(0)
	v_and_b32_e32 v49, 0xffff0000, v68
	v_lshlrev_b32_e32 v52, 16, v70
	v_and_b32_e32 v53, 0xffff0000, v70
	v_lshlrev_b32_e32 v54, 16, v71
	v_and_b32_e32 v55, 0xffff0000, v71
	v_pk_add_f32 v[44:45], v[44:45], v[48:49]
	v_lshlrev_b32_e32 v50, 16, v69
	v_and_b32_e32 v51, 0xffff0000, v69
	v_pk_add_f32 v[48:49], v[42:43], v[54:55]
	v_pk_add_f32 v[42:43], v[40:41], v[52:53]
	v_cvt_pk_bf16_f32 v40, v44, v45
	v_lshl_add_u64 v[44:45], s[68:69], 0, v[78:79]
	v_pk_add_f32 v[46:47], v[46:47], v[50:51]
	v_lshl_add_u64 v[44:45], v[168:169], 1, v[44:45]
	v_cvt_pk_bf16_f32 v41, v46, v47
	v_cvt_pk_bf16_f32 v42, v42, v43
	v_cvt_pk_bf16_f32 v43, v48, v49
	global_store_dwordx4 v[44:45], v[40:43], off nt
	v_lshlrev_b32_e32 v46, 16, v40
	v_and_b32_e32 v47, 0xffff0000, v66
	v_and_b32_e32 v40, 0xffff0000, v40
	v_mul_f32_e32 v40, v40, v40
	v_fmac_f32_e32 v40, v46, v46
	v_lshlrev_b32_e32 v46, 16, v41
	v_and_b32_e32 v41, 0xffff0000, v41
	v_mul_f32_e32 v41, v41, v41
	v_fmac_f32_e32 v41, v46, v46
	v_add_f32_e32 v40, v40, v41
	v_lshlrev_b32_e32 v41, 16, v42
	v_and_b32_e32 v42, 0xffff0000, v42
	v_mul_f32_e32 v42, v42, v42
	v_fmac_f32_e32 v42, v41, v41
	v_add_f32_e32 v40, v40, v42
	v_and_b32_e32 v42, 0xffff0000, v43
	v_lshlrev_b32_e32 v41, 16, v43
	v_mul_f32_e32 v42, v42, v42
	v_fmac_f32_e32 v42, v41, v41
	v_add_f32_e32 v50, v40, v42
	v_lshlrev_b32_e32 v40, 16, v64
	v_and_b32_e32 v41, 0xffff0000, v64
	v_lshlrev_b32_e32 v46, 16, v66
	v_lshlrev_b32_e32 v42, 16, v65
	v_and_b32_e32 v43, 0xffff0000, v65
	v_lshlrev_b32_e32 v48, 16, v67
	v_and_b32_e32 v49, 0xffff0000, v67
	v_pk_add_f32 v[36:37], v[36:37], v[40:41]
	v_pk_add_f32 v[32:33], v[32:33], v[46:47]
	v_pk_add_f32 v[38:39], v[38:39], v[42:43]
	v_pk_add_f32 v[40:41], v[34:35], v[48:49]
	v_cvt_pk_bf16_f32 v34, v36, v37
	v_cvt_pk_bf16_f32 v35, v38, v39
	v_cvt_pk_bf16_f32 v36, v32, v33
	s_nop 0
	v_and_b32_e32 v33, 0xffff0000, v34
	v_lshlrev_b32_e32 v32, 16, v34
	v_mul_f32_e32 v33, v33, v33
	v_fmac_f32_e32 v33, v32, v32
	v_and_b32_e32 v38, 0xffff0000, v35
	v_add_f32_e32 v32, v50, v33
	v_lshlrev_b32_e32 v33, 16, v35
	v_mul_f32_e32 v38, v38, v38
	v_fmac_f32_e32 v38, v33, v33
	v_add_f32_e32 v32, v32, v38
	v_and_b32_e32 v38, 0xffff0000, v36
	v_lshlrev_b32_e32 v33, 16, v36
	v_mul_f32_e32 v38, v38, v38
	v_fmac_f32_e32 v38, v33, v33
	v_cvt_pk_bf16_f32 v37, v40, v41
	v_add_f32_e32 v32, v32, v38
	v_and_b32_e32 v38, 0xffff0000, v37
	v_lshlrev_b32_e32 v33, 16, v37
	v_mul_f32_e32 v38, v38, v38
	v_fmac_f32_e32 v38, v33, v33
	v_add_f32_e32 v32, v32, v38
	v_mov_b32_e32 v33, v32
	s_nop 1
	v_permlane16_swap_b32_e32 v33, v32
	global_store_dwordx4 v[44:45], v[34:37], off offset:256 nt
	s_waitcnt lgkmcnt(0)
	v_add_f32_e32 v32, v32, v33
	v_mov_b32_e32 v33, v32
	s_nop 1
	v_permlane32_swap_b32_e32 v33, v32
	s_and_saveexec_b64 s[6:7], vcc
	s_cbranch_execz .LBB0_348
	s_waitcnt lgkmcnt(0)
	v_add_f32_e32 v34, v32, v33
	v_lshlrev_b64 v[32:33], 6, v[76:77]
	v_lshl_add_u64 v[32:33], s[46:47], 0, v[32:33]
	v_lshl_add_u64 v[32:33], s[56:57], 2, v[32:33]
	s_lshl_b32 s38, s8, 2
	v_lshl_add_u64 v[32:33], v[32:33], 0, s[38:39]
	flat_store_dword v[32:33], v34
.LBB0_348:
	s_or_b64 exec, exec, s[6:7]
	v_add_u32_e32 v48, 0xa0, v170
	v_ashrrev_i32_e32 v49, 31, v48
	v_lshlrev_b64 v[54:55], 11, v[48:49]
	s_waitcnt lgkmcnt(0)
	v_lshl_add_u64 v[32:33], v[172:173], 0, v[54:55]
	global_load_dwordx4 v[50:53], v[32:33], off
	global_load_dwordx4 v[40:43], v[32:33], off offset:256
	v_add_u32_e32 v44, 0xb0, v170
	v_ashrrev_i32_e32 v45, 31, v44
	v_lshlrev_b64 v[46:47], 11, v[44:45]
	v_lshl_add_u64 v[32:33], v[172:173], 0, v[46:47]
	global_load_dwordx4 v[36:39], v[32:33], off
	s_nop 0
	global_load_dwordx4 v[32:35], v[32:33], off offset:256
	s_waitcnt vmcnt(0)
	v_lshlrev_b32_e32 v56, 16, v50
	v_and_b32_e32 v57, 0xffff0000, v50
	v_lshlrev_b32_e32 v50, 16, v51
	v_and_b32_e32 v51, 0xffff0000, v51
	v_lshlrev_b32_e32 v58, 16, v52
	v_and_b32_e32 v59, 0xffff0000, v52
	v_lshlrev_b32_e32 v52, 16, v53
	v_and_b32_e32 v53, 0xffff0000, v53
	v_pk_add_f32 v[28:29], v[28:29], v[56:57]
	v_pk_add_f32 v[30:31], v[30:31], v[50:51]
	v_pk_add_f32 v[50:51], v[26:27], v[52:53]
	v_pk_add_f32 v[26:27], v[24:25], v[58:59]
	v_cvt_pk_bf16_f32 v24, v28, v29
	v_lshl_add_u64 v[28:29], s[68:69], 0, v[54:55]
	v_lshl_add_u64 v[28:29], v[168:169], 1, v[28:29]
	v_cvt_pk_bf16_f32 v25, v30, v31
	v_cvt_pk_bf16_f32 v26, v26, v27
	v_cvt_pk_bf16_f32 v27, v50, v51
	global_store_dwordx4 v[28:29], v[24:27], off nt
	v_lshlrev_b32_e32 v30, 16, v24
	v_and_b32_e32 v31, 0xffff0000, v42
	v_and_b32_e32 v24, 0xffff0000, v24
	v_mul_f32_e32 v24, v24, v24
	v_fmac_f32_e32 v24, v30, v30
	v_lshlrev_b32_e32 v30, 16, v25
	v_and_b32_e32 v25, 0xffff0000, v25
	v_mul_f32_e32 v25, v25, v25
	v_fmac_f32_e32 v25, v30, v30
	v_add_f32_e32 v24, v24, v25
	v_lshlrev_b32_e32 v25, 16, v26
	v_and_b32_e32 v26, 0xffff0000, v26
	v_mul_f32_e32 v26, v26, v26
	v_fmac_f32_e32 v26, v25, v25
	v_add_f32_e32 v24, v24, v26
	v_and_b32_e32 v26, 0xffff0000, v27
	v_lshlrev_b32_e32 v25, 16, v27
	v_mul_f32_e32 v26, v26, v26
	v_fmac_f32_e32 v26, v25, v25
	v_add_f32_e32 v50, v24, v26
	v_lshlrev_b32_e32 v24, 16, v40
	v_and_b32_e32 v25, 0xffff0000, v40
	v_lshlrev_b32_e32 v26, 16, v41
	v_and_b32_e32 v27, 0xffff0000, v41
	v_lshlrev_b32_e32 v30, 16, v42
	v_lshlrev_b32_e32 v40, 16, v43
	v_and_b32_e32 v41, 0xffff0000, v43
	v_pk_add_f32 v[20:21], v[20:21], v[24:25]
	v_pk_add_f32 v[24:25], v[18:19], v[40:41]
	v_pk_add_f32 v[18:19], v[16:17], v[30:31]
	v_cvt_pk_bf16_f32 v16, v20, v21
	v_pk_add_f32 v[22:23], v[22:23], v[26:27]
	v_lshlrev_b32_e32 v20, 16, v16
	v_cvt_pk_bf16_f32 v17, v22, v23
	v_cvt_pk_bf16_f32 v18, v18, v19
	v_cvt_pk_bf16_f32 v19, v24, v25
	global_store_dwordx4 v[28:29], v[16:19], off offset:256 nt
	s_nop 1
	v_and_b32_e32 v16, 0xffff0000, v16
	v_mul_f32_e32 v16, v16, v16
	v_fmac_f32_e32 v16, v20, v20
	v_lshlrev_b32_e32 v20, 16, v17
	v_and_b32_e32 v17, 0xffff0000, v17
	v_mul_f32_e32 v17, v17, v17
	v_add_f32_e32 v16, v50, v16
	v_fmac_f32_e32 v17, v20, v20
	v_add_f32_e32 v16, v16, v17
	v_lshlrev_b32_e32 v17, 16, v18
	v_and_b32_e32 v18, 0xffff0000, v18
	v_mul_f32_e32 v18, v18, v18
	v_fmac_f32_e32 v18, v17, v17
	v_add_f32_e32 v16, v16, v18
	v_and_b32_e32 v18, 0xffff0000, v19
	v_lshlrev_b32_e32 v17, 16, v19
	v_mul_f32_e32 v18, v18, v18
	v_fmac_f32_e32 v18, v17, v17
	v_add_f32_e32 v16, v16, v18
	v_mov_b32_e32 v17, v16
	s_nop 1
	v_permlane16_swap_b32_e32 v17, v16
	s_waitcnt lgkmcnt(0)
	v_add_f32_e32 v16, v16, v17
	v_mov_b32_e32 v17, v16
	s_nop 1
	v_permlane32_swap_b32_e32 v17, v16
	s_and_saveexec_b64 s[6:7], vcc
	s_cbranch_execz .LBB0_350
	s_waitcnt lgkmcnt(0)
	v_add_f32_e32 v18, v16, v17
	v_lshlrev_b64 v[16:17], 6, v[48:49]
	v_lshl_add_u64 v[16:17], s[46:47], 0, v[16:17]
	v_lshl_add_u64 v[16:17], s[56:57], 2, v[16:17]
	s_lshl_b32 s38, s8, 2
	v_lshl_add_u64 v[16:17], v[16:17], 0, s[38:39]
	flat_store_dword v[16:17], v18
.LBB0_350:
	s_or_b64 exec, exec, s[6:7]
	v_lshlrev_b32_e32 v16, 16, v36
	s_waitcnt lgkmcnt(0)
	v_and_b32_e32 v17, 0xffff0000, v36
	v_lshlrev_b32_e32 v20, 16, v38
	v_and_b32_e32 v21, 0xffff0000, v38
	v_lshlrev_b32_e32 v22, 16, v39
	v_and_b32_e32 v23, 0xffff0000, v39
	v_pk_add_f32 v[12:13], v[12:13], v[16:17]
	v_lshlrev_b32_e32 v18, 16, v37
	v_and_b32_e32 v19, 0xffff0000, v37
	v_pk_add_f32 v[16:17], v[10:11], v[22:23]
	v_pk_add_f32 v[10:11], v[8:9], v[20:21]
	v_cvt_pk_bf16_f32 v8, v12, v13
	v_lshl_add_u64 v[12:13], s[68:69], 0, v[46:47]
	v_pk_add_f32 v[14:15], v[14:15], v[18:19]
	v_lshl_add_u64 v[12:13], v[168:169], 1, v[12:13]
	v_cvt_pk_bf16_f32 v9, v14, v15
	v_cvt_pk_bf16_f32 v10, v10, v11
	v_cvt_pk_bf16_f32 v11, v16, v17
	global_store_dwordx4 v[12:13], v[8:11], off nt
	v_lshlrev_b32_e32 v14, 16, v8
	v_and_b32_e32 v15, 0xffff0000, v34
	v_and_b32_e32 v8, 0xffff0000, v8
	v_mul_f32_e32 v8, v8, v8
	v_fmac_f32_e32 v8, v14, v14
	v_lshlrev_b32_e32 v14, 16, v9
	v_and_b32_e32 v9, 0xffff0000, v9
	v_mul_f32_e32 v9, v9, v9
	v_fmac_f32_e32 v9, v14, v14
	v_add_f32_e32 v8, v8, v9
	v_lshlrev_b32_e32 v9, 16, v10
	v_and_b32_e32 v10, 0xffff0000, v10
	v_mul_f32_e32 v10, v10, v10
	v_fmac_f32_e32 v10, v9, v9
	v_add_f32_e32 v8, v8, v10
	v_and_b32_e32 v10, 0xffff0000, v11
	v_lshlrev_b32_e32 v9, 16, v11
	v_mul_f32_e32 v10, v10, v10
	v_fmac_f32_e32 v10, v9, v9
	v_add_f32_e32 v18, v8, v10
	v_lshlrev_b32_e32 v8, 16, v32
	v_and_b32_e32 v9, 0xffff0000, v32
	v_lshlrev_b32_e32 v14, 16, v34
	v_lshlrev_b32_e32 v10, 16, v33
	v_and_b32_e32 v11, 0xffff0000, v33
	v_lshlrev_b32_e32 v16, 16, v35
	v_and_b32_e32 v17, 0xffff0000, v35
	v_pk_add_f32 v[4:5], v[4:5], v[8:9]
	v_pk_add_f32 v[0:1], v[0:1], v[14:15]
	v_pk_add_f32 v[6:7], v[6:7], v[10:11]
	v_pk_add_f32 v[8:9], v[2:3], v[16:17]
	v_cvt_pk_bf16_f32 v2, v4, v5
	v_cvt_pk_bf16_f32 v3, v6, v7
	v_cvt_pk_bf16_f32 v4, v0, v1
	s_nop 0
	v_and_b32_e32 v1, 0xffff0000, v2
	v_lshlrev_b32_e32 v0, 16, v2
	v_mul_f32_e32 v1, v1, v1
	v_fmac_f32_e32 v1, v0, v0
	v_and_b32_e32 v6, 0xffff0000, v3
	v_add_f32_e32 v0, v18, v1
	v_lshlrev_b32_e32 v1, 16, v3
	v_mul_f32_e32 v6, v6, v6
	v_fmac_f32_e32 v6, v1, v1
	v_add_f32_e32 v0, v0, v6
	v_and_b32_e32 v6, 0xffff0000, v4
	v_lshlrev_b32_e32 v1, 16, v4
	v_mul_f32_e32 v6, v6, v6
	v_fmac_f32_e32 v6, v1, v1
	v_cvt_pk_bf16_f32 v5, v8, v9
	v_add_f32_e32 v0, v0, v6
	v_and_b32_e32 v6, 0xffff0000, v5
	v_lshlrev_b32_e32 v1, 16, v5
	v_mul_f32_e32 v6, v6, v6
	v_fmac_f32_e32 v6, v1, v1
	v_add_f32_e32 v0, v0, v6
	v_mov_b32_e32 v1, v0
	s_nop 1
	v_permlane16_swap_b32_e32 v1, v0
	global_store_dwordx4 v[12:13], v[2:5], off offset:256 nt
	s_waitcnt lgkmcnt(0)
	v_add_f32_e32 v0, v0, v1
	v_mov_b32_e32 v1, v0
	s_nop 1
	v_permlane32_swap_b32_e32 v1, v0
	s_and_saveexec_b64 s[6:7], vcc
	s_cbranch_execz .LBB0_352
	s_waitcnt lgkmcnt(0)
	v_add_f32_e32 v2, v0, v1
	v_lshlrev_b64 v[0:1], 6, v[44:45]
	v_lshl_add_u64 v[0:1], s[46:47], 0, v[0:1]
	v_lshl_add_u64 v[0:1], s[56:57], 2, v[0:1]
	s_lshl_b32 s38, s8, 2
	v_lshl_add_u64 v[0:1], v[0:1], 0, s[38:39]
	flat_store_dword v[0:1], v2

.LBB0_378:
	s_mov_b32 s6, -1
	s_lshl_b32 s5, s5, 8
	v_mbcnt_lo_u32_b32 v128, s6, 0
	v_mbcnt_hi_u32_b32 v128, s6, v128
	s_getreg_b32 s6, hwreg(HW_REG_HW_ID, 0, 6)
	s_and_b32 s6, s6, 63
	s_lshl_b32 s6, s6, 2
	s_add_i32 s6, s6, 0
	s_add_i32 s6, s6, 0x20200
	v_mov_b32_e32 v129, s6
	ds_read_b32 v129, v129
	v_bfrev_b32_e32 v130, 0.5
	s_lshl_b32 s56, s4, 2
	s_ashr_i32 s57, s56, 31
	s_waitcnt lgkmcnt(0)
	v_readfirstlane_b32 s6, v129
	s_nop 1
	v_lshl_add_u32 v128, s6, 6, v128
	s_nop 0
	v_readfirstlane_b32 s6, v128
	s_bfe_u32 s8, s6, 0x20006
	s_ashr_i32 s6, s6, 2
	s_andn2_b32 s6, s6, 63
	s_add_i32 s6, s6, s5
	v_and_or_b32 v170, v128, 15, s6
	s_lshl_b32 s5, s4, 8
	s_lshl_b32 s6, s8, 5
	v_bfe_u32 v129, v128, 4, 2
	s_or_b32 s5, s6, s5
	v_lshl_or_b32 v168, v129, 3, s5
	v_ashrrev_i32_e32 v169, 31, v168
	v_lshlrev_b64 v[146:147], 1, v[168:169]
	v_ashrrev_i32_e32 v171, 31, v170
	v_lshlrev_b32_e32 v128, 2, v128
	v_lshl_add_u64 v[172:173], s[68:69], 0, v[146:147]
	v_lshlrev_b64 v[148:149], 11, v[170:171]
	v_bitop3_b32 v181, v128, 64, v130 bitop3:0x6c
	v_bitop3_b32 v180, v128, s84, v130 bitop3:0x6c
	v_cmp_eq_u32_e32 vcc, 0, v129
	v_lshl_add_u64 v[128:129], v[172:173], 0, v[148:149]
	global_load_dwordx4 v[142:145], v[128:129], off
	global_load_dwordx4 v[136:139], v[128:129], off offset:256
	v_or_b32_e32 v174, 16, v170
	v_ashrrev_i32_e32 v175, 31, v174
	v_lshlrev_b64 v[176:177], 11, v[174:175]
	v_lshl_add_u64 v[128:129], v[172:173], 0, v[176:177]
	global_load_dwordx4 v[132:135], v[128:129], off
	s_nop 0
	global_load_dwordx4 v[128:131], v[128:129], off offset:256
	s_waitcnt vmcnt(0)
	v_lshlrev_b32_e32 v150, 16, v142
	v_and_b32_e32 v151, 0xffff0000, v142
	v_lshlrev_b32_e32 v142, 16, v143
	v_and_b32_e32 v143, 0xffff0000, v143
	v_lshlrev_b32_e32 v152, 16, v144
	v_and_b32_e32 v153, 0xffff0000, v144
	v_lshlrev_b32_e32 v144, 16, v145
	v_and_b32_e32 v145, 0xffff0000, v145
	v_pk_add_f32 v[124:125], v[124:125], v[150:151]
	v_pk_add_f32 v[126:127], v[126:127], v[142:143]
	v_pk_add_f32 v[142:143], v[122:123], v[144:145]
	v_pk_add_f32 v[122:123], v[120:121], v[152:153]
	v_cvt_pk_bf16_f32 v120, v124, v125
	v_lshl_add_u64 v[124:125], s[68:69], 0, v[148:149]
	v_lshl_add_u64 v[124:125], v[124:125], 0, v[146:147]
	v_cvt_pk_bf16_f32 v121, v126, v127
	v_cvt_pk_bf16_f32 v122, v122, v123
	v_cvt_pk_bf16_f32 v123, v142, v143
	global_store_dwordx4 v[124:125], v[120:123], off nt
	v_lshlrev_b32_e32 v126, 16, v120
	v_and_b32_e32 v127, 0xffff0000, v138
	v_and_b32_e32 v120, 0xffff0000, v120
	v_mul_f32_e32 v120, v120, v120
	v_fmac_f32_e32 v120, v126, v126
	v_lshlrev_b32_e32 v126, 16, v121
	v_and_b32_e32 v121, 0xffff0000, v121
	v_mul_f32_e32 v121, v121, v121
	v_fmac_f32_e32 v121, v126, v126
	v_add_f32_e32 v120, v120, v121
	v_lshlrev_b32_e32 v121, 16, v122
	v_and_b32_e32 v122, 0xffff0000, v122
	v_mul_f32_e32 v122, v122, v122
	v_fmac_f32_e32 v122, v121, v121
	v_add_f32_e32 v120, v120, v122
	v_and_b32_e32 v122, 0xffff0000, v123
	v_lshlrev_b32_e32 v121, 16, v123
	v_mul_f32_e32 v122, v122, v122
	v_fmac_f32_e32 v122, v121, v121
	v_add_f32_e32 v142, v120, v122
	v_lshlrev_b32_e32 v120, 16, v136
	v_and_b32_e32 v121, 0xffff0000, v136
	v_lshlrev_b32_e32 v122, 16, v137
	v_and_b32_e32 v123, 0xffff0000, v137
	v_lshlrev_b32_e32 v126, 16, v138
	v_lshlrev_b32_e32 v136, 16, v139
	v_and_b32_e32 v137, 0xffff0000, v139
	v_pk_add_f32 v[116:117], v[116:117], v[120:121]
	v_pk_add_f32 v[120:121], v[114:115], v[136:137]
	v_pk_add_f32 v[114:115], v[112:113], v[126:127]
	v_cvt_pk_bf16_f32 v112, v116, v117
	v_pk_add_f32 v[118:119], v[118:119], v[122:123]
	v_lshlrev_b32_e32 v116, 16, v112
	v_cvt_pk_bf16_f32 v113, v118, v119
	v_cvt_pk_bf16_f32 v114, v114, v115
	v_cvt_pk_bf16_f32 v115, v120, v121
	global_store_dwordx4 v[124:125], v[112:115], off offset:256 nt
	s_nop 1
	v_and_b32_e32 v112, 0xffff0000, v112
	v_mul_f32_e32 v112, v112, v112
	v_fmac_f32_e32 v112, v116, v116
	v_lshlrev_b32_e32 v116, 16, v113
	v_and_b32_e32 v113, 0xffff0000, v113
	v_mul_f32_e32 v113, v113, v113
	v_add_f32_e32 v112, v142, v112
	v_fmac_f32_e32 v113, v116, v116
	v_add_f32_e32 v112, v112, v113
	v_lshlrev_b32_e32 v113, 16, v114
	v_and_b32_e32 v114, 0xffff0000, v114
	v_mul_f32_e32 v114, v114, v114
	v_fmac_f32_e32 v114, v113, v113
	v_add_f32_e32 v112, v112, v114
	v_and_b32_e32 v114, 0xffff0000, v115
	v_lshlrev_b32_e32 v113, 16, v115
	v_mul_f32_e32 v114, v114, v114
	v_fmac_f32_e32 v114, v113, v113
	v_add_f32_e32 v112, v112, v114
	v_mov_b32_e32 v113, v112
	s_nop 1
	v_permlane16_swap_b32_e32 v113, v112
	s_waitcnt lgkmcnt(0)
	v_add_f32_e32 v112, v112, v113
	v_mov_b32_e32 v113, v112
	s_nop 1
	v_permlane32_swap_b32_e32 v113, v112
	s_and_saveexec_b64 s[6:7], vcc
	s_cbranch_execz .LBB0_380
	v_lshlrev_b64 v[114:115], 6, v[170:171]
	v_lshl_add_u64 v[114:115], s[46:47], 0, v[114:115]
	v_lshl_add_u64 v[114:115], s[56:57], 2, v[114:115]
	s_lshl_b32 s38, s8, 2
	v_lshl_add_u64 v[114:115], v[114:115], 0, s[38:39]
	s_waitcnt lgkmcnt(0)
	v_add_f32_e32 v112, v112, v113
	flat_store_dword v[114:115], v112
.LBB0_380:
	s_or_b64 exec, exec, s[6:7]
	v_lshlrev_b32_e32 v112, 16, v132
	s_waitcnt lgkmcnt(0)
	v_and_b32_e32 v113, 0xffff0000, v132
	v_lshlrev_b32_e32 v116, 16, v134
	v_and_b32_e32 v117, 0xffff0000, v134
	v_lshlrev_b32_e32 v118, 16, v135
	v_and_b32_e32 v119, 0xffff0000, v135
	v_pk_add_f32 v[108:109], v[108:109], v[112:113]
	v_lshlrev_b32_e32 v114, 16, v133
	v_and_b32_e32 v115, 0xffff0000, v133
	v_pk_add_f32 v[112:113], v[106:107], v[118:119]
	v_pk_add_f32 v[106:107], v[104:105], v[116:117]
	v_cvt_pk_bf16_f32 v104, v108, v109
	v_lshl_add_u64 v[108:109], s[68:69], 0, v[176:177]
	v_pk_add_f32 v[110:111], v[110:111], v[114:115]
	v_lshl_add_u64 v[108:109], v[168:169], 1, v[108:109]
	v_cvt_pk_bf16_f32 v105, v110, v111
	v_cvt_pk_bf16_f32 v106, v106, v107
	v_cvt_pk_bf16_f32 v107, v112, v113
	global_store_dwordx4 v[108:109], v[104:107], off nt
	v_lshlrev_b32_e32 v110, 16, v104
	v_and_b32_e32 v111, 0xffff0000, v130
	v_and_b32_e32 v104, 0xffff0000, v104
	v_mul_f32_e32 v104, v104, v104
	v_fmac_f32_e32 v104, v110, v110
	v_lshlrev_b32_e32 v110, 16, v105
	v_and_b32_e32 v105, 0xffff0000, v105
	v_mul_f32_e32 v105, v105, v105
	v_fmac_f32_e32 v105, v110, v110
	v_add_f32_e32 v104, v104, v105
	v_lshlrev_b32_e32 v105, 16, v106
	v_and_b32_e32 v106, 0xffff0000, v106
	v_mul_f32_e32 v106, v106, v106
	v_fmac_f32_e32 v106, v105, v105
	v_add_f32_e32 v104, v104, v106
	v_and_b32_e32 v106, 0xffff0000, v107
	v_lshlrev_b32_e32 v105, 16, v107
	v_mul_f32_e32 v106, v106, v106
	v_fmac_f32_e32 v106, v105, v105
	v_add_f32_e32 v114, v104, v106
	v_lshlrev_b32_e32 v104, 16, v128
	v_and_b32_e32 v105, 0xffff0000, v128
	v_lshlrev_b32_e32 v110, 16, v130
	v_lshlrev_b32_e32 v106, 16, v129
	v_and_b32_e32 v107, 0xffff0000, v129
	v_lshlrev_b32_e32 v112, 16, v131
	v_and_b32_e32 v113, 0xffff0000, v131
	v_pk_add_f32 v[100:101], v[100:101], v[104:105]
	v_pk_add_f32 v[96:97], v[96:97], v[110:111]
	v_pk_add_f32 v[102:103], v[102:103], v[106:107]
	v_pk_add_f32 v[104:105], v[98:99], v[112:113]
	v_cvt_pk_bf16_f32 v98, v100, v101
	v_cvt_pk_bf16_f32 v99, v102, v103
	v_cvt_pk_bf16_f32 v100, v96, v97
	s_nop 0
	v_and_b32_e32 v97, 0xffff0000, v98
	v_lshlrev_b32_e32 v96, 16, v98
	v_mul_f32_e32 v97, v97, v97
	v_fmac_f32_e32 v97, v96, v96
	v_and_b32_e32 v102, 0xffff0000, v99
	v_add_f32_e32 v96, v114, v97
	v_lshlrev_b32_e32 v97, 16, v99
	v_mul_f32_e32 v102, v102, v102
	v_fmac_f32_e32 v102, v97, v97
	v_add_f32_e32 v96, v96, v102
	v_and_b32_e32 v102, 0xffff0000, v100
	v_lshlrev_b32_e32 v97, 16, v100
	v_mul_f32_e32 v102, v102, v102
	v_fmac_f32_e32 v102, v97, v97
	v_cvt_pk_bf16_f32 v101, v104, v105
	v_add_f32_e32 v96, v96, v102
	v_and_b32_e32 v102, 0xffff0000, v101
	v_lshlrev_b32_e32 v97, 16, v101
	v_mul_f32_e32 v102, v102, v102
	v_fmac_f32_e32 v102, v97, v97
	v_add_f32_e32 v96, v96, v102
	v_mov_b32_e32 v97, v96
	s_nop 1
	v_permlane16_swap_b32_e32 v97, v96
	global_store_dwordx4 v[108:109], v[98:101], off offset:256 nt
	s_waitcnt lgkmcnt(0)
	v_add_f32_e32 v96, v96, v97
	v_mov_b32_e32 v97, v96
	s_nop 1
	v_permlane32_swap_b32_e32 v97, v96
	s_and_saveexec_b64 s[6:7], vcc
	s_cbranch_execz .LBB0_382
	v_lshlrev_b64 v[98:99], 6, v[174:175]
	v_lshl_add_u64 v[98:99], s[46:47], 0, v[98:99]
	v_lshl_add_u64 v[98:99], s[56:57], 2, v[98:99]
	s_lshl_b32 s38, s8, 2
	v_lshl_add_u64 v[98:99], v[98:99], 0, s[38:39]
	s_waitcnt lgkmcnt(0)
	v_add_f32_e32 v96, v96, v97
	flat_store_dword v[98:99], v96
.LBB0_382:
	s_or_b64 exec, exec, s[6:7]
	v_or_b32_e32 v112, 32, v170
	v_ashrrev_i32_e32 v113, 31, v112
	v_lshlrev_b64 v[118:119], 11, v[112:113]
	s_waitcnt lgkmcnt(0)
	v_lshl_add_u64 v[96:97], v[172:173], 0, v[118:119]
	global_load_dwordx4 v[114:117], v[96:97], off
	global_load_dwordx4 v[104:107], v[96:97], off offset:256
	v_or_b32_e32 v108, 48, v170
	v_ashrrev_i32_e32 v109, 31, v108
	v_lshlrev_b64 v[110:111], 11, v[108:109]
	v_lshl_add_u64 v[96:97], v[172:173], 0, v[110:111]
	global_load_dwordx4 v[100:103], v[96:97], off
	s_nop 0
	global_load_dwordx4 v[96:99], v[96:97], off offset:256
	s_waitcnt vmcnt(0)
	v_lshlrev_b32_e32 v120, 16, v114
	v_and_b32_e32 v121, 0xffff0000, v114
	v_lshlrev_b32_e32 v114, 16, v115
	v_and_b32_e32 v115, 0xffff0000, v115
	v_lshlrev_b32_e32 v122, 16, v116
	v_and_b32_e32 v123, 0xffff0000, v116
	v_lshlrev_b32_e32 v116, 16, v117
	v_and_b32_e32 v117, 0xffff0000, v117
	v_pk_add_f32 v[92:93], v[92:93], v[120:121]
	v_pk_add_f32 v[94:95], v[94:95], v[114:115]
	v_pk_add_f32 v[114:115], v[90:91], v[116:117]
	v_pk_add_f32 v[90:91], v[88:89], v[122:123]
	v_cvt_pk_bf16_f32 v88, v92, v93
	v_lshl_add_u64 v[92:93], s[68:69], 0, v[118:119]
	v_lshl_add_u64 v[92:93], v[168:169], 1, v[92:93]
	v_cvt_pk_bf16_f32 v89, v94, v95
	v_cvt_pk_bf16_f32 v90, v90, v91
	v_cvt_pk_bf16_f32 v91, v114, v115
	global_store_dwordx4 v[92:93], v[88:91], off nt
	v_lshlrev_b32_e32 v94, 16, v88
	v_and_b32_e32 v95, 0xffff0000, v106
	v_and_b32_e32 v88, 0xffff0000, v88
	v_mul_f32_e32 v88, v88, v88
	v_fmac_f32_e32 v88, v94, v94
	v_lshlrev_b32_e32 v94, 16, v89
	v_and_b32_e32 v89, 0xffff0000, v89
	v_mul_f32_e32 v89, v89, v89
	v_fmac_f32_e32 v89, v94, v94
	v_add_f32_e32 v88, v88, v89
	v_lshlrev_b32_e32 v89, 16, v90
	v_and_b32_e32 v90, 0xffff0000, v90
	v_mul_f32_e32 v90, v90, v90
	v_fmac_f32_e32 v90, v89, v89
	v_add_f32_e32 v88, v88, v90
	v_and_b32_e32 v90, 0xffff0000, v91
	v_lshlrev_b32_e32 v89, 16, v91
	v_mul_f32_e32 v90, v90, v90
	v_fmac_f32_e32 v90, v89, v89
	v_add_f32_e32 v114, v88, v90
	v_lshlrev_b32_e32 v88, 16, v104
	v_and_b32_e32 v89, 0xffff0000, v104
	v_lshlrev_b32_e32 v90, 16, v105
	v_and_b32_e32 v91, 0xffff0000, v105
	v_lshlrev_b32_e32 v94, 16, v106
	v_lshlrev_b32_e32 v104, 16, v107
	v_and_b32_e32 v105, 0xffff0000, v107
	v_pk_add_f32 v[84:85], v[84:85], v[88:89]
	v_pk_add_f32 v[88:89], v[82:83], v[104:105]
	v_pk_add_f32 v[82:83], v[80:81], v[94:95]
	v_cvt_pk_bf16_f32 v80, v84, v85
	v_pk_add_f32 v[86:87], v[86:87], v[90:91]
	v_lshlrev_b32_e32 v84, 16, v80
	v_cvt_pk_bf16_f32 v81, v86, v87
	v_cvt_pk_bf16_f32 v82, v82, v83
	v_cvt_pk_bf16_f32 v83, v88, v89
	global_store_dwordx4 v[92:93], v[80:83], off offset:256 nt
	s_nop 1
	v_and_b32_e32 v80, 0xffff0000, v80
	v_mul_f32_e32 v80, v80, v80
	v_fmac_f32_e32 v80, v84, v84
	v_lshlrev_b32_e32 v84, 16, v81
	v_and_b32_e32 v81, 0xffff0000, v81
	v_mul_f32_e32 v81, v81, v81
	v_add_f32_e32 v80, v114, v80
	v_fmac_f32_e32 v81, v84, v84
	v_add_f32_e32 v80, v80, v81
	v_lshlrev_b32_e32 v81, 16, v82
	v_and_b32_e32 v82, 0xffff0000, v82
	v_mul_f32_e32 v82, v82, v82
	v_fmac_f32_e32 v82, v81, v81
	v_add_f32_e32 v80, v80, v82
	v_and_b32_e32 v82, 0xffff0000, v83
	v_lshlrev_b32_e32 v81, 16, v83
	v_mul_f32_e32 v82, v82, v82
	v_fmac_f32_e32 v82, v81, v81
	v_add_f32_e32 v80, v80, v82
	v_mov_b32_e32 v81, v80
	s_nop 1
	v_permlane16_swap_b32_e32 v81, v80
	s_waitcnt lgkmcnt(0)
	v_add_f32_e32 v80, v80, v81
	v_mov_b32_e32 v81, v80
	s_nop 1
	v_permlane32_swap_b32_e32 v81, v80
	s_mov_b64 s[6:7], exec
	s_and_b64 s[4:5], s[6:7], vcc
	v_mov_b32_e32 v198, v220
	v_mov_b32_e32 v199, v221
	v_mov_b32_e32 v248, v222
	v_mov_b32_e32 v205, v223
	v_mov_b32_e32 v196, v224
	s_mov_b64 exec, s[4:5]
	s_cbranch_execz .LBB0_384
	v_lshlrev_b64 v[82:83], 6, v[112:113]
	v_lshl_add_u64 v[82:83], s[46:47], 0, v[82:83]
	v_lshl_add_u64 v[82:83], s[56:57], 2, v[82:83]
	s_lshl_b32 s38, s8, 2
	v_lshl_add_u64 v[82:83], v[82:83], 0, s[38:39]
	s_waitcnt lgkmcnt(0)
	v_add_f32_e32 v80, v80, v81
	flat_store_dword v[82:83], v80
.LBB0_384:
	s_or_b64 exec, exec, s[6:7]
	v_lshlrev_b32_e32 v80, 16, v100
	s_waitcnt lgkmcnt(0)
	v_and_b32_e32 v81, 0xffff0000, v100
	v_lshlrev_b32_e32 v84, 16, v102
	v_and_b32_e32 v85, 0xffff0000, v102
	v_lshlrev_b32_e32 v86, 16, v103
	v_and_b32_e32 v87, 0xffff0000, v103
	v_pk_add_f32 v[76:77], v[76:77], v[80:81]
	v_lshlrev_b32_e32 v82, 16, v101
	v_and_b32_e32 v83, 0xffff0000, v101
	v_pk_add_f32 v[80:81], v[74:75], v[86:87]
	v_pk_add_f32 v[74:75], v[72:73], v[84:85]
	v_cvt_pk_bf16_f32 v72, v76, v77
	v_lshl_add_u64 v[76:77], s[68:69], 0, v[110:111]
	v_pk_add_f32 v[78:79], v[78:79], v[82:83]
	v_lshl_add_u64 v[76:77], v[168:169], 1, v[76:77]
	v_cvt_pk_bf16_f32 v73, v78, v79
	v_cvt_pk_bf16_f32 v74, v74, v75
	v_cvt_pk_bf16_f32 v75, v80, v81
	global_store_dwordx4 v[76:77], v[72:75], off nt
	v_lshlrev_b32_e32 v78, 16, v72
	v_and_b32_e32 v79, 0xffff0000, v98
	v_and_b32_e32 v72, 0xffff0000, v72
	v_mul_f32_e32 v72, v72, v72
	v_fmac_f32_e32 v72, v78, v78
	v_lshlrev_b32_e32 v78, 16, v73
	v_and_b32_e32 v73, 0xffff0000, v73
	v_mul_f32_e32 v73, v73, v73
	v_fmac_f32_e32 v73, v78, v78
	v_add_f32_e32 v72, v72, v73
	v_lshlrev_b32_e32 v73, 16, v74
	v_and_b32_e32 v74, 0xffff0000, v74
	v_mul_f32_e32 v74, v74, v74
	v_fmac_f32_e32 v74, v73, v73
	v_add_f32_e32 v72, v72, v74
	v_and_b32_e32 v74, 0xffff0000, v75
	v_lshlrev_b32_e32 v73, 16, v75
	v_mul_f32_e32 v74, v74, v74
	v_fmac_f32_e32 v74, v73, v73
	v_add_f32_e32 v82, v72, v74
	v_lshlrev_b32_e32 v72, 16, v96
	v_and_b32_e32 v73, 0xffff0000, v96
	v_lshlrev_b32_e32 v78, 16, v98
	v_lshlrev_b32_e32 v74, 16, v97
	v_and_b32_e32 v75, 0xffff0000, v97
	v_lshlrev_b32_e32 v80, 16, v99
	v_and_b32_e32 v81, 0xffff0000, v99
	v_pk_add_f32 v[68:69], v[68:69], v[72:73]
	v_pk_add_f32 v[64:65], v[64:65], v[78:79]
	v_pk_add_f32 v[70:71], v[70:71], v[74:75]
	v_pk_add_f32 v[72:73], v[66:67], v[80:81]
	v_cvt_pk_bf16_f32 v66, v68, v69
	v_cvt_pk_bf16_f32 v67, v70, v71
	v_cvt_pk_bf16_f32 v68, v64, v65
	s_nop 0
	v_and_b32_e32 v65, 0xffff0000, v66
	v_lshlrev_b32_e32 v64, 16, v66
	v_mul_f32_e32 v65, v65, v65
	v_fmac_f32_e32 v65, v64, v64
	v_and_b32_e32 v70, 0xffff0000, v67
	v_add_f32_e32 v64, v82, v65
	v_lshlrev_b32_e32 v65, 16, v67
	v_mul_f32_e32 v70, v70, v70
	v_fmac_f32_e32 v70, v65, v65
	v_add_f32_e32 v64, v64, v70
	v_and_b32_e32 v70, 0xffff0000, v68
	v_lshlrev_b32_e32 v65, 16, v68
	v_mul_f32_e32 v70, v70, v70
	v_fmac_f32_e32 v70, v65, v65
	v_cvt_pk_bf16_f32 v69, v72, v73
	v_add_f32_e32 v64, v64, v70
	v_and_b32_e32 v70, 0xffff0000, v69
	v_lshlrev_b32_e32 v65, 16, v69
	v_mul_f32_e32 v70, v70, v70
	v_fmac_f32_e32 v70, v65, v65
	v_add_f32_e32 v64, v64, v70
	v_mov_b32_e32 v65, v64
	s_nop 1
	v_permlane16_swap_b32_e32 v65, v64
	global_store_dwordx4 v[76:77], v[66:69], off offset:256 nt
	s_waitcnt lgkmcnt(0)
	v_add_f32_e32 v64, v64, v65
	v_mov_b32_e32 v65, v64
	s_nop 1
	v_permlane32_swap_b32_e32 v65, v64
	s_and_saveexec_b64 s[6:7], vcc
	s_cbranch_execz .LBB0_386
	v_lshlrev_b64 v[66:67], 6, v[108:109]
	v_lshl_add_u64 v[66:67], s[46:47], 0, v[66:67]
	v_lshl_add_u64 v[66:67], s[56:57], 2, v[66:67]
	s_lshl_b32 s38, s8, 2
	v_lshl_add_u64 v[66:67], v[66:67], 0, s[38:39]
	s_waitcnt lgkmcnt(0)
	v_add_f32_e32 v64, v64, v65
	flat_store_dword v[66:67], v64
.LBB0_386:
	s_or_b64 exec, exec, s[6:7]
	v_add_u32_e32 v80, 0x80, v170
	v_ashrrev_i32_e32 v81, 31, v80
	v_lshlrev_b64 v[86:87], 11, v[80:81]
	s_waitcnt lgkmcnt(0)
	v_lshl_add_u64 v[64:65], v[172:173], 0, v[86:87]
	global_load_dwordx4 v[82:85], v[64:65], off
	global_load_dwordx4 v[72:75], v[64:65], off offset:256
	v_add_u32_e32 v76, 0x90, v170
	v_ashrrev_i32_e32 v77, 31, v76
	v_lshlrev_b64 v[78:79], 11, v[76:77]
	v_lshl_add_u64 v[64:65], v[172:173], 0, v[78:79]
	global_load_dwordx4 v[68:71], v[64:65], off
	s_nop 0
	global_load_dwordx4 v[64:67], v[64:65], off offset:256
	s_waitcnt vmcnt(0)
	v_lshlrev_b32_e32 v88, 16, v82
	v_and_b32_e32 v89, 0xffff0000, v82
	v_lshlrev_b32_e32 v82, 16, v83
	v_and_b32_e32 v83, 0xffff0000, v83
	v_lshlrev_b32_e32 v90, 16, v84
	v_and_b32_e32 v91, 0xffff0000, v84
	v_lshlrev_b32_e32 v84, 16, v85
	v_and_b32_e32 v85, 0xffff0000, v85
	v_pk_add_f32 v[60:61], v[60:61], v[88:89]
	v_pk_add_f32 v[62:63], v[62:63], v[82:83]
	v_pk_add_f32 v[82:83], v[58:59], v[84:85]
	v_pk_add_f32 v[58:59], v[56:57], v[90:91]
	v_cvt_pk_bf16_f32 v56, v60, v61
	v_lshl_add_u64 v[60:61], s[68:69], 0, v[86:87]
	v_lshl_add_u64 v[60:61], v[168:169], 1, v[60:61]
	v_cvt_pk_bf16_f32 v57, v62, v63
	v_cvt_pk_bf16_f32 v58, v58, v59
	v_cvt_pk_bf16_f32 v59, v82, v83
	global_store_dwordx4 v[60:61], v[56:59], off nt
	v_lshlrev_b32_e32 v62, 16, v56
	v_and_b32_e32 v63, 0xffff0000, v74
	v_and_b32_e32 v56, 0xffff0000, v56
	v_mul_f32_e32 v56, v56, v56
	v_fmac_f32_e32 v56, v62, v62
	v_lshlrev_b32_e32 v62, 16, v57
	v_and_b32_e32 v57, 0xffff0000, v57
	v_mul_f32_e32 v57, v57, v57
	v_fmac_f32_e32 v57, v62, v62
	v_add_f32_e32 v56, v56, v57
	v_lshlrev_b32_e32 v57, 16, v58
	v_and_b32_e32 v58, 0xffff0000, v58
	v_mul_f32_e32 v58, v58, v58
	v_fmac_f32_e32 v58, v57, v57
	v_add_f32_e32 v56, v56, v58
	v_and_b32_e32 v58, 0xffff0000, v59
	v_lshlrev_b32_e32 v57, 16, v59
	v_mul_f32_e32 v58, v58, v58
	v_fmac_f32_e32 v58, v57, v57
	v_add_f32_e32 v82, v56, v58
	v_lshlrev_b32_e32 v56, 16, v72
	v_and_b32_e32 v57, 0xffff0000, v72
	v_lshlrev_b32_e32 v58, 16, v73
	v_and_b32_e32 v59, 0xffff0000, v73
	v_lshlrev_b32_e32 v62, 16, v74
	v_lshlrev_b32_e32 v72, 16, v75
	v_and_b32_e32 v73, 0xffff0000, v75
	v_pk_add_f32 v[52:53], v[52:53], v[56:57]
	v_pk_add_f32 v[56:57], v[50:51], v[72:73]
	v_pk_add_f32 v[50:51], v[48:49], v[62:63]
	v_cvt_pk_bf16_f32 v48, v52, v53
	v_pk_add_f32 v[54:55], v[54:55], v[58:59]
	v_lshlrev_b32_e32 v52, 16, v48
	v_cvt_pk_bf16_f32 v49, v54, v55
	v_cvt_pk_bf16_f32 v50, v50, v51
	v_cvt_pk_bf16_f32 v51, v56, v57
	global_store_dwordx4 v[60:61], v[48:51], off offset:256 nt
	s_nop 1
	v_and_b32_e32 v48, 0xffff0000, v48
	v_mul_f32_e32 v48, v48, v48
	v_fmac_f32_e32 v48, v52, v52
	v_lshlrev_b32_e32 v52, 16, v49
	v_and_b32_e32 v49, 0xffff0000, v49
	v_mul_f32_e32 v49, v49, v49
	v_add_f32_e32 v48, v82, v48
	v_fmac_f32_e32 v49, v52, v52
	v_add_f32_e32 v48, v48, v49
	v_lshlrev_b32_e32 v49, 16, v50
	v_and_b32_e32 v50, 0xffff0000, v50
	v_mul_f32_e32 v50, v50, v50
	v_fmac_f32_e32 v50, v49, v49
	v_add_f32_e32 v48, v48, v50
	v_and_b32_e32 v50, 0xffff0000, v51
	v_lshlrev_b32_e32 v49, 16, v51
	v_mul_f32_e32 v50, v50, v50
	v_fmac_f32_e32 v50, v49, v49
	v_add_f32_e32 v48, v48, v50
	v_mov_b32_e32 v49, v48
	s_nop 1
	v_permlane16_swap_b32_e32 v49, v48
	s_waitcnt lgkmcnt(0)
	v_add_f32_e32 v48, v48, v49
	v_mov_b32_e32 v49, v48
	s_nop 1
	v_permlane32_swap_b32_e32 v49, v48
	s_and_saveexec_b64 s[6:7], vcc
	s_cbranch_execz .LBB0_388
	v_lshlrev_b64 v[50:51], 6, v[80:81]
	v_lshl_add_u64 v[50:51], s[46:47], 0, v[50:51]
	v_lshl_add_u64 v[50:51], s[56:57], 2, v[50:51]
	s_lshl_b32 s38, s8, 2
	v_lshl_add_u64 v[50:51], v[50:51], 0, s[38:39]
	s_waitcnt lgkmcnt(0)
	v_add_f32_e32 v48, v48, v49
	flat_store_dword v[50:51], v48
.LBB0_388:
	s_or_b64 exec, exec, s[6:7]
	v_lshlrev_b32_e32 v48, 16, v68
	s_waitcnt lgkmcnt(0)
	v_and_b32_e32 v49, 0xffff0000, v68
	v_lshlrev_b32_e32 v52, 16, v70
	v_and_b32_e32 v53, 0xffff0000, v70
	v_lshlrev_b32_e32 v54, 16, v71
	v_and_b32_e32 v55, 0xffff0000, v71
	v_pk_add_f32 v[44:45], v[44:45], v[48:49]
	v_lshlrev_b32_e32 v50, 16, v69
	v_and_b32_e32 v51, 0xffff0000, v69
	v_pk_add_f32 v[48:49], v[42:43], v[54:55]
	v_pk_add_f32 v[42:43], v[40:41], v[52:53]
	v_cvt_pk_bf16_f32 v40, v44, v45
	v_lshl_add_u64 v[44:45], s[68:69], 0, v[78:79]
	v_pk_add_f32 v[46:47], v[46:47], v[50:51]
	v_lshl_add_u64 v[44:45], v[168:169], 1, v[44:45]
	v_cvt_pk_bf16_f32 v41, v46, v47
	v_cvt_pk_bf16_f32 v42, v42, v43
	v_cvt_pk_bf16_f32 v43, v48, v49
	global_store_dwordx4 v[44:45], v[40:43], off nt
	v_lshlrev_b32_e32 v46, 16, v40
	v_and_b32_e32 v47, 0xffff0000, v66
	v_and_b32_e32 v40, 0xffff0000, v40
	v_mul_f32_e32 v40, v40, v40
	v_fmac_f32_e32 v40, v46, v46
	v_lshlrev_b32_e32 v46, 16, v41
	v_and_b32_e32 v41, 0xffff0000, v41
	v_mul_f32_e32 v41, v41, v41
	v_fmac_f32_e32 v41, v46, v46
	v_add_f32_e32 v40, v40, v41
	v_lshlrev_b32_e32 v41, 16, v42
	v_and_b32_e32 v42, 0xffff0000, v42
	v_mul_f32_e32 v42, v42, v42
	v_fmac_f32_e32 v42, v41, v41
	v_add_f32_e32 v40, v40, v42
	v_and_b32_e32 v42, 0xffff0000, v43
	v_lshlrev_b32_e32 v41, 16, v43
	v_mul_f32_e32 v42, v42, v42
	v_fmac_f32_e32 v42, v41, v41
	v_add_f32_e32 v50, v40, v42
	v_lshlrev_b32_e32 v40, 16, v64
	v_and_b32_e32 v41, 0xffff0000, v64
	v_lshlrev_b32_e32 v46, 16, v66
	v_lshlrev_b32_e32 v42, 16, v65
	v_and_b32_e32 v43, 0xffff0000, v65
	v_lshlrev_b32_e32 v48, 16, v67
	v_and_b32_e32 v49, 0xffff0000, v67
	v_pk_add_f32 v[36:37], v[36:37], v[40:41]
	v_pk_add_f32 v[32:33], v[32:33], v[46:47]
	v_pk_add_f32 v[38:39], v[38:39], v[42:43]
	v_pk_add_f32 v[40:41], v[34:35], v[48:49]
	v_cvt_pk_bf16_f32 v34, v36, v37
	v_cvt_pk_bf16_f32 v35, v38, v39
	v_cvt_pk_bf16_f32 v36, v32, v33
	s_nop 0
	v_and_b32_e32 v33, 0xffff0000, v34
	v_lshlrev_b32_e32 v32, 16, v34
	v_mul_f32_e32 v33, v33, v33
	v_fmac_f32_e32 v33, v32, v32
	v_and_b32_e32 v38, 0xffff0000, v35
	v_add_f32_e32 v32, v50, v33
	v_lshlrev_b32_e32 v33, 16, v35
	v_mul_f32_e32 v38, v38, v38
	v_fmac_f32_e32 v38, v33, v33
	v_add_f32_e32 v32, v32, v38
	v_and_b32_e32 v38, 0xffff0000, v36
	v_lshlrev_b32_e32 v33, 16, v36
	v_mul_f32_e32 v38, v38, v38
	v_fmac_f32_e32 v38, v33, v33
	v_cvt_pk_bf16_f32 v37, v40, v41
	v_add_f32_e32 v32, v32, v38
	v_and_b32_e32 v38, 0xffff0000, v37
	v_lshlrev_b32_e32 v33, 16, v37
	v_mul_f32_e32 v38, v38, v38
	v_fmac_f32_e32 v38, v33, v33
	v_add_f32_e32 v32, v32, v38
	v_mov_b32_e32 v33, v32
	s_nop 1
	v_permlane16_swap_b32_e32 v33, v32
	global_store_dwordx4 v[44:45], v[34:37], off offset:256 nt
	s_waitcnt lgkmcnt(0)
	v_add_f32_e32 v32, v32, v33
	v_mov_b32_e32 v33, v32
	s_nop 1
	v_permlane32_swap_b32_e32 v33, v32
	s_and_saveexec_b64 s[6:7], vcc
	s_cbranch_execz .LBB0_390
	v_lshlrev_b64 v[34:35], 6, v[76:77]
	v_lshl_add_u64 v[34:35], s[46:47], 0, v[34:35]
	v_lshl_add_u64 v[34:35], s[56:57], 2, v[34:35]
	s_lshl_b32 s38, s8, 2
	v_lshl_add_u64 v[34:35], v[34:35], 0, s[38:39]
	s_waitcnt lgkmcnt(0)
	v_add_f32_e32 v32, v32, v33
	flat_store_dword v[34:35], v32
.LBB0_390:
	s_or_b64 exec, exec, s[6:7]
	v_add_u32_e32 v48, 0xa0, v170
	v_ashrrev_i32_e32 v49, 31, v48
	v_lshlrev_b64 v[54:55], 11, v[48:49]
	s_waitcnt lgkmcnt(0)
	v_lshl_add_u64 v[32:33], v[172:173], 0, v[54:55]
	global_load_dwordx4 v[50:53], v[32:33], off
	global_load_dwordx4 v[40:43], v[32:33], off offset:256
	v_add_u32_e32 v44, 0xb0, v170
	v_ashrrev_i32_e32 v45, 31, v44
	v_lshlrev_b64 v[46:47], 11, v[44:45]
	v_lshl_add_u64 v[32:33], v[172:173], 0, v[46:47]
	global_load_dwordx4 v[36:39], v[32:33], off
	s_nop 0
	global_load_dwordx4 v[32:35], v[32:33], off offset:256
	s_waitcnt vmcnt(0)
	v_lshlrev_b32_e32 v56, 16, v50
	v_and_b32_e32 v57, 0xffff0000, v50
	v_lshlrev_b32_e32 v50, 16, v51
	v_and_b32_e32 v51, 0xffff0000, v51
	v_lshlrev_b32_e32 v58, 16, v52
	v_and_b32_e32 v59, 0xffff0000, v52
	v_lshlrev_b32_e32 v52, 16, v53
	v_and_b32_e32 v53, 0xffff0000, v53
	v_pk_add_f32 v[28:29], v[28:29], v[56:57]
	v_pk_add_f32 v[30:31], v[30:31], v[50:51]
	v_pk_add_f32 v[50:51], v[26:27], v[52:53]
	v_pk_add_f32 v[26:27], v[24:25], v[58:59]
	v_cvt_pk_bf16_f32 v24, v28, v29
	v_lshl_add_u64 v[28:29], s[68:69], 0, v[54:55]
	v_lshl_add_u64 v[28:29], v[168:169], 1, v[28:29]
	v_cvt_pk_bf16_f32 v25, v30, v31
	v_cvt_pk_bf16_f32 v26, v26, v27
	v_cvt_pk_bf16_f32 v27, v50, v51
	global_store_dwordx4 v[28:29], v[24:27], off nt
	v_lshlrev_b32_e32 v30, 16, v24
	v_and_b32_e32 v31, 0xffff0000, v42
	v_and_b32_e32 v24, 0xffff0000, v24
	v_mul_f32_e32 v24, v24, v24
	v_fmac_f32_e32 v24, v30, v30
	v_lshlrev_b32_e32 v30, 16, v25
	v_and_b32_e32 v25, 0xffff0000, v25
	v_mul_f32_e32 v25, v25, v25
	v_fmac_f32_e32 v25, v30, v30
	v_add_f32_e32 v24, v24, v25
	v_lshlrev_b32_e32 v25, 16, v26
	v_and_b32_e32 v26, 0xffff0000, v26
	v_mul_f32_e32 v26, v26, v26
	v_fmac_f32_e32 v26, v25, v25
	v_add_f32_e32 v24, v24, v26
	v_and_b32_e32 v26, 0xffff0000, v27
	v_lshlrev_b32_e32 v25, 16, v27
	v_mul_f32_e32 v26, v26, v26
	v_fmac_f32_e32 v26, v25, v25
	v_add_f32_e32 v50, v24, v26
	v_lshlrev_b32_e32 v24, 16, v40
	v_and_b32_e32 v25, 0xffff0000, v40
	v_lshlrev_b32_e32 v26, 16, v41
	v_and_b32_e32 v27, 0xffff0000, v41
	v_lshlrev_b32_e32 v30, 16, v42
	v_lshlrev_b32_e32 v40, 16, v43
	v_and_b32_e32 v41, 0xffff0000, v43
	v_pk_add_f32 v[20:21], v[20:21], v[24:25]
	v_pk_add_f32 v[24:25], v[18:19], v[40:41]
	v_pk_add_f32 v[18:19], v[16:17], v[30:31]
	v_cvt_pk_bf16_f32 v16, v20, v21
	v_pk_add_f32 v[22:23], v[22:23], v[26:27]
	v_lshlrev_b32_e32 v20, 16, v16
	v_cvt_pk_bf16_f32 v17, v22, v23
	v_cvt_pk_bf16_f32 v18, v18, v19
	v_cvt_pk_bf16_f32 v19, v24, v25
	global_store_dwordx4 v[28:29], v[16:19], off offset:256 nt
	s_nop 1
	v_and_b32_e32 v16, 0xffff0000, v16
	v_mul_f32_e32 v16, v16, v16
	v_fmac_f32_e32 v16, v20, v20
	v_lshlrev_b32_e32 v20, 16, v17
	v_and_b32_e32 v17, 0xffff0000, v17
	v_mul_f32_e32 v17, v17, v17
	v_add_f32_e32 v16, v50, v16
	v_fmac_f32_e32 v17, v20, v20
	v_add_f32_e32 v16, v16, v17
	v_lshlrev_b32_e32 v17, 16, v18
	v_and_b32_e32 v18, 0xffff0000, v18
	v_mul_f32_e32 v18, v18, v18
	v_fmac_f32_e32 v18, v17, v17
	v_add_f32_e32 v16, v16, v18
	v_and_b32_e32 v18, 0xffff0000, v19
	v_lshlrev_b32_e32 v17, 16, v19
	v_mul_f32_e32 v18, v18, v18
	v_fmac_f32_e32 v18, v17, v17
	v_add_f32_e32 v16, v16, v18
	v_mov_b32_e32 v17, v16
	s_nop 1
	v_permlane16_swap_b32_e32 v17, v16
	s_waitcnt lgkmcnt(0)
	v_add_f32_e32 v16, v16, v17
	v_mov_b32_e32 v17, v16
	s_nop 1
	v_permlane32_swap_b32_e32 v17, v16
	s_and_saveexec_b64 s[6:7], vcc
	s_cbranch_execz .LBB0_392
	v_lshlrev_b64 v[18:19], 6, v[48:49]
	v_lshl_add_u64 v[18:19], s[46:47], 0, v[18:19]
	v_lshl_add_u64 v[18:19], s[56:57], 2, v[18:19]
	s_lshl_b32 s38, s8, 2
	v_lshl_add_u64 v[18:19], v[18:19], 0, s[38:39]
	s_waitcnt lgkmcnt(0)
	v_add_f32_e32 v16, v16, v17
	flat_store_dword v[18:19], v16
.LBB0_392:
	s_or_b64 exec, exec, s[6:7]
	v_lshlrev_b32_e32 v16, 16, v36
	s_waitcnt lgkmcnt(0)
	v_and_b32_e32 v17, 0xffff0000, v36
	v_lshlrev_b32_e32 v20, 16, v38
	v_and_b32_e32 v21, 0xffff0000, v38
	v_lshlrev_b32_e32 v22, 16, v39
	v_and_b32_e32 v23, 0xffff0000, v39
	v_pk_add_f32 v[12:13], v[12:13], v[16:17]
	v_lshlrev_b32_e32 v18, 16, v37
	v_and_b32_e32 v19, 0xffff0000, v37
	v_pk_add_f32 v[16:17], v[10:11], v[22:23]
	v_pk_add_f32 v[10:11], v[8:9], v[20:21]
	v_cvt_pk_bf16_f32 v8, v12, v13
	v_lshl_add_u64 v[12:13], s[68:69], 0, v[46:47]
	v_pk_add_f32 v[14:15], v[14:15], v[18:19]
	v_lshl_add_u64 v[12:13], v[168:169], 1, v[12:13]
	v_cvt_pk_bf16_f32 v9, v14, v15
	v_cvt_pk_bf16_f32 v10, v10, v11
	v_cvt_pk_bf16_f32 v11, v16, v17
	global_store_dwordx4 v[12:13], v[8:11], off nt
	v_lshlrev_b32_e32 v14, 16, v8
	v_and_b32_e32 v15, 0xffff0000, v34
	v_and_b32_e32 v8, 0xffff0000, v8
	v_mul_f32_e32 v8, v8, v8
	v_fmac_f32_e32 v8, v14, v14
	v_lshlrev_b32_e32 v14, 16, v9
	v_and_b32_e32 v9, 0xffff0000, v9
	v_mul_f32_e32 v9, v9, v9
	v_fmac_f32_e32 v9, v14, v14
	v_add_f32_e32 v8, v8, v9
	v_lshlrev_b32_e32 v9, 16, v10
	v_and_b32_e32 v10, 0xffff0000, v10
	v_mul_f32_e32 v10, v10, v10
	v_fmac_f32_e32 v10, v9, v9
	v_add_f32_e32 v8, v8, v10
	v_and_b32_e32 v10, 0xffff0000, v11
	v_lshlrev_b32_e32 v9, 16, v11
	v_mul_f32_e32 v10, v10, v10
	v_fmac_f32_e32 v10, v9, v9
	v_add_f32_e32 v18, v8, v10
	v_lshlrev_b32_e32 v8, 16, v32
	v_and_b32_e32 v9, 0xffff0000, v32
	v_lshlrev_b32_e32 v14, 16, v34
	v_lshlrev_b32_e32 v10, 16, v33
	v_and_b32_e32 v11, 0xffff0000, v33
	v_lshlrev_b32_e32 v16, 16, v35
	v_and_b32_e32 v17, 0xffff0000, v35
	v_pk_add_f32 v[4:5], v[4:5], v[8:9]
	v_pk_add_f32 v[0:1], v[0:1], v[14:15]
	v_pk_add_f32 v[6:7], v[6:7], v[10:11]
	v_pk_add_f32 v[8:9], v[2:3], v[16:17]
	v_cvt_pk_bf16_f32 v2, v4, v5
	v_cvt_pk_bf16_f32 v3, v6, v7
	v_cvt_pk_bf16_f32 v4, v0, v1
	s_nop 0
	v_and_b32_e32 v1, 0xffff0000, v2
	v_lshlrev_b32_e32 v0, 16, v2
	v_mul_f32_e32 v1, v1, v1
	v_fmac_f32_e32 v1, v0, v0
	v_and_b32_e32 v6, 0xffff0000, v3
	v_add_f32_e32 v0, v18, v1
	v_lshlrev_b32_e32 v1, 16, v3
	v_mul_f32_e32 v6, v6, v6
	v_fmac_f32_e32 v6, v1, v1
	v_add_f32_e32 v0, v0, v6
	v_and_b32_e32 v6, 0xffff0000, v4
	v_lshlrev_b32_e32 v1, 16, v4
	v_mul_f32_e32 v6, v6, v6
	v_fmac_f32_e32 v6, v1, v1
	v_cvt_pk_bf16_f32 v5, v8, v9
	v_add_f32_e32 v0, v0, v6
	v_and_b32_e32 v6, 0xffff0000, v5
	v_lshlrev_b32_e32 v1, 16, v5
	v_mul_f32_e32 v6, v6, v6
	v_fmac_f32_e32 v6, v1, v1
	v_add_f32_e32 v0, v0, v6
	v_mov_b32_e32 v1, v0
	s_nop 1
	v_permlane16_swap_b32_e32 v1, v0
	global_store_dwordx4 v[12:13], v[2:5], off offset:256 nt
	s_waitcnt lgkmcnt(0)
	v_add_f32_e32 v0, v0, v1
	v_mov_b32_e32 v1, v0
	s_nop 1
	v_permlane32_swap_b32_e32 v1, v0
	s_and_saveexec_b64 s[6:7], vcc
	s_cbranch_execz .LBB0_394
	v_lshlrev_b64 v[2:3], 6, v[44:45]
	v_lshl_add_u64 v[2:3], s[46:47], 0, v[2:3]
	v_lshl_add_u64 v[2:3], s[56:57], 2, v[2:3]
	s_lshl_b32 s38, s8, 2
	v_lshl_add_u64 v[2:3], v[2:3], 0, s[38:39]
	s_waitcnt lgkmcnt(0)
	v_add_f32_e32 v0, v0, v1
	flat_store_dword v[2:3], v0

.LBB0_419:
	s_mov_b32 s6, -1
	s_lshl_b32 s5, s5, 8
	v_mbcnt_lo_u32_b32 v112, s6, 0
	v_mbcnt_hi_u32_b32 v112, s6, v112
	s_getreg_b32 s6, hwreg(HW_REG_HW_ID, 0, 6)
	s_and_b32 s6, s6, 63
	s_lshl_b32 s6, s6, 2
	s_add_i32 s6, s6, 0
	s_add_i32 s6, s6, 0x20200
	v_mov_b32_e32 v113, s6
	ds_read_b32 v113, v113
	v_bfrev_b32_e32 v114, 0.5
	s_movk_i32 s84, 0x80
	s_lshl_b32 s58, s4, 2
	s_ashr_i32 s59, s58, 31
	s_waitcnt lgkmcnt(0)
	v_readfirstlane_b32 s6, v113
	s_nop 1
	v_lshl_add_u32 v112, s6, 6, v112
	s_nop 0
	v_readfirstlane_b32 s6, v112
	s_bfe_u32 s8, s6, 0x20006
	s_ashr_i32 s6, s6, 2
	s_andn2_b32 s6, s6, 63
	s_add_i32 s6, s6, s5
	v_and_or_b32 v166, v112, 15, s6
	s_lshl_b32 s5, s4, 8
	s_lshl_b32 s6, s8, 5
	v_bfe_u32 v113, v112, 4, 2
	s_or_b32 s5, s6, s5
	v_lshl_or_b32 v164, v113, 3, s5
	v_ashrrev_i32_e32 v165, 31, v164
	v_lshlrev_b64 v[146:147], 1, v[164:165]
	v_ashrrev_i32_e32 v167, 31, v166
	v_lshlrev_b32_e32 v112, 2, v112
	v_lshl_add_u64 v[168:169], s[68:69], 0, v[146:147]
	v_lshlrev_b64 v[148:149], 11, v[166:167]
	v_bitop3_b32 v176, v112, 64, v114 bitop3:0x6c
	v_bitop3_b32 v177, v112, s84, v114 bitop3:0x6c
	v_cmp_eq_u32_e32 vcc, 0, v113
	v_lshl_add_u64 v[112:113], v[168:169], 0, v[148:149]
	global_load_dwordx4 v[142:145], v[112:113], off
	global_load_dwordx4 v[128:131], v[112:113], off offset:256
	v_or_b32_e32 v170, 16, v166
	v_ashrrev_i32_e32 v171, 31, v170
	v_lshlrev_b64 v[172:173], 11, v[170:171]
	v_lshl_add_u64 v[112:113], v[168:169], 0, v[172:173]
	global_load_dwordx4 v[116:119], v[112:113], off
	s_nop 0
	global_load_dwordx4 v[112:115], v[112:113], off offset:256
	s_waitcnt vmcnt(0)
	v_lshlrev_b32_e32 v150, 16, v142
	v_and_b32_e32 v151, 0xffff0000, v142
	v_lshlrev_b32_e32 v142, 16, v143
	v_and_b32_e32 v143, 0xffff0000, v143
	v_lshlrev_b32_e32 v152, 16, v144
	v_and_b32_e32 v153, 0xffff0000, v144
	v_pk_add_f32 v[134:135], v[134:135], v[142:143]
	v_pk_add_f32 v[132:133], v[132:133], v[150:151]
	v_pk_add_f32 v[136:137], v[136:137], v[152:153]
	v_lshlrev_b32_e32 v144, 16, v145
	v_and_b32_e32 v145, 0xffff0000, v145
	v_cvt_pk_bf16_f32 v132, v132, v133
	v_cvt_pk_bf16_f32 v133, v134, v135
	v_cvt_pk_bf16_f32 v134, v136, v137
	v_lshl_add_u64 v[136:137], s[68:69], 0, v[148:149]
	v_pk_add_f32 v[138:139], v[138:139], v[144:145]
	v_lshl_add_u64 v[136:137], v[136:137], 0, v[146:147]
	v_cvt_pk_bf16_f32 v135, v138, v139
	global_store_dwordx4 v[136:137], v[132:135], off nt
	v_lshlrev_b32_e32 v138, 16, v132
	s_nop 0
	v_and_b32_e32 v132, 0xffff0000, v132
	v_mul_f32_e32 v132, v132, v132
	v_fmac_f32_e32 v132, v138, v138
	v_lshlrev_b32_e32 v138, 16, v133
	v_and_b32_e32 v133, 0xffff0000, v133
	v_mul_f32_e32 v133, v133, v133
	v_fmac_f32_e32 v133, v138, v138
	v_add_f32_e32 v132, v132, v133
	v_lshlrev_b32_e32 v133, 16, v134
	v_and_b32_e32 v134, 0xffff0000, v134
	v_mul_f32_e32 v134, v134, v134
	v_fmac_f32_e32 v134, v133, v133
	v_add_f32_e32 v132, v132, v134
	v_and_b32_e32 v134, 0xffff0000, v135
	v_lshlrev_b32_e32 v133, 16, v135
	v_mul_f32_e32 v134, v134, v134
	v_fmac_f32_e32 v134, v133, v133
	v_add_f32_e32 v138, v132, v134
	v_lshlrev_b32_e32 v132, 16, v128
	v_and_b32_e32 v133, 0xffff0000, v128
	v_lshlrev_b32_e32 v128, 16, v129
	v_and_b32_e32 v129, 0xffff0000, v129
	v_lshlrev_b32_e32 v134, 16, v130
	v_and_b32_e32 v135, 0xffff0000, v130
	v_lshlrev_b32_e32 v130, 16, v131
	v_and_b32_e32 v131, 0xffff0000, v131
	v_pk_add_f32 v[126:127], v[126:127], v[128:129]
	v_pk_add_f32 v[124:125], v[124:125], v[132:133]
	v_pk_add_f32 v[128:129], v[122:123], v[130:131]
	v_pk_add_f32 v[122:123], v[120:121], v[134:135]
	v_cvt_pk_bf16_f32 v120, v124, v125
	v_cvt_pk_bf16_f32 v121, v126, v127
	s_nop 0
	v_cvt_pk_bf16_f32 v122, v122, v123
	v_cvt_pk_bf16_f32 v123, v128, v129
	global_store_dwordx4 v[136:137], v[120:123], off offset:256 nt
	v_lshlrev_b32_e32 v124, 16, v120
	s_nop 0
	v_and_b32_e32 v120, 0xffff0000, v120
	v_mul_f32_e32 v120, v120, v120
	v_fmac_f32_e32 v120, v124, v124
	v_lshlrev_b32_e32 v124, 16, v121
	v_and_b32_e32 v121, 0xffff0000, v121
	v_mul_f32_e32 v121, v121, v121
	v_add_f32_e32 v120, v138, v120
	v_fmac_f32_e32 v121, v124, v124
	v_add_f32_e32 v120, v120, v121
	v_lshlrev_b32_e32 v121, 16, v122
	v_and_b32_e32 v122, 0xffff0000, v122
	v_mul_f32_e32 v122, v122, v122
	v_fmac_f32_e32 v122, v121, v121
	v_add_f32_e32 v120, v120, v122
	v_and_b32_e32 v122, 0xffff0000, v123
	v_lshlrev_b32_e32 v121, 16, v123
	v_mul_f32_e32 v122, v122, v122
	v_fmac_f32_e32 v122, v121, v121
	v_add_f32_e32 v120, v120, v122
	v_mov_b32_e32 v121, v120
	s_nop 1
	v_permlane16_swap_b32_e32 v121, v120
	s_waitcnt lgkmcnt(0)
	v_add_f32_e32 v120, v120, v121
	v_mov_b32_e32 v121, v120
	s_nop 1
	v_permlane32_swap_b32_e32 v121, v120
	s_and_saveexec_b64 s[6:7], vcc
	s_cbranch_execz .LBB0_421
	s_waitcnt lgkmcnt(0)
	v_add_f32_e32 v122, v120, v121
	v_lshlrev_b64 v[120:121], 6, v[166:167]
	v_lshl_add_u64 v[120:121], s[46:47], 0, v[120:121]
	v_lshl_add_u64 v[120:121], s[58:59], 2, v[120:121]
	s_lshl_b32 s38, s8, 2
	v_lshl_add_u64 v[120:121], v[120:121], 0, s[38:39]
	flat_store_dword v[120:121], v122
.LBB0_421:
	s_or_b64 exec, exec, s[6:7]
	v_lshlrev_b32_e32 v120, 16, v116
	s_waitcnt lgkmcnt(0)
	v_and_b32_e32 v121, 0xffff0000, v116
	v_lshlrev_b32_e32 v116, 16, v117
	v_and_b32_e32 v117, 0xffff0000, v117
	v_lshlrev_b32_e32 v122, 16, v118
	v_and_b32_e32 v123, 0xffff0000, v118
	v_lshlrev_b32_e32 v118, 16, v119
	v_and_b32_e32 v119, 0xffff0000, v119
	v_pk_add_f32 v[108:109], v[108:109], v[120:121]
	v_pk_add_f32 v[110:111], v[110:111], v[116:117]
	v_pk_add_f32 v[116:117], v[106:107], v[118:119]
	v_pk_add_f32 v[106:107], v[104:105], v[122:123]
	v_cvt_pk_bf16_f32 v104, v108, v109
	v_lshl_add_u64 v[108:109], s[68:69], 0, v[172:173]
	v_lshl_add_u64 v[108:109], v[164:165], 1, v[108:109]
	v_cvt_pk_bf16_f32 v105, v110, v111
	v_cvt_pk_bf16_f32 v106, v106, v107
	v_cvt_pk_bf16_f32 v107, v116, v117
	global_store_dwordx4 v[108:109], v[104:107], off nt
	v_lshlrev_b32_e32 v110, 16, v104
	v_and_b32_e32 v111, 0xffff0000, v114
	v_and_b32_e32 v104, 0xffff0000, v104
	v_mul_f32_e32 v104, v104, v104
	v_fmac_f32_e32 v104, v110, v110
	v_lshlrev_b32_e32 v110, 16, v105
	v_and_b32_e32 v105, 0xffff0000, v105
	v_mul_f32_e32 v105, v105, v105
	v_fmac_f32_e32 v105, v110, v110
	v_add_f32_e32 v104, v104, v105
	v_lshlrev_b32_e32 v105, 16, v106
	v_and_b32_e32 v106, 0xffff0000, v106
	v_mul_f32_e32 v106, v106, v106
	v_fmac_f32_e32 v106, v105, v105
	v_add_f32_e32 v104, v104, v106
	v_and_b32_e32 v106, 0xffff0000, v107
	v_lshlrev_b32_e32 v105, 16, v107
	v_mul_f32_e32 v106, v106, v106
	v_fmac_f32_e32 v106, v105, v105
	v_add_f32_e32 v116, v104, v106
	v_lshlrev_b32_e32 v104, 16, v112
	v_and_b32_e32 v105, 0xffff0000, v112
	v_lshlrev_b32_e32 v110, 16, v114
	v_lshlrev_b32_e32 v106, 16, v113
	v_and_b32_e32 v107, 0xffff0000, v113
	v_lshlrev_b32_e32 v112, 16, v115
	v_and_b32_e32 v113, 0xffff0000, v115
	v_pk_add_f32 v[100:101], v[100:101], v[104:105]
	v_pk_add_f32 v[96:97], v[96:97], v[110:111]
	v_pk_add_f32 v[102:103], v[102:103], v[106:107]
	v_pk_add_f32 v[104:105], v[98:99], v[112:113]
	v_cvt_pk_bf16_f32 v98, v100, v101
	v_cvt_pk_bf16_f32 v99, v102, v103
	v_cvt_pk_bf16_f32 v100, v96, v97
	s_nop 0
	v_and_b32_e32 v97, 0xffff0000, v98
	v_lshlrev_b32_e32 v96, 16, v98
	v_mul_f32_e32 v97, v97, v97
	v_fmac_f32_e32 v97, v96, v96
	v_and_b32_e32 v102, 0xffff0000, v99
	v_add_f32_e32 v96, v116, v97
	v_lshlrev_b32_e32 v97, 16, v99
	v_mul_f32_e32 v102, v102, v102
	v_fmac_f32_e32 v102, v97, v97
	v_add_f32_e32 v96, v96, v102
	v_and_b32_e32 v102, 0xffff0000, v100
	v_lshlrev_b32_e32 v97, 16, v100
	v_mul_f32_e32 v102, v102, v102
	v_fmac_f32_e32 v102, v97, v97
	v_cvt_pk_bf16_f32 v101, v104, v105
	v_add_f32_e32 v96, v96, v102
	v_and_b32_e32 v102, 0xffff0000, v101
	v_lshlrev_b32_e32 v97, 16, v101
	v_mul_f32_e32 v102, v102, v102
	v_fmac_f32_e32 v102, v97, v97
	v_add_f32_e32 v96, v96, v102
	v_mov_b32_e32 v97, v96
	s_nop 1
	v_permlane16_swap_b32_e32 v97, v96
	global_store_dwordx4 v[108:109], v[98:101], off offset:256 nt
	s_waitcnt lgkmcnt(0)
	v_add_f32_e32 v96, v96, v97
	v_mov_b32_e32 v97, v96
	s_nop 1
	v_permlane32_swap_b32_e32 v97, v96
	s_mov_b64 s[6:7], exec
	s_and_b64 s[4:5], s[6:7], vcc
	v_mov_b32_e32 v198, v246
	v_mov_b32_e32 v199, v247
	v_mov_b32_e32 v205, v249
	v_mov_b32_e32 v196, v251
	v_mov_b32_e32 v251, 0x260
	s_mov_b64 exec, s[4:5]
	s_cbranch_execz .LBB0_423
	s_waitcnt lgkmcnt(0)
	v_add_f32_e32 v98, v96, v97
	v_lshlrev_b64 v[96:97], 6, v[170:171]
	v_lshl_add_u64 v[96:97], s[46:47], 0, v[96:97]
	v_lshl_add_u64 v[96:97], s[58:59], 2, v[96:97]
	s_lshl_b32 s38, s8, 2
	v_lshl_add_u64 v[96:97], v[96:97], 0, s[38:39]
	flat_store_dword v[96:97], v98
.LBB0_423:
	s_or_b64 exec, exec, s[6:7]
	v_or_b32_e32 v112, 32, v166
	v_ashrrev_i32_e32 v113, 31, v112
	v_lshlrev_b64 v[118:119], 11, v[112:113]
	s_waitcnt lgkmcnt(0)
	v_lshl_add_u64 v[96:97], v[168:169], 0, v[118:119]
	global_load_dwordx4 v[114:117], v[96:97], off
	global_load_dwordx4 v[104:107], v[96:97], off offset:256
	v_or_b32_e32 v108, 48, v166
	v_ashrrev_i32_e32 v109, 31, v108
	v_lshlrev_b64 v[110:111], 11, v[108:109]
	v_lshl_add_u64 v[96:97], v[168:169], 0, v[110:111]
	global_load_dwordx4 v[100:103], v[96:97], off
	s_nop 0
	global_load_dwordx4 v[96:99], v[96:97], off offset:256
	s_waitcnt vmcnt(0)
	v_lshlrev_b32_e32 v120, 16, v114
	v_and_b32_e32 v121, 0xffff0000, v114
	v_lshlrev_b32_e32 v114, 16, v115
	v_and_b32_e32 v115, 0xffff0000, v115
	v_lshlrev_b32_e32 v122, 16, v116
	v_and_b32_e32 v123, 0xffff0000, v116
	v_pk_add_f32 v[90:91], v[90:91], v[114:115]
	v_pk_add_f32 v[88:89], v[88:89], v[120:121]
	v_pk_add_f32 v[92:93], v[92:93], v[122:123]
	v_lshlrev_b32_e32 v116, 16, v117
	v_and_b32_e32 v117, 0xffff0000, v117
	v_cvt_pk_bf16_f32 v88, v88, v89
	v_cvt_pk_bf16_f32 v89, v90, v91
	v_cvt_pk_bf16_f32 v90, v92, v93
	v_lshl_add_u64 v[92:93], s[68:69], 0, v[118:119]
	v_pk_add_f32 v[94:95], v[94:95], v[116:117]
	v_lshl_add_u64 v[92:93], v[164:165], 1, v[92:93]
	v_cvt_pk_bf16_f32 v91, v94, v95
	global_store_dwordx4 v[92:93], v[88:91], off nt
	v_lshlrev_b32_e32 v94, 16, v88
	v_and_b32_e32 v95, 0xffff0000, v106
	v_and_b32_e32 v88, 0xffff0000, v88
	v_mul_f32_e32 v88, v88, v88
	v_fmac_f32_e32 v88, v94, v94
	v_lshlrev_b32_e32 v94, 16, v89
	v_and_b32_e32 v89, 0xffff0000, v89
	v_mul_f32_e32 v89, v89, v89
	v_fmac_f32_e32 v89, v94, v94
	v_add_f32_e32 v88, v88, v89
	v_lshlrev_b32_e32 v89, 16, v90
	v_and_b32_e32 v90, 0xffff0000, v90
	v_mul_f32_e32 v90, v90, v90
	v_fmac_f32_e32 v90, v89, v89
	v_add_f32_e32 v88, v88, v90
	v_and_b32_e32 v90, 0xffff0000, v91
	v_lshlrev_b32_e32 v89, 16, v91
	v_mul_f32_e32 v90, v90, v90
	v_fmac_f32_e32 v90, v89, v89
	v_add_f32_e32 v114, v88, v90
	v_lshlrev_b32_e32 v88, 16, v104
	v_and_b32_e32 v89, 0xffff0000, v104
	v_lshlrev_b32_e32 v90, 16, v105
	v_and_b32_e32 v91, 0xffff0000, v105
	v_lshlrev_b32_e32 v94, 16, v106
	v_lshlrev_b32_e32 v104, 16, v107
	v_and_b32_e32 v105, 0xffff0000, v107
	v_pk_add_f32 v[84:85], v[84:85], v[88:89]
	v_pk_add_f32 v[88:89], v[82:83], v[104:105]
	v_pk_add_f32 v[82:83], v[80:81], v[94:95]
	v_cvt_pk_bf16_f32 v80, v84, v85
	v_pk_add_f32 v[86:87], v[86:87], v[90:91]
	v_lshlrev_b32_e32 v84, 16, v80
	v_cvt_pk_bf16_f32 v81, v86, v87
	v_cvt_pk_bf16_f32 v82, v82, v83
	v_cvt_pk_bf16_f32 v83, v88, v89
	global_store_dwordx4 v[92:93], v[80:83], off offset:256 nt
	s_nop 1
	v_and_b32_e32 v80, 0xffff0000, v80
	v_mul_f32_e32 v80, v80, v80
	v_fmac_f32_e32 v80, v84, v84
	v_lshlrev_b32_e32 v84, 16, v81
	v_and_b32_e32 v81, 0xffff0000, v81
	v_mul_f32_e32 v81, v81, v81
	v_add_f32_e32 v80, v114, v80
	v_fmac_f32_e32 v81, v84, v84
	v_add_f32_e32 v80, v80, v81
	v_lshlrev_b32_e32 v81, 16, v82
	v_and_b32_e32 v82, 0xffff0000, v82
	v_mul_f32_e32 v82, v82, v82
	v_fmac_f32_e32 v82, v81, v81
	v_add_f32_e32 v80, v80, v82
	v_and_b32_e32 v82, 0xffff0000, v83
	v_lshlrev_b32_e32 v81, 16, v83
	v_mul_f32_e32 v82, v82, v82
	v_fmac_f32_e32 v82, v81, v81
	v_add_f32_e32 v80, v80, v82
	v_mov_b32_e32 v81, v80
	s_nop 1
	v_permlane16_swap_b32_e32 v81, v80
	s_waitcnt lgkmcnt(0)
	v_add_f32_e32 v80, v80, v81
	v_mov_b32_e32 v81, v80
	s_nop 1
	v_permlane32_swap_b32_e32 v81, v80
	s_and_saveexec_b64 s[6:7], vcc
	s_cbranch_execz .LBB0_425
	s_waitcnt lgkmcnt(0)
	v_add_f32_e32 v82, v80, v81
	v_lshlrev_b64 v[80:81], 6, v[112:113]
	v_lshl_add_u64 v[80:81], s[46:47], 0, v[80:81]
	v_lshl_add_u64 v[80:81], s[58:59], 2, v[80:81]
	s_lshl_b32 s38, s8, 2
	v_lshl_add_u64 v[80:81], v[80:81], 0, s[38:39]
	flat_store_dword v[80:81], v82
.LBB0_425:
	s_or_b64 exec, exec, s[6:7]
	v_lshlrev_b32_e32 v80, 16, v100
	s_waitcnt lgkmcnt(0)
	v_and_b32_e32 v81, 0xffff0000, v100
	v_lshlrev_b32_e32 v84, 16, v102
	v_and_b32_e32 v85, 0xffff0000, v102
	v_lshlrev_b32_e32 v86, 16, v103
	v_and_b32_e32 v87, 0xffff0000, v103
	v_pk_add_f32 v[76:77], v[76:77], v[80:81]
	v_lshlrev_b32_e32 v82, 16, v101
	v_and_b32_e32 v83, 0xffff0000, v101
	v_pk_add_f32 v[80:81], v[74:75], v[86:87]
	v_pk_add_f32 v[74:75], v[72:73], v[84:85]
	v_cvt_pk_bf16_f32 v72, v76, v77
	v_lshl_add_u64 v[76:77], s[68:69], 0, v[110:111]
	v_pk_add_f32 v[78:79], v[78:79], v[82:83]
	v_lshl_add_u64 v[76:77], v[164:165], 1, v[76:77]
	v_cvt_pk_bf16_f32 v73, v78, v79
	v_cvt_pk_bf16_f32 v74, v74, v75
	v_cvt_pk_bf16_f32 v75, v80, v81
	global_store_dwordx4 v[76:77], v[72:75], off nt
	v_lshlrev_b32_e32 v78, 16, v72
	v_and_b32_e32 v79, 0xffff0000, v98
	v_and_b32_e32 v72, 0xffff0000, v72
	v_mul_f32_e32 v72, v72, v72
	v_fmac_f32_e32 v72, v78, v78
	v_lshlrev_b32_e32 v78, 16, v73
	v_and_b32_e32 v73, 0xffff0000, v73
	v_mul_f32_e32 v73, v73, v73
	v_fmac_f32_e32 v73, v78, v78
	v_add_f32_e32 v72, v72, v73
	v_lshlrev_b32_e32 v73, 16, v74
	v_and_b32_e32 v74, 0xffff0000, v74
	v_mul_f32_e32 v74, v74, v74
	v_fmac_f32_e32 v74, v73, v73
	v_add_f32_e32 v72, v72, v74
	v_and_b32_e32 v74, 0xffff0000, v75
	v_lshlrev_b32_e32 v73, 16, v75
	v_mul_f32_e32 v74, v74, v74
	v_fmac_f32_e32 v74, v73, v73
	v_add_f32_e32 v82, v72, v74
	v_lshlrev_b32_e32 v72, 16, v96
	v_and_b32_e32 v73, 0xffff0000, v96
	v_lshlrev_b32_e32 v78, 16, v98
	v_lshlrev_b32_e32 v74, 16, v97
	v_and_b32_e32 v75, 0xffff0000, v97
	v_lshlrev_b32_e32 v80, 16, v99
	v_and_b32_e32 v81, 0xffff0000, v99
	v_pk_add_f32 v[68:69], v[68:69], v[72:73]
	v_pk_add_f32 v[64:65], v[64:65], v[78:79]
	v_pk_add_f32 v[70:71], v[70:71], v[74:75]
	v_pk_add_f32 v[72:73], v[66:67], v[80:81]
	v_cvt_pk_bf16_f32 v66, v68, v69
	v_cvt_pk_bf16_f32 v67, v70, v71
	v_cvt_pk_bf16_f32 v68, v64, v65
	s_nop 0
	v_and_b32_e32 v65, 0xffff0000, v66
	v_lshlrev_b32_e32 v64, 16, v66
	v_mul_f32_e32 v65, v65, v65
	v_fmac_f32_e32 v65, v64, v64
	v_and_b32_e32 v70, 0xffff0000, v67
	v_add_f32_e32 v64, v82, v65
	v_lshlrev_b32_e32 v65, 16, v67
	v_mul_f32_e32 v70, v70, v70
	v_fmac_f32_e32 v70, v65, v65
	v_add_f32_e32 v64, v64, v70
	v_and_b32_e32 v70, 0xffff0000, v68
	v_lshlrev_b32_e32 v65, 16, v68
	v_mul_f32_e32 v70, v70, v70
	v_fmac_f32_e32 v70, v65, v65
	v_cvt_pk_bf16_f32 v69, v72, v73
	v_add_f32_e32 v64, v64, v70
	v_and_b32_e32 v70, 0xffff0000, v69
	v_lshlrev_b32_e32 v65, 16, v69
	v_mul_f32_e32 v70, v70, v70
	v_fmac_f32_e32 v70, v65, v65
	v_add_f32_e32 v64, v64, v70
	v_mov_b32_e32 v65, v64
	s_nop 1
	v_permlane16_swap_b32_e32 v65, v64
	global_store_dwordx4 v[76:77], v[66:69], off offset:256 nt
	s_waitcnt lgkmcnt(0)
	v_add_f32_e32 v64, v64, v65
	v_mov_b32_e32 v65, v64
	s_nop 1
	v_permlane32_swap_b32_e32 v65, v64
	s_and_saveexec_b64 s[6:7], vcc
	s_cbranch_execz .LBB0_427
	s_waitcnt lgkmcnt(0)
	v_add_f32_e32 v66, v64, v65
	v_lshlrev_b64 v[64:65], 6, v[108:109]
	v_lshl_add_u64 v[64:65], s[46:47], 0, v[64:65]
	v_lshl_add_u64 v[64:65], s[58:59], 2, v[64:65]
	s_lshl_b32 s38, s8, 2
	v_lshl_add_u64 v[64:65], v[64:65], 0, s[38:39]
	flat_store_dword v[64:65], v66
.LBB0_427:
	s_or_b64 exec, exec, s[6:7]
	v_add_u32_e32 v80, 0x80, v166
	v_ashrrev_i32_e32 v81, 31, v80
	v_lshlrev_b64 v[86:87], 11, v[80:81]
	s_waitcnt lgkmcnt(0)
	v_lshl_add_u64 v[64:65], v[168:169], 0, v[86:87]
	global_load_dwordx4 v[82:85], v[64:65], off
	global_load_dwordx4 v[72:75], v[64:65], off offset:256
	v_add_u32_e32 v76, 0x90, v166
	v_ashrrev_i32_e32 v77, 31, v76
	v_lshlrev_b64 v[78:79], 11, v[76:77]
	v_lshl_add_u64 v[64:65], v[168:169], 0, v[78:79]
	global_load_dwordx4 v[68:71], v[64:65], off
	s_nop 0
	global_load_dwordx4 v[64:67], v[64:65], off offset:256
	s_waitcnt vmcnt(0)
	v_lshlrev_b32_e32 v88, 16, v82
	v_and_b32_e32 v89, 0xffff0000, v82
	v_lshlrev_b32_e32 v82, 16, v83
	v_and_b32_e32 v83, 0xffff0000, v83
	v_lshlrev_b32_e32 v90, 16, v84
	v_and_b32_e32 v91, 0xffff0000, v84
	v_pk_add_f32 v[58:59], v[58:59], v[82:83]
	v_pk_add_f32 v[56:57], v[56:57], v[88:89]
	v_pk_add_f32 v[60:61], v[60:61], v[90:91]
	v_lshlrev_b32_e32 v84, 16, v85
	v_and_b32_e32 v85, 0xffff0000, v85
	v_cvt_pk_bf16_f32 v56, v56, v57
	v_cvt_pk_bf16_f32 v57, v58, v59
	v_cvt_pk_bf16_f32 v58, v60, v61
	v_lshl_add_u64 v[60:61], s[68:69], 0, v[86:87]
	v_pk_add_f32 v[62:63], v[62:63], v[84:85]
	v_lshl_add_u64 v[60:61], v[164:165], 1, v[60:61]
	v_cvt_pk_bf16_f32 v59, v62, v63
	global_store_dwordx4 v[60:61], v[56:59], off nt
	v_lshlrev_b32_e32 v62, 16, v56
	v_and_b32_e32 v63, 0xffff0000, v74
	v_and_b32_e32 v56, 0xffff0000, v56
	v_mul_f32_e32 v56, v56, v56
	v_fmac_f32_e32 v56, v62, v62
	v_lshlrev_b32_e32 v62, 16, v57
	v_and_b32_e32 v57, 0xffff0000, v57
	v_mul_f32_e32 v57, v57, v57
	v_fmac_f32_e32 v57, v62, v62
	v_add_f32_e32 v56, v56, v57
	v_lshlrev_b32_e32 v57, 16, v58
	v_and_b32_e32 v58, 0xffff0000, v58
	v_mul_f32_e32 v58, v58, v58
	v_fmac_f32_e32 v58, v57, v57
	v_add_f32_e32 v56, v56, v58
	v_and_b32_e32 v58, 0xffff0000, v59
	v_lshlrev_b32_e32 v57, 16, v59
	v_mul_f32_e32 v58, v58, v58
	v_fmac_f32_e32 v58, v57, v57
	v_add_f32_e32 v82, v56, v58
	v_lshlrev_b32_e32 v56, 16, v72
	v_and_b32_e32 v57, 0xffff0000, v72
	v_lshlrev_b32_e32 v58, 16, v73
	v_and_b32_e32 v59, 0xffff0000, v73
	v_lshlrev_b32_e32 v62, 16, v74
	v_lshlrev_b32_e32 v72, 16, v75
	v_and_b32_e32 v73, 0xffff0000, v75
	v_pk_add_f32 v[52:53], v[52:53], v[56:57]
	v_pk_add_f32 v[56:57], v[50:51], v[72:73]
	v_pk_add_f32 v[50:51], v[48:49], v[62:63]
	v_cvt_pk_bf16_f32 v48, v52, v53
	v_pk_add_f32 v[54:55], v[54:55], v[58:59]
	v_lshlrev_b32_e32 v52, 16, v48
	v_cvt_pk_bf16_f32 v49, v54, v55
	v_cvt_pk_bf16_f32 v50, v50, v51
	v_cvt_pk_bf16_f32 v51, v56, v57
	global_store_dwordx4 v[60:61], v[48:51], off offset:256 nt
	s_nop 1
	v_and_b32_e32 v48, 0xffff0000, v48
	v_mul_f32_e32 v48, v48, v48
	v_fmac_f32_e32 v48, v52, v52
	v_lshlrev_b32_e32 v52, 16, v49
	v_and_b32_e32 v49, 0xffff0000, v49
	v_mul_f32_e32 v49, v49, v49
	v_add_f32_e32 v48, v82, v48
	v_fmac_f32_e32 v49, v52, v52
	v_add_f32_e32 v48, v48, v49
	v_lshlrev_b32_e32 v49, 16, v50
	v_and_b32_e32 v50, 0xffff0000, v50
	v_mul_f32_e32 v50, v50, v50
	v_fmac_f32_e32 v50, v49, v49
	v_add_f32_e32 v48, v48, v50
	v_and_b32_e32 v50, 0xffff0000, v51
	v_lshlrev_b32_e32 v49, 16, v51
	v_mul_f32_e32 v50, v50, v50
	v_fmac_f32_e32 v50, v49, v49
	v_add_f32_e32 v48, v48, v50
	v_mov_b32_e32 v49, v48
	s_nop 1
	v_permlane16_swap_b32_e32 v49, v48
	s_waitcnt lgkmcnt(0)
	v_add_f32_e32 v48, v48, v49
	v_mov_b32_e32 v49, v48
	s_nop 1
	v_permlane32_swap_b32_e32 v49, v48
	s_and_saveexec_b64 s[6:7], vcc
	s_cbranch_execz .LBB0_429
	s_waitcnt lgkmcnt(0)
	v_add_f32_e32 v50, v48, v49
	v_lshlrev_b64 v[48:49], 6, v[80:81]
	v_lshl_add_u64 v[48:49], s[46:47], 0, v[48:49]
	v_lshl_add_u64 v[48:49], s[58:59], 2, v[48:49]
	s_lshl_b32 s38, s8, 2
	v_lshl_add_u64 v[48:49], v[48:49], 0, s[38:39]
	flat_store_dword v[48:49], v50
.LBB0_429:
	s_or_b64 exec, exec, s[6:7]
	v_lshlrev_b32_e32 v48, 16, v68
	s_waitcnt lgkmcnt(0)
	v_and_b32_e32 v49, 0xffff0000, v68
	v_lshlrev_b32_e32 v52, 16, v70
	v_and_b32_e32 v53, 0xffff0000, v70
	v_lshlrev_b32_e32 v54, 16, v71
	v_and_b32_e32 v55, 0xffff0000, v71
	v_pk_add_f32 v[44:45], v[44:45], v[48:49]
	v_lshlrev_b32_e32 v50, 16, v69
	v_and_b32_e32 v51, 0xffff0000, v69
	v_pk_add_f32 v[48:49], v[42:43], v[54:55]
	v_pk_add_f32 v[42:43], v[40:41], v[52:53]
	v_cvt_pk_bf16_f32 v40, v44, v45
	v_lshl_add_u64 v[44:45], s[68:69], 0, v[78:79]
	v_pk_add_f32 v[46:47], v[46:47], v[50:51]
	v_lshl_add_u64 v[44:45], v[164:165], 1, v[44:45]
	v_cvt_pk_bf16_f32 v41, v46, v47
	v_cvt_pk_bf16_f32 v42, v42, v43
	v_cvt_pk_bf16_f32 v43, v48, v49
	global_store_dwordx4 v[44:45], v[40:43], off nt
	v_lshlrev_b32_e32 v46, 16, v40
	v_and_b32_e32 v47, 0xffff0000, v66
	v_and_b32_e32 v40, 0xffff0000, v40
	v_mul_f32_e32 v40, v40, v40
	v_fmac_f32_e32 v40, v46, v46
	v_lshlrev_b32_e32 v46, 16, v41
	v_and_b32_e32 v41, 0xffff0000, v41
	v_mul_f32_e32 v41, v41, v41
	v_fmac_f32_e32 v41, v46, v46
	v_add_f32_e32 v40, v40, v41
	v_lshlrev_b32_e32 v41, 16, v42
	v_and_b32_e32 v42, 0xffff0000, v42
	v_mul_f32_e32 v42, v42, v42
	v_fmac_f32_e32 v42, v41, v41
	v_add_f32_e32 v40, v40, v42
	v_and_b32_e32 v42, 0xffff0000, v43
	v_lshlrev_b32_e32 v41, 16, v43
	v_mul_f32_e32 v42, v42, v42
	v_fmac_f32_e32 v42, v41, v41
	v_add_f32_e32 v50, v40, v42
	v_lshlrev_b32_e32 v40, 16, v64
	v_and_b32_e32 v41, 0xffff0000, v64
	v_lshlrev_b32_e32 v46, 16, v66
	v_lshlrev_b32_e32 v42, 16, v65
	v_and_b32_e32 v43, 0xffff0000, v65
	v_lshlrev_b32_e32 v48, 16, v67
	v_and_b32_e32 v49, 0xffff0000, v67
	v_pk_add_f32 v[36:37], v[36:37], v[40:41]
	v_pk_add_f32 v[32:33], v[32:33], v[46:47]
	v_pk_add_f32 v[38:39], v[38:39], v[42:43]
	v_pk_add_f32 v[40:41], v[34:35], v[48:49]
	v_cvt_pk_bf16_f32 v34, v36, v37
	v_cvt_pk_bf16_f32 v35, v38, v39
	v_cvt_pk_bf16_f32 v36, v32, v33
	s_nop 0
	v_and_b32_e32 v33, 0xffff0000, v34
	v_lshlrev_b32_e32 v32, 16, v34
	v_mul_f32_e32 v33, v33, v33
	v_fmac_f32_e32 v33, v32, v32
	v_and_b32_e32 v38, 0xffff0000, v35
	v_add_f32_e32 v32, v50, v33
	v_lshlrev_b32_e32 v33, 16, v35
	v_mul_f32_e32 v38, v38, v38
	v_fmac_f32_e32 v38, v33, v33
	v_add_f32_e32 v32, v32, v38
	v_and_b32_e32 v38, 0xffff0000, v36
	v_lshlrev_b32_e32 v33, 16, v36
	v_mul_f32_e32 v38, v38, v38
	v_fmac_f32_e32 v38, v33, v33
	v_cvt_pk_bf16_f32 v37, v40, v41
	v_add_f32_e32 v32, v32, v38
	v_and_b32_e32 v38, 0xffff0000, v37
	v_lshlrev_b32_e32 v33, 16, v37
	v_mul_f32_e32 v38, v38, v38
	v_fmac_f32_e32 v38, v33, v33
	v_add_f32_e32 v32, v32, v38
	v_mov_b32_e32 v33, v32
	s_nop 1
	v_permlane16_swap_b32_e32 v33, v32
	global_store_dwordx4 v[44:45], v[34:37], off offset:256 nt
	s_waitcnt lgkmcnt(0)
	v_add_f32_e32 v32, v32, v33
	v_mov_b32_e32 v33, v32
	s_nop 1
	v_permlane32_swap_b32_e32 v33, v32
	s_and_saveexec_b64 s[6:7], vcc
	s_cbranch_execz .LBB0_431
	s_waitcnt lgkmcnt(0)
	v_add_f32_e32 v34, v32, v33
	v_lshlrev_b64 v[32:33], 6, v[76:77]
	v_lshl_add_u64 v[32:33], s[46:47], 0, v[32:33]
	v_lshl_add_u64 v[32:33], s[58:59], 2, v[32:33]
	s_lshl_b32 s38, s8, 2
	v_lshl_add_u64 v[32:33], v[32:33], 0, s[38:39]
	flat_store_dword v[32:33], v34
.LBB0_431:
	s_or_b64 exec, exec, s[6:7]
	v_add_u32_e32 v48, 0xa0, v166
	v_ashrrev_i32_e32 v49, 31, v48
	v_lshlrev_b64 v[54:55], 11, v[48:49]
	s_waitcnt lgkmcnt(0)
	v_lshl_add_u64 v[32:33], v[168:169], 0, v[54:55]
	global_load_dwordx4 v[50:53], v[32:33], off
	global_load_dwordx4 v[40:43], v[32:33], off offset:256
	v_add_u32_e32 v44, 0xb0, v166
	v_ashrrev_i32_e32 v45, 31, v44
	v_lshlrev_b64 v[46:47], 11, v[44:45]
	v_lshl_add_u64 v[32:33], v[168:169], 0, v[46:47]
	global_load_dwordx4 v[36:39], v[32:33], off
	s_nop 0
	global_load_dwordx4 v[32:35], v[32:33], off offset:256
	s_waitcnt vmcnt(0)
	v_lshlrev_b32_e32 v56, 16, v50
	v_and_b32_e32 v57, 0xffff0000, v50
	v_lshlrev_b32_e32 v50, 16, v51
	v_and_b32_e32 v51, 0xffff0000, v51
	v_lshlrev_b32_e32 v58, 16, v52
	v_and_b32_e32 v59, 0xffff0000, v52
	v_pk_add_f32 v[26:27], v[26:27], v[50:51]
	v_pk_add_f32 v[24:25], v[24:25], v[56:57]
	v_pk_add_f32 v[28:29], v[28:29], v[58:59]
	v_lshlrev_b32_e32 v52, 16, v53
	v_and_b32_e32 v53, 0xffff0000, v53
	v_cvt_pk_bf16_f32 v24, v24, v25
	v_cvt_pk_bf16_f32 v25, v26, v27
	v_cvt_pk_bf16_f32 v26, v28, v29
	v_lshl_add_u64 v[28:29], s[68:69], 0, v[54:55]
	v_pk_add_f32 v[30:31], v[30:31], v[52:53]
	v_lshl_add_u64 v[28:29], v[164:165], 1, v[28:29]
	v_cvt_pk_bf16_f32 v27, v30, v31
	global_store_dwordx4 v[28:29], v[24:27], off nt
	v_lshlrev_b32_e32 v30, 16, v24
	v_and_b32_e32 v31, 0xffff0000, v42
	v_and_b32_e32 v24, 0xffff0000, v24
	v_mul_f32_e32 v24, v24, v24
	v_fmac_f32_e32 v24, v30, v30
	v_lshlrev_b32_e32 v30, 16, v25
	v_and_b32_e32 v25, 0xffff0000, v25
	v_mul_f32_e32 v25, v25, v25
	v_fmac_f32_e32 v25, v30, v30
	v_add_f32_e32 v24, v24, v25
	v_lshlrev_b32_e32 v25, 16, v26
	v_and_b32_e32 v26, 0xffff0000, v26
	v_mul_f32_e32 v26, v26, v26
	v_fmac_f32_e32 v26, v25, v25
	v_add_f32_e32 v24, v24, v26
	v_and_b32_e32 v26, 0xffff0000, v27
	v_lshlrev_b32_e32 v25, 16, v27
	v_mul_f32_e32 v26, v26, v26
	v_fmac_f32_e32 v26, v25, v25
	v_add_f32_e32 v50, v24, v26
	v_lshlrev_b32_e32 v24, 16, v40
	v_and_b32_e32 v25, 0xffff0000, v40
	v_lshlrev_b32_e32 v26, 16, v41
	v_and_b32_e32 v27, 0xffff0000, v41
	v_lshlrev_b32_e32 v30, 16, v42
	v_lshlrev_b32_e32 v40, 16, v43
	v_and_b32_e32 v41, 0xffff0000, v43
	v_pk_add_f32 v[20:21], v[20:21], v[24:25]
	v_pk_add_f32 v[24:25], v[18:19], v[40:41]
	v_pk_add_f32 v[18:19], v[16:17], v[30:31]
	v_cvt_pk_bf16_f32 v16, v20, v21
	v_pk_add_f32 v[22:23], v[22:23], v[26:27]
	v_lshlrev_b32_e32 v20, 16, v16
	v_cvt_pk_bf16_f32 v17, v22, v23
	v_cvt_pk_bf16_f32 v18, v18, v19
	v_cvt_pk_bf16_f32 v19, v24, v25
	global_store_dwordx4 v[28:29], v[16:19], off offset:256 nt
	s_nop 1
	v_and_b32_e32 v16, 0xffff0000, v16
	v_mul_f32_e32 v16, v16, v16
	v_fmac_f32_e32 v16, v20, v20
	v_lshlrev_b32_e32 v20, 16, v17
	v_and_b32_e32 v17, 0xffff0000, v17
	v_mul_f32_e32 v17, v17, v17
	v_add_f32_e32 v16, v50, v16
	v_fmac_f32_e32 v17, v20, v20
	v_add_f32_e32 v16, v16, v17
	v_lshlrev_b32_e32 v17, 16, v18
	v_and_b32_e32 v18, 0xffff0000, v18
	v_mul_f32_e32 v18, v18, v18
	v_fmac_f32_e32 v18, v17, v17
	v_add_f32_e32 v16, v16, v18
	v_and_b32_e32 v18, 0xffff0000, v19
	v_lshlrev_b32_e32 v17, 16, v19
	v_mul_f32_e32 v18, v18, v18
	v_fmac_f32_e32 v18, v17, v17
	v_add_f32_e32 v16, v16, v18
	v_mov_b32_e32 v17, v16
	s_nop 1
	v_permlane16_swap_b32_e32 v17, v16
	s_waitcnt lgkmcnt(0)
	v_add_f32_e32 v16, v16, v17
	v_mov_b32_e32 v17, v16
	s_nop 1
	v_permlane32_swap_b32_e32 v17, v16
	s_and_saveexec_b64 s[6:7], vcc
	s_cbranch_execz .LBB0_433
	s_waitcnt lgkmcnt(0)
	v_add_f32_e32 v18, v16, v17
	v_lshlrev_b64 v[16:17], 6, v[48:49]
	v_lshl_add_u64 v[16:17], s[46:47], 0, v[16:17]
	v_lshl_add_u64 v[16:17], s[58:59], 2, v[16:17]
	s_lshl_b32 s38, s8, 2
	v_lshl_add_u64 v[16:17], v[16:17], 0, s[38:39]
	flat_store_dword v[16:17], v18
.LBB0_433:
	s_or_b64 exec, exec, s[6:7]
	v_lshlrev_b32_e32 v16, 16, v36
	s_waitcnt lgkmcnt(0)
	v_and_b32_e32 v17, 0xffff0000, v36
	v_lshlrev_b32_e32 v20, 16, v38
	v_and_b32_e32 v21, 0xffff0000, v38
	v_lshlrev_b32_e32 v22, 16, v39
	v_and_b32_e32 v23, 0xffff0000, v39
	v_pk_add_f32 v[12:13], v[12:13], v[16:17]
	v_lshlrev_b32_e32 v18, 16, v37
	v_and_b32_e32 v19, 0xffff0000, v37
	v_pk_add_f32 v[16:17], v[10:11], v[22:23]
	v_pk_add_f32 v[10:11], v[8:9], v[20:21]
	v_cvt_pk_bf16_f32 v8, v12, v13
	v_lshl_add_u64 v[12:13], s[68:69], 0, v[46:47]
	v_pk_add_f32 v[14:15], v[14:15], v[18:19]
	v_lshl_add_u64 v[12:13], v[164:165], 1, v[12:13]
	v_cvt_pk_bf16_f32 v9, v14, v15
	v_cvt_pk_bf16_f32 v10, v10, v11
	v_cvt_pk_bf16_f32 v11, v16, v17
	global_store_dwordx4 v[12:13], v[8:11], off nt
	v_lshlrev_b32_e32 v14, 16, v8
	v_and_b32_e32 v15, 0xffff0000, v34
	v_and_b32_e32 v8, 0xffff0000, v8
	v_mul_f32_e32 v8, v8, v8
	v_fmac_f32_e32 v8, v14, v14
	v_lshlrev_b32_e32 v14, 16, v9
	v_and_b32_e32 v9, 0xffff0000, v9
	v_mul_f32_e32 v9, v9, v9
	v_fmac_f32_e32 v9, v14, v14
	v_add_f32_e32 v8, v8, v9
	v_lshlrev_b32_e32 v9, 16, v10
	v_and_b32_e32 v10, 0xffff0000, v10
	v_mul_f32_e32 v10, v10, v10
	v_fmac_f32_e32 v10, v9, v9
	v_add_f32_e32 v8, v8, v10
	v_and_b32_e32 v10, 0xffff0000, v11
	v_lshlrev_b32_e32 v9, 16, v11
	v_mul_f32_e32 v10, v10, v10
	v_fmac_f32_e32 v10, v9, v9
	v_add_f32_e32 v18, v8, v10
	v_lshlrev_b32_e32 v8, 16, v32
	v_and_b32_e32 v9, 0xffff0000, v32
	v_lshlrev_b32_e32 v14, 16, v34
	v_lshlrev_b32_e32 v10, 16, v33
	v_and_b32_e32 v11, 0xffff0000, v33
	v_lshlrev_b32_e32 v16, 16, v35
	v_and_b32_e32 v17, 0xffff0000, v35
	v_pk_add_f32 v[4:5], v[4:5], v[8:9]
	v_pk_add_f32 v[0:1], v[0:1], v[14:15]
	v_pk_add_f32 v[6:7], v[6:7], v[10:11]
	v_pk_add_f32 v[8:9], v[2:3], v[16:17]
	v_cvt_pk_bf16_f32 v2, v4, v5
	v_cvt_pk_bf16_f32 v3, v6, v7
	v_cvt_pk_bf16_f32 v4, v0, v1
	s_nop 0
	v_and_b32_e32 v1, 0xffff0000, v2
	v_lshlrev_b32_e32 v0, 16, v2
	v_mul_f32_e32 v1, v1, v1
	v_fmac_f32_e32 v1, v0, v0
	v_and_b32_e32 v6, 0xffff0000, v3
	v_add_f32_e32 v0, v18, v1
	v_lshlrev_b32_e32 v1, 16, v3
	v_mul_f32_e32 v6, v6, v6
	v_fmac_f32_e32 v6, v1, v1
	v_add_f32_e32 v0, v0, v6
	v_and_b32_e32 v6, 0xffff0000, v4
	v_lshlrev_b32_e32 v1, 16, v4
	v_mul_f32_e32 v6, v6, v6
	v_fmac_f32_e32 v6, v1, v1
	v_cvt_pk_bf16_f32 v5, v8, v9
	v_add_f32_e32 v0, v0, v6
	v_and_b32_e32 v6, 0xffff0000, v5
	v_lshlrev_b32_e32 v1, 16, v5
	v_mul_f32_e32 v6, v6, v6
	v_fmac_f32_e32 v6, v1, v1
	v_add_f32_e32 v0, v0, v6
	v_mov_b32_e32 v1, v0
	s_nop 1
	v_permlane16_swap_b32_e32 v1, v0
	global_store_dwordx4 v[12:13], v[2:5], off offset:256 nt
	s_waitcnt lgkmcnt(0)
	v_add_f32_e32 v0, v0, v1
	v_mov_b32_e32 v1, v0
	s_nop 1
	v_permlane32_swap_b32_e32 v1, v0
	s_and_saveexec_b64 s[6:7], vcc
	s_cbranch_execz .LBB0_435
	s_waitcnt lgkmcnt(0)
	v_add_f32_e32 v2, v0, v1
	v_lshlrev_b64 v[0:1], 6, v[44:45]
	v_lshl_add_u64 v[0:1], s[46:47], 0, v[0:1]
	v_lshl_add_u64 v[0:1], s[58:59], 2, v[0:1]
	s_lshl_b32 s38, s8, 2
	v_lshl_add_u64 v[0:1], v[0:1], 0, s[38:39]
	flat_store_dword v[0:1], v2

.LBB0_459:
	s_mov_b32 s6, -1
	s_lshl_b32 s5, s5, 8
	v_mbcnt_lo_u32_b32 v134, s6, 0
	v_mbcnt_hi_u32_b32 v134, s6, v134
	s_getreg_b32 s6, hwreg(HW_REG_HW_ID, 0, 6)
	s_and_b32 s6, s6, 63
	s_lshl_b32 s6, s6, 2
	s_add_i32 s6, s6, 0
	s_add_i32 s6, s6, 0x20200
	v_mov_b32_e32 v135, s6
	ds_read_b32 v135, v135
	v_bfrev_b32_e32 v143, 0.5
	s_movk_i32 s84, 0x80
	s_waitcnt lgkmcnt(0)
	v_readfirstlane_b32 s6, v135
	s_nop 1
	v_lshl_add_u32 v137, s6, 6, v134
	s_nop 0
	v_readfirstlane_b32 s6, v137
	s_bfe_u32 s10, s6, 0x20006
	s_ashr_i32 s6, s6, 2
	s_andn2_b32 s6, s6, 63
	s_add_i32 s6, s6, s5
	v_bfe_u32 v142, v137, 4, 2
	v_and_or_b32 v136, v137, 15, s6
	s_lshl_b32 s5, s4, 8
	s_lshl_b32 s6, s10, 5
	v_lshlrev_b32_e32 v137, 2, v137
	s_or_b32 s5, s6, s5
	v_bitop3_b32 v158, v137, 64, v143 bitop3:0x6c
	v_bitop3_b32 v159, v137, s84, v143 bitop3:0x6c
	v_ashrrev_i32_e32 v137, 31, v136
	v_lshl_or_b32 v134, v142, 3, s5
	v_cmp_eq_u32_e32 vcc, 0, v142
	v_lshlrev_b64 v[142:143], 12, v[136:137]
	v_ashrrev_i32_e32 v135, 31, v134
	v_lshl_add_u64 v[142:143], s[44:45], 0, v[142:143]
	v_lshl_add_u64 v[154:155], v[134:135], 2, v[142:143]
	v_mov_b32_e32 v162, v154
	v_mov_b32_e32 v163, v155
	global_load_dwordx4 v[142:145], v[154:155], off offset:16
	global_load_dwordx4 v[146:149], v[154:155], off
	global_load_dwordx4 v[150:153], v[154:155], off offset:528
	s_nop 0
	global_load_dwordx4 v[154:157], v[154:155], off offset:512
	s_mov_b64 s[100:101], 0x10000
	v_lshl_add_u64 v[164:165], v[162:163], 0, s[100:101]
	global_load_dwordx4 v[168:171], v[164:165], off
	global_load_dwordx4 v[172:175], v[164:165], off offset:16
	global_load_dwordx4 v[176:179], v[164:165], off offset:512
	global_load_dwordx4 v[180:183], v[164:165], off offset:528
	s_mov_b64 s[100:101], 0x20000
	v_lshl_add_u64 v[164:165], v[162:163], 0, s[100:101]
	global_load_dwordx4 v[184:187], v[164:165], off
	global_load_dwordx4 v[188:191], v[164:165], off offset:16
	global_load_dwordx4 v[192:195], v[164:165], off offset:512
	global_load_dwordx4 v[208:211], v[164:165], off offset:528
	s_mov_b64 s[100:101], 0x30000
	v_lshl_add_u64 v[164:165], v[162:163], 0, s[100:101]
	global_load_dwordx4 v[212:215], v[164:165], off
	global_load_dwordx4 v[216:219], v[164:165], off offset:16
	global_load_dwordx4 v[220:223], v[164:165], off offset:512
	global_load_dwordx4 v[224:227], v[164:165], off offset:528
	s_mov_b64 s[100:101], 0x80000
	v_lshl_add_u64 v[164:165], v[162:163], 0, s[100:101]
	global_load_dwordx4 v[228:231], v[164:165], off
	global_load_dwordx4 v[232:235], v[164:165], off offset:16
	global_load_dwordx4 v[236:239], v[164:165], off offset:512
	global_load_dwordx4 v[240:243], v[164:165], off offset:528
	v_lshlrev_b64 v[160:161], 11, v[136:137]
	s_lshl_b32 s6, s4, 2
	s_ashr_i32 s7, s6, 31
	s_waitcnt vmcnt(16)
	v_pk_add_f32 v[124:125], v[124:125], v[142:143]
	v_pk_add_f32 v[122:123], v[122:123], v[148:149]
	v_pk_add_f32 v[120:121], v[120:121], v[146:147]
	v_pk_add_f32 v[126:127], v[126:127], v[144:145]
	v_cvt_pk_bf16_f32 v120, v120, v121
	v_cvt_pk_bf16_f32 v121, v122, v123
	v_cvt_pk_bf16_f32 v122, v124, v125
	v_lshl_add_u64 v[124:125], s[68:69], 0, v[160:161]
	v_lshl_add_u64 v[124:125], v[134:135], 1, v[124:125]
	v_cvt_pk_bf16_f32 v123, v126, v127
	global_store_dwordx4 v[124:125], v[120:123], off nt
	v_lshlrev_b32_e32 v126, 16, v120
	v_pk_add_f32 v[116:117], v[116:117], v[154:155]
	v_and_b32_e32 v120, 0xffff0000, v120
	v_mul_f32_e32 v120, v120, v120
	v_fmac_f32_e32 v120, v126, v126
	v_lshlrev_b32_e32 v126, 16, v121
	v_and_b32_e32 v121, 0xffff0000, v121
	v_mul_f32_e32 v121, v121, v121
	v_fmac_f32_e32 v121, v126, v126
	v_add_f32_e32 v120, v120, v121
	v_lshlrev_b32_e32 v121, 16, v122
	v_and_b32_e32 v122, 0xffff0000, v122
	v_mul_f32_e32 v122, v122, v122
	v_fmac_f32_e32 v122, v121, v121
	v_add_f32_e32 v120, v120, v122
	v_and_b32_e32 v122, 0xffff0000, v123
	v_lshlrev_b32_e32 v121, 16, v123
	v_mul_f32_e32 v122, v122, v122
	v_fmac_f32_e32 v122, v121, v121
	v_add_f32_e32 v122, v120, v122
	v_pk_add_f32 v[120:121], v[114:115], v[152:153]
	v_pk_add_f32 v[114:115], v[112:113], v[150:151]
	v_cvt_pk_bf16_f32 v112, v116, v117
	v_pk_add_f32 v[118:119], v[118:119], v[156:157]
	v_lshlrev_b32_e32 v116, 16, v112
	v_cvt_pk_bf16_f32 v113, v118, v119
	v_cvt_pk_bf16_f32 v114, v114, v115
	v_cvt_pk_bf16_f32 v115, v120, v121
	global_store_dwordx4 v[124:125], v[112:115], off offset:256 nt
	s_nop 1
	v_and_b32_e32 v112, 0xffff0000, v112
	v_mul_f32_e32 v112, v112, v112
	v_fmac_f32_e32 v112, v116, v116
	v_lshlrev_b32_e32 v116, 16, v113
	v_and_b32_e32 v113, 0xffff0000, v113
	v_mul_f32_e32 v113, v113, v113
	v_add_f32_e32 v112, v122, v112
	v_fmac_f32_e32 v113, v116, v116
	v_add_f32_e32 v112, v112, v113
	v_lshlrev_b32_e32 v113, 16, v114
	v_and_b32_e32 v114, 0xffff0000, v114
	v_mul_f32_e32 v114, v114, v114
	v_fmac_f32_e32 v114, v113, v113
	v_add_f32_e32 v112, v112, v114
	v_and_b32_e32 v114, 0xffff0000, v115
	v_lshlrev_b32_e32 v113, 16, v115
	v_mul_f32_e32 v114, v114, v114
	v_fmac_f32_e32 v114, v113, v113
	v_add_f32_e32 v112, v112, v114
	v_mov_b32_e32 v113, v112
	s_nop 1
	v_permlane16_swap_b32_e32 v113, v112
	s_waitcnt lgkmcnt(0)
	v_add_f32_e32 v112, v112, v113
	v_mov_b32_e32 v113, v112
	s_nop 1
	v_permlane32_swap_b32_e32 v113, v112
	s_and_saveexec_b64 s[8:9], vcc
	s_cbranch_execz .LBB0_461
	v_lshlrev_b64 v[114:115], 6, v[136:137]
	v_lshl_add_u64 v[114:115], s[66:67], 0, v[114:115]
	v_lshl_add_u64 v[114:115], s[6:7], 2, v[114:115]
	s_lshl_b32 s38, s10, 2
	v_lshl_add_u64 v[114:115], v[114:115], 0, s[38:39]
	s_waitcnt lgkmcnt(0)
	v_add_f32_e32 v112, v112, v113
	global_store_dword v[114:115], v112, off
.LBB0_461:
	s_or_b64 exec, exec, s[8:9]
	v_or_b32_e32 v112, 16, v136
	s_waitcnt lgkmcnt(0)
	v_ashrrev_i32_e32 v113, 31, v112
	v_lshlrev_b64 v[114:115], 12, v[112:113]
	v_lshl_add_u64 v[114:115], s[44:45], 0, v[114:115]
	v_lshl_add_u64 v[126:127], v[134:135], 2, v[114:115]
	v_lshlrev_b64 v[126:127], 11, v[112:113]
	v_lshl_add_u64 v[126:127], s[68:69], 0, v[126:127]
	v_lshl_add_u64 v[126:127], v[134:135], 1, v[126:127]
	s_waitcnt vmcnt(15)
	v_mov_b32_e32 v114, v168
	v_mov_b32_e32 v115, v169
	v_mov_b32_e32 v116, v170
	v_mov_b32_e32 v117, v171
	v_mov_b32_e32 v118, v172
	v_mov_b32_e32 v119, v173
	v_mov_b32_e32 v120, v174
	v_mov_b32_e32 v121, v175
	v_mov_b32_e32 v122, v176
	v_mov_b32_e32 v123, v177
	v_mov_b32_e32 v124, v178
	v_mov_b32_e32 v125, v179
	v_mov_b32_e32 v142, v180
	v_mov_b32_e32 v143, v181
	v_mov_b32_e32 v144, v182
	v_mov_b32_e32 v145, v183
	s_mov_b64 s[100:101], 0x90000
	v_lshl_add_u64 v[164:165], v[162:163], 0, s[100:101]
	global_load_dwordx4 v[168:171], v[164:165], off
	global_load_dwordx4 v[172:175], v[164:165], off offset:16
	global_load_dwordx4 v[176:179], v[164:165], off offset:512
	global_load_dwordx4 v[180:183], v[164:165], off offset:528
	v_pk_add_f32 v[106:107], v[106:107], v[116:117]
	v_pk_add_f32 v[104:105], v[104:105], v[114:115]
	s_nop 0
	v_pk_add_f32 v[110:111], v[110:111], v[120:121]
	s_nop 0
	v_pk_add_f32 v[116:117], v[96:97], v[142:143]
	v_cvt_pk_bf16_f32 v96, v104, v105
	v_cvt_pk_bf16_f32 v97, v106, v107
	v_pk_add_f32 v[108:109], v[108:109], v[118:119]
	v_pk_add_f32 v[114:115], v[98:99], v[144:145]
	v_cvt_pk_bf16_f32 v98, v108, v109
	v_cvt_pk_bf16_f32 v99, v110, v111
	global_store_dwordx4 v[126:127], v[96:99], off nt
	v_lshlrev_b32_e32 v104, 16, v96
	v_lshlrev_b32_e32 v105, 16, v97
	v_and_b32_e32 v96, 0xffff0000, v96
	v_and_b32_e32 v97, 0xffff0000, v97
	v_pk_add_f32 v[102:103], v[102:103], v[124:125]
	v_and_b32_e32 v107, 0xffff0000, v98
	v_mul_f32_e32 v96, v96, v96
	v_mul_f32_e32 v97, v97, v97
	v_pk_add_f32 v[100:101], v[100:101], v[122:123]
	v_lshlrev_b32_e32 v106, 16, v98
	v_lshlrev_b32_e32 v108, 16, v99
	v_and_b32_e32 v109, 0xffff0000, v99
	v_cvt_pk_bf16_f32 v98, v100, v101
	v_cvt_pk_bf16_f32 v99, v102, v103
	v_mul_f32_e32 v102, v107, v107
	v_fmac_f32_e32 v96, v104, v104
	v_fmac_f32_e32 v97, v105, v105
	v_mul_f32_e32 v103, v109, v109
	v_and_b32_e32 v109, 0xffff0000, v98
	v_fmac_f32_e32 v102, v106, v106
	v_add_f32_e32 v96, v96, v97
	v_lshlrev_b32_e32 v107, 16, v98
	v_and_b32_e32 v111, 0xffff0000, v99
	v_fmac_f32_e32 v103, v108, v108
	v_mul_f32_e32 v104, v109, v109
	v_add_f32_e32 v96, v96, v102
	v_cvt_pk_bf16_f32 v100, v116, v117
	v_cvt_pk_bf16_f32 v101, v114, v115
	v_lshlrev_b32_e32 v110, 16, v99
	v_and_b32_e32 v115, 0xffff0000, v100
	v_mul_f32_e32 v105, v111, v111
	v_fmac_f32_e32 v104, v107, v107
	v_add_f32_e32 v96, v96, v103
	v_lshlrev_b32_e32 v114, 16, v100
	v_and_b32_e32 v117, 0xffff0000, v101
	v_mul_f32_e32 v106, v115, v115
	v_fmac_f32_e32 v105, v110, v110
	v_add_f32_e32 v96, v96, v104
	v_lshlrev_b32_e32 v116, 16, v101
	v_mul_f32_e32 v108, v117, v117
	v_fmac_f32_e32 v106, v114, v114
	v_add_f32_e32 v96, v96, v105
	v_add_f32_e32 v96, v96, v106
	v_fmac_f32_e32 v108, v116, v116
	v_add_f32_e32 v96, v96, v108
	v_mov_b32_e32 v97, v96
	s_nop 1
	v_permlane16_swap_b32_e32 v97, v96
	global_store_dwordx4 v[126:127], v[98:101], off offset:256 nt
	s_waitcnt lgkmcnt(0)
	v_add_f32_e32 v96, v96, v97
	v_mov_b32_e32 v97, v96
	s_nop 1
	v_permlane32_swap_b32_e32 v97, v96
	s_mov_b64 s[8:9], exec
	s_and_b64 s[4:5], s[8:9], vcc
	v_mov_b32_e32 v198, v246
	v_mov_b32_e32 v199, v247
	v_mov_b32_e32 v205, v249
	v_mov_b32_e32 v196, v251
	v_mov_b32_e32 v251, 0x260
	s_mov_b64 exec, s[4:5]
	s_cbranch_execz .LBB0_463
	v_lshlrev_b64 v[98:99], 6, v[112:113]
	v_lshl_add_u64 v[98:99], s[66:67], 0, v[98:99]
	v_lshl_add_u64 v[98:99], s[6:7], 2, v[98:99]
	s_lshl_b32 s38, s10, 2
	v_lshl_add_u64 v[98:99], v[98:99], 0, s[38:39]
	s_waitcnt lgkmcnt(0)
	v_add_f32_e32 v96, v96, v97
	global_store_dword v[98:99], v96, off
.LBB0_463:
	s_or_b64 exec, exec, s[8:9]
	v_or_b32_e32 v96, 32, v136
	s_waitcnt lgkmcnt(0)
	v_ashrrev_i32_e32 v97, 31, v96
	v_lshlrev_b64 v[98:99], 12, v[96:97]
	v_lshl_add_u64 v[98:99], s[44:45], 0, v[98:99]
	v_lshl_add_u64 v[110:111], v[134:135], 2, v[98:99]
	s_nop 0
	v_lshlrev_b64 v[114:115], 11, v[96:97]
	v_lshl_add_u64 v[114:115], s[68:69], 0, v[114:115]
	v_lshl_add_u64 v[114:115], v[134:135], 1, v[114:115]
	s_waitcnt vmcnt(18)
	v_mov_b32_e32 v98, v184
	v_mov_b32_e32 v99, v185
	v_mov_b32_e32 v100, v186
	v_mov_b32_e32 v101, v187
	v_mov_b32_e32 v102, v188
	v_mov_b32_e32 v103, v189
	v_mov_b32_e32 v104, v190
	v_mov_b32_e32 v105, v191
	v_mov_b32_e32 v106, v192
	v_mov_b32_e32 v107, v193
	v_mov_b32_e32 v108, v194
	v_mov_b32_e32 v109, v195
	v_mov_b32_e32 v110, v208
	v_mov_b32_e32 v111, v209
	v_mov_b32_e32 v112, v210
	v_mov_b32_e32 v113, v211
	s_mov_b64 s[100:101], 0xa0000
	v_lshl_add_u64 v[164:165], v[162:163], 0, s[100:101]
	global_load_dwordx4 v[184:187], v[164:165], off
	global_load_dwordx4 v[188:191], v[164:165], off offset:16
	global_load_dwordx4 v[192:195], v[164:165], off offset:512
	global_load_dwordx4 v[208:211], v[164:165], off offset:528
	v_pk_add_f32 v[90:91], v[90:91], v[100:101]
	v_pk_add_f32 v[88:89], v[88:89], v[98:99]
	s_nop 0
	v_pk_add_f32 v[94:95], v[94:95], v[104:105]
	s_nop 0
	v_pk_add_f32 v[100:101], v[80:81], v[110:111]
	v_cvt_pk_bf16_f32 v80, v88, v89
	v_cvt_pk_bf16_f32 v81, v90, v91
	v_pk_add_f32 v[92:93], v[92:93], v[102:103]
	v_pk_add_f32 v[98:99], v[82:83], v[112:113]
	v_cvt_pk_bf16_f32 v82, v92, v93
	v_cvt_pk_bf16_f32 v83, v94, v95
	global_store_dwordx4 v[114:115], v[80:83], off nt
	v_lshlrev_b32_e32 v88, 16, v80
	v_lshlrev_b32_e32 v89, 16, v81
	v_and_b32_e32 v80, 0xffff0000, v80
	v_and_b32_e32 v81, 0xffff0000, v81
	v_pk_add_f32 v[86:87], v[86:87], v[108:109]
	v_and_b32_e32 v91, 0xffff0000, v82
	v_mul_f32_e32 v80, v80, v80
	v_mul_f32_e32 v81, v81, v81
	v_pk_add_f32 v[84:85], v[84:85], v[106:107]
	v_lshlrev_b32_e32 v90, 16, v82
	v_lshlrev_b32_e32 v92, 16, v83
	v_and_b32_e32 v93, 0xffff0000, v83
	v_cvt_pk_bf16_f32 v82, v84, v85
	v_cvt_pk_bf16_f32 v83, v86, v87
	v_mul_f32_e32 v86, v91, v91
	v_fmac_f32_e32 v80, v88, v88
	v_fmac_f32_e32 v81, v89, v89
	v_mul_f32_e32 v87, v93, v93
	v_and_b32_e32 v93, 0xffff0000, v82
	v_fmac_f32_e32 v86, v90, v90
	v_add_f32_e32 v80, v80, v81
	v_lshlrev_b32_e32 v91, 16, v82
	v_and_b32_e32 v95, 0xffff0000, v83
	v_fmac_f32_e32 v87, v92, v92
	v_mul_f32_e32 v88, v93, v93
	v_add_f32_e32 v80, v80, v86
	v_cvt_pk_bf16_f32 v84, v100, v101
	v_cvt_pk_bf16_f32 v85, v98, v99
	v_lshlrev_b32_e32 v94, 16, v83
	v_and_b32_e32 v99, 0xffff0000, v84
	v_mul_f32_e32 v89, v95, v95
	v_fmac_f32_e32 v88, v91, v91
	v_add_f32_e32 v80, v80, v87
	v_lshlrev_b32_e32 v98, 16, v84
	v_and_b32_e32 v101, 0xffff0000, v85
	v_mul_f32_e32 v90, v99, v99
	v_fmac_f32_e32 v89, v94, v94
	v_add_f32_e32 v80, v80, v88
	v_lshlrev_b32_e32 v100, 16, v85
	v_mul_f32_e32 v92, v101, v101
	v_fmac_f32_e32 v90, v98, v98
	v_add_f32_e32 v80, v80, v89
	v_add_f32_e32 v80, v80, v90
	v_fmac_f32_e32 v92, v100, v100
	v_add_f32_e32 v80, v80, v92
	v_mov_b32_e32 v81, v80
	s_nop 1
	v_permlane16_swap_b32_e32 v81, v80
	global_store_dwordx4 v[114:115], v[82:85], off offset:256 nt
	s_waitcnt lgkmcnt(0)
	v_add_f32_e32 v80, v80, v81
	v_mov_b32_e32 v81, v80
	s_nop 1
	v_permlane32_swap_b32_e32 v81, v80
	s_and_saveexec_b64 s[8:9], vcc
	s_cbranch_execz .LBB0_465
	v_lshlrev_b64 v[82:83], 6, v[96:97]
	v_lshl_add_u64 v[82:83], s[66:67], 0, v[82:83]
	v_lshl_add_u64 v[82:83], s[6:7], 2, v[82:83]
	s_lshl_b32 s38, s10, 2
	v_lshl_add_u64 v[82:83], v[82:83], 0, s[38:39]
	s_waitcnt lgkmcnt(0)
	v_add_f32_e32 v80, v80, v81
	global_store_dword v[82:83], v80, off
.LBB0_465:
	s_or_b64 exec, exec, s[8:9]
	v_or_b32_e32 v80, 48, v136
	s_waitcnt lgkmcnt(0)
	v_ashrrev_i32_e32 v81, 31, v80
	v_lshlrev_b64 v[82:83], 12, v[80:81]
	v_lshl_add_u64 v[82:83], s[44:45], 0, v[82:83]
	v_lshl_add_u64 v[94:95], v[134:135], 2, v[82:83]
	s_nop 0
	v_lshlrev_b64 v[98:99], 11, v[80:81]
	v_lshl_add_u64 v[98:99], s[68:69], 0, v[98:99]
	v_lshl_add_u64 v[98:99], v[134:135], 1, v[98:99]
	s_waitcnt vmcnt(21)
	v_mov_b32_e32 v82, v212
	v_mov_b32_e32 v83, v213
	v_mov_b32_e32 v84, v214
	v_mov_b32_e32 v85, v215
	v_mov_b32_e32 v86, v216
	v_mov_b32_e32 v87, v217
	v_mov_b32_e32 v88, v218
	v_mov_b32_e32 v89, v219
	v_mov_b32_e32 v90, v220
	v_mov_b32_e32 v91, v221
	v_mov_b32_e32 v92, v222
	v_mov_b32_e32 v93, v223
	v_mov_b32_e32 v94, v224
	v_mov_b32_e32 v95, v225
	v_mov_b32_e32 v96, v226
	v_mov_b32_e32 v97, v227
	s_mov_b64 s[100:101], 0xb0000
	v_lshl_add_u64 v[164:165], v[162:163], 0, s[100:101]
	global_load_dwordx4 v[212:215], v[164:165], off
	global_load_dwordx4 v[216:219], v[164:165], off offset:16
	global_load_dwordx4 v[220:223], v[164:165], off offset:512
	global_load_dwordx4 v[224:227], v[164:165], off offset:528
	v_pk_add_f32 v[74:75], v[74:75], v[84:85]
	v_pk_add_f32 v[72:73], v[72:73], v[82:83]
	s_nop 0
	v_pk_add_f32 v[78:79], v[78:79], v[88:89]
	s_nop 0
	v_pk_add_f32 v[84:85], v[64:65], v[94:95]
	v_cvt_pk_bf16_f32 v64, v72, v73
	v_cvt_pk_bf16_f32 v65, v74, v75
	v_pk_add_f32 v[76:77], v[76:77], v[86:87]
	v_pk_add_f32 v[82:83], v[66:67], v[96:97]
	v_cvt_pk_bf16_f32 v66, v76, v77
	v_cvt_pk_bf16_f32 v67, v78, v79
	global_store_dwordx4 v[98:99], v[64:67], off nt
	v_lshlrev_b32_e32 v72, 16, v64
	v_lshlrev_b32_e32 v73, 16, v65
	v_and_b32_e32 v64, 0xffff0000, v64
	v_and_b32_e32 v65, 0xffff0000, v65
	v_pk_add_f32 v[70:71], v[70:71], v[92:93]
	v_and_b32_e32 v75, 0xffff0000, v66
	v_mul_f32_e32 v64, v64, v64
	v_mul_f32_e32 v65, v65, v65
	v_pk_add_f32 v[68:69], v[68:69], v[90:91]
	v_lshlrev_b32_e32 v74, 16, v66
	v_lshlrev_b32_e32 v76, 16, v67
	v_and_b32_e32 v77, 0xffff0000, v67
	v_cvt_pk_bf16_f32 v66, v68, v69
	v_cvt_pk_bf16_f32 v67, v70, v71
	v_mul_f32_e32 v70, v75, v75
	v_fmac_f32_e32 v64, v72, v72
	v_fmac_f32_e32 v65, v73, v73
	v_mul_f32_e32 v71, v77, v77
	v_and_b32_e32 v77, 0xffff0000, v66
	v_fmac_f32_e32 v70, v74, v74
	v_add_f32_e32 v64, v64, v65
	v_lshlrev_b32_e32 v75, 16, v66
	v_and_b32_e32 v79, 0xffff0000, v67
	v_fmac_f32_e32 v71, v76, v76
	v_mul_f32_e32 v72, v77, v77
	v_add_f32_e32 v64, v64, v70
	v_cvt_pk_bf16_f32 v68, v84, v85
	v_cvt_pk_bf16_f32 v69, v82, v83
	v_lshlrev_b32_e32 v78, 16, v67
	v_and_b32_e32 v83, 0xffff0000, v68
	v_mul_f32_e32 v73, v79, v79
	v_fmac_f32_e32 v72, v75, v75
	v_add_f32_e32 v64, v64, v71
	v_lshlrev_b32_e32 v82, 16, v68
	v_and_b32_e32 v85, 0xffff0000, v69
	v_mul_f32_e32 v74, v83, v83
	v_fmac_f32_e32 v73, v78, v78
	v_add_f32_e32 v64, v64, v72
	v_lshlrev_b32_e32 v84, 16, v69
	v_mul_f32_e32 v76, v85, v85
	v_fmac_f32_e32 v74, v82, v82
	v_add_f32_e32 v64, v64, v73
	v_add_f32_e32 v64, v64, v74
	v_fmac_f32_e32 v76, v84, v84
	v_add_f32_e32 v64, v64, v76
	v_mov_b32_e32 v65, v64
	s_nop 1
	v_permlane16_swap_b32_e32 v65, v64
	global_store_dwordx4 v[98:99], v[66:69], off offset:256 nt
	s_waitcnt lgkmcnt(0)
	v_add_f32_e32 v64, v64, v65
	v_mov_b32_e32 v65, v64
	s_nop 1
	v_permlane32_swap_b32_e32 v65, v64
	s_and_saveexec_b64 s[8:9], vcc
	s_cbranch_execz .LBB0_467
	v_lshlrev_b64 v[66:67], 6, v[80:81]
	v_lshl_add_u64 v[66:67], s[66:67], 0, v[66:67]
	v_lshl_add_u64 v[66:67], s[6:7], 2, v[66:67]
	s_lshl_b32 s38, s10, 2
	v_lshl_add_u64 v[66:67], v[66:67], 0, s[38:39]
	s_waitcnt lgkmcnt(0)
	v_add_f32_e32 v64, v64, v65
	global_store_dword v[66:67], v64, off
.LBB0_467:
	s_or_b64 exec, exec, s[8:9]
	v_add_u32_e32 v64, 0x80, v136
	s_waitcnt lgkmcnt(0)
	v_ashrrev_i32_e32 v65, 31, v64
	v_lshlrev_b64 v[66:67], 12, v[64:65]
	v_lshl_add_u64 v[66:67], s[44:45], 0, v[66:67]
	v_lshl_add_u64 v[78:79], v[134:135], 2, v[66:67]
	s_nop 0
	v_lshlrev_b64 v[82:83], 11, v[64:65]
	v_lshl_add_u64 v[82:83], s[68:69], 0, v[82:83]
	v_lshl_add_u64 v[82:83], v[134:135], 1, v[82:83]
	s_waitcnt vmcnt(24)
	v_mov_b32_e32 v66, v228
	v_mov_b32_e32 v67, v229
	v_mov_b32_e32 v68, v230
	v_mov_b32_e32 v69, v231
	v_mov_b32_e32 v70, v232
	v_mov_b32_e32 v71, v233
	v_mov_b32_e32 v72, v234
	v_mov_b32_e32 v73, v235
	v_mov_b32_e32 v74, v236
	v_mov_b32_e32 v75, v237
	v_mov_b32_e32 v76, v238
	v_mov_b32_e32 v77, v239
	v_mov_b32_e32 v78, v240
	v_mov_b32_e32 v79, v241
	v_mov_b32_e32 v80, v242
	v_mov_b32_e32 v81, v243
	v_pk_add_f32 v[58:59], v[58:59], v[68:69]
	v_pk_add_f32 v[56:57], v[56:57], v[66:67]
	s_nop 0
	v_pk_add_f32 v[62:63], v[62:63], v[72:73]
	s_nop 0
	v_pk_add_f32 v[68:69], v[48:49], v[78:79]
	v_cvt_pk_bf16_f32 v48, v56, v57
	v_cvt_pk_bf16_f32 v49, v58, v59
	v_pk_add_f32 v[60:61], v[60:61], v[70:71]
	v_pk_add_f32 v[66:67], v[50:51], v[80:81]
	v_cvt_pk_bf16_f32 v50, v60, v61
	v_cvt_pk_bf16_f32 v51, v62, v63
	global_store_dwordx4 v[82:83], v[48:51], off nt
	v_lshlrev_b32_e32 v56, 16, v48
	v_lshlrev_b32_e32 v57, 16, v49
	v_and_b32_e32 v48, 0xffff0000, v48
	v_and_b32_e32 v49, 0xffff0000, v49
	v_pk_add_f32 v[54:55], v[54:55], v[76:77]
	v_and_b32_e32 v59, 0xffff0000, v50
	v_mul_f32_e32 v48, v48, v48
	v_mul_f32_e32 v49, v49, v49
	v_pk_add_f32 v[52:53], v[52:53], v[74:75]
	v_lshlrev_b32_e32 v58, 16, v50
	v_lshlrev_b32_e32 v60, 16, v51
	v_and_b32_e32 v61, 0xffff0000, v51
	v_cvt_pk_bf16_f32 v50, v52, v53
	v_cvt_pk_bf16_f32 v51, v54, v55
	v_mul_f32_e32 v54, v59, v59
	v_fmac_f32_e32 v48, v56, v56
	v_fmac_f32_e32 v49, v57, v57
	v_mul_f32_e32 v55, v61, v61
	v_and_b32_e32 v61, 0xffff0000, v50
	v_fmac_f32_e32 v54, v58, v58
	v_add_f32_e32 v48, v48, v49
	v_lshlrev_b32_e32 v59, 16, v50
	v_and_b32_e32 v63, 0xffff0000, v51
	v_fmac_f32_e32 v55, v60, v60
	v_mul_f32_e32 v56, v61, v61
	v_add_f32_e32 v48, v48, v54
	v_cvt_pk_bf16_f32 v52, v68, v69
	v_cvt_pk_bf16_f32 v53, v66, v67
	v_lshlrev_b32_e32 v62, 16, v51
	v_and_b32_e32 v67, 0xffff0000, v52
	v_mul_f32_e32 v57, v63, v63
	v_fmac_f32_e32 v56, v59, v59
	v_add_f32_e32 v48, v48, v55
	v_lshlrev_b32_e32 v66, 16, v52
	v_and_b32_e32 v69, 0xffff0000, v53
	v_mul_f32_e32 v58, v67, v67
	v_fmac_f32_e32 v57, v62, v62
	v_add_f32_e32 v48, v48, v56
	v_lshlrev_b32_e32 v68, 16, v53
	v_mul_f32_e32 v60, v69, v69
	v_fmac_f32_e32 v58, v66, v66
	v_add_f32_e32 v48, v48, v57
	v_add_f32_e32 v48, v48, v58
	v_fmac_f32_e32 v60, v68, v68
	v_add_f32_e32 v48, v48, v60
	v_mov_b32_e32 v49, v48
	s_nop 1
	v_permlane16_swap_b32_e32 v49, v48
	global_store_dwordx4 v[82:83], v[50:53], off offset:256 nt
	s_waitcnt lgkmcnt(0)
	v_add_f32_e32 v48, v48, v49
	v_mov_b32_e32 v49, v48
	s_nop 1
	v_permlane32_swap_b32_e32 v49, v48
	s_and_saveexec_b64 s[8:9], vcc
	s_cbranch_execz .LBB0_469
	v_lshlrev_b64 v[50:51], 6, v[64:65]
	v_lshl_add_u64 v[50:51], s[66:67], 0, v[50:51]
	v_lshl_add_u64 v[50:51], s[6:7], 2, v[50:51]
	s_lshl_b32 s38, s10, 2
	v_lshl_add_u64 v[50:51], v[50:51], 0, s[38:39]
	s_waitcnt lgkmcnt(0)
	v_add_f32_e32 v48, v48, v49
	global_store_dword v[50:51], v48, off
.LBB0_469:
	s_or_b64 exec, exec, s[8:9]
	v_add_u32_e32 v48, 0x90, v136
	s_waitcnt lgkmcnt(0)
	v_ashrrev_i32_e32 v49, 31, v48
	v_lshlrev_b64 v[50:51], 12, v[48:49]
	v_lshl_add_u64 v[50:51], s[44:45], 0, v[50:51]
	v_lshl_add_u64 v[62:63], v[134:135], 2, v[50:51]
	s_nop 0
	v_lshlrev_b64 v[66:67], 11, v[48:49]
	v_lshl_add_u64 v[66:67], s[68:69], 0, v[66:67]
	v_lshl_add_u64 v[66:67], v[134:135], 1, v[66:67]
	s_waitcnt vmcnt(20)
	v_mov_b32_e32 v50, v168
	v_mov_b32_e32 v51, v169
	v_mov_b32_e32 v52, v170
	v_mov_b32_e32 v53, v171
	v_mov_b32_e32 v54, v172
	v_mov_b32_e32 v55, v173
	v_mov_b32_e32 v56, v174
	v_mov_b32_e32 v57, v175
	v_mov_b32_e32 v58, v176
	v_mov_b32_e32 v59, v177
	v_mov_b32_e32 v60, v178
	v_mov_b32_e32 v61, v179
	v_mov_b32_e32 v62, v180
	v_mov_b32_e32 v63, v181
	v_mov_b32_e32 v64, v182
	v_mov_b32_e32 v65, v183
	v_pk_add_f32 v[42:43], v[42:43], v[52:53]
	v_pk_add_f32 v[40:41], v[40:41], v[50:51]
	s_nop 0
	v_pk_add_f32 v[46:47], v[46:47], v[56:57]
	s_nop 0
	v_pk_add_f32 v[52:53], v[32:33], v[62:63]
	v_cvt_pk_bf16_f32 v32, v40, v41
	v_cvt_pk_bf16_f32 v33, v42, v43
	v_pk_add_f32 v[44:45], v[44:45], v[54:55]
	v_pk_add_f32 v[50:51], v[34:35], v[64:65]
	v_cvt_pk_bf16_f32 v34, v44, v45
	v_cvt_pk_bf16_f32 v35, v46, v47
	global_store_dwordx4 v[66:67], v[32:35], off nt
	v_lshlrev_b32_e32 v40, 16, v32
	v_lshlrev_b32_e32 v41, 16, v33
	v_and_b32_e32 v32, 0xffff0000, v32
	v_and_b32_e32 v33, 0xffff0000, v33
	v_pk_add_f32 v[38:39], v[38:39], v[60:61]
	v_and_b32_e32 v43, 0xffff0000, v34
	v_mul_f32_e32 v32, v32, v32
	v_mul_f32_e32 v33, v33, v33
	v_pk_add_f32 v[36:37], v[36:37], v[58:59]
	v_lshlrev_b32_e32 v42, 16, v34
	v_lshlrev_b32_e32 v44, 16, v35
	v_and_b32_e32 v45, 0xffff0000, v35
	v_cvt_pk_bf16_f32 v34, v36, v37
	v_cvt_pk_bf16_f32 v35, v38, v39
	v_mul_f32_e32 v38, v43, v43
	v_fmac_f32_e32 v32, v40, v40
	v_fmac_f32_e32 v33, v41, v41
	v_mul_f32_e32 v39, v45, v45
	v_and_b32_e32 v45, 0xffff0000, v34
	v_fmac_f32_e32 v38, v42, v42
	v_add_f32_e32 v32, v32, v33
	v_lshlrev_b32_e32 v43, 16, v34
	v_and_b32_e32 v47, 0xffff0000, v35
	v_fmac_f32_e32 v39, v44, v44
	v_mul_f32_e32 v40, v45, v45
	v_add_f32_e32 v32, v32, v38
	v_cvt_pk_bf16_f32 v36, v52, v53
	v_cvt_pk_bf16_f32 v37, v50, v51
	v_lshlrev_b32_e32 v46, 16, v35
	v_and_b32_e32 v51, 0xffff0000, v36
	v_mul_f32_e32 v41, v47, v47
	v_fmac_f32_e32 v40, v43, v43
	v_add_f32_e32 v32, v32, v39
	v_lshlrev_b32_e32 v50, 16, v36
	v_and_b32_e32 v53, 0xffff0000, v37
	v_mul_f32_e32 v42, v51, v51
	v_fmac_f32_e32 v41, v46, v46
	v_add_f32_e32 v32, v32, v40
	v_lshlrev_b32_e32 v52, 16, v37
	v_mul_f32_e32 v44, v53, v53
	v_fmac_f32_e32 v42, v50, v50
	v_add_f32_e32 v32, v32, v41
	v_add_f32_e32 v32, v32, v42
	v_fmac_f32_e32 v44, v52, v52
	v_add_f32_e32 v32, v32, v44
	v_mov_b32_e32 v33, v32
	s_nop 1
	v_permlane16_swap_b32_e32 v33, v32
	global_store_dwordx4 v[66:67], v[34:37], off offset:256 nt
	s_waitcnt lgkmcnt(0)
	v_add_f32_e32 v32, v32, v33
	v_mov_b32_e32 v33, v32
	s_nop 1
	v_permlane32_swap_b32_e32 v33, v32
	s_and_saveexec_b64 s[8:9], vcc
	s_cbranch_execz .LBB0_471
	v_lshlrev_b64 v[34:35], 6, v[48:49]
	v_lshl_add_u64 v[34:35], s[66:67], 0, v[34:35]
	v_lshl_add_u64 v[34:35], s[6:7], 2, v[34:35]
	s_lshl_b32 s38, s10, 2
	v_lshl_add_u64 v[34:35], v[34:35], 0, s[38:39]
	s_waitcnt lgkmcnt(0)
	v_add_f32_e32 v32, v32, v33
	global_store_dword v[34:35], v32, off
.LBB0_471:
	s_or_b64 exec, exec, s[8:9]
	v_add_u32_e32 v32, 0xa0, v136
	s_waitcnt lgkmcnt(0)
	v_ashrrev_i32_e32 v33, 31, v32
	v_lshlrev_b64 v[34:35], 12, v[32:33]
	v_lshl_add_u64 v[34:35], s[44:45], 0, v[34:35]
	v_lshl_add_u64 v[46:47], v[134:135], 2, v[34:35]
	s_nop 0
	v_lshlrev_b64 v[50:51], 11, v[32:33]
	v_lshl_add_u64 v[50:51], s[68:69], 0, v[50:51]
	v_lshl_add_u64 v[50:51], v[134:135], 1, v[50:51]
	s_waitcnt vmcnt(16)
	v_mov_b32_e32 v34, v184
	v_mov_b32_e32 v35, v185
	v_mov_b32_e32 v36, v186
	v_mov_b32_e32 v37, v187
	v_mov_b32_e32 v38, v188
	v_mov_b32_e32 v39, v189
	v_mov_b32_e32 v40, v190
	v_mov_b32_e32 v41, v191
	v_mov_b32_e32 v42, v192
	v_mov_b32_e32 v43, v193
	v_mov_b32_e32 v44, v194
	v_mov_b32_e32 v45, v195
	v_mov_b32_e32 v46, v208
	v_mov_b32_e32 v47, v209
	v_mov_b32_e32 v48, v210
	v_mov_b32_e32 v49, v211
	v_pk_add_f32 v[26:27], v[26:27], v[36:37]
	v_pk_add_f32 v[24:25], v[24:25], v[34:35]
	s_nop 0
	v_pk_add_f32 v[30:31], v[30:31], v[40:41]
	s_nop 0
	v_pk_add_f32 v[36:37], v[16:17], v[46:47]
	v_cvt_pk_bf16_f32 v16, v24, v25
	v_cvt_pk_bf16_f32 v17, v26, v27
	v_pk_add_f32 v[28:29], v[28:29], v[38:39]
	v_pk_add_f32 v[34:35], v[18:19], v[48:49]
	v_cvt_pk_bf16_f32 v18, v28, v29
	v_cvt_pk_bf16_f32 v19, v30, v31
	global_store_dwordx4 v[50:51], v[16:19], off nt
	v_lshlrev_b32_e32 v24, 16, v16
	v_lshlrev_b32_e32 v25, 16, v17
	v_and_b32_e32 v16, 0xffff0000, v16
	v_and_b32_e32 v17, 0xffff0000, v17
	v_pk_add_f32 v[22:23], v[22:23], v[44:45]
	v_and_b32_e32 v27, 0xffff0000, v18
	v_mul_f32_e32 v16, v16, v16
	v_mul_f32_e32 v17, v17, v17
	v_pk_add_f32 v[20:21], v[20:21], v[42:43]
	v_lshlrev_b32_e32 v26, 16, v18
	v_lshlrev_b32_e32 v28, 16, v19
	v_and_b32_e32 v29, 0xffff0000, v19
	v_cvt_pk_bf16_f32 v18, v20, v21
	v_cvt_pk_bf16_f32 v19, v22, v23
	v_mul_f32_e32 v22, v27, v27
	v_fmac_f32_e32 v16, v24, v24
	v_fmac_f32_e32 v17, v25, v25
	v_mul_f32_e32 v23, v29, v29
	v_and_b32_e32 v29, 0xffff0000, v18
	v_fmac_f32_e32 v22, v26, v26
	v_add_f32_e32 v16, v16, v17
	v_lshlrev_b32_e32 v27, 16, v18
	v_and_b32_e32 v31, 0xffff0000, v19
	v_fmac_f32_e32 v23, v28, v28
	v_mul_f32_e32 v24, v29, v29
	v_add_f32_e32 v16, v16, v22
	v_cvt_pk_bf16_f32 v20, v36, v37
	v_cvt_pk_bf16_f32 v21, v34, v35
	v_lshlrev_b32_e32 v30, 16, v19
	v_and_b32_e32 v35, 0xffff0000, v20
	v_mul_f32_e32 v25, v31, v31
	v_fmac_f32_e32 v24, v27, v27
	v_add_f32_e32 v16, v16, v23
	v_lshlrev_b32_e32 v34, 16, v20
	v_and_b32_e32 v37, 0xffff0000, v21
	v_mul_f32_e32 v26, v35, v35
	v_fmac_f32_e32 v25, v30, v30
	v_add_f32_e32 v16, v16, v24
	v_lshlrev_b32_e32 v36, 16, v21
	v_mul_f32_e32 v28, v37, v37
	v_fmac_f32_e32 v26, v34, v34
	v_add_f32_e32 v16, v16, v25
	v_add_f32_e32 v16, v16, v26
	v_fmac_f32_e32 v28, v36, v36
	v_add_f32_e32 v16, v16, v28
	v_mov_b32_e32 v17, v16
	s_nop 1
	v_permlane16_swap_b32_e32 v17, v16
	global_store_dwordx4 v[50:51], v[18:21], off offset:256 nt
	s_waitcnt lgkmcnt(0)
	v_add_f32_e32 v16, v16, v17
	v_mov_b32_e32 v17, v16
	s_nop 1
	v_permlane32_swap_b32_e32 v17, v16
	s_and_saveexec_b64 s[8:9], vcc
	s_cbranch_execz .LBB0_473
	v_lshlrev_b64 v[18:19], 6, v[32:33]
	v_lshl_add_u64 v[18:19], s[66:67], 0, v[18:19]
	v_lshl_add_u64 v[18:19], s[6:7], 2, v[18:19]
	s_lshl_b32 s38, s10, 2
	v_lshl_add_u64 v[18:19], v[18:19], 0, s[38:39]
	s_waitcnt lgkmcnt(0)
	v_add_f32_e32 v16, v16, v17
	global_store_dword v[18:19], v16, off
.LBB0_473:
	s_or_b64 exec, exec, s[8:9]
	v_add_u32_e32 v16, 0xb0, v136
	s_waitcnt lgkmcnt(0)
	v_ashrrev_i32_e32 v17, 31, v16
	v_lshlrev_b64 v[18:19], 12, v[16:17]
	v_lshl_add_u64 v[18:19], s[44:45], 0, v[18:19]
	v_lshl_add_u64 v[30:31], v[134:135], 2, v[18:19]
	s_nop 0
	v_lshlrev_b64 v[34:35], 11, v[16:17]
	v_lshl_add_u64 v[34:35], s[68:69], 0, v[34:35]
	v_lshl_add_u64 v[34:35], v[134:135], 1, v[34:35]
	s_waitcnt vmcnt(12)
	v_mov_b32_e32 v18, v212
	v_mov_b32_e32 v19, v213
	v_mov_b32_e32 v20, v214
	v_mov_b32_e32 v21, v215
	v_mov_b32_e32 v22, v216
	v_mov_b32_e32 v23, v217
	v_mov_b32_e32 v24, v218
	v_mov_b32_e32 v25, v219
	v_mov_b32_e32 v26, v220
	v_mov_b32_e32 v27, v221
	v_mov_b32_e32 v28, v222
	v_mov_b32_e32 v29, v223
	v_mov_b32_e32 v30, v224
	v_mov_b32_e32 v31, v225
	v_mov_b32_e32 v32, v226
	v_mov_b32_e32 v33, v227
	v_pk_add_f32 v[10:11], v[10:11], v[20:21]
	v_pk_add_f32 v[8:9], v[8:9], v[18:19]
	s_nop 0
	v_pk_add_f32 v[14:15], v[14:15], v[24:25]
	s_nop 0
	v_pk_add_f32 v[20:21], v[0:1], v[30:31]
	v_cvt_pk_bf16_f32 v0, v8, v9
	v_cvt_pk_bf16_f32 v1, v10, v11
	v_pk_add_f32 v[12:13], v[12:13], v[22:23]
	v_pk_add_f32 v[18:19], v[2:3], v[32:33]
	v_cvt_pk_bf16_f32 v2, v12, v13
	v_cvt_pk_bf16_f32 v3, v14, v15
	global_store_dwordx4 v[34:35], v[0:3], off nt
	v_lshlrev_b32_e32 v8, 16, v0
	v_lshlrev_b32_e32 v9, 16, v1
	v_and_b32_e32 v0, 0xffff0000, v0
	v_and_b32_e32 v1, 0xffff0000, v1
	v_pk_add_f32 v[6:7], v[6:7], v[28:29]
	v_and_b32_e32 v11, 0xffff0000, v2
	v_mul_f32_e32 v0, v0, v0
	v_mul_f32_e32 v1, v1, v1
	v_pk_add_f32 v[4:5], v[4:5], v[26:27]
	v_lshlrev_b32_e32 v10, 16, v2
	v_lshlrev_b32_e32 v12, 16, v3
	v_and_b32_e32 v13, 0xffff0000, v3
	v_cvt_pk_bf16_f32 v2, v4, v5
	v_cvt_pk_bf16_f32 v3, v6, v7
	v_mul_f32_e32 v6, v11, v11
	v_fmac_f32_e32 v0, v8, v8
	v_fmac_f32_e32 v1, v9, v9
	v_mul_f32_e32 v7, v13, v13
	v_and_b32_e32 v13, 0xffff0000, v2
	v_fmac_f32_e32 v6, v10, v10
	v_add_f32_e32 v0, v0, v1
	v_lshlrev_b32_e32 v11, 16, v2
	v_and_b32_e32 v15, 0xffff0000, v3
	v_fmac_f32_e32 v7, v12, v12
	v_mul_f32_e32 v8, v13, v13
	v_add_f32_e32 v0, v0, v6
	v_cvt_pk_bf16_f32 v4, v20, v21
	v_cvt_pk_bf16_f32 v5, v18, v19
	v_lshlrev_b32_e32 v14, 16, v3
	v_and_b32_e32 v19, 0xffff0000, v4
	v_mul_f32_e32 v9, v15, v15
	v_fmac_f32_e32 v8, v11, v11
	v_add_f32_e32 v0, v0, v7
	v_lshlrev_b32_e32 v18, 16, v4
	v_and_b32_e32 v21, 0xffff0000, v5
	v_mul_f32_e32 v10, v19, v19
	v_fmac_f32_e32 v9, v14, v14
	v_add_f32_e32 v0, v0, v8
	v_lshlrev_b32_e32 v20, 16, v5
	v_mul_f32_e32 v12, v21, v21
	v_fmac_f32_e32 v10, v18, v18
	v_add_f32_e32 v0, v0, v9
	v_add_f32_e32 v0, v0, v10
	v_fmac_f32_e32 v12, v20, v20
	v_add_f32_e32 v0, v0, v12
	v_mov_b32_e32 v1, v0
	s_nop 1
	v_permlane16_swap_b32_e32 v1, v0
	global_store_dwordx4 v[34:35], v[2:5], off offset:256 nt
	s_waitcnt lgkmcnt(0)
	v_add_f32_e32 v0, v0, v1
	v_mov_b32_e32 v1, v0
	s_nop 1
	v_permlane32_swap_b32_e32 v1, v0
	s_and_saveexec_b64 s[8:9], vcc
	s_cbranch_execz .LBB0_475
	v_lshlrev_b64 v[2:3], 6, v[16:17]
	v_lshl_add_u64 v[2:3], s[66:67], 0, v[2:3]
	v_lshl_add_u64 v[2:3], s[6:7], 2, v[2:3]
	s_lshl_b32 s38, s10, 2
	v_lshl_add_u64 v[2:3], v[2:3], 0, s[38:39]
	s_waitcnt lgkmcnt(0)
	v_add_f32_e32 v0, v0, v1
	global_store_dword v[2:3], v0, off

.LBB0_555:
	s_mov_b32 s4, -1
	s_getreg_b32 s5, hwreg(HW_REG_HW_ID, 0, 6)
	s_and_b32 s5, s5, 63
	s_lshl_b32 s5, s5, 2
	s_add_i32 s5, s5, 0
	s_add_i32 s5, s5, 0x20200
	v_mov_b32_e32 v140, s5
	ds_read_b32 v140, v140
	v_mbcnt_lo_u32_b32 v142, s4, 0
	v_mbcnt_hi_u32_b32 v142, s4, v142
	v_bfrev_b32_e32 v143, 0.5
	s_mov_b64 s[6:7], -1
	s_waitcnt lgkmcnt(0)
	v_readfirstlane_b32 s4, v140
	s_nop 1
	v_lshl_add_u32 v140, s4, 6, v142
	s_nop 0
	v_readfirstlane_b32 s4, v140
	s_ashr_i32 s5, s4, 2
	s_andn2_b32 s5, s5, 63
	v_bfe_u32 v162, v140, 4, 2
	v_and_or_b32 v169, v140, 15, s5
	s_cmp_gt_u32 s28, 3
	v_lshl_add_u32 v158, s94, 8, v169
	v_lshlrev_b32_e32 v142, 2, v162
	v_lshlrev_b32_e32 v140, 2, v140
	s_cselect_b64 s[56:57], -1, 0
	v_bitop3_b32 v168, v140, 64, v143 bitop3:0x6c
	v_bitop3_b32 v167, v140, s84, v143 bitop3:0x6c
	s_and_b64 vcc, exec, s[56:57]
	v_ashrrev_i32_e32 v159, 31, v158
	v_lshlrev_b32_e32 v140, 2, v142
	s_cbranch_vccz .LBB0_557
	v_lshlrev_b64 v[142:143], 6, v[158:159]
	v_lshl_add_u64 v[142:143], s[48:49], 0, v[142:143]
	v_lshl_add_u64 v[142:143], v[142:143], 0, v[140:141]
	flat_load_dwordx4 v[170:173], v[142:143]
	s_mov_b64 s[6:7], 0
	s_waitcnt vmcnt(0) lgkmcnt(0)
	v_mov_b32_e32 v142, v171
	v_mov_b32_e32 v143, v172
	v_mov_b32_e32 v171, v173
	v_pk_add_f32 v[142:143], v[142:143], v[170:171]
	s_nop 0
	v_add_f32_e32 v142, v142, v143
	v_mov_b32_e32 v143, v142
	s_nop 1
	v_permlane16_swap_b32_e32 v143, v142
	s_waitcnt lgkmcnt(0)
	v_add_f32_e32 v142, v142, v143
	v_mov_b32_e32 v143, v142
	s_nop 1
	v_permlane32_swap_b32_e32 v143, v142
	s_waitcnt lgkmcnt(0)
	v_add_f32_e32 v142, v142, v143
	v_fmamk_f32 v142, v142, 0x3a800000, v250
	v_rsq_f32_e32 v164, v142

.LBB0_559:
	s_waitcnt lgkmcnt(0)
	v_pk_mul_f32 v[120:121], v[120:121], v[164:165] op_sel_hi:[1,0]
	s_bfe_u32 s8, s4, 0x20006
	v_mul_f32_e32 v145, 0x3d372713, v121
	v_mul_f32_e32 v145, v121, v145
	v_fma_f32 v145, v121, v145, v121
	v_mul_f32_e32 v145, 0x3f4c422a, v145
	s_lshl_b32 s4, s95, 8
	s_lshl_b32 s5, s8, 5
	v_pk_mul_f32 v[126:127], v[126:127], v[164:165] op_sel_hi:[1,0]
	v_pk_mul_f32 v[122:123], v[122:123], v[164:165] op_sel_hi:[1,0]
	v_mul_f32_e32 v145, 0xc038aa3b, v145
	s_or_b32 s4, s5, s4
	v_exp_f32_e32 v145, v145
	v_mul_f32_e32 v147, 0x3d372713, v126
	v_mul_f32_e32 v148, 0x3d372713, v122
	v_lshl_or_b32 v160, v162, 3, s4
	v_lshlrev_b64 v[142:143], 12, v[158:159]
	v_mul_f32_e32 v147, v126, v147
	v_mul_f32_e32 v148, v122, v148
	v_ashrrev_i32_e32 v161, 31, v160
	v_lshl_add_u64 v[142:143], s[70:71], 0, v[142:143]
	v_fma_f32 v147, v126, v147, v126
	v_fma_f32 v148, v122, v148, v122
	v_cmp_eq_u32_e32 vcc, 0, v162
	v_lshl_add_u64 v[162:163], v[160:161], 1, v[142:143]
	v_pk_mul_f32 v[124:125], v[124:125], v[164:165] op_sel_hi:[1,0]
	v_mul_f32_e32 v143, 0x3d372713, v120
	v_mul_f32_e32 v147, 0x3f4c422a, v147
	v_mul_f32_e32 v148, 0x3f4c422a, v148
	v_mul_f32_e32 v142, 0x3d372713, v124
	v_mul_f32_e32 v143, v120, v143
	v_add_f32_e32 v145, 1.0, v145
	v_mul_f32_e32 v147, 0xc038aa3b, v147
	v_mul_f32_e32 v148, 0xc038aa3b, v148
	v_mul_f32_e32 v142, v124, v142
	v_fma_f32 v143, v120, v143, v120
	v_mul_f32_e32 v144, 0x3d372713, v125
	v_rcp_f32_e32 v145, v145
	v_exp_f32_e32 v147, v147
	v_exp_f32_e32 v148, v148
	v_fma_f32 v142, v124, v142, v124
	v_mul_f32_e32 v143, 0x3f4c422a, v143
	v_mul_f32_e32 v144, v125, v144
	v_mul_f32_e32 v142, 0x3f4c422a, v142
	v_mul_f32_e32 v143, 0xc038aa3b, v143
	v_fma_f32 v144, v125, v144, v125
	v_mul_f32_e32 v142, 0xc038aa3b, v142
	v_exp_f32_e32 v143, v143
	v_mul_f32_e32 v144, 0x3f4c422a, v144
	v_mul_f32_e32 v149, 0x3d372713, v123
	v_exp_f32_e32 v142, v142
	v_mul_f32_e32 v144, 0xc038aa3b, v144
	v_mul_f32_e32 v145, v121, v145
	v_add_f32_e32 v121, 1.0, v147
	v_add_f32_e32 v147, 1.0, v148
	v_mul_f32_e32 v148, 0x3d372713, v127
	v_mul_f32_e32 v149, v123, v149
	v_exp_f32_e32 v144, v144
	v_mul_f32_e32 v148, v127, v148
	v_fma_f32 v149, v123, v149, v123
	v_fma_f32 v148, v127, v148, v127
	v_mul_f32_e32 v149, 0x3f4c422a, v149
	v_add_f32_e32 v143, 1.0, v143
	v_mul_f32_e32 v148, 0x3f4c422a, v148
	v_mul_f32_e32 v149, 0xc038aa3b, v149
	v_add_f32_e32 v142, 1.0, v142
	v_rcp_f32_e32 v143, v143
	v_mul_f32_e32 v148, 0xc038aa3b, v148
	v_exp_f32_e32 v149, v149
	v_rcp_f32_e32 v142, v142
	v_add_f32_e32 v144, 1.0, v144
	v_exp_f32_e32 v148, v148
	v_rcp_f32_e32 v144, v144
	v_rcp_f32_e32 v147, v147
	v_rcp_f32_e32 v121, v121
	v_mul_f32_e32 v143, v120, v143
	v_add_f32_e32 v149, 1.0, v149
	v_mul_f32_e32 v146, v124, v142
	v_add_f32_e32 v148, 1.0, v148
	v_rcp_f32_e32 v149, v149
	v_fma_f32 v124, v124, v142, v143
	v_mul_f32_e32 v120, v125, v144
	v_rcp_f32_e32 v148, v148
	v_mul_f32_e32 v147, v122, v147
	v_add_f32_e32 v124, 0, v124
	v_fma_f32 v125, v125, v144, v145
	v_mul_f32_e32 v150, v126, v121
	v_mul_f32_e32 v142, v143, v143
	v_add_f32_e32 v124, v125, v124
	v_mul_f32_e32 v125, v145, v145
	v_fma_f32 v121, v126, v121, v147
	v_fmac_f32_e32 v142, v146, v146
	v_fmac_f32_e32 v125, v120, v120
	v_add_f32_e32 v121, v121, v124
	v_mul_f32_e32 v124, v147, v147
	v_mul_f32_e32 v123, v123, v149
	v_add_f32_e32 v125, v142, v125
	v_fmac_f32_e32 v124, v150, v150
	v_add_f32_e32 v124, v124, v125
	v_fma_f32 v125, v127, v148, v123
	v_mul_f32_e32 v122, v127, v148
	v_add_f32_e32 v125, v125, v121
	v_mul_f32_e32 v121, v123, v123
	v_fmac_f32_e32 v121, v122, v122
	v_add_f32_e32 v124, v121, v124
	v_cvt_pk_bf16_f32 v120, v146, v120
	v_cvt_pk_bf16_f32 v121, v150, v122
	v_cvt_pk_bf16_f32 v122, v143, v145
	v_cvt_pk_bf16_f32 v123, v147, v123
	v_pk_mul_f32 v[112:113], v[112:113], v[164:165] op_sel_hi:[1,0]
	global_store_dwordx4 v[162:163], v[120:123], off nt
	v_pk_mul_f32 v[118:119], v[118:119], v[164:165] op_sel_hi:[1,0]
	v_pk_mul_f32 v[114:115], v[114:115], v[164:165] op_sel_hi:[1,0]
	v_mul_f32_e32 v123, 0x3d372713, v113
	v_mul_f32_e32 v123, v113, v123
	v_fma_f32 v123, v113, v123, v113
	v_mul_f32_e32 v123, 0x3f4c422a, v123
	v_mul_f32_e32 v123, 0xc038aa3b, v123
	v_exp_f32_e32 v123, v123
	v_mul_f32_e32 v127, 0x3d372713, v118
	v_mul_f32_e32 v142, 0x3d372713, v114
	v_mul_f32_e32 v127, v118, v127
	v_mul_f32_e32 v142, v114, v142
	v_fma_f32 v127, v118, v127, v118
	v_fma_f32 v142, v114, v142, v114
	v_pk_mul_f32 v[116:117], v[116:117], v[164:165] op_sel_hi:[1,0]
	v_mul_f32_e32 v121, 0x3d372713, v112
	v_mul_f32_e32 v127, 0x3f4c422a, v127
	v_mul_f32_e32 v142, 0x3f4c422a, v142
	v_mul_f32_e32 v120, 0x3d372713, v116
	v_mul_f32_e32 v121, v112, v121
	v_add_f32_e32 v123, 1.0, v123
	v_mul_f32_e32 v127, 0xc038aa3b, v127
	v_mul_f32_e32 v142, 0xc038aa3b, v142
	v_mul_f32_e32 v120, v116, v120
	v_fma_f32 v121, v112, v121, v112
	v_mul_f32_e32 v122, 0x3d372713, v117
	v_rcp_f32_e32 v123, v123
	v_exp_f32_e32 v127, v127
	v_exp_f32_e32 v142, v142
	v_fma_f32 v120, v116, v120, v116
	v_mul_f32_e32 v121, 0x3f4c422a, v121
	v_mul_f32_e32 v122, v117, v122
	v_mul_f32_e32 v120, 0x3f4c422a, v120
	v_mul_f32_e32 v121, 0xc038aa3b, v121
	v_fma_f32 v122, v117, v122, v117
	v_mul_f32_e32 v120, 0xc038aa3b, v120
	v_exp_f32_e32 v121, v121
	v_mul_f32_e32 v122, 0x3f4c422a, v122
	v_mul_f32_e32 v143, 0x3d372713, v115
	v_exp_f32_e32 v120, v120
	v_mul_f32_e32 v122, 0xc038aa3b, v122
	v_mul_f32_e32 v113, v113, v123
	v_add_f32_e32 v123, 1.0, v127
	v_add_f32_e32 v127, 1.0, v142
	v_mul_f32_e32 v142, 0x3d372713, v119
	v_mul_f32_e32 v143, v115, v143
	v_exp_f32_e32 v122, v122
	v_mul_f32_e32 v142, v119, v142
	v_fma_f32 v143, v115, v143, v115
	v_fma_f32 v142, v119, v142, v119
	v_mul_f32_e32 v143, 0x3f4c422a, v143
	v_add_f32_e32 v121, 1.0, v121
	v_mul_f32_e32 v142, 0x3f4c422a, v142
	v_mul_f32_e32 v143, 0xc038aa3b, v143
	v_add_f32_e32 v120, 1.0, v120
	v_rcp_f32_e32 v121, v121
	v_mul_f32_e32 v142, 0xc038aa3b, v142
	v_exp_f32_e32 v143, v143
	v_rcp_f32_e32 v120, v120
	v_add_f32_e32 v122, 1.0, v122
	v_exp_f32_e32 v142, v142
	v_rcp_f32_e32 v122, v122
	v_rcp_f32_e32 v127, v127
	v_rcp_f32_e32 v123, v123
	v_mul_f32_e32 v112, v112, v121
	v_add_f32_e32 v143, 1.0, v143
	v_mul_f32_e32 v126, v116, v120
	v_add_f32_e32 v142, 1.0, v142
	v_rcp_f32_e32 v143, v143
	v_fma_f32 v116, v116, v120, v112
	v_mul_f32_e32 v121, v117, v122
	v_rcp_f32_e32 v142, v142
	v_mul_f32_e32 v114, v114, v127
	v_add_f32_e32 v116, v116, v125
	v_mul_f32_e32 v120, v112, v112
	v_fma_f32 v117, v117, v122, v113
	v_mul_f32_e32 v144, v118, v123
	v_fmac_f32_e32 v120, v126, v126
	v_add_f32_e32 v116, v117, v116
	v_mul_f32_e32 v117, v113, v113
	v_fma_f32 v118, v118, v123, v114
	v_add_f32_e32 v120, v120, v124
	v_fmac_f32_e32 v117, v121, v121
	v_add_f32_e32 v116, v118, v116
	v_mul_f32_e32 v118, v114, v114
	v_mul_f32_e32 v115, v115, v143
	v_add_f32_e32 v117, v117, v120
	v_fmac_f32_e32 v118, v144, v144
	v_add_f32_e32 v117, v118, v117
	v_fma_f32 v118, v119, v142, v115
	v_mul_f32_e32 v127, v119, v142
	v_add_f32_e32 v120, v118, v116
	v_mul_f32_e32 v116, v115, v115
	v_fmac_f32_e32 v116, v127, v127
	v_add_f32_e32 v122, v116, v117
	v_cvt_pk_bf16_f32 v116, v126, v121
	v_mov_b32_e32 v121, v120
	s_nop 1
	v_permlane16_swap_b32_e32 v121, v120
	v_mov_b32_e32 v123, v122
	s_nop 1
	v_permlane16_swap_b32_e32 v123, v122
	v_cvt_pk_bf16_f32 v117, v144, v127
	v_cvt_pk_bf16_f32 v118, v112, v113
	v_cvt_pk_bf16_f32 v119, v114, v115
	s_waitcnt lgkmcnt(0)
	v_add_f32_e32 v112, v120, v121
	v_add_f32_e32 v114, v122, v123
	v_mov_b32_e32 v113, v112
	s_nop 1
	v_permlane32_swap_b32_e32 v113, v112
	v_mov_b32_e32 v115, v114
	s_nop 1
	v_permlane32_swap_b32_e32 v115, v114
	s_cmp_gt_i32 s95, 3
	s_cselect_b64 s[4:5], -1, 0
	s_and_b64 s[58:59], s[4:5], vcc
	global_store_dwordx4 v[162:163], v[116:119], off offset:256 nt
	s_and_saveexec_b64 s[6:7], s[58:59]
	s_cbranch_execz .LBB0_561
	s_waitcnt lgkmcnt(0)
	v_add_f32_e32 v114, v114, v115
	v_add_f32_e32 v115, v112, v113
	s_lshl_b32 s4, s95, 2
	v_lshlrev_b64 v[112:113], 7, v[158:159]
	s_add_i32 s38, s4, -16
	v_lshl_add_u64 v[112:113], s[72:73], 0, v[112:113]
	v_lshl_add_u64 v[112:113], s[38:39], 2, v[112:113]
	s_lshl_b32 s38, s8, 2
	v_lshl_add_u64 v[112:113], v[112:113], 0, s[38:39]
	global_store_dword v[112:113], v115, off
	global_store_dword v[112:113], v114, off offset:64
.LBB0_561:
	s_or_b64 exec, exec, s[6:7]
	v_or_b32_e32 v112, 16, v158
	s_mov_b64 s[6:7], -1
	s_and_b64 vcc, exec, s[56:57]
	s_waitcnt lgkmcnt(0)
	v_ashrrev_i32_e32 v113, 31, v112
	s_cbranch_vccz .LBB0_563
	v_lshlrev_b64 v[114:115], 6, v[112:113]
	v_lshl_add_u64 v[114:115], s[48:49], 0, v[114:115]
	v_lshl_add_u64 v[114:115], v[114:115], 0, v[140:141]
	flat_load_dwordx4 v[114:117], v[114:115]
	s_mov_b64 s[6:7], 0
	s_waitcnt vmcnt(0) lgkmcnt(0)
	v_mov_b32_e32 v118, v115
	v_mov_b32_e32 v119, v116
	v_mov_b32_e32 v115, v117
	v_pk_add_f32 v[114:115], v[118:119], v[114:115]
	s_nop 0
	v_add_f32_e32 v114, v114, v115
	v_mov_b32_e32 v115, v114
	s_nop 1
	v_permlane16_swap_b32_e32 v115, v114
	s_waitcnt lgkmcnt(0)
	v_add_f32_e32 v114, v114, v115
	v_mov_b32_e32 v115, v114
	s_nop 1
	v_permlane32_swap_b32_e32 v115, v114
	s_waitcnt lgkmcnt(0)
	v_add_f32_e32 v114, v114, v115
	v_fmamk_f32 v114, v114, 0x3a800000, v250
	v_rsq_f32_e32 v116, v114

.LBB0_565:
	s_waitcnt lgkmcnt(0)
	v_pk_mul_f32 v[108:109], v[108:109], v[116:117] op_sel_hi:[1,0]
	v_lshlrev_b64 v[114:115], 12, v[112:113]
	v_mul_f32_e32 v117, 0x3d372713, v108
	v_mul_f32_e32 v117, v108, v117
	v_fma_f32 v117, v108, v117, v108
	v_mul_f32_e32 v117, 0x3f4c422a, v117
	v_mul_f32_e32 v117, 0xc038aa3b, v117
	v_exp_f32_e32 v117, v117
	v_mul_f32_e32 v119, 0x3d372713, v109
	v_mul_f32_e32 v119, v109, v119
	v_fma_f32 v119, v109, v119, v109
	v_pk_mul_f32 v[104:105], v[104:105], v[116:117] op_sel_hi:[1,0]
	v_pk_mul_f32 v[110:111], v[110:111], v[116:117] op_sel_hi:[1,0]
	v_mul_f32_e32 v120, 0x3d372713, v105
	v_mul_f32_e32 v120, v105, v120
	v_fma_f32 v120, v105, v120, v105
	v_mul_f32_e32 v120, 0x3f4c422a, v120
	v_pk_mul_f32 v[106:107], v[106:107], v[116:117] op_sel_hi:[1,0]
	v_mul_f32_e32 v120, 0xc038aa3b, v120
	v_exp_f32_e32 v120, v120
	v_mul_f32_e32 v122, 0x3d372713, v110
	v_mul_f32_e32 v123, 0x3d372713, v106
	v_mul_f32_e32 v122, v110, v122
	v_mul_f32_e32 v123, v106, v123
	v_mul_f32_e32 v118, 0x3d372713, v104
	v_fma_f32 v122, v110, v122, v110
	v_fma_f32 v123, v106, v123, v106
	v_mul_f32_e32 v118, v104, v118
	v_mul_f32_e32 v122, 0x3f4c422a, v122
	v_mul_f32_e32 v123, 0x3f4c422a, v123
	v_fma_f32 v118, v104, v118, v104
	v_add_f32_e32 v120, 1.0, v120
	v_mul_f32_e32 v122, 0xc038aa3b, v122
	v_mul_f32_e32 v123, 0xc038aa3b, v123
	v_mul_f32_e32 v118, 0x3f4c422a, v118
	v_rcp_f32_e32 v120, v120
	v_exp_f32_e32 v122, v122
	v_exp_f32_e32 v123, v123
	v_mul_f32_e32 v118, 0xc038aa3b, v118
	v_exp_f32_e32 v118, v118
	v_mul_f32_e32 v119, 0x3f4c422a, v119
	v_mul_f32_e32 v119, 0xc038aa3b, v119
	v_mul_f32_e32 v124, 0x3d372713, v107
	v_exp_f32_e32 v119, v119
	v_mul_f32_e32 v120, v105, v120
	v_add_f32_e32 v105, 1.0, v122
	v_add_f32_e32 v122, 1.0, v123
	v_mul_f32_e32 v123, 0x3d372713, v111
	v_mul_f32_e32 v124, v107, v124
	v_mul_f32_e32 v123, v111, v123
	v_fma_f32 v124, v107, v124, v107
	v_add_f32_e32 v118, 1.0, v118
	v_fma_f32 v123, v111, v123, v111
	v_mul_f32_e32 v124, 0x3f4c422a, v124
	v_add_f32_e32 v117, 1.0, v117
	v_rcp_f32_e32 v118, v118
	v_mul_f32_e32 v123, 0x3f4c422a, v123
	v_mul_f32_e32 v124, 0xc038aa3b, v124
	v_rcp_f32_e32 v117, v117
	v_add_f32_e32 v119, 1.0, v119
	v_mul_f32_e32 v123, 0xc038aa3b, v123
	v_exp_f32_e32 v124, v124
	v_rcp_f32_e32 v119, v119
	v_exp_f32_e32 v123, v123
	v_rcp_f32_e32 v122, v122
	v_mul_f32_e32 v118, v104, v118
	v_rcp_f32_e32 v105, v105
	v_mul_f32_e32 v121, v108, v117
	v_add_f32_e32 v124, 1.0, v124
	v_fma_f32 v108, v108, v117, v118
	v_mul_f32_e32 v104, v109, v119
	v_add_f32_e32 v123, 1.0, v123
	v_rcp_f32_e32 v124, v124
	v_add_f32_e32 v108, 0, v108
	v_mul_f32_e32 v117, v118, v118
	v_fma_f32 v109, v109, v119, v120
	v_rcp_f32_e32 v123, v123
	v_mul_f32_e32 v122, v106, v122
	v_fmac_f32_e32 v117, v121, v121
	v_add_f32_e32 v108, v109, v108
	v_mul_f32_e32 v109, v120, v120
	v_mul_f32_e32 v125, v110, v105
	v_fmac_f32_e32 v109, v104, v104
	v_fma_f32 v105, v110, v105, v122
	v_pk_mul_f32 v[96:97], v[96:97], v[116:117] op_sel_hi:[1,0]
	v_add_f32_e32 v109, v117, v109
	v_add_f32_e32 v105, v105, v108
	v_mul_f32_e32 v108, v122, v122
	v_pk_mul_f32 v[100:101], v[100:101], v[116:117] op_sel_hi:[1,0]
	v_pk_mul_f32 v[102:103], v[102:103], v[116:117] op_sel_hi:[1,0]
	v_pk_mul_f32 v[98:99], v[98:99], v[116:117] op_sel_hi:[1,0]
	v_mul_f32_e32 v117, 0x3d372713, v97
	v_mul_f32_e32 v107, v107, v124
	v_fmac_f32_e32 v108, v125, v125
	v_mul_f32_e32 v117, v97, v117
	v_add_f32_e32 v108, v108, v109
	v_fma_f32 v109, v111, v123, v107
	v_fma_f32 v117, v97, v117, v97
	v_mul_f32_e32 v106, v111, v123
	v_add_f32_e32 v109, v109, v105
	v_mul_f32_e32 v105, v107, v107
	v_mul_f32_e32 v117, 0x3f4c422a, v117
	v_fmac_f32_e32 v105, v106, v106
	v_mul_f32_e32 v117, 0xc038aa3b, v117
	v_add_f32_e32 v108, v105, v108
	v_cvt_pk_bf16_f32 v104, v121, v104
	v_cvt_pk_bf16_f32 v105, v125, v106
	v_cvt_pk_bf16_f32 v106, v118, v120
	v_exp_f32_e32 v117, v117
	v_mul_f32_e32 v119, 0x3d372713, v102
	v_mul_f32_e32 v120, 0x3d372713, v98
	v_mul_f32_e32 v119, v102, v119
	v_mul_f32_e32 v120, v98, v120
	v_fma_f32 v119, v102, v119, v102
	v_fma_f32 v120, v98, v120, v98
	v_mul_f32_e32 v111, 0x3d372713, v96
	v_mul_f32_e32 v119, 0x3f4c422a, v119
	v_mul_f32_e32 v120, 0x3f4c422a, v120
	v_mul_f32_e32 v110, 0x3d372713, v100
	v_mul_f32_e32 v111, v96, v111
	v_add_f32_e32 v117, 1.0, v117
	v_mul_f32_e32 v119, 0xc038aa3b, v119
	v_mul_f32_e32 v120, 0xc038aa3b, v120
	v_mul_f32_e32 v110, v100, v110
	v_fma_f32 v111, v96, v111, v96
	v_mul_f32_e32 v116, 0x3d372713, v101
	v_rcp_f32_e32 v117, v117
	v_exp_f32_e32 v119, v119
	v_exp_f32_e32 v120, v120
	v_mul_f32_e32 v121, 0x3d372713, v99
	v_fma_f32 v110, v100, v110, v100
	v_mul_f32_e32 v111, 0x3f4c422a, v111
	v_mul_f32_e32 v116, v101, v116
	v_mul_f32_e32 v121, v99, v121
	v_mul_f32_e32 v110, 0x3f4c422a, v110
	v_mul_f32_e32 v111, 0xc038aa3b, v111
	v_fma_f32 v116, v101, v116, v101
	v_fma_f32 v121, v99, v121, v99
	v_mul_f32_e32 v110, 0xc038aa3b, v110
	v_exp_f32_e32 v111, v111
	v_mul_f32_e32 v116, 0x3f4c422a, v116
	v_mul_f32_e32 v121, 0x3f4c422a, v121
	v_exp_f32_e32 v110, v110
	v_mul_f32_e32 v116, 0xc038aa3b, v116
	v_mul_f32_e32 v117, v97, v117
	v_add_f32_e32 v97, 1.0, v119
	v_add_f32_e32 v119, 1.0, v120
	v_mul_f32_e32 v120, 0x3d372713, v103
	v_mul_f32_e32 v121, 0xc038aa3b, v121
	v_exp_f32_e32 v116, v116
	v_mul_f32_e32 v120, v103, v120
	v_exp_f32_e32 v121, v121
	v_fma_f32 v120, v103, v120, v103
	v_add_f32_e32 v111, 1.0, v111
	v_mul_f32_e32 v120, 0x3f4c422a, v120
	v_add_f32_e32 v110, 1.0, v110
	v_rcp_f32_e32 v111, v111
	v_mul_f32_e32 v120, 0xc038aa3b, v120
	v_rcp_f32_e32 v110, v110
	v_add_f32_e32 v116, 1.0, v116
	v_exp_f32_e32 v120, v120
	v_rcp_f32_e32 v119, v119
	v_add_f32_e32 v121, 1.0, v121
	v_rcp_f32_e32 v116, v116
	v_rcp_f32_e32 v121, v121
	v_rcp_f32_e32 v97, v97
	v_mul_f32_e32 v111, v96, v111
	v_add_f32_e32 v120, 1.0, v120
	v_mul_f32_e32 v119, v98, v119
	v_fma_f32 v98, v100, v110, v111
	v_mul_f32_e32 v118, v100, v110
	v_rcp_f32_e32 v120, v120
	v_mul_f32_e32 v121, v99, v121
	v_add_f32_e32 v98, v98, v109
	v_mul_f32_e32 v99, v111, v111
	v_fma_f32 v100, v101, v116, v117
	v_cvt_pk_bf16_f32 v107, v122, v107
	v_mul_f32_e32 v96, v101, v116
	v_mul_f32_e32 v122, v102, v97
	v_fmac_f32_e32 v99, v118, v118
	v_add_f32_e32 v98, v100, v98
	v_mul_f32_e32 v100, v117, v117
	v_fma_f32 v97, v102, v97, v119
	v_add_f32_e32 v99, v99, v108
	v_fmac_f32_e32 v100, v96, v96
	v_add_f32_e32 v97, v97, v98
	v_mul_f32_e32 v98, v119, v119
	v_add_f32_e32 v99, v100, v99
	v_fmac_f32_e32 v98, v122, v122
	v_add_f32_e32 v98, v98, v99
	v_fma_f32 v99, v103, v120, v121
	v_mul_f32_e32 v123, v103, v120
	v_add_f32_e32 v97, v99, v97
	v_mul_f32_e32 v99, v121, v121
	v_fmac_f32_e32 v99, v123, v123
	v_add_f32_e32 v98, v99, v98
	v_mov_b32_e32 v101, v97
	s_nop 1
	v_permlane16_swap_b32_e32 v101, v97
	v_mov_b32_e32 v99, v98
	s_nop 1
	v_permlane16_swap_b32_e32 v99, v98
	v_lshl_add_u64 v[114:115], s[70:71], 0, v[114:115]
	v_lshl_add_u64 v[114:115], v[160:161], 1, v[114:115]
	global_store_dwordx4 v[114:115], v[104:107], off nt
	v_cvt_pk_bf16_f32 v100, v118, v96
	s_waitcnt lgkmcnt(0)
	v_add_f32_e32 v96, v97, v101
	v_add_f32_e32 v98, v98, v99
	v_mov_b32_e32 v97, v96
	s_nop 1
	v_permlane32_swap_b32_e32 v97, v96
	v_mov_b32_e32 v99, v98
	s_nop 1
	v_permlane32_swap_b32_e32 v99, v98
	v_cvt_pk_bf16_f32 v101, v122, v123
	v_cvt_pk_bf16_f32 v102, v111, v117
	v_cvt_pk_bf16_f32 v103, v119, v121
	global_store_dwordx4 v[114:115], v[100:103], off offset:256 nt
	s_and_saveexec_b64 s[6:7], s[58:59]
	s_cbranch_execz .LBB0_567
	s_waitcnt lgkmcnt(0)
	v_add_f32_e32 v98, v98, v99
	v_add_f32_e32 v99, v96, v97
	s_lshl_b32 s4, s95, 2
	v_lshlrev_b64 v[96:97], 7, v[112:113]
	s_add_i32 s38, s4, -16
	v_lshl_add_u64 v[96:97], s[72:73], 0, v[96:97]
	v_lshl_add_u64 v[96:97], s[38:39], 2, v[96:97]
	s_lshl_b32 s38, s8, 2
	v_lshl_add_u64 v[96:97], v[96:97], 0, s[38:39]
	global_store_dword v[96:97], v99, off
	global_store_dword v[96:97], v98, off offset:64
.LBB0_567:
	s_or_b64 exec, exec, s[6:7]
	v_or_b32_e32 v96, 32, v158
	s_mov_b64 s[6:7], -1
	s_and_b64 vcc, exec, s[56:57]
	s_waitcnt lgkmcnt(0)
	v_ashrrev_i32_e32 v97, 31, v96
	s_cbranch_vccz .LBB0_569
	v_lshlrev_b64 v[98:99], 6, v[96:97]
	v_lshl_add_u64 v[98:99], s[48:49], 0, v[98:99]
	v_lshl_add_u64 v[98:99], v[98:99], 0, v[140:141]
	flat_load_dwordx4 v[98:101], v[98:99]
	s_mov_b64 s[6:7], 0
	s_waitcnt vmcnt(0) lgkmcnt(0)
	v_mov_b32_e32 v102, v99
	v_mov_b32_e32 v103, v100
	v_mov_b32_e32 v99, v101
	v_pk_add_f32 v[98:99], v[102:103], v[98:99]
	s_nop 0
	v_add_f32_e32 v98, v98, v99
	v_mov_b32_e32 v99, v98
	s_nop 1
	v_permlane16_swap_b32_e32 v99, v98
	s_waitcnt lgkmcnt(0)
	v_add_f32_e32 v98, v98, v99
	v_mov_b32_e32 v99, v98
	s_nop 1
	v_permlane32_swap_b32_e32 v99, v98
	s_waitcnt lgkmcnt(0)
	v_add_f32_e32 v98, v98, v99
	v_fmamk_f32 v98, v98, 0x3a800000, v250
	v_rsq_f32_e32 v100, v98

.LBB0_571:
	s_waitcnt lgkmcnt(0)
	v_pk_mul_f32 v[92:93], v[92:93], v[100:101] op_sel_hi:[1,0]
	v_lshlrev_b64 v[98:99], 12, v[96:97]
	v_mul_f32_e32 v101, 0x3d372713, v92
	v_mul_f32_e32 v101, v92, v101
	v_fma_f32 v101, v92, v101, v92
	v_mul_f32_e32 v101, 0x3f4c422a, v101
	v_mul_f32_e32 v101, 0xc038aa3b, v101
	v_exp_f32_e32 v101, v101
	v_mul_f32_e32 v103, 0x3d372713, v93
	v_mul_f32_e32 v103, v93, v103
	v_fma_f32 v103, v93, v103, v93
	v_pk_mul_f32 v[88:89], v[88:89], v[100:101] op_sel_hi:[1,0]
	v_pk_mul_f32 v[94:95], v[94:95], v[100:101] op_sel_hi:[1,0]
	v_mul_f32_e32 v104, 0x3d372713, v89
	v_mul_f32_e32 v104, v89, v104
	v_fma_f32 v104, v89, v104, v89
	v_mul_f32_e32 v104, 0x3f4c422a, v104
	v_pk_mul_f32 v[90:91], v[90:91], v[100:101] op_sel_hi:[1,0]
	v_mul_f32_e32 v104, 0xc038aa3b, v104
	v_exp_f32_e32 v104, v104
	v_mul_f32_e32 v106, 0x3d372713, v94
	v_mul_f32_e32 v107, 0x3d372713, v90
	v_mul_f32_e32 v106, v94, v106
	v_mul_f32_e32 v107, v90, v107
	v_mul_f32_e32 v102, 0x3d372713, v88
	v_fma_f32 v106, v94, v106, v94
	v_fma_f32 v107, v90, v107, v90
	v_mul_f32_e32 v102, v88, v102
	v_mul_f32_e32 v106, 0x3f4c422a, v106
	v_mul_f32_e32 v107, 0x3f4c422a, v107
	v_fma_f32 v102, v88, v102, v88
	v_add_f32_e32 v104, 1.0, v104
	v_mul_f32_e32 v106, 0xc038aa3b, v106
	v_mul_f32_e32 v107, 0xc038aa3b, v107
	v_mul_f32_e32 v102, 0x3f4c422a, v102
	v_rcp_f32_e32 v104, v104
	v_exp_f32_e32 v106, v106
	v_exp_f32_e32 v107, v107
	v_mul_f32_e32 v102, 0xc038aa3b, v102
	v_exp_f32_e32 v102, v102
	v_mul_f32_e32 v103, 0x3f4c422a, v103
	v_mul_f32_e32 v103, 0xc038aa3b, v103
	v_mul_f32_e32 v108, 0x3d372713, v91
	v_exp_f32_e32 v103, v103
	v_mul_f32_e32 v104, v89, v104
	v_add_f32_e32 v89, 1.0, v106
	v_add_f32_e32 v106, 1.0, v107
	v_mul_f32_e32 v107, 0x3d372713, v95
	v_mul_f32_e32 v108, v91, v108
	v_mul_f32_e32 v107, v95, v107
	v_fma_f32 v108, v91, v108, v91
	v_add_f32_e32 v102, 1.0, v102
	v_fma_f32 v107, v95, v107, v95
	v_mul_f32_e32 v108, 0x3f4c422a, v108
	v_add_f32_e32 v101, 1.0, v101
	v_rcp_f32_e32 v102, v102
	v_mul_f32_e32 v107, 0x3f4c422a, v107
	v_mul_f32_e32 v108, 0xc038aa3b, v108
	v_rcp_f32_e32 v101, v101
	v_add_f32_e32 v103, 1.0, v103
	v_mul_f32_e32 v107, 0xc038aa3b, v107
	v_exp_f32_e32 v108, v108
	v_rcp_f32_e32 v103, v103
	v_exp_f32_e32 v107, v107
	v_rcp_f32_e32 v106, v106
	v_mul_f32_e32 v102, v88, v102
	v_rcp_f32_e32 v89, v89
	v_mul_f32_e32 v105, v92, v101
	v_add_f32_e32 v108, 1.0, v108
	v_fma_f32 v92, v92, v101, v102
	v_mul_f32_e32 v88, v93, v103
	v_add_f32_e32 v107, 1.0, v107
	v_rcp_f32_e32 v108, v108
	v_add_f32_e32 v92, 0, v92
	v_mul_f32_e32 v101, v102, v102
	v_fma_f32 v93, v93, v103, v104
	v_rcp_f32_e32 v107, v107
	v_mul_f32_e32 v106, v90, v106
	v_fmac_f32_e32 v101, v105, v105
	v_add_f32_e32 v92, v93, v92
	v_mul_f32_e32 v93, v104, v104
	v_mul_f32_e32 v109, v94, v89
	v_fmac_f32_e32 v93, v88, v88
	v_fma_f32 v89, v94, v89, v106
	v_pk_mul_f32 v[80:81], v[80:81], v[100:101] op_sel_hi:[1,0]
	v_add_f32_e32 v93, v101, v93
	v_add_f32_e32 v89, v89, v92
	v_mul_f32_e32 v92, v106, v106
	v_pk_mul_f32 v[84:85], v[84:85], v[100:101] op_sel_hi:[1,0]
	v_pk_mul_f32 v[86:87], v[86:87], v[100:101] op_sel_hi:[1,0]
	v_pk_mul_f32 v[82:83], v[82:83], v[100:101] op_sel_hi:[1,0]
	v_mul_f32_e32 v101, 0x3d372713, v81
	v_mul_f32_e32 v91, v91, v108
	v_fmac_f32_e32 v92, v109, v109
	v_mul_f32_e32 v101, v81, v101
	v_add_f32_e32 v92, v92, v93
	v_fma_f32 v93, v95, v107, v91
	v_fma_f32 v101, v81, v101, v81
	v_mul_f32_e32 v90, v95, v107
	v_add_f32_e32 v93, v93, v89
	v_mul_f32_e32 v89, v91, v91
	v_mul_f32_e32 v101, 0x3f4c422a, v101
	v_fmac_f32_e32 v89, v90, v90
	v_mul_f32_e32 v101, 0xc038aa3b, v101
	v_add_f32_e32 v92, v89, v92
	v_cvt_pk_bf16_f32 v88, v105, v88
	v_cvt_pk_bf16_f32 v89, v109, v90
	v_cvt_pk_bf16_f32 v90, v102, v104
	v_exp_f32_e32 v101, v101
	v_mul_f32_e32 v103, 0x3d372713, v86
	v_mul_f32_e32 v104, 0x3d372713, v82
	v_mul_f32_e32 v103, v86, v103
	v_mul_f32_e32 v104, v82, v104
	v_fma_f32 v103, v86, v103, v86
	v_fma_f32 v104, v82, v104, v82
	v_mul_f32_e32 v95, 0x3d372713, v80
	v_mul_f32_e32 v103, 0x3f4c422a, v103
	v_mul_f32_e32 v104, 0x3f4c422a, v104
	v_mul_f32_e32 v94, 0x3d372713, v84
	v_mul_f32_e32 v95, v80, v95
	v_add_f32_e32 v101, 1.0, v101
	v_mul_f32_e32 v103, 0xc038aa3b, v103
	v_mul_f32_e32 v104, 0xc038aa3b, v104
	v_mul_f32_e32 v94, v84, v94
	v_fma_f32 v95, v80, v95, v80
	v_mul_f32_e32 v100, 0x3d372713, v85
	v_rcp_f32_e32 v101, v101
	v_exp_f32_e32 v103, v103
	v_exp_f32_e32 v104, v104
	v_mul_f32_e32 v105, 0x3d372713, v83
	v_fma_f32 v94, v84, v94, v84
	v_mul_f32_e32 v95, 0x3f4c422a, v95
	v_mul_f32_e32 v100, v85, v100
	v_mul_f32_e32 v105, v83, v105
	v_mul_f32_e32 v94, 0x3f4c422a, v94
	v_mul_f32_e32 v95, 0xc038aa3b, v95
	v_fma_f32 v100, v85, v100, v85
	v_fma_f32 v105, v83, v105, v83
	v_mul_f32_e32 v94, 0xc038aa3b, v94
	v_exp_f32_e32 v95, v95
	v_mul_f32_e32 v100, 0x3f4c422a, v100
	v_mul_f32_e32 v105, 0x3f4c422a, v105
	v_exp_f32_e32 v94, v94
	v_mul_f32_e32 v100, 0xc038aa3b, v100
	v_mul_f32_e32 v101, v81, v101
	v_add_f32_e32 v81, 1.0, v103
	v_add_f32_e32 v103, 1.0, v104
	v_mul_f32_e32 v104, 0x3d372713, v87
	v_mul_f32_e32 v105, 0xc038aa3b, v105
	v_exp_f32_e32 v100, v100
	v_mul_f32_e32 v104, v87, v104
	v_exp_f32_e32 v105, v105
	v_fma_f32 v104, v87, v104, v87
	v_add_f32_e32 v95, 1.0, v95
	v_mul_f32_e32 v104, 0x3f4c422a, v104
	v_add_f32_e32 v94, 1.0, v94
	v_rcp_f32_e32 v95, v95
	v_mul_f32_e32 v104, 0xc038aa3b, v104
	v_rcp_f32_e32 v94, v94
	v_add_f32_e32 v100, 1.0, v100
	v_exp_f32_e32 v104, v104
	v_rcp_f32_e32 v103, v103
	v_add_f32_e32 v105, 1.0, v105
	v_rcp_f32_e32 v100, v100
	v_rcp_f32_e32 v105, v105
	v_rcp_f32_e32 v81, v81
	v_mul_f32_e32 v95, v80, v95
	v_add_f32_e32 v104, 1.0, v104
	v_mul_f32_e32 v103, v82, v103
	v_fma_f32 v82, v84, v94, v95
	v_mul_f32_e32 v102, v84, v94
	v_rcp_f32_e32 v104, v104
	v_mul_f32_e32 v105, v83, v105
	v_add_f32_e32 v82, v82, v93
	v_mul_f32_e32 v83, v95, v95
	v_fma_f32 v84, v85, v100, v101
	v_cvt_pk_bf16_f32 v91, v106, v91
	v_mul_f32_e32 v80, v85, v100
	v_mul_f32_e32 v106, v86, v81
	v_fmac_f32_e32 v83, v102, v102
	v_add_f32_e32 v82, v84, v82
	v_mul_f32_e32 v84, v101, v101
	v_fma_f32 v81, v86, v81, v103
	v_add_f32_e32 v83, v83, v92
	v_fmac_f32_e32 v84, v80, v80
	v_add_f32_e32 v81, v81, v82
	v_mul_f32_e32 v82, v103, v103
	v_add_f32_e32 v83, v84, v83
	v_fmac_f32_e32 v82, v106, v106
	v_add_f32_e32 v82, v82, v83
	v_fma_f32 v83, v87, v104, v105
	v_mul_f32_e32 v107, v87, v104
	v_add_f32_e32 v81, v83, v81
	v_mul_f32_e32 v83, v105, v105
	v_fmac_f32_e32 v83, v107, v107
	v_add_f32_e32 v82, v83, v82
	v_mov_b32_e32 v85, v81
	s_nop 1
	v_permlane16_swap_b32_e32 v85, v81
	v_mov_b32_e32 v83, v82
	s_nop 1
	v_permlane16_swap_b32_e32 v83, v82
	v_lshl_add_u64 v[98:99], s[70:71], 0, v[98:99]
	v_lshl_add_u64 v[98:99], v[160:161], 1, v[98:99]
	global_store_dwordx4 v[98:99], v[88:91], off nt
	v_cvt_pk_bf16_f32 v84, v102, v80
	s_waitcnt lgkmcnt(0)
	v_add_f32_e32 v80, v81, v85
	v_add_f32_e32 v82, v82, v83
	v_mov_b32_e32 v81, v80
	s_nop 1
	v_permlane32_swap_b32_e32 v81, v80
	v_mov_b32_e32 v83, v82
	s_nop 1
	v_permlane32_swap_b32_e32 v83, v82
	v_cvt_pk_bf16_f32 v85, v106, v107
	v_cvt_pk_bf16_f32 v86, v95, v101
	v_cvt_pk_bf16_f32 v87, v103, v105
	global_store_dwordx4 v[98:99], v[84:87], off offset:256 nt
	s_and_saveexec_b64 s[6:7], s[58:59]
	s_cbranch_execz .LBB0_573
	s_waitcnt lgkmcnt(0)
	v_add_f32_e32 v82, v82, v83
	v_add_f32_e32 v83, v80, v81
	s_lshl_b32 s4, s95, 2
	v_lshlrev_b64 v[80:81], 7, v[96:97]
	s_add_i32 s38, s4, -16
	v_lshl_add_u64 v[80:81], s[72:73], 0, v[80:81]
	v_lshl_add_u64 v[80:81], s[38:39], 2, v[80:81]
	s_lshl_b32 s38, s8, 2
	v_lshl_add_u64 v[80:81], v[80:81], 0, s[38:39]
	global_store_dword v[80:81], v83, off
	global_store_dword v[80:81], v82, off offset:64
.LBB0_573:
	s_or_b64 exec, exec, s[6:7]
	v_or_b32_e32 v80, 48, v158
	s_mov_b64 s[6:7], -1
	s_and_b64 vcc, exec, s[56:57]
	s_waitcnt lgkmcnt(0)
	v_ashrrev_i32_e32 v81, 31, v80
	s_cbranch_vccz .LBB0_575
	v_lshlrev_b64 v[82:83], 6, v[80:81]
	v_lshl_add_u64 v[82:83], s[48:49], 0, v[82:83]
	v_lshl_add_u64 v[82:83], v[82:83], 0, v[140:141]
	flat_load_dwordx4 v[82:85], v[82:83]
	s_mov_b64 s[6:7], 0
	s_waitcnt vmcnt(0) lgkmcnt(0)
	v_mov_b32_e32 v86, v83
	v_mov_b32_e32 v87, v84
	v_mov_b32_e32 v83, v85
	v_pk_add_f32 v[82:83], v[86:87], v[82:83]
	s_nop 0
	v_add_f32_e32 v82, v82, v83
	v_mov_b32_e32 v83, v82
	s_nop 1
	v_permlane16_swap_b32_e32 v83, v82
	s_waitcnt lgkmcnt(0)
	v_add_f32_e32 v82, v82, v83
	v_mov_b32_e32 v83, v82
	s_nop 1
	v_permlane32_swap_b32_e32 v83, v82
	s_waitcnt lgkmcnt(0)
	v_add_f32_e32 v82, v82, v83
	v_fmamk_f32 v82, v82, 0x3a800000, v250
	v_rsq_f32_e32 v84, v82

.LBB0_577:
	s_waitcnt lgkmcnt(0)
	v_pk_mul_f32 v[76:77], v[76:77], v[84:85] op_sel_hi:[1,0]
	v_lshlrev_b64 v[82:83], 12, v[80:81]
	v_mul_f32_e32 v85, 0x3d372713, v76
	v_mul_f32_e32 v85, v76, v85
	v_fma_f32 v85, v76, v85, v76
	v_mul_f32_e32 v85, 0x3f4c422a, v85
	v_mul_f32_e32 v85, 0xc038aa3b, v85
	v_exp_f32_e32 v85, v85
	v_mul_f32_e32 v87, 0x3d372713, v77
	v_mul_f32_e32 v87, v77, v87
	v_fma_f32 v87, v77, v87, v77
	v_pk_mul_f32 v[72:73], v[72:73], v[84:85] op_sel_hi:[1,0]
	v_pk_mul_f32 v[78:79], v[78:79], v[84:85] op_sel_hi:[1,0]
	v_mul_f32_e32 v88, 0x3d372713, v73
	v_mul_f32_e32 v88, v73, v88
	v_fma_f32 v88, v73, v88, v73
	v_mul_f32_e32 v88, 0x3f4c422a, v88
	v_pk_mul_f32 v[74:75], v[74:75], v[84:85] op_sel_hi:[1,0]
	v_mul_f32_e32 v88, 0xc038aa3b, v88
	v_exp_f32_e32 v88, v88
	v_mul_f32_e32 v90, 0x3d372713, v78
	v_mul_f32_e32 v91, 0x3d372713, v74
	v_mul_f32_e32 v90, v78, v90
	v_mul_f32_e32 v91, v74, v91
	v_mul_f32_e32 v86, 0x3d372713, v72
	v_fma_f32 v90, v78, v90, v78
	v_fma_f32 v91, v74, v91, v74
	v_mul_f32_e32 v86, v72, v86
	v_mul_f32_e32 v90, 0x3f4c422a, v90
	v_mul_f32_e32 v91, 0x3f4c422a, v91
	v_fma_f32 v86, v72, v86, v72
	v_add_f32_e32 v88, 1.0, v88
	v_mul_f32_e32 v90, 0xc038aa3b, v90
	v_mul_f32_e32 v91, 0xc038aa3b, v91
	v_mul_f32_e32 v86, 0x3f4c422a, v86
	v_rcp_f32_e32 v88, v88
	v_exp_f32_e32 v90, v90
	v_exp_f32_e32 v91, v91
	v_mul_f32_e32 v86, 0xc038aa3b, v86
	v_exp_f32_e32 v86, v86
	v_mul_f32_e32 v87, 0x3f4c422a, v87
	v_mul_f32_e32 v87, 0xc038aa3b, v87
	v_mul_f32_e32 v92, 0x3d372713, v75
	v_exp_f32_e32 v87, v87
	v_mul_f32_e32 v88, v73, v88
	v_add_f32_e32 v73, 1.0, v90
	v_add_f32_e32 v90, 1.0, v91
	v_mul_f32_e32 v91, 0x3d372713, v79
	v_mul_f32_e32 v92, v75, v92
	v_mul_f32_e32 v91, v79, v91
	v_fma_f32 v92, v75, v92, v75
	v_add_f32_e32 v86, 1.0, v86
	v_fma_f32 v91, v79, v91, v79
	v_mul_f32_e32 v92, 0x3f4c422a, v92
	v_add_f32_e32 v85, 1.0, v85
	v_rcp_f32_e32 v86, v86
	v_mul_f32_e32 v91, 0x3f4c422a, v91
	v_mul_f32_e32 v92, 0xc038aa3b, v92
	v_rcp_f32_e32 v85, v85
	v_add_f32_e32 v87, 1.0, v87
	v_mul_f32_e32 v91, 0xc038aa3b, v91
	v_exp_f32_e32 v92, v92
	v_rcp_f32_e32 v87, v87
	v_exp_f32_e32 v91, v91
	v_rcp_f32_e32 v90, v90
	v_mul_f32_e32 v86, v72, v86
	v_rcp_f32_e32 v73, v73
	v_mul_f32_e32 v89, v76, v85
	v_add_f32_e32 v92, 1.0, v92
	v_fma_f32 v76, v76, v85, v86
	v_mul_f32_e32 v72, v77, v87
	v_add_f32_e32 v91, 1.0, v91
	v_rcp_f32_e32 v92, v92
	v_add_f32_e32 v76, 0, v76
	v_mul_f32_e32 v85, v86, v86
	v_fma_f32 v77, v77, v87, v88
	v_rcp_f32_e32 v91, v91
	v_mul_f32_e32 v90, v74, v90
	v_fmac_f32_e32 v85, v89, v89
	v_add_f32_e32 v76, v77, v76
	v_mul_f32_e32 v77, v88, v88
	v_mul_f32_e32 v93, v78, v73
	v_fmac_f32_e32 v77, v72, v72
	v_fma_f32 v73, v78, v73, v90
	v_pk_mul_f32 v[64:65], v[64:65], v[84:85] op_sel_hi:[1,0]
	v_add_f32_e32 v77, v85, v77
	v_add_f32_e32 v73, v73, v76
	v_mul_f32_e32 v76, v90, v90
	v_pk_mul_f32 v[68:69], v[68:69], v[84:85] op_sel_hi:[1,0]
	v_pk_mul_f32 v[70:71], v[70:71], v[84:85] op_sel_hi:[1,0]
	v_pk_mul_f32 v[66:67], v[66:67], v[84:85] op_sel_hi:[1,0]
	v_mul_f32_e32 v85, 0x3d372713, v65
	v_mul_f32_e32 v75, v75, v92
	v_fmac_f32_e32 v76, v93, v93
	v_mul_f32_e32 v85, v65, v85
	v_add_f32_e32 v76, v76, v77
	v_fma_f32 v77, v79, v91, v75
	v_fma_f32 v85, v65, v85, v65
	v_mul_f32_e32 v74, v79, v91
	v_add_f32_e32 v77, v77, v73
	v_mul_f32_e32 v73, v75, v75
	v_mul_f32_e32 v85, 0x3f4c422a, v85
	v_fmac_f32_e32 v73, v74, v74
	v_mul_f32_e32 v85, 0xc038aa3b, v85
	v_add_f32_e32 v76, v73, v76
	v_cvt_pk_bf16_f32 v72, v89, v72
	v_cvt_pk_bf16_f32 v73, v93, v74
	v_cvt_pk_bf16_f32 v74, v86, v88
	v_exp_f32_e32 v85, v85
	v_mul_f32_e32 v87, 0x3d372713, v70
	v_mul_f32_e32 v88, 0x3d372713, v66
	v_mul_f32_e32 v87, v70, v87
	v_mul_f32_e32 v88, v66, v88
	v_fma_f32 v87, v70, v87, v70
	v_fma_f32 v88, v66, v88, v66
	v_mul_f32_e32 v79, 0x3d372713, v64
	v_mul_f32_e32 v87, 0x3f4c422a, v87
	v_mul_f32_e32 v88, 0x3f4c422a, v88
	v_mul_f32_e32 v78, 0x3d372713, v68
	v_mul_f32_e32 v79, v64, v79
	v_add_f32_e32 v85, 1.0, v85
	v_mul_f32_e32 v87, 0xc038aa3b, v87
	v_mul_f32_e32 v88, 0xc038aa3b, v88
	v_mul_f32_e32 v78, v68, v78
	v_fma_f32 v79, v64, v79, v64
	v_mul_f32_e32 v84, 0x3d372713, v69
	v_rcp_f32_e32 v85, v85
	v_exp_f32_e32 v87, v87
	v_exp_f32_e32 v88, v88
	v_mul_f32_e32 v89, 0x3d372713, v67
	v_fma_f32 v78, v68, v78, v68
	v_mul_f32_e32 v79, 0x3f4c422a, v79
	v_mul_f32_e32 v84, v69, v84
	v_mul_f32_e32 v89, v67, v89
	v_mul_f32_e32 v78, 0x3f4c422a, v78
	v_mul_f32_e32 v79, 0xc038aa3b, v79
	v_fma_f32 v84, v69, v84, v69
	v_fma_f32 v89, v67, v89, v67
	v_mul_f32_e32 v78, 0xc038aa3b, v78
	v_exp_f32_e32 v79, v79
	v_mul_f32_e32 v84, 0x3f4c422a, v84
	v_mul_f32_e32 v89, 0x3f4c422a, v89
	v_exp_f32_e32 v78, v78
	v_mul_f32_e32 v84, 0xc038aa3b, v84
	v_mul_f32_e32 v85, v65, v85
	v_add_f32_e32 v65, 1.0, v87
	v_add_f32_e32 v87, 1.0, v88
	v_mul_f32_e32 v88, 0x3d372713, v71
	v_mul_f32_e32 v89, 0xc038aa3b, v89
	v_exp_f32_e32 v84, v84
	v_mul_f32_e32 v88, v71, v88
	v_exp_f32_e32 v89, v89
	v_fma_f32 v88, v71, v88, v71
	v_add_f32_e32 v79, 1.0, v79
	v_mul_f32_e32 v88, 0x3f4c422a, v88
	v_add_f32_e32 v78, 1.0, v78
	v_rcp_f32_e32 v79, v79
	v_mul_f32_e32 v88, 0xc038aa3b, v88
	v_rcp_f32_e32 v78, v78
	v_add_f32_e32 v84, 1.0, v84
	v_exp_f32_e32 v88, v88
	v_rcp_f32_e32 v87, v87
	v_add_f32_e32 v89, 1.0, v89
	v_rcp_f32_e32 v84, v84
	v_rcp_f32_e32 v89, v89
	v_rcp_f32_e32 v65, v65
	v_mul_f32_e32 v79, v64, v79
	v_add_f32_e32 v88, 1.0, v88
	v_mul_f32_e32 v87, v66, v87
	v_fma_f32 v66, v68, v78, v79
	v_mul_f32_e32 v86, v68, v78
	v_rcp_f32_e32 v88, v88
	v_mul_f32_e32 v89, v67, v89
	v_add_f32_e32 v66, v66, v77
	v_mul_f32_e32 v67, v79, v79
	v_fma_f32 v68, v69, v84, v85
	v_cvt_pk_bf16_f32 v75, v90, v75
	v_mul_f32_e32 v64, v69, v84
	v_mul_f32_e32 v90, v70, v65
	v_fmac_f32_e32 v67, v86, v86
	v_add_f32_e32 v66, v68, v66
	v_mul_f32_e32 v68, v85, v85
	v_fma_f32 v65, v70, v65, v87
	v_add_f32_e32 v67, v67, v76
	v_fmac_f32_e32 v68, v64, v64
	v_add_f32_e32 v65, v65, v66
	v_mul_f32_e32 v66, v87, v87
	v_add_f32_e32 v67, v68, v67
	v_fmac_f32_e32 v66, v90, v90
	v_add_f32_e32 v66, v66, v67
	v_fma_f32 v67, v71, v88, v89
	v_mul_f32_e32 v91, v71, v88
	v_add_f32_e32 v65, v67, v65
	v_mul_f32_e32 v67, v89, v89
	v_fmac_f32_e32 v67, v91, v91
	v_add_f32_e32 v66, v67, v66
	v_mov_b32_e32 v69, v65
	s_nop 1
	v_permlane16_swap_b32_e32 v69, v65
	v_mov_b32_e32 v67, v66
	s_nop 1
	v_permlane16_swap_b32_e32 v67, v66
	v_lshl_add_u64 v[82:83], s[70:71], 0, v[82:83]
	v_lshl_add_u64 v[82:83], v[160:161], 1, v[82:83]
	global_store_dwordx4 v[82:83], v[72:75], off nt
	v_cvt_pk_bf16_f32 v68, v86, v64
	s_waitcnt lgkmcnt(0)
	v_add_f32_e32 v64, v65, v69
	v_add_f32_e32 v66, v66, v67
	v_mov_b32_e32 v65, v64
	s_nop 1
	v_permlane32_swap_b32_e32 v65, v64
	v_mov_b32_e32 v67, v66
	s_nop 1
	v_permlane32_swap_b32_e32 v67, v66
	v_cvt_pk_bf16_f32 v69, v90, v91
	v_cvt_pk_bf16_f32 v70, v79, v85
	v_cvt_pk_bf16_f32 v71, v87, v89
	global_store_dwordx4 v[82:83], v[68:71], off offset:256 nt
	s_and_saveexec_b64 s[6:7], s[58:59]
	s_cbranch_execz .LBB0_579
	s_waitcnt lgkmcnt(0)
	v_add_f32_e32 v66, v66, v67
	v_add_f32_e32 v67, v64, v65
	s_lshl_b32 s4, s95, 2
	v_lshlrev_b64 v[64:65], 7, v[80:81]
	s_add_i32 s38, s4, -16
	v_lshl_add_u64 v[64:65], s[72:73], 0, v[64:65]
	v_lshl_add_u64 v[64:65], s[38:39], 2, v[64:65]
	s_lshl_b32 s38, s8, 2
	v_lshl_add_u64 v[64:65], v[64:65], 0, s[38:39]
	global_store_dword v[64:65], v67, off
	global_store_dword v[64:65], v66, off offset:64
.LBB0_579:
	s_or_b64 exec, exec, s[6:7]
	v_add_u32_e32 v64, 0x80, v158
	s_mov_b64 s[6:7], -1
	s_and_b64 vcc, exec, s[56:57]
	s_waitcnt lgkmcnt(0)
	v_ashrrev_i32_e32 v65, 31, v64
	s_cbranch_vccz .LBB0_581
	v_lshlrev_b64 v[66:67], 6, v[64:65]
	v_lshl_add_u64 v[66:67], s[48:49], 0, v[66:67]
	v_lshl_add_u64 v[66:67], v[66:67], 0, v[140:141]
	flat_load_dwordx4 v[66:69], v[66:67]
	s_mov_b64 s[6:7], 0
	s_waitcnt vmcnt(0) lgkmcnt(0)
	v_mov_b32_e32 v70, v67
	v_mov_b32_e32 v71, v68
	v_mov_b32_e32 v67, v69
	v_pk_add_f32 v[66:67], v[70:71], v[66:67]
	s_nop 0
	v_add_f32_e32 v66, v66, v67
	v_mov_b32_e32 v67, v66
	s_nop 1
	v_permlane16_swap_b32_e32 v67, v66
	s_waitcnt lgkmcnt(0)
	v_add_f32_e32 v66, v66, v67
	v_mov_b32_e32 v67, v66
	s_nop 1
	v_permlane32_swap_b32_e32 v67, v66
	s_waitcnt lgkmcnt(0)
	v_add_f32_e32 v66, v66, v67
	v_fmamk_f32 v66, v66, 0x3a800000, v250
	v_rsq_f32_e32 v68, v66

.LBB0_583:
	s_waitcnt lgkmcnt(0)
	v_pk_mul_f32 v[60:61], v[60:61], v[68:69] op_sel_hi:[1,0]
	v_lshlrev_b64 v[66:67], 12, v[64:65]
	v_mul_f32_e32 v69, 0x3d372713, v60
	v_mul_f32_e32 v69, v60, v69
	v_fma_f32 v69, v60, v69, v60
	v_mul_f32_e32 v69, 0x3f4c422a, v69
	v_mul_f32_e32 v69, 0xc038aa3b, v69
	v_exp_f32_e32 v69, v69
	v_mul_f32_e32 v71, 0x3d372713, v61
	v_mul_f32_e32 v71, v61, v71
	v_fma_f32 v71, v61, v71, v61
	v_pk_mul_f32 v[56:57], v[56:57], v[68:69] op_sel_hi:[1,0]
	v_pk_mul_f32 v[62:63], v[62:63], v[68:69] op_sel_hi:[1,0]
	v_mul_f32_e32 v72, 0x3d372713, v57
	v_mul_f32_e32 v72, v57, v72
	v_fma_f32 v72, v57, v72, v57
	v_mul_f32_e32 v72, 0x3f4c422a, v72
	v_pk_mul_f32 v[58:59], v[58:59], v[68:69] op_sel_hi:[1,0]
	v_mul_f32_e32 v72, 0xc038aa3b, v72
	v_exp_f32_e32 v72, v72
	v_mul_f32_e32 v74, 0x3d372713, v62
	v_mul_f32_e32 v75, 0x3d372713, v58
	v_mul_f32_e32 v74, v62, v74
	v_mul_f32_e32 v75, v58, v75
	v_mul_f32_e32 v70, 0x3d372713, v56
	v_fma_f32 v74, v62, v74, v62
	v_fma_f32 v75, v58, v75, v58
	v_mul_f32_e32 v70, v56, v70
	v_mul_f32_e32 v74, 0x3f4c422a, v74
	v_mul_f32_e32 v75, 0x3f4c422a, v75
	v_fma_f32 v70, v56, v70, v56
	v_add_f32_e32 v72, 1.0, v72
	v_mul_f32_e32 v74, 0xc038aa3b, v74
	v_mul_f32_e32 v75, 0xc038aa3b, v75
	v_mul_f32_e32 v70, 0x3f4c422a, v70
	v_rcp_f32_e32 v72, v72
	v_exp_f32_e32 v74, v74
	v_exp_f32_e32 v75, v75
	v_mul_f32_e32 v70, 0xc038aa3b, v70
	v_exp_f32_e32 v70, v70
	v_mul_f32_e32 v71, 0x3f4c422a, v71
	v_mul_f32_e32 v71, 0xc038aa3b, v71
	v_mul_f32_e32 v76, 0x3d372713, v59
	v_exp_f32_e32 v71, v71
	v_mul_f32_e32 v72, v57, v72
	v_add_f32_e32 v57, 1.0, v74
	v_add_f32_e32 v74, 1.0, v75
	v_mul_f32_e32 v75, 0x3d372713, v63
	v_mul_f32_e32 v76, v59, v76
	v_mul_f32_e32 v75, v63, v75
	v_fma_f32 v76, v59, v76, v59
	v_add_f32_e32 v70, 1.0, v70
	v_fma_f32 v75, v63, v75, v63
	v_mul_f32_e32 v76, 0x3f4c422a, v76
	v_add_f32_e32 v69, 1.0, v69
	v_rcp_f32_e32 v70, v70
	v_mul_f32_e32 v75, 0x3f4c422a, v75
	v_mul_f32_e32 v76, 0xc038aa3b, v76
	v_rcp_f32_e32 v69, v69
	v_add_f32_e32 v71, 1.0, v71
	v_mul_f32_e32 v75, 0xc038aa3b, v75
	v_exp_f32_e32 v76, v76
	v_rcp_f32_e32 v71, v71
	v_exp_f32_e32 v75, v75
	v_rcp_f32_e32 v74, v74
	v_mul_f32_e32 v70, v56, v70
	v_rcp_f32_e32 v57, v57
	v_mul_f32_e32 v73, v60, v69
	v_add_f32_e32 v76, 1.0, v76
	v_fma_f32 v60, v60, v69, v70
	v_mul_f32_e32 v56, v61, v71
	v_add_f32_e32 v75, 1.0, v75
	v_rcp_f32_e32 v76, v76
	v_add_f32_e32 v60, 0, v60
	v_mul_f32_e32 v69, v70, v70
	v_fma_f32 v61, v61, v71, v72
	v_rcp_f32_e32 v75, v75
	v_mul_f32_e32 v74, v58, v74
	v_fmac_f32_e32 v69, v73, v73
	v_add_f32_e32 v60, v61, v60
	v_mul_f32_e32 v61, v72, v72
	v_mul_f32_e32 v77, v62, v57
	v_fmac_f32_e32 v61, v56, v56
	v_fma_f32 v57, v62, v57, v74
	v_pk_mul_f32 v[48:49], v[48:49], v[68:69] op_sel_hi:[1,0]
	v_add_f32_e32 v61, v69, v61
	v_add_f32_e32 v57, v57, v60
	v_mul_f32_e32 v60, v74, v74
	v_pk_mul_f32 v[52:53], v[52:53], v[68:69] op_sel_hi:[1,0]
	v_pk_mul_f32 v[54:55], v[54:55], v[68:69] op_sel_hi:[1,0]
	v_pk_mul_f32 v[50:51], v[50:51], v[68:69] op_sel_hi:[1,0]
	v_mul_f32_e32 v69, 0x3d372713, v49
	v_mul_f32_e32 v59, v59, v76
	v_fmac_f32_e32 v60, v77, v77
	v_mul_f32_e32 v69, v49, v69
	v_add_f32_e32 v60, v60, v61
	v_fma_f32 v61, v63, v75, v59
	v_fma_f32 v69, v49, v69, v49
	v_mul_f32_e32 v58, v63, v75
	v_add_f32_e32 v61, v61, v57
	v_mul_f32_e32 v57, v59, v59
	v_mul_f32_e32 v69, 0x3f4c422a, v69
	v_fmac_f32_e32 v57, v58, v58
	v_mul_f32_e32 v69, 0xc038aa3b, v69
	v_add_f32_e32 v60, v57, v60
	v_cvt_pk_bf16_f32 v56, v73, v56
	v_cvt_pk_bf16_f32 v57, v77, v58
	v_cvt_pk_bf16_f32 v58, v70, v72
	v_exp_f32_e32 v69, v69
	v_mul_f32_e32 v71, 0x3d372713, v54
	v_mul_f32_e32 v72, 0x3d372713, v50
	v_mul_f32_e32 v71, v54, v71
	v_mul_f32_e32 v72, v50, v72
	v_fma_f32 v71, v54, v71, v54
	v_fma_f32 v72, v50, v72, v50
	v_mul_f32_e32 v63, 0x3d372713, v48
	v_mul_f32_e32 v71, 0x3f4c422a, v71
	v_mul_f32_e32 v72, 0x3f4c422a, v72
	v_mul_f32_e32 v62, 0x3d372713, v52
	v_mul_f32_e32 v63, v48, v63
	v_add_f32_e32 v69, 1.0, v69
	v_mul_f32_e32 v71, 0xc038aa3b, v71
	v_mul_f32_e32 v72, 0xc038aa3b, v72
	v_mul_f32_e32 v62, v52, v62
	v_fma_f32 v63, v48, v63, v48
	v_mul_f32_e32 v68, 0x3d372713, v53
	v_rcp_f32_e32 v69, v69
	v_exp_f32_e32 v71, v71
	v_exp_f32_e32 v72, v72
	v_mul_f32_e32 v73, 0x3d372713, v51
	v_fma_f32 v62, v52, v62, v52
	v_mul_f32_e32 v63, 0x3f4c422a, v63
	v_mul_f32_e32 v68, v53, v68
	v_mul_f32_e32 v73, v51, v73
	v_mul_f32_e32 v62, 0x3f4c422a, v62
	v_mul_f32_e32 v63, 0xc038aa3b, v63
	v_fma_f32 v68, v53, v68, v53
	v_fma_f32 v73, v51, v73, v51
	v_mul_f32_e32 v62, 0xc038aa3b, v62
	v_exp_f32_e32 v63, v63
	v_mul_f32_e32 v68, 0x3f4c422a, v68
	v_mul_f32_e32 v73, 0x3f4c422a, v73
	v_exp_f32_e32 v62, v62
	v_mul_f32_e32 v68, 0xc038aa3b, v68
	v_mul_f32_e32 v69, v49, v69
	v_add_f32_e32 v49, 1.0, v71
	v_add_f32_e32 v71, 1.0, v72
	v_mul_f32_e32 v72, 0x3d372713, v55
	v_mul_f32_e32 v73, 0xc038aa3b, v73
	v_exp_f32_e32 v68, v68
	v_mul_f32_e32 v72, v55, v72
	v_exp_f32_e32 v73, v73
	v_fma_f32 v72, v55, v72, v55
	v_add_f32_e32 v63, 1.0, v63
	v_mul_f32_e32 v72, 0x3f4c422a, v72
	v_add_f32_e32 v62, 1.0, v62
	v_rcp_f32_e32 v63, v63
	v_mul_f32_e32 v72, 0xc038aa3b, v72
	v_rcp_f32_e32 v62, v62
	v_add_f32_e32 v68, 1.0, v68
	v_exp_f32_e32 v72, v72
	v_rcp_f32_e32 v71, v71
	v_add_f32_e32 v73, 1.0, v73
	v_rcp_f32_e32 v68, v68
	v_rcp_f32_e32 v73, v73
	v_rcp_f32_e32 v49, v49
	v_mul_f32_e32 v63, v48, v63
	v_add_f32_e32 v72, 1.0, v72
	v_mul_f32_e32 v71, v50, v71
	v_fma_f32 v50, v52, v62, v63
	v_mul_f32_e32 v70, v52, v62
	v_rcp_f32_e32 v72, v72
	v_mul_f32_e32 v73, v51, v73
	v_add_f32_e32 v50, v50, v61
	v_mul_f32_e32 v51, v63, v63
	v_fma_f32 v52, v53, v68, v69
	v_cvt_pk_bf16_f32 v59, v74, v59
	v_mul_f32_e32 v48, v53, v68
	v_mul_f32_e32 v74, v54, v49
	v_fmac_f32_e32 v51, v70, v70
	v_add_f32_e32 v50, v52, v50
	v_mul_f32_e32 v52, v69, v69
	v_fma_f32 v49, v54, v49, v71
	v_add_f32_e32 v51, v51, v60
	v_fmac_f32_e32 v52, v48, v48
	v_add_f32_e32 v49, v49, v50
	v_mul_f32_e32 v50, v71, v71
	v_add_f32_e32 v51, v52, v51
	v_fmac_f32_e32 v50, v74, v74
	v_add_f32_e32 v50, v50, v51
	v_fma_f32 v51, v55, v72, v73
	v_mul_f32_e32 v75, v55, v72
	v_add_f32_e32 v49, v51, v49
	v_mul_f32_e32 v51, v73, v73
	v_fmac_f32_e32 v51, v75, v75
	v_add_f32_e32 v50, v51, v50
	v_mov_b32_e32 v53, v49
	s_nop 1
	v_permlane16_swap_b32_e32 v53, v49
	v_mov_b32_e32 v51, v50
	s_nop 1
	v_permlane16_swap_b32_e32 v51, v50
	v_lshl_add_u64 v[66:67], s[70:71], 0, v[66:67]
	v_lshl_add_u64 v[66:67], v[160:161], 1, v[66:67]
	global_store_dwordx4 v[66:67], v[56:59], off nt
	v_cvt_pk_bf16_f32 v52, v70, v48
	s_waitcnt lgkmcnt(0)
	v_add_f32_e32 v48, v49, v53
	v_add_f32_e32 v50, v50, v51
	v_mov_b32_e32 v49, v48
	s_nop 1
	v_permlane32_swap_b32_e32 v49, v48
	v_mov_b32_e32 v51, v50
	s_nop 1
	v_permlane32_swap_b32_e32 v51, v50
	v_cvt_pk_bf16_f32 v53, v74, v75
	v_cvt_pk_bf16_f32 v54, v63, v69
	v_cvt_pk_bf16_f32 v55, v71, v73
	global_store_dwordx4 v[66:67], v[52:55], off offset:256 nt
	s_and_saveexec_b64 s[6:7], s[58:59]
	s_cbranch_execz .LBB0_585
	s_waitcnt lgkmcnt(0)
	v_add_f32_e32 v50, v50, v51
	v_add_f32_e32 v51, v48, v49
	s_lshl_b32 s4, s95, 2
	v_lshlrev_b64 v[48:49], 7, v[64:65]
	s_add_i32 s38, s4, -16
	v_lshl_add_u64 v[48:49], s[72:73], 0, v[48:49]
	v_lshl_add_u64 v[48:49], s[38:39], 2, v[48:49]
	s_lshl_b32 s38, s8, 2
	v_lshl_add_u64 v[48:49], v[48:49], 0, s[38:39]
	global_store_dword v[48:49], v51, off
	global_store_dword v[48:49], v50, off offset:64
.LBB0_585:
	s_or_b64 exec, exec, s[6:7]
	v_add_u32_e32 v48, 0x90, v158
	s_mov_b64 s[6:7], -1
	s_and_b64 vcc, exec, s[56:57]
	s_waitcnt lgkmcnt(0)
	v_ashrrev_i32_e32 v49, 31, v48
	s_cbranch_vccz .LBB0_587
	v_lshlrev_b64 v[50:51], 6, v[48:49]
	v_lshl_add_u64 v[50:51], s[48:49], 0, v[50:51]
	v_lshl_add_u64 v[50:51], v[50:51], 0, v[140:141]
	flat_load_dwordx4 v[50:53], v[50:51]
	s_mov_b64 s[6:7], 0
	s_waitcnt vmcnt(0) lgkmcnt(0)
	v_mov_b32_e32 v54, v51
	v_mov_b32_e32 v55, v52
	v_mov_b32_e32 v51, v53
	v_pk_add_f32 v[50:51], v[54:55], v[50:51]
	s_nop 0
	v_add_f32_e32 v50, v50, v51
	v_mov_b32_e32 v51, v50
	s_nop 1
	v_permlane16_swap_b32_e32 v51, v50
	s_waitcnt lgkmcnt(0)
	v_add_f32_e32 v50, v50, v51
	v_mov_b32_e32 v51, v50
	s_nop 1
	v_permlane32_swap_b32_e32 v51, v50
	s_waitcnt lgkmcnt(0)
	v_add_f32_e32 v50, v50, v51
	v_fmamk_f32 v50, v50, 0x3a800000, v250
	v_rsq_f32_e32 v52, v50

.LBB0_589:
	s_waitcnt lgkmcnt(0)
	v_pk_mul_f32 v[44:45], v[44:45], v[52:53] op_sel_hi:[1,0]
	v_lshlrev_b64 v[50:51], 12, v[48:49]
	v_mul_f32_e32 v53, 0x3d372713, v44
	v_mul_f32_e32 v53, v44, v53
	v_fma_f32 v53, v44, v53, v44
	v_mul_f32_e32 v53, 0x3f4c422a, v53
	v_mul_f32_e32 v53, 0xc038aa3b, v53
	v_exp_f32_e32 v53, v53
	v_mul_f32_e32 v55, 0x3d372713, v45
	v_mul_f32_e32 v55, v45, v55
	v_fma_f32 v55, v45, v55, v45
	v_pk_mul_f32 v[40:41], v[40:41], v[52:53] op_sel_hi:[1,0]
	v_pk_mul_f32 v[46:47], v[46:47], v[52:53] op_sel_hi:[1,0]
	v_mul_f32_e32 v56, 0x3d372713, v41
	v_mul_f32_e32 v56, v41, v56
	v_fma_f32 v56, v41, v56, v41
	v_mul_f32_e32 v56, 0x3f4c422a, v56
	v_pk_mul_f32 v[42:43], v[42:43], v[52:53] op_sel_hi:[1,0]
	v_mul_f32_e32 v56, 0xc038aa3b, v56
	v_exp_f32_e32 v56, v56
	v_mul_f32_e32 v58, 0x3d372713, v46
	v_mul_f32_e32 v59, 0x3d372713, v42
	v_mul_f32_e32 v58, v46, v58
	v_mul_f32_e32 v59, v42, v59
	v_mul_f32_e32 v54, 0x3d372713, v40
	v_fma_f32 v58, v46, v58, v46
	v_fma_f32 v59, v42, v59, v42
	v_mul_f32_e32 v54, v40, v54
	v_mul_f32_e32 v58, 0x3f4c422a, v58
	v_mul_f32_e32 v59, 0x3f4c422a, v59
	v_fma_f32 v54, v40, v54, v40
	v_add_f32_e32 v56, 1.0, v56
	v_mul_f32_e32 v58, 0xc038aa3b, v58
	v_mul_f32_e32 v59, 0xc038aa3b, v59
	v_mul_f32_e32 v54, 0x3f4c422a, v54
	v_rcp_f32_e32 v56, v56
	v_exp_f32_e32 v58, v58
	v_exp_f32_e32 v59, v59
	v_mul_f32_e32 v54, 0xc038aa3b, v54
	v_exp_f32_e32 v54, v54
	v_mul_f32_e32 v55, 0x3f4c422a, v55
	v_mul_f32_e32 v55, 0xc038aa3b, v55
	v_mul_f32_e32 v60, 0x3d372713, v43
	v_exp_f32_e32 v55, v55
	v_mul_f32_e32 v56, v41, v56
	v_add_f32_e32 v41, 1.0, v58
	v_add_f32_e32 v58, 1.0, v59
	v_mul_f32_e32 v59, 0x3d372713, v47
	v_mul_f32_e32 v60, v43, v60
	v_mul_f32_e32 v59, v47, v59
	v_fma_f32 v60, v43, v60, v43
	v_add_f32_e32 v54, 1.0, v54
	v_fma_f32 v59, v47, v59, v47
	v_mul_f32_e32 v60, 0x3f4c422a, v60
	v_add_f32_e32 v53, 1.0, v53
	v_rcp_f32_e32 v54, v54
	v_mul_f32_e32 v59, 0x3f4c422a, v59
	v_mul_f32_e32 v60, 0xc038aa3b, v60
	v_rcp_f32_e32 v53, v53
	v_add_f32_e32 v55, 1.0, v55
	v_mul_f32_e32 v59, 0xc038aa3b, v59
	v_exp_f32_e32 v60, v60
	v_rcp_f32_e32 v55, v55
	v_exp_f32_e32 v59, v59
	v_rcp_f32_e32 v58, v58
	v_mul_f32_e32 v54, v40, v54
	v_rcp_f32_e32 v41, v41
	v_mul_f32_e32 v57, v44, v53
	v_add_f32_e32 v60, 1.0, v60
	v_fma_f32 v44, v44, v53, v54
	v_mul_f32_e32 v40, v45, v55
	v_add_f32_e32 v59, 1.0, v59
	v_rcp_f32_e32 v60, v60
	v_add_f32_e32 v44, 0, v44
	v_mul_f32_e32 v53, v54, v54
	v_fma_f32 v45, v45, v55, v56
	v_rcp_f32_e32 v59, v59
	v_mul_f32_e32 v58, v42, v58
	v_fmac_f32_e32 v53, v57, v57
	v_add_f32_e32 v44, v45, v44
	v_mul_f32_e32 v45, v56, v56
	v_mul_f32_e32 v61, v46, v41
	v_fmac_f32_e32 v45, v40, v40
	v_fma_f32 v41, v46, v41, v58
	v_pk_mul_f32 v[32:33], v[32:33], v[52:53] op_sel_hi:[1,0]
	v_add_f32_e32 v45, v53, v45
	v_add_f32_e32 v41, v41, v44
	v_mul_f32_e32 v44, v58, v58
	v_pk_mul_f32 v[36:37], v[36:37], v[52:53] op_sel_hi:[1,0]
	v_pk_mul_f32 v[38:39], v[38:39], v[52:53] op_sel_hi:[1,0]
	v_pk_mul_f32 v[34:35], v[34:35], v[52:53] op_sel_hi:[1,0]
	v_mul_f32_e32 v53, 0x3d372713, v33
	v_mul_f32_e32 v43, v43, v60
	v_fmac_f32_e32 v44, v61, v61
	v_mul_f32_e32 v53, v33, v53
	v_add_f32_e32 v44, v44, v45
	v_fma_f32 v45, v47, v59, v43
	v_fma_f32 v53, v33, v53, v33
	v_mul_f32_e32 v42, v47, v59
	v_add_f32_e32 v45, v45, v41
	v_mul_f32_e32 v41, v43, v43
	v_mul_f32_e32 v53, 0x3f4c422a, v53
	v_fmac_f32_e32 v41, v42, v42
	v_mul_f32_e32 v53, 0xc038aa3b, v53
	v_add_f32_e32 v44, v41, v44
	v_cvt_pk_bf16_f32 v40, v57, v40
	v_cvt_pk_bf16_f32 v41, v61, v42
	v_cvt_pk_bf16_f32 v42, v54, v56
	v_exp_f32_e32 v53, v53
	v_mul_f32_e32 v55, 0x3d372713, v38
	v_mul_f32_e32 v56, 0x3d372713, v34
	v_mul_f32_e32 v55, v38, v55
	v_mul_f32_e32 v56, v34, v56
	v_fma_f32 v55, v38, v55, v38
	v_fma_f32 v56, v34, v56, v34
	v_mul_f32_e32 v47, 0x3d372713, v32
	v_mul_f32_e32 v55, 0x3f4c422a, v55
	v_mul_f32_e32 v56, 0x3f4c422a, v56
	v_mul_f32_e32 v46, 0x3d372713, v36
	v_mul_f32_e32 v47, v32, v47
	v_add_f32_e32 v53, 1.0, v53
	v_mul_f32_e32 v55, 0xc038aa3b, v55
	v_mul_f32_e32 v56, 0xc038aa3b, v56
	v_mul_f32_e32 v46, v36, v46
	v_fma_f32 v47, v32, v47, v32
	v_mul_f32_e32 v52, 0x3d372713, v37
	v_rcp_f32_e32 v53, v53
	v_exp_f32_e32 v55, v55
	v_exp_f32_e32 v56, v56
	v_mul_f32_e32 v57, 0x3d372713, v35
	v_fma_f32 v46, v36, v46, v36
	v_mul_f32_e32 v47, 0x3f4c422a, v47
	v_mul_f32_e32 v52, v37, v52
	v_mul_f32_e32 v57, v35, v57
	v_mul_f32_e32 v46, 0x3f4c422a, v46
	v_mul_f32_e32 v47, 0xc038aa3b, v47
	v_fma_f32 v52, v37, v52, v37
	v_fma_f32 v57, v35, v57, v35
	v_mul_f32_e32 v46, 0xc038aa3b, v46
	v_exp_f32_e32 v47, v47
	v_mul_f32_e32 v52, 0x3f4c422a, v52
	v_mul_f32_e32 v57, 0x3f4c422a, v57
	v_exp_f32_e32 v46, v46
	v_mul_f32_e32 v52, 0xc038aa3b, v52
	v_mul_f32_e32 v53, v33, v53
	v_add_f32_e32 v33, 1.0, v55
	v_add_f32_e32 v55, 1.0, v56
	v_mul_f32_e32 v56, 0x3d372713, v39
	v_mul_f32_e32 v57, 0xc038aa3b, v57
	v_exp_f32_e32 v52, v52
	v_mul_f32_e32 v56, v39, v56
	v_exp_f32_e32 v57, v57
	v_fma_f32 v56, v39, v56, v39
	v_add_f32_e32 v47, 1.0, v47
	v_mul_f32_e32 v56, 0x3f4c422a, v56
	v_add_f32_e32 v46, 1.0, v46
	v_rcp_f32_e32 v47, v47
	v_mul_f32_e32 v56, 0xc038aa3b, v56
	v_rcp_f32_e32 v46, v46
	v_add_f32_e32 v52, 1.0, v52
	v_exp_f32_e32 v56, v56
	v_rcp_f32_e32 v55, v55
	v_add_f32_e32 v57, 1.0, v57
	v_rcp_f32_e32 v52, v52
	v_rcp_f32_e32 v57, v57
	v_rcp_f32_e32 v33, v33
	v_mul_f32_e32 v47, v32, v47
	v_add_f32_e32 v56, 1.0, v56
	v_mul_f32_e32 v55, v34, v55
	v_fma_f32 v34, v36, v46, v47
	v_mul_f32_e32 v54, v36, v46
	v_rcp_f32_e32 v56, v56
	v_mul_f32_e32 v57, v35, v57
	v_add_f32_e32 v34, v34, v45
	v_mul_f32_e32 v35, v47, v47
	v_fma_f32 v36, v37, v52, v53
	v_cvt_pk_bf16_f32 v43, v58, v43
	v_mul_f32_e32 v32, v37, v52
	v_mul_f32_e32 v58, v38, v33
	v_fmac_f32_e32 v35, v54, v54
	v_add_f32_e32 v34, v36, v34
	v_mul_f32_e32 v36, v53, v53
	v_fma_f32 v33, v38, v33, v55
	v_add_f32_e32 v35, v35, v44
	v_fmac_f32_e32 v36, v32, v32
	v_add_f32_e32 v33, v33, v34
	v_mul_f32_e32 v34, v55, v55
	v_add_f32_e32 v35, v36, v35
	v_fmac_f32_e32 v34, v58, v58
	v_add_f32_e32 v34, v34, v35
	v_fma_f32 v35, v39, v56, v57
	v_mul_f32_e32 v59, v39, v56
	v_add_f32_e32 v33, v35, v33
	v_mul_f32_e32 v35, v57, v57
	v_fmac_f32_e32 v35, v59, v59
	v_add_f32_e32 v34, v35, v34
	v_mov_b32_e32 v37, v33
	s_nop 1
	v_permlane16_swap_b32_e32 v37, v33
	v_mov_b32_e32 v35, v34
	s_nop 1
	v_permlane16_swap_b32_e32 v35, v34
	v_lshl_add_u64 v[50:51], s[70:71], 0, v[50:51]
	v_lshl_add_u64 v[50:51], v[160:161], 1, v[50:51]
	global_store_dwordx4 v[50:51], v[40:43], off nt
	v_cvt_pk_bf16_f32 v36, v54, v32
	s_waitcnt lgkmcnt(0)
	v_add_f32_e32 v32, v33, v37
	v_add_f32_e32 v34, v34, v35
	v_mov_b32_e32 v33, v32
	s_nop 1
	v_permlane32_swap_b32_e32 v33, v32
	v_mov_b32_e32 v35, v34
	s_nop 1
	v_permlane32_swap_b32_e32 v35, v34
	v_cvt_pk_bf16_f32 v37, v58, v59
	v_cvt_pk_bf16_f32 v38, v47, v53
	v_cvt_pk_bf16_f32 v39, v55, v57
	global_store_dwordx4 v[50:51], v[36:39], off offset:256 nt
	s_and_saveexec_b64 s[6:7], s[58:59]
	s_cbranch_execz .LBB0_591
	s_waitcnt lgkmcnt(0)
	v_add_f32_e32 v34, v34, v35
	v_add_f32_e32 v35, v32, v33
	s_lshl_b32 s4, s95, 2
	v_lshlrev_b64 v[32:33], 7, v[48:49]
	s_add_i32 s38, s4, -16
	v_lshl_add_u64 v[32:33], s[72:73], 0, v[32:33]
	v_lshl_add_u64 v[32:33], s[38:39], 2, v[32:33]
	s_lshl_b32 s38, s8, 2
	v_lshl_add_u64 v[32:33], v[32:33], 0, s[38:39]
	global_store_dword v[32:33], v35, off
	global_store_dword v[32:33], v34, off offset:64
.LBB0_591:
	s_or_b64 exec, exec, s[6:7]
	v_add_u32_e32 v32, 0xa0, v158
	s_mov_b64 s[6:7], -1
	s_and_b64 vcc, exec, s[56:57]
	s_waitcnt lgkmcnt(0)
	v_ashrrev_i32_e32 v33, 31, v32
	s_cbranch_vccz .LBB0_593
	v_lshlrev_b64 v[34:35], 6, v[32:33]
	v_lshl_add_u64 v[34:35], s[48:49], 0, v[34:35]
	v_lshl_add_u64 v[34:35], v[34:35], 0, v[140:141]
	flat_load_dwordx4 v[34:37], v[34:35]
	s_mov_b64 s[6:7], 0
	s_waitcnt vmcnt(0) lgkmcnt(0)
	v_mov_b32_e32 v38, v35
	v_mov_b32_e32 v39, v36
	v_mov_b32_e32 v35, v37
	v_pk_add_f32 v[34:35], v[38:39], v[34:35]
	s_nop 0
	v_add_f32_e32 v34, v34, v35
	v_mov_b32_e32 v35, v34
	s_nop 1
	v_permlane16_swap_b32_e32 v35, v34
	s_waitcnt lgkmcnt(0)
	v_add_f32_e32 v34, v34, v35
	v_mov_b32_e32 v35, v34
	s_nop 1
	v_permlane32_swap_b32_e32 v35, v34
	s_waitcnt lgkmcnt(0)
	v_add_f32_e32 v34, v34, v35
	v_fmamk_f32 v34, v34, 0x3a800000, v250
	v_rsq_f32_e32 v36, v34

.LBB0_595:
	s_waitcnt lgkmcnt(0)
	v_pk_mul_f32 v[28:29], v[28:29], v[36:37] op_sel_hi:[1,0]
	v_lshlrev_b64 v[34:35], 12, v[32:33]
	v_mul_f32_e32 v37, 0x3d372713, v28
	v_mul_f32_e32 v37, v28, v37
	v_fma_f32 v37, v28, v37, v28
	v_mul_f32_e32 v37, 0x3f4c422a, v37
	v_mul_f32_e32 v37, 0xc038aa3b, v37
	v_exp_f32_e32 v37, v37
	v_mul_f32_e32 v39, 0x3d372713, v29
	v_mul_f32_e32 v39, v29, v39
	v_fma_f32 v39, v29, v39, v29
	v_pk_mul_f32 v[24:25], v[24:25], v[36:37] op_sel_hi:[1,0]
	v_pk_mul_f32 v[30:31], v[30:31], v[36:37] op_sel_hi:[1,0]
	v_mul_f32_e32 v40, 0x3d372713, v25
	v_mul_f32_e32 v40, v25, v40
	v_fma_f32 v40, v25, v40, v25
	v_mul_f32_e32 v40, 0x3f4c422a, v40
	v_pk_mul_f32 v[26:27], v[26:27], v[36:37] op_sel_hi:[1,0]
	v_mul_f32_e32 v40, 0xc038aa3b, v40
	v_exp_f32_e32 v40, v40
	v_mul_f32_e32 v42, 0x3d372713, v30
	v_mul_f32_e32 v43, 0x3d372713, v26
	v_mul_f32_e32 v42, v30, v42
	v_mul_f32_e32 v43, v26, v43
	v_mul_f32_e32 v38, 0x3d372713, v24
	v_fma_f32 v42, v30, v42, v30
	v_fma_f32 v43, v26, v43, v26
	v_mul_f32_e32 v38, v24, v38
	v_mul_f32_e32 v42, 0x3f4c422a, v42
	v_mul_f32_e32 v43, 0x3f4c422a, v43
	v_fma_f32 v38, v24, v38, v24
	v_add_f32_e32 v40, 1.0, v40
	v_mul_f32_e32 v42, 0xc038aa3b, v42
	v_mul_f32_e32 v43, 0xc038aa3b, v43
	v_mul_f32_e32 v38, 0x3f4c422a, v38
	v_rcp_f32_e32 v40, v40
	v_exp_f32_e32 v42, v42
	v_exp_f32_e32 v43, v43
	v_mul_f32_e32 v38, 0xc038aa3b, v38
	v_exp_f32_e32 v38, v38
	v_mul_f32_e32 v39, 0x3f4c422a, v39
	v_mul_f32_e32 v39, 0xc038aa3b, v39
	v_mul_f32_e32 v44, 0x3d372713, v27
	v_exp_f32_e32 v39, v39
	v_mul_f32_e32 v40, v25, v40
	v_add_f32_e32 v25, 1.0, v42
	v_add_f32_e32 v42, 1.0, v43
	v_mul_f32_e32 v43, 0x3d372713, v31
	v_mul_f32_e32 v44, v27, v44
	v_mul_f32_e32 v43, v31, v43
	v_fma_f32 v44, v27, v44, v27
	v_add_f32_e32 v38, 1.0, v38
	v_fma_f32 v43, v31, v43, v31
	v_mul_f32_e32 v44, 0x3f4c422a, v44
	v_add_f32_e32 v37, 1.0, v37
	v_rcp_f32_e32 v38, v38
	v_mul_f32_e32 v43, 0x3f4c422a, v43
	v_mul_f32_e32 v44, 0xc038aa3b, v44
	v_rcp_f32_e32 v37, v37
	v_add_f32_e32 v39, 1.0, v39
	v_mul_f32_e32 v43, 0xc038aa3b, v43
	v_exp_f32_e32 v44, v44
	v_rcp_f32_e32 v39, v39
	v_exp_f32_e32 v43, v43
	v_rcp_f32_e32 v42, v42
	v_mul_f32_e32 v38, v24, v38
	v_rcp_f32_e32 v25, v25
	v_mul_f32_e32 v41, v28, v37
	v_add_f32_e32 v44, 1.0, v44
	v_fma_f32 v28, v28, v37, v38
	v_mul_f32_e32 v24, v29, v39
	v_add_f32_e32 v43, 1.0, v43
	v_rcp_f32_e32 v44, v44
	v_add_f32_e32 v28, 0, v28
	v_mul_f32_e32 v37, v38, v38
	v_fma_f32 v29, v29, v39, v40
	v_rcp_f32_e32 v43, v43
	v_mul_f32_e32 v42, v26, v42
	v_fmac_f32_e32 v37, v41, v41
	v_add_f32_e32 v28, v29, v28
	v_mul_f32_e32 v29, v40, v40
	v_mul_f32_e32 v45, v30, v25
	v_fmac_f32_e32 v29, v24, v24
	v_fma_f32 v25, v30, v25, v42
	v_pk_mul_f32 v[16:17], v[16:17], v[36:37] op_sel_hi:[1,0]
	v_add_f32_e32 v29, v37, v29
	v_add_f32_e32 v25, v25, v28
	v_mul_f32_e32 v28, v42, v42
	v_pk_mul_f32 v[20:21], v[20:21], v[36:37] op_sel_hi:[1,0]
	v_pk_mul_f32 v[22:23], v[22:23], v[36:37] op_sel_hi:[1,0]
	v_pk_mul_f32 v[18:19], v[18:19], v[36:37] op_sel_hi:[1,0]
	v_mul_f32_e32 v37, 0x3d372713, v17
	v_mul_f32_e32 v27, v27, v44
	v_fmac_f32_e32 v28, v45, v45
	v_mul_f32_e32 v37, v17, v37
	v_add_f32_e32 v28, v28, v29
	v_fma_f32 v29, v31, v43, v27
	v_fma_f32 v37, v17, v37, v17
	v_mul_f32_e32 v26, v31, v43
	v_add_f32_e32 v29, v29, v25
	v_mul_f32_e32 v25, v27, v27
	v_mul_f32_e32 v37, 0x3f4c422a, v37
	v_fmac_f32_e32 v25, v26, v26
	v_mul_f32_e32 v37, 0xc038aa3b, v37
	v_add_f32_e32 v28, v25, v28
	v_cvt_pk_bf16_f32 v24, v41, v24
	v_cvt_pk_bf16_f32 v25, v45, v26
	v_cvt_pk_bf16_f32 v26, v38, v40
	v_exp_f32_e32 v37, v37
	v_mul_f32_e32 v39, 0x3d372713, v22
	v_mul_f32_e32 v40, 0x3d372713, v18
	v_mul_f32_e32 v39, v22, v39
	v_mul_f32_e32 v40, v18, v40
	v_fma_f32 v39, v22, v39, v22
	v_fma_f32 v40, v18, v40, v18
	v_mul_f32_e32 v31, 0x3d372713, v16
	v_mul_f32_e32 v39, 0x3f4c422a, v39
	v_mul_f32_e32 v40, 0x3f4c422a, v40
	v_mul_f32_e32 v30, 0x3d372713, v20
	v_mul_f32_e32 v31, v16, v31
	v_add_f32_e32 v37, 1.0, v37
	v_mul_f32_e32 v39, 0xc038aa3b, v39
	v_mul_f32_e32 v40, 0xc038aa3b, v40
	v_mul_f32_e32 v30, v20, v30
	v_fma_f32 v31, v16, v31, v16
	v_mul_f32_e32 v36, 0x3d372713, v21
	v_rcp_f32_e32 v37, v37
	v_exp_f32_e32 v39, v39
	v_exp_f32_e32 v40, v40
	v_mul_f32_e32 v41, 0x3d372713, v19
	v_fma_f32 v30, v20, v30, v20
	v_mul_f32_e32 v31, 0x3f4c422a, v31
	v_mul_f32_e32 v36, v21, v36
	v_mul_f32_e32 v41, v19, v41
	v_mul_f32_e32 v30, 0x3f4c422a, v30
	v_mul_f32_e32 v31, 0xc038aa3b, v31
	v_fma_f32 v36, v21, v36, v21
	v_fma_f32 v41, v19, v41, v19
	v_mul_f32_e32 v30, 0xc038aa3b, v30
	v_exp_f32_e32 v31, v31
	v_mul_f32_e32 v36, 0x3f4c422a, v36
	v_mul_f32_e32 v41, 0x3f4c422a, v41
	v_exp_f32_e32 v30, v30
	v_mul_f32_e32 v36, 0xc038aa3b, v36
	v_mul_f32_e32 v37, v17, v37
	v_add_f32_e32 v17, 1.0, v39
	v_add_f32_e32 v39, 1.0, v40
	v_mul_f32_e32 v40, 0x3d372713, v23
	v_mul_f32_e32 v41, 0xc038aa3b, v41
	v_exp_f32_e32 v36, v36
	v_mul_f32_e32 v40, v23, v40
	v_exp_f32_e32 v41, v41
	v_fma_f32 v40, v23, v40, v23
	v_add_f32_e32 v31, 1.0, v31
	v_mul_f32_e32 v40, 0x3f4c422a, v40
	v_add_f32_e32 v30, 1.0, v30
	v_rcp_f32_e32 v31, v31
	v_mul_f32_e32 v40, 0xc038aa3b, v40
	v_rcp_f32_e32 v30, v30
	v_add_f32_e32 v36, 1.0, v36
	v_exp_f32_e32 v40, v40
	v_rcp_f32_e32 v39, v39
	v_add_f32_e32 v41, 1.0, v41
	v_rcp_f32_e32 v36, v36
	v_rcp_f32_e32 v41, v41
	v_rcp_f32_e32 v17, v17
	v_mul_f32_e32 v31, v16, v31
	v_add_f32_e32 v40, 1.0, v40
	v_mul_f32_e32 v39, v18, v39
	v_fma_f32 v18, v20, v30, v31
	v_mul_f32_e32 v38, v20, v30
	v_rcp_f32_e32 v40, v40
	v_mul_f32_e32 v41, v19, v41
	v_add_f32_e32 v18, v18, v29
	v_mul_f32_e32 v19, v31, v31
	v_fma_f32 v20, v21, v36, v37
	v_cvt_pk_bf16_f32 v27, v42, v27
	v_mul_f32_e32 v16, v21, v36
	v_mul_f32_e32 v42, v22, v17
	v_fmac_f32_e32 v19, v38, v38
	v_add_f32_e32 v18, v20, v18
	v_mul_f32_e32 v20, v37, v37
	v_fma_f32 v17, v22, v17, v39
	v_add_f32_e32 v19, v19, v28
	v_fmac_f32_e32 v20, v16, v16
	v_add_f32_e32 v17, v17, v18
	v_mul_f32_e32 v18, v39, v39
	v_add_f32_e32 v19, v20, v19
	v_fmac_f32_e32 v18, v42, v42
	v_add_f32_e32 v18, v18, v19
	v_fma_f32 v19, v23, v40, v41
	v_mul_f32_e32 v43, v23, v40
	v_add_f32_e32 v17, v19, v17
	v_mul_f32_e32 v19, v41, v41
	v_fmac_f32_e32 v19, v43, v43
	v_add_f32_e32 v18, v19, v18
	v_mov_b32_e32 v21, v17
	s_nop 1
	v_permlane16_swap_b32_e32 v21, v17
	v_mov_b32_e32 v19, v18
	s_nop 1
	v_permlane16_swap_b32_e32 v19, v18
	v_lshl_add_u64 v[34:35], s[70:71], 0, v[34:35]
	v_lshl_add_u64 v[34:35], v[160:161], 1, v[34:35]
	global_store_dwordx4 v[34:35], v[24:27], off nt
	v_cvt_pk_bf16_f32 v20, v38, v16
	s_waitcnt lgkmcnt(0)
	v_add_f32_e32 v16, v17, v21
	v_add_f32_e32 v18, v18, v19
	v_mov_b32_e32 v17, v16
	s_nop 1
	v_permlane32_swap_b32_e32 v17, v16
	v_mov_b32_e32 v19, v18
	s_nop 1
	v_permlane32_swap_b32_e32 v19, v18
	v_cvt_pk_bf16_f32 v21, v42, v43
	v_cvt_pk_bf16_f32 v22, v31, v37
	v_cvt_pk_bf16_f32 v23, v39, v41
	global_store_dwordx4 v[34:35], v[20:23], off offset:256 nt
	s_and_saveexec_b64 s[6:7], s[58:59]
	s_cbranch_execz .LBB0_597
	s_waitcnt lgkmcnt(0)
	v_add_f32_e32 v18, v18, v19
	v_add_f32_e32 v19, v16, v17
	s_lshl_b32 s4, s95, 2
	v_lshlrev_b64 v[16:17], 7, v[32:33]
	s_add_i32 s38, s4, -16
	v_lshl_add_u64 v[16:17], s[72:73], 0, v[16:17]
	v_lshl_add_u64 v[16:17], s[38:39], 2, v[16:17]
	s_lshl_b32 s38, s8, 2
	v_lshl_add_u64 v[16:17], v[16:17], 0, s[38:39]
	global_store_dword v[16:17], v19, off
	global_store_dword v[16:17], v18, off offset:64
.LBB0_597:
	s_or_b64 exec, exec, s[6:7]
	v_add_u32_e32 v16, 0xb0, v158
	s_mov_b64 s[6:7], -1
	s_and_b64 vcc, exec, s[56:57]
	s_waitcnt lgkmcnt(0)
	v_ashrrev_i32_e32 v17, 31, v16
	s_cbranch_vccz .LBB0_599
	v_lshlrev_b64 v[18:19], 6, v[16:17]
	v_lshl_add_u64 v[18:19], s[48:49], 0, v[18:19]
	v_lshl_add_u64 v[18:19], v[18:19], 0, v[140:141]
	flat_load_dwordx4 v[18:21], v[18:19]
	s_mov_b64 s[6:7], 0
	s_waitcnt vmcnt(0) lgkmcnt(0)
	v_mov_b32_e32 v22, v19
	v_mov_b32_e32 v23, v20
	v_mov_b32_e32 v19, v21
	v_pk_add_f32 v[18:19], v[22:23], v[18:19]
	s_nop 0
	v_add_f32_e32 v18, v18, v19
	v_mov_b32_e32 v19, v18
	s_nop 1
	v_permlane16_swap_b32_e32 v19, v18
	s_waitcnt lgkmcnt(0)
	v_add_f32_e32 v18, v18, v19
	v_mov_b32_e32 v19, v18
	s_nop 1
	v_permlane32_swap_b32_e32 v19, v18
	s_waitcnt lgkmcnt(0)
	v_add_f32_e32 v18, v18, v19
	v_fmamk_f32 v18, v18, 0x3a800000, v250
	v_rsq_f32_e32 v20, v18

.LBB0_601:
	s_waitcnt lgkmcnt(0)
	v_pk_mul_f32 v[12:13], v[12:13], v[20:21] op_sel_hi:[1,0]
	v_lshlrev_b64 v[18:19], 12, v[16:17]
	v_mul_f32_e32 v21, 0x3d372713, v12
	v_mul_f32_e32 v21, v12, v21
	v_fma_f32 v21, v12, v21, v12
	v_mul_f32_e32 v21, 0x3f4c422a, v21
	v_mul_f32_e32 v21, 0xc038aa3b, v21
	v_exp_f32_e32 v21, v21
	v_mul_f32_e32 v23, 0x3d372713, v13
	v_mul_f32_e32 v23, v13, v23
	v_fma_f32 v23, v13, v23, v13
	v_pk_mul_f32 v[8:9], v[8:9], v[20:21] op_sel_hi:[1,0]
	v_pk_mul_f32 v[14:15], v[14:15], v[20:21] op_sel_hi:[1,0]
	v_mul_f32_e32 v24, 0x3d372713, v9
	v_mul_f32_e32 v24, v9, v24
	v_fma_f32 v24, v9, v24, v9
	v_mul_f32_e32 v24, 0x3f4c422a, v24
	v_pk_mul_f32 v[10:11], v[10:11], v[20:21] op_sel_hi:[1,0]
	v_mul_f32_e32 v24, 0xc038aa3b, v24
	v_exp_f32_e32 v24, v24
	v_mul_f32_e32 v26, 0x3d372713, v14
	v_mul_f32_e32 v27, 0x3d372713, v10
	v_mul_f32_e32 v26, v14, v26
	v_mul_f32_e32 v27, v10, v27
	v_mul_f32_e32 v22, 0x3d372713, v8
	v_fma_f32 v26, v14, v26, v14
	v_fma_f32 v27, v10, v27, v10
	v_mul_f32_e32 v22, v8, v22
	v_mul_f32_e32 v26, 0x3f4c422a, v26
	v_mul_f32_e32 v27, 0x3f4c422a, v27
	v_fma_f32 v22, v8, v22, v8
	v_add_f32_e32 v24, 1.0, v24
	v_mul_f32_e32 v26, 0xc038aa3b, v26
	v_mul_f32_e32 v27, 0xc038aa3b, v27
	v_mul_f32_e32 v22, 0x3f4c422a, v22
	v_rcp_f32_e32 v24, v24
	v_exp_f32_e32 v26, v26
	v_exp_f32_e32 v27, v27
	v_mul_f32_e32 v22, 0xc038aa3b, v22
	v_exp_f32_e32 v22, v22
	v_mul_f32_e32 v23, 0x3f4c422a, v23
	v_mul_f32_e32 v23, 0xc038aa3b, v23
	v_mul_f32_e32 v28, 0x3d372713, v11
	v_exp_f32_e32 v23, v23
	v_mul_f32_e32 v24, v9, v24
	v_add_f32_e32 v9, 1.0, v26
	v_add_f32_e32 v26, 1.0, v27
	v_mul_f32_e32 v27, 0x3d372713, v15
	v_mul_f32_e32 v28, v11, v28
	v_mul_f32_e32 v27, v15, v27
	v_fma_f32 v28, v11, v28, v11
	v_add_f32_e32 v22, 1.0, v22
	v_fma_f32 v27, v15, v27, v15
	v_mul_f32_e32 v28, 0x3f4c422a, v28
	v_add_f32_e32 v21, 1.0, v21
	v_rcp_f32_e32 v22, v22
	v_mul_f32_e32 v27, 0x3f4c422a, v27
	v_mul_f32_e32 v28, 0xc038aa3b, v28
	v_rcp_f32_e32 v21, v21
	v_add_f32_e32 v23, 1.0, v23
	v_mul_f32_e32 v27, 0xc038aa3b, v27
	v_exp_f32_e32 v28, v28
	v_rcp_f32_e32 v23, v23
	v_exp_f32_e32 v27, v27
	v_rcp_f32_e32 v26, v26
	v_mul_f32_e32 v22, v8, v22
	v_rcp_f32_e32 v9, v9
	v_mul_f32_e32 v25, v12, v21
	v_add_f32_e32 v28, 1.0, v28
	v_fma_f32 v12, v12, v21, v22
	v_mul_f32_e32 v8, v13, v23
	v_add_f32_e32 v27, 1.0, v27
	v_rcp_f32_e32 v28, v28
	v_add_f32_e32 v12, 0, v12
	v_mul_f32_e32 v21, v22, v22
	v_fma_f32 v13, v13, v23, v24
	v_rcp_f32_e32 v27, v27
	v_mul_f32_e32 v26, v10, v26
	v_fmac_f32_e32 v21, v25, v25
	v_add_f32_e32 v12, v13, v12
	v_mul_f32_e32 v13, v24, v24
	v_mul_f32_e32 v29, v14, v9
	v_fmac_f32_e32 v13, v8, v8
	v_fma_f32 v9, v14, v9, v26
	v_pk_mul_f32 v[0:1], v[0:1], v[20:21] op_sel_hi:[1,0]
	v_add_f32_e32 v13, v21, v13
	v_add_f32_e32 v9, v9, v12
	v_mul_f32_e32 v12, v26, v26
	v_pk_mul_f32 v[4:5], v[4:5], v[20:21] op_sel_hi:[1,0]
	v_pk_mul_f32 v[6:7], v[6:7], v[20:21] op_sel_hi:[1,0]
	v_pk_mul_f32 v[2:3], v[2:3], v[20:21] op_sel_hi:[1,0]
	v_mul_f32_e32 v21, 0x3d372713, v1
	v_mul_f32_e32 v11, v11, v28
	v_fmac_f32_e32 v12, v29, v29
	v_mul_f32_e32 v21, v1, v21
	v_add_f32_e32 v12, v12, v13
	v_fma_f32 v13, v15, v27, v11
	v_fma_f32 v21, v1, v21, v1
	v_mul_f32_e32 v10, v15, v27
	v_add_f32_e32 v13, v13, v9
	v_mul_f32_e32 v9, v11, v11
	v_mul_f32_e32 v21, 0x3f4c422a, v21
	v_fmac_f32_e32 v9, v10, v10
	v_mul_f32_e32 v21, 0xc038aa3b, v21
	v_add_f32_e32 v12, v9, v12
	v_cvt_pk_bf16_f32 v8, v25, v8
	v_cvt_pk_bf16_f32 v9, v29, v10
	v_cvt_pk_bf16_f32 v10, v22, v24
	v_exp_f32_e32 v21, v21
	v_mul_f32_e32 v23, 0x3d372713, v6
	v_mul_f32_e32 v24, 0x3d372713, v2
	v_mul_f32_e32 v23, v6, v23
	v_mul_f32_e32 v24, v2, v24
	v_fma_f32 v23, v6, v23, v6
	v_fma_f32 v24, v2, v24, v2
	v_mul_f32_e32 v15, 0x3d372713, v0
	v_mul_f32_e32 v23, 0x3f4c422a, v23
	v_mul_f32_e32 v24, 0x3f4c422a, v24
	v_mul_f32_e32 v14, 0x3d372713, v4
	v_mul_f32_e32 v15, v0, v15
	v_add_f32_e32 v21, 1.0, v21
	v_mul_f32_e32 v23, 0xc038aa3b, v23
	v_mul_f32_e32 v24, 0xc038aa3b, v24
	v_mul_f32_e32 v14, v4, v14
	v_fma_f32 v15, v0, v15, v0
	v_mul_f32_e32 v20, 0x3d372713, v5
	v_rcp_f32_e32 v21, v21
	v_exp_f32_e32 v23, v23
	v_exp_f32_e32 v24, v24
	v_mul_f32_e32 v25, 0x3d372713, v3
	v_fma_f32 v14, v4, v14, v4
	v_mul_f32_e32 v15, 0x3f4c422a, v15
	v_mul_f32_e32 v20, v5, v20
	v_mul_f32_e32 v25, v3, v25
	v_mul_f32_e32 v14, 0x3f4c422a, v14
	v_mul_f32_e32 v15, 0xc038aa3b, v15
	v_fma_f32 v20, v5, v20, v5
	v_fma_f32 v25, v3, v25, v3
	v_mul_f32_e32 v14, 0xc038aa3b, v14
	v_exp_f32_e32 v15, v15
	v_mul_f32_e32 v20, 0x3f4c422a, v20
	v_mul_f32_e32 v25, 0x3f4c422a, v25
	v_exp_f32_e32 v14, v14
	v_mul_f32_e32 v20, 0xc038aa3b, v20
	v_mul_f32_e32 v21, v1, v21
	v_add_f32_e32 v1, 1.0, v23
	v_add_f32_e32 v23, 1.0, v24
	v_mul_f32_e32 v24, 0x3d372713, v7
	v_mul_f32_e32 v25, 0xc038aa3b, v25
	v_exp_f32_e32 v20, v20
	v_mul_f32_e32 v24, v7, v24
	v_exp_f32_e32 v25, v25
	v_fma_f32 v24, v7, v24, v7
	v_add_f32_e32 v15, 1.0, v15
	v_mul_f32_e32 v24, 0x3f4c422a, v24
	v_add_f32_e32 v14, 1.0, v14
	v_rcp_f32_e32 v15, v15
	v_mul_f32_e32 v24, 0xc038aa3b, v24
	v_rcp_f32_e32 v14, v14
	v_add_f32_e32 v20, 1.0, v20
	v_exp_f32_e32 v24, v24
	v_rcp_f32_e32 v23, v23
	v_add_f32_e32 v25, 1.0, v25
	v_rcp_f32_e32 v20, v20
	v_rcp_f32_e32 v25, v25
	v_rcp_f32_e32 v1, v1
	v_mul_f32_e32 v15, v0, v15
	v_add_f32_e32 v24, 1.0, v24
	v_mul_f32_e32 v23, v2, v23
	v_fma_f32 v2, v4, v14, v15
	v_mul_f32_e32 v22, v4, v14
	v_rcp_f32_e32 v24, v24
	v_mul_f32_e32 v25, v3, v25
	v_add_f32_e32 v2, v2, v13
	v_mul_f32_e32 v3, v15, v15
	v_fma_f32 v4, v5, v20, v21
	v_cvt_pk_bf16_f32 v11, v26, v11
	v_mul_f32_e32 v0, v5, v20
	v_mul_f32_e32 v26, v6, v1
	v_fmac_f32_e32 v3, v22, v22
	v_add_f32_e32 v2, v4, v2
	v_mul_f32_e32 v4, v21, v21
	v_fma_f32 v1, v6, v1, v23
	v_add_f32_e32 v3, v3, v12
	v_fmac_f32_e32 v4, v0, v0
	v_add_f32_e32 v1, v1, v2
	v_mul_f32_e32 v2, v23, v23
	v_add_f32_e32 v3, v4, v3
	v_fmac_f32_e32 v2, v26, v26
	v_add_f32_e32 v2, v2, v3
	v_fma_f32 v3, v7, v24, v25
	v_mul_f32_e32 v27, v7, v24
	v_add_f32_e32 v1, v3, v1
	v_mul_f32_e32 v3, v25, v25
	v_fmac_f32_e32 v3, v27, v27
	v_add_f32_e32 v2, v3, v2
	v_mov_b32_e32 v5, v1
	s_nop 1
	v_permlane16_swap_b32_e32 v5, v1
	v_mov_b32_e32 v3, v2
	s_nop 1
	v_permlane16_swap_b32_e32 v3, v2
	v_lshl_add_u64 v[18:19], s[70:71], 0, v[18:19]
	v_lshl_add_u64 v[18:19], v[160:161], 1, v[18:19]
	global_store_dwordx4 v[18:19], v[8:11], off nt
	v_cvt_pk_bf16_f32 v4, v22, v0
	s_waitcnt lgkmcnt(0)
	v_add_f32_e32 v0, v1, v5
	v_add_f32_e32 v2, v2, v3
	v_mov_b32_e32 v1, v0
	s_nop 1
	v_permlane32_swap_b32_e32 v1, v0
	v_mov_b32_e32 v3, v2
	s_nop 1
	v_permlane32_swap_b32_e32 v3, v2
	v_cvt_pk_bf16_f32 v5, v26, v27
	v_cvt_pk_bf16_f32 v6, v15, v21
	v_cvt_pk_bf16_f32 v7, v23, v25
	global_store_dwordx4 v[18:19], v[4:7], off offset:256 nt
	s_and_saveexec_b64 s[6:7], s[58:59]
	s_cbranch_execz .LBB0_603
	s_waitcnt lgkmcnt(0)
	v_add_f32_e32 v2, v2, v3
	v_add_f32_e32 v3, v0, v1
	s_lshl_b32 s4, s95, 2
	v_lshlrev_b64 v[0:1], 7, v[16:17]
	s_add_i32 s38, s4, -16
	v_lshl_add_u64 v[0:1], s[72:73], 0, v[0:1]
	v_lshl_add_u64 v[0:1], s[38:39], 2, v[0:1]
	s_lshl_b32 s38, s8, 2
	v_lshl_add_u64 v[0:1], v[0:1], 0, s[38:39]
	global_store_dword v[0:1], v3, off
	global_store_dword v[0:1], v2, off offset:64

.LBB0_809:
	global_load_dwordx4 v[12:15], v[18:19], off offset:-3072
	global_load_dwordx4 v[0:3], v[18:19], off offset:-2048
	global_load_dwordx4 v[4:7], v[18:19], off offset:-1024
	global_load_dwordx4 v[8:11], v[18:19], off
	s_waitcnt vmcnt(3)
	v_mul_f32_e32 v26, v13, v13
	v_mul_f32_e32 v27, v15, v15
	s_waitcnt vmcnt(2)
	v_mul_f32_e32 v28, v1, v1
	v_mul_f32_e32 v29, v3, v3
	s_waitcnt vmcnt(1)
	v_mul_f32_e32 v30, v5, v5
	v_mul_f32_e32 v31, v7, v7
	v_fmac_f32_e32 v26, v12, v12
	v_fmac_f32_e32 v27, v14, v14
	v_fmac_f32_e32 v28, v0, v0
	v_fmac_f32_e32 v29, v2, v2
	s_waitcnt vmcnt(0)
	v_mul_f32_e32 v32, v9, v9
	v_mul_f32_e32 v33, v11, v11
	v_fmac_f32_e32 v30, v4, v4
	v_fmac_f32_e32 v31, v6, v6
	v_add_f32_e32 v26, v26, v27
	v_add_f32_e32 v27, v28, v29
	v_fmac_f32_e32 v32, v8, v8
	v_fmac_f32_e32 v33, v10, v10
	v_add_f32_e32 v28, v30, v31
	v_add_f32_e32 v26, v26, v27
	v_add_f32_e32 v26, v26, v28
	v_add_f32_e32 v27, v32, v33
	v_add_f32_e32 v26, v26, v27
	ds_bpermute_b32 v27, v20, v26
	s_waitcnt lgkmcnt(0)
	v_add_f32_e32 v26, v26, v27
	ds_bpermute_b32 v27, v21, v26
	s_waitcnt lgkmcnt(0)
	v_add_f32_e32 v26, v26, v27
	ds_bpermute_b32 v27, v22, v26
	s_waitcnt lgkmcnt(0)
	v_add_f32_e32 v26, v26, v27
	ds_bpermute_b32 v27, v23, v26
	s_waitcnt lgkmcnt(0)
	v_add_f32_e32 v26, v26, v27
	v_mov_b32_e32 v27, v26
	s_nop 1
	v_permlane16_swap_b32_e32 v27, v26
	s_waitcnt lgkmcnt(0)
	v_add_f32_e32 v26, v26, v27
	v_mov_b32_e32 v27, v26
	s_nop 1
	v_permlane32_swap_b32_e32 v27, v26
	s_and_saveexec_b64 s[0:1], s[40:41]
	s_cbranch_execz .LBB0_808
	s_waitcnt lgkmcnt(0)
	v_add_f32_e32 v26, v26, v27
	v_fmamk_f32 v26, v26, 0x3a800000, v250
	v_mul_f32_e32 v27, 0x4f800000, v26
	v_cmp_gt_f32_e32 vcc, s94, v26
	s_nop 1
	v_cndmask_b32_e32 v26, v26, v27, vcc
	v_sqrt_f32_e32 v27, v26
	s_nop 0
	v_add_u32_e32 v28, -1, v27
	v_fma_f32 v30, -v28, v27, v26
	v_add_u32_e32 v29, 1, v27
	v_cmp_ge_f32_e64 s[42:43], 0, v30
	s_nop 1
	v_cndmask_b32_e64 v28, v27, v28, s[42:43]
	v_fma_f32 v27, -v29, v27, v26
	v_cmp_lt_f32_e64 s[42:43], 0, v27
	s_nop 1
	v_cndmask_b32_e64 v27, v28, v29, s[42:43]
	v_mul_f32_e32 v28, 0x37800000, v27
	v_cndmask_b32_e32 v27, v27, v28, vcc
	v_cmp_class_f32_e32 vcc, v26, v251
	s_nop 1
	v_cndmask_b32_e32 v26, v27, v26, vcc
	v_div_scale_f32 v27, s[8:9], v26, v26, 1.0
	v_rcp_f32_e32 v28, v27
	s_add_u32 s8, s86, s4
	s_addc_u32 s9, s87, s5
	v_fma_f32 v29, -v27, v28, 1.0
	v_fmac_f32_e32 v28, v29, v28
	v_div_scale_f32 v29, vcc, 1.0, v26, 1.0
	v_mul_f32_e32 v30, v29, v28
	v_fma_f32 v31, -v27, v30, v29
	v_fmac_f32_e32 v30, v31, v28
	v_fma_f32 v27, -v27, v30, v29
	v_div_fmas_f32 v27, v27, v28, v30
	v_div_fixup_f32 v26, v27, v26, 1.0
	global_store_dword v141, v26, s[8:9]
	s_branch .LBB0_808

.Lxs_nopf:
	v_mul_f32_e32 v11, v11, v11
	v_mul_f32_e32 v13, v13, v13
	v_mul_f32_e32 v15, v15, v15
	v_mul_f32_e32 v17, v17, v17
	v_mul_f32_e32 v19, v19, v19
	v_mul_f32_e32 v21, v21, v21
	v_fmac_f32_e32 v11, v10, v10
	v_fmac_f32_e32 v13, v12, v12
	v_mul_f32_e32 v10, v27, v27
	v_mul_f32_e32 v12, v29, v29
	v_fmac_f32_e32 v15, v14, v14
	v_fmac_f32_e32 v17, v16, v16
	v_mul_f32_e32 v14, v31, v31
	v_mul_f32_e32 v16, v33, v33
	v_mul_f32_e32 v23, v23, v23
	v_mul_f32_e32 v25, v25, v25
	v_fmac_f32_e32 v19, v18, v18
	v_fmac_f32_e32 v21, v20, v20
	v_mul_f32_e32 v18, v35, v35
	v_mul_f32_e32 v20, v37, v37
	v_fmac_f32_e32 v10, v26, v26
	v_fmac_f32_e32 v12, v28, v28
	v_fmac_f32_e32 v14, v30, v30
	v_fmac_f32_e32 v16, v32, v32
	v_fmac_f32_e32 v23, v22, v22
	v_fmac_f32_e32 v25, v24, v24
	v_mul_f32_e32 v22, v39, v39
	v_mul_f32_e32 v24, v41, v41
	v_add_f32_e32 v11, v11, v13
	v_add_f32_e32 v13, v15, v17
	v_fmac_f32_e32 v18, v34, v34
	v_fmac_f32_e32 v20, v36, v36
	v_add_f32_e32 v10, v10, v12
	v_add_f32_e32 v12, v14, v16
	v_add_f32_e32 v15, v19, v21
	v_fmac_f32_e32 v22, v38, v38
	v_fmac_f32_e32 v24, v40, v40
	v_add_f32_e32 v11, v11, v13
	v_add_f32_e32 v13, v18, v20
	v_add_f32_e32 v10, v10, v12
	v_add_f32_e32 v17, v23, v25
	v_add_f32_e32 v14, v22, v24
	v_add_f32_e32 v11, v11, v15
	v_add_f32_e32 v10, v10, v13
	v_add_f32_e32 v11, v11, v17
	v_add_f32_e32 v10, v10, v14
	ds_bpermute_b32 v12, v4, v11
	ds_bpermute_b32 v13, v4, v10
	s_waitcnt lgkmcnt(1)
	v_add_f32_e32 v11, v11, v12
	s_waitcnt lgkmcnt(0)
	v_add_f32_e32 v10, v10, v13
	ds_bpermute_b32 v12, v5, v11
	ds_bpermute_b32 v13, v5, v10
	s_waitcnt lgkmcnt(1)
	v_add_f32_e32 v11, v11, v12
	s_waitcnt lgkmcnt(0)
	v_add_f32_e32 v10, v10, v13
	ds_bpermute_b32 v12, v6, v11
	ds_bpermute_b32 v13, v6, v10
	s_waitcnt lgkmcnt(1)
	v_add_f32_e32 v11, v11, v12
	s_waitcnt lgkmcnt(0)
	v_add_f32_e32 v10, v10, v13
	ds_bpermute_b32 v12, v7, v11
	ds_bpermute_b32 v13, v7, v10
	s_waitcnt lgkmcnt(1)
	v_add_f32_e32 v11, v11, v12
	s_waitcnt lgkmcnt(0)
	v_add_f32_e32 v10, v10, v13
	v_mov_b32_e32 v12, v11
	s_nop 1
	v_permlane16_swap_b32_e32 v12, v11
	v_mov_b32_e32 v14, v10
	s_nop 1
	v_permlane16_swap_b32_e32 v14, v10
	s_waitcnt lgkmcnt(1)
	v_add_f32_e32 v12, v11, v12
	s_waitcnt lgkmcnt(0)
	v_add_f32_e32 v10, v10, v14
	v_mov_b32_e32 v13, v12
	s_nop 1
	v_permlane32_swap_b32_e32 v13, v12
	v_mov_b32_e32 v11, v10
	s_nop 1
	v_permlane32_swap_b32_e32 v11, v10
	s_and_saveexec_b64 s[8:9], vcc
	s_cbranch_execz .LBB0_813
	s_waitcnt lgkmcnt(1)
	v_add_f32_e32 v12, v12, v13
	s_lshl_b64 s[10:11], s[6:7], 6
	v_cndmask_b32_e64 v14, 0, v12, s[40:41]
	v_lshl_add_u64 v[12:13], v[2:3], 0, s[10:11]
	s_cmp_eq_u32 s6, s0
	global_store_dword v[12:13], v14, off
	s_cbranch_scc1 .LBB0_813
	s_waitcnt lgkmcnt(0)
	v_add_f32_e32 v10, v10, v11
	s_lshl_b64 s[0:1], s[0:1], 6
	v_cndmask_b32_e64 v12, 0, v10, s[40:41]
	v_lshl_add_u64 v[10:11], v[2:3], 0, s[0:1]
	global_store_dword v[10:11], v12, off
	s_branch .LBB0_813
